# EpiResid row sum-of-squares: ds_bpermute butterfly replaced by DPP adds (3 GEMM epilogues), on top of rotated k-loops
# speedup vs baseline: 1.0338x; 1.0032x over previous
; #define MFMA16(a, b, c) __builtin_amdgcn_mfma_f32_16x16x32_bf16((a), (b), (c), 0, 0, 0)
; DI bf16x8 ldfrag(const char* lds, int row, int chunk) { return *(const bf16x8*)(lds + swz(row, chunk)); }
; #define GEMM_SG1() do { __builtin_amdgcn_sched_group_barrier(0x100, 1, 0); __builtin_amdgcn_sched_group_barrier(0x008, 4, 0); } while (0)
; template <bool RSTD, bool SWAP>
; DI void gemm_tile(gacc_t& acc, const bf16_t* __restrict__ A, int lda, const bf16_t* __restrict__ Bt, int ldb, int K,
;                   char* lds, int tid, int wr, int wc, int lane, const float* ssq_row) {
;     ...
;     GEMM_ISSUE(0, 0);
;     if (RSTD && tid < 256) {
;         const f32x4 q = *(const f32x4*)ssq_row;
;         ((float*)(lds + RSTD_OFF))[tid] = 1.0f / sqrtf(((q.x + q.y) + (q.z + q.w)) * (1.0f / 1024.0f) + 1e-6f);
;     }
;     asm volatile("s_waitcnt vmcnt(0)" ::: "memory");
;     __syncthreads();
;     for (int kt = 0; kt < nk; ++kt) {
;         const char* cur = lds + (kt & 1) * 65536;
;         if (kt + 1 < nk) GEMM_ISSUE(kt + 1, (kt + 1) & 1);
;         bf16x8 bfr[2][4], afr[3];
; #pragma unroll
;         for (int n = 0; n < 4; ++n) bfr[0][n] = ldfrag(cur + 32768, wc * 64 + n * 16 + fr, fq);
;         afr[0] = ldfrag(cur, wr * 128 + fr, fq);
;         afr[1] = ldfrag(cur, wr * 128 + 16 + fr, fq);
; #pragma unroll
;         for (int idx = 0; idx < 16; ++idx) {
;             const int ks = idx >> 3, m = idx & 7;
;             if (idx < 14) afr[(idx + 2) % 3] = ldfrag(cur, wr * 128 + ((idx + 2) & 7) * 16 + fr, ((idx + 2) >> 3) * 4 + fq);
;             if (ks == 0 && m >= 2 && m < 6) bfr[1][m - 2] = ldfrag(cur + 32768, wc * 64 + (m - 2) * 16 + fr, 4 + fq);
; #pragma unroll
;             for (int n = 0; n < 4; ++n) acc[m][n] = SWAP ? MFMA16(bfr[ks][n], afr[idx % 3], acc[m][n]) : MFMA16(afr[idx % 3], bfr[ks][n], acc[m][n]);
;         }
;         __builtin_amdgcn_sched_group_barrier(0x100, 6, 0);
;     ...
;         GEMM_SG1(); GEMM_SG1(); GEMM_SG2(); GEMM_SG2(); GEMM_SG2(); GEMM_SG2(); GEMM_SG1(); GEMM_SG1();
;         GEMM_SG1(); GEMM_SG1(); GEMM_SG1(); GEMM_SG1(); GEMM_SG1(); GEMM_SG1();
;         __builtin_amdgcn_sched_group_barrier(0x008, 8, 0);
;         __builtin_amdgcn_sched_barrier(0);
;         asm volatile("s_waitcnt vmcnt(0)" ::: "memory");
;         __syncthreads();
.LBB0_281:
	v_lshl_add_u64 v[158:159], v[136:137], 0, s[4:5]
	s_mov_b64 s[20:21], 0x1880080
	v_lshl_add_u64 v[162:163], v[158:159], 0, s[20:21]
	s_mov_b64 s[20:21], 0x18a0080
	s_add_i32 s18, s17, 0xffff0000
	s_and_b32 s19, s17, 0x10000
	v_lshl_add_u64 v[166:167], v[158:159], 0, s[20:21]
	s_mov_b64 s[20:21], 0x18c0080
	s_and_b32 s23, s18, 0x10000
	s_add_i32 s18, s19, 0
	v_lshl_add_u64 v[174:175], v[158:159], 0, s[20:21]
	s_mov_b64 s[20:21], 0x18e0080
	v_lshl_add_u64 v[156:157], v[138:139], 0, s[4:5]
	v_lshl_add_u64 v[158:159], v[158:159], 0, s[20:21]
	s_add_i32 s20, s18, s16
	v_lshl_add_u64 v[160:161], v[156:157], 0, s[14:15]
	s_add_i32 s21, s20, 0x8000
	s_mov_b32 m0, s20
	v_lshl_add_u64 v[164:165], v[156:157], 0, s[72:73]
	global_load_lds_dwordx4 v[160:161], off
	v_mfma_f32_16x16x32_bf16 v[60:63], v[194:197], v[236:239], v[60:63]
	s_mov_b32 m0, s21
	v_lshl_add_u64 v[172:173], v[156:157], 0, s[76:77]
	global_load_lds_dwordx4 v[162:163], off
	v_mfma_f32_16x16x32_bf16 v[56:59], v[198:201], v[236:239], v[56:59]
	s_add_i32 m0, s20, 0x2000
	v_lshl_add_u64 v[156:157], v[156:157], 0, s[0:1]
	global_load_lds_dwordx4 v[164:165], off
	v_mfma_f32_16x16x32_bf16 v[52:55], v[202:205], v[236:239], v[52:55]
	s_add_i32 m0, s20, 0xa000
	s_add_i32 s19, s23, 0
	global_load_lds_dwordx4 v[166:167], off
	v_mfma_f32_16x16x32_bf16 v[48:51], v[206:209], v[236:239], v[48:51]
	s_add_i32 m0, s20, 0x4000
	v_add_u32_e32 v146, s19, v142
	global_load_lds_dwordx4 v[172:173], off
	v_mfma_f32_16x16x32_bf16 v[44:47], v[194:197], v[240:243], v[44:47]
	s_add_i32 m0, s20, 0xc000
	v_add3_u32 v155, v146, v148, v149
	global_load_lds_dwordx4 v[174:175], off
	v_mfma_f32_16x16x32_bf16 v[40:43], v[198:201], v[240:243], v[40:43]
	s_add_i32 m0, s20, 0x6000
	v_add_u32_e32 v252, v146, v144
	global_load_lds_dwordx4 v[156:157], off
	v_mfma_f32_16x16x32_bf16 v[36:39], v[202:205], v[240:243], v[36:39]
	s_add_i32 m0, s20, 0xe000
	s_nop 0
	global_load_lds_dwordx4 v[158:159], off
	v_mfma_f32_16x16x32_bf16 v[32:35], v[206:209], v[240:243], v[32:35]
	ds_read_b128 v[156:159], v155 offset:32768
	ds_read_b128 v[160:163], v155 offset:34816
	ds_read_b128 v[172:175], v155 offset:36864
	ds_read_b128 v[176:179], v155 offset:38912
	ds_read_b128 v[164:167], v252
	ds_read_b128 v[180:183], v252 offset:2048
	ds_read_b128 v[190:193], v252 offset:4096
	v_add_u32_e32 v155, v146, v150
	v_mfma_f32_16x16x32_bf16 v[28:31], v[194:197], v[244:247], v[28:31]
	v_mfma_f32_16x16x32_bf16 v[24:27], v[198:201], v[244:247], v[24:27]
	v_mfma_f32_16x16x32_bf16 v[20:23], v[202:205], v[244:247], v[20:23]
	v_mfma_f32_16x16x32_bf16 v[16:19], v[206:209], v[244:247], v[16:19]
	v_mfma_f32_16x16x32_bf16 v[12:15], v[194:197], v[248:251], v[12:15]
	v_mfma_f32_16x16x32_bf16 v[8:11], v[198:201], v[248:251], v[8:11]
	v_mfma_f32_16x16x32_bf16 v[4:7], v[202:205], v[248:251], v[4:7]
	v_mfma_f32_16x16x32_bf16 v[0:3], v[206:209], v[248:251], v[0:3]
	s_waitcnt lgkmcnt(0)
	v_mfma_f32_16x16x32_bf16 v[124:127], v[156:159], v[164:167], v[124:127]
	v_add_u32_e32 v146, v146, v152
	v_mfma_f32_16x16x32_bf16 v[120:123], v[160:163], v[164:167], v[120:123]
	v_mfma_f32_16x16x32_bf16 v[116:119], v[172:175], v[164:167], v[116:119]
	v_mfma_f32_16x16x32_bf16 v[112:115], v[176:179], v[164:167], v[112:115]
	ds_read_b128 v[164:167], v155
	v_add_u32_e32 v155, s19, v145
	v_add_u32_e32 v203, v155, v151
	v_mfma_f32_16x16x32_bf16 v[108:111], v[156:159], v[180:183], v[108:111]
	v_add_u32_e32 v206, v155, v153
	v_mfma_f32_16x16x32_bf16 v[104:107], v[160:163], v[180:183], v[104:107]
	v_mfma_f32_16x16x32_bf16 v[100:103], v[172:175], v[180:183], v[100:103]
	v_mfma_f32_16x16x32_bf16 v[96:99], v[176:179], v[180:183], v[96:99]
	ds_read_b128 v[180:183], v252 offset:8192
	ds_read_b128 v[194:197], v203 offset:32768
	v_mfma_f32_16x16x32_bf16 v[92:95], v[156:159], v[190:193], v[92:95]
	v_mfma_f32_16x16x32_bf16 v[88:91], v[160:163], v[190:193], v[88:91]
	v_mfma_f32_16x16x32_bf16 v[84:87], v[172:175], v[190:193], v[84:87]
	v_mfma_f32_16x16x32_bf16 v[80:83], v[176:179], v[190:193], v[80:83]
	ds_read_b128 v[190:193], v252 offset:10240
	ds_read_b128 v[198:201], v203 offset:34816
	s_waitcnt lgkmcnt(0)
	v_mfma_f32_16x16x32_bf16 v[76:79], v[156:159], v[164:167], v[76:79]
	v_mfma_f32_16x16x32_bf16 v[72:75], v[160:163], v[164:167], v[72:75]
	v_mfma_f32_16x16x32_bf16 v[68:71], v[172:175], v[164:167], v[68:71]
	v_mfma_f32_16x16x32_bf16 v[64:67], v[176:179], v[164:167], v[64:67]
	ds_read_b128 v[164:167], v252 offset:12288
	ds_read_b128 v[202:205], v203 offset:36864
	v_mfma_f32_16x16x32_bf16 v[60:63], v[156:159], v[180:183], v[60:63]
	v_mfma_f32_16x16x32_bf16 v[56:59], v[160:163], v[180:183], v[56:59]
	v_mfma_f32_16x16x32_bf16 v[52:55], v[172:175], v[180:183], v[52:55]
	v_mfma_f32_16x16x32_bf16 v[48:51], v[176:179], v[180:183], v[48:51]
	ds_read_b128 v[206:209], v206 offset:38912
	ds_read_b128 v[180:183], v146
	v_add_u32_e32 v146, v155, v144
	v_mfma_f32_16x16x32_bf16 v[44:47], v[156:159], v[190:193], v[44:47]
	v_mfma_f32_16x16x32_bf16 v[40:43], v[160:163], v[190:193], v[40:43]
	v_mfma_f32_16x16x32_bf16 v[36:39], v[172:175], v[190:193], v[36:39]
	v_mfma_f32_16x16x32_bf16 v[32:35], v[176:179], v[190:193], v[32:35]
	ds_read_b128 v[190:193], v146
	s_waitcnt lgkmcnt(0)
; #define MFMA16(a, b, c) __builtin_amdgcn_mfma_f32_16x16x32_bf16((a), (b), (c), 0, 0, 0)
; DI bf16x8 ldfrag(const char* lds, int row, int chunk) { return *(const bf16x8*)(lds + swz(row, chunk)); }
; #define GEMM_SG1() do { __builtin_amdgcn_sched_group_barrier(0x100, 1, 0); __builtin_amdgcn_sched_group_barrier(0x008, 4, 0); } while (0)
; #define GEMM_SG2() do { __builtin_amdgcn_sched_group_barrier(0x100, 2, 0); __builtin_amdgcn_sched_group_barrier(0x008, 4, 0); } while (0)
; template <bool RSTD, bool SWAP>
; DI void gemm_tile(gacc_t& acc, const bf16_t* __restrict__ A, int lda, const bf16_t* __restrict__ Bt, int ldb, int K,
;                   char* lds, int tid, int wr, int wc, int lane, const float* ssq_row) {
;     ...
;     for (int kt = 0; kt < nk; ++kt) {
;         const char* cur = lds + (kt & 1) * 65536;
;         if (kt + 1 < nk) GEMM_ISSUE(kt + 1, (kt + 1) & 1);
;         bf16x8 bfr[2][4], afr[3];
; #pragma unroll
;         for (int n = 0; n < 4; ++n) bfr[0][n] = ldfrag(cur + 32768, wc * 64 + n * 16 + fr, fq);
;         afr[0] = ldfrag(cur, wr * 128 + fr, fq);
;         afr[1] = ldfrag(cur, wr * 128 + 16 + fr, fq);
; #pragma unroll
;         for (int idx = 0; idx < 16; ++idx) {
;             const int ks = idx >> 3, m = idx & 7;
;             if (idx < 14) afr[(idx + 2) % 3] = ldfrag(cur, wr * 128 + ((idx + 2) & 7) * 16 + fr, ((idx + 2) >> 3) * 4 + fq);
;             if (ks == 0 && m >= 2 && m < 6) bfr[1][m - 2] = ldfrag(cur + 32768, wc * 64 + (m - 2) * 16 + fr, 4 + fq);
; #pragma unroll
;             for (int n = 0; n < 4; ++n) acc[m][n] = SWAP ? MFMA16(bfr[ks][n], afr[idx % 3], acc[m][n]) : MFMA16(afr[idx % 3], bfr[ks][n], acc[m][n]);
;         }
;         __builtin_amdgcn_sched_group_barrier(0x100, 6, 0);
;     ...
;         GEMM_SG1(); GEMM_SG1(); GEMM_SG2(); GEMM_SG2(); GEMM_SG2(); GEMM_SG2(); GEMM_SG1(); GEMM_SG1();
;         GEMM_SG1(); GEMM_SG1(); GEMM_SG1(); GEMM_SG1(); GEMM_SG1(); GEMM_SG1();
;         __builtin_amdgcn_sched_group_barrier(0x008, 8, 0);
;         __builtin_amdgcn_sched_barrier(0);
;         asm volatile("s_waitcnt vmcnt(0)" ::: "memory");
;         __syncthreads();
	v_mfma_f32_16x16x32_bf16 v[28:31], v[156:159], v[164:167], v[28:31]
	v_mfma_f32_16x16x32_bf16 v[24:27], v[160:163], v[164:167], v[24:27]
	v_mfma_f32_16x16x32_bf16 v[20:23], v[172:175], v[164:167], v[20:23]
	v_mfma_f32_16x16x32_bf16 v[16:19], v[176:179], v[164:167], v[16:19]
	ds_read_b128 v[164:167], v146 offset:2048
	v_mfma_f32_16x16x32_bf16 v[8:11], v[160:163], v[180:183], v[8:11]
	v_add_u32_e32 v160, v155, v150
	v_mfma_f32_16x16x32_bf16 v[12:15], v[156:159], v[180:183], v[12:15]
	v_mfma_f32_16x16x32_bf16 v[4:7], v[172:175], v[180:183], v[4:7]
	v_mfma_f32_16x16x32_bf16 v[0:3], v[176:179], v[180:183], v[0:3]
	ds_read_b128 v[156:159], v146 offset:4096
	v_mfma_f32_16x16x32_bf16 v[124:127], v[194:197], v[190:193], v[124:127]
	v_mfma_f32_16x16x32_bf16 v[120:123], v[198:201], v[190:193], v[120:123]
	v_mfma_f32_16x16x32_bf16 v[116:119], v[202:205], v[190:193], v[116:119]
	v_mfma_f32_16x16x32_bf16 v[112:115], v[206:209], v[190:193], v[112:115]
	ds_read_b128 v[160:163], v160
	s_waitcnt lgkmcnt(0)
	v_mfma_f32_16x16x32_bf16 v[108:111], v[194:197], v[164:167], v[108:111]
	v_mfma_f32_16x16x32_bf16 v[104:107], v[198:201], v[164:167], v[104:107]
	v_mfma_f32_16x16x32_bf16 v[100:103], v[202:205], v[164:167], v[100:103]
	v_mfma_f32_16x16x32_bf16 v[96:99], v[206:209], v[164:167], v[96:99]
	ds_read_b128 v[236:239], v146 offset:8192
	v_mfma_f32_16x16x32_bf16 v[92:95], v[194:197], v[156:159], v[92:95]
	v_mfma_f32_16x16x32_bf16 v[88:91], v[198:201], v[156:159], v[88:91]
	v_mfma_f32_16x16x32_bf16 v[84:87], v[202:205], v[156:159], v[84:87]
	v_mfma_f32_16x16x32_bf16 v[80:83], v[206:209], v[156:159], v[80:83]
	ds_read_b128 v[240:243], v146 offset:10240
	ds_read_b128 v[244:247], v146 offset:12288
	v_add_u32_e32 v146, v155, v152
	ds_read_b128 v[248:251], v146
	v_mfma_f32_16x16x32_bf16 v[76:79], v[194:197], v[160:163], v[76:79]
	v_mfma_f32_16x16x32_bf16 v[72:75], v[198:201], v[160:163], v[72:75]
	v_mfma_f32_16x16x32_bf16 v[68:71], v[202:205], v[160:163], v[68:71]
	v_mfma_f32_16x16x32_bf16 v[64:67], v[206:209], v[160:163], v[64:67]
	s_waitcnt lgkmcnt(0)
	s_waitcnt vmcnt(0)
	s_add_u32 s4, s4, 0x80
	s_addc_u32 s5, s5, 0
	s_add_i32 s17, s17, 0x10000
	s_cmpk_eq_i32 s4, 0x780
	s_waitcnt vmcnt(0)
	s_barrier
	s_cbranch_scc0 .LBB0_281
	v_mfma_f32_16x16x32_bf16 v[60:63], v[194:197], v[236:239], v[60:63]
	v_mfma_f32_16x16x32_bf16 v[56:59], v[198:201], v[236:239], v[56:59]
	v_mfma_f32_16x16x32_bf16 v[52:55], v[202:205], v[236:239], v[52:55]
	v_mfma_f32_16x16x32_bf16 v[48:51], v[206:209], v[236:239], v[48:51]
	v_mfma_f32_16x16x32_bf16 v[44:47], v[194:197], v[240:243], v[44:47]
	v_mfma_f32_16x16x32_bf16 v[40:43], v[198:201], v[240:243], v[40:43]
	v_mfma_f32_16x16x32_bf16 v[36:39], v[202:205], v[240:243], v[36:39]
	v_mfma_f32_16x16x32_bf16 v[32:35], v[206:209], v[240:243], v[32:35]
	v_mfma_f32_16x16x32_bf16 v[28:31], v[194:197], v[244:247], v[28:31]
	v_mfma_f32_16x16x32_bf16 v[24:27], v[198:201], v[244:247], v[24:27]
	v_mfma_f32_16x16x32_bf16 v[20:23], v[202:205], v[244:247], v[20:23]
	v_mfma_f32_16x16x32_bf16 v[16:19], v[206:209], v[244:247], v[16:19]
	v_mfma_f32_16x16x32_bf16 v[12:15], v[194:197], v[248:251], v[12:15]
	v_mfma_f32_16x16x32_bf16 v[8:11], v[198:201], v[248:251], v[8:11]
	v_mfma_f32_16x16x32_bf16 v[4:7], v[202:205], v[248:251], v[4:7]
	v_mfma_f32_16x16x32_bf16 v[0:3], v[206:209], v[248:251], v[0:3]
	v_add_u32_e32 v146, s18, v142
	v_add3_u32 v155, v146, v148, v149
	ds_read_b128 v[136:139], v155 offset:32768
	ds_read_b128 v[156:159], v155 offset:34816
	ds_read_b128 v[164:167], v155 offset:36864
	ds_read_b128 v[172:175], v155 offset:38912
	v_add_u32_e32 v198, v146, v144
	ds_read_b128 v[160:163], v198
	ds_read_b128 v[176:179], v198 offset:2048
	v_add_u32_e32 v155, v146, v150
	ds_read_b128 v[180:183], v198 offset:4096
	s_waitcnt lgkmcnt(2)
	v_mfma_f32_16x16x32_bf16 v[124:127], v[136:139], v[160:163], v[124:127]
	v_add_u32_e32 v146, v146, v152
	s_lshl_b64 s[16:17], s[8:9], 8
	v_mfma_f32_16x16x32_bf16 v[120:123], v[156:159], v[160:163], v[120:123]
	v_mfma_f32_16x16x32_bf16 v[116:119], v[164:167], v[160:163], v[116:119]
	v_mfma_f32_16x16x32_bf16 v[112:115], v[172:175], v[160:163], v[112:115]
	ds_read_b128 v[160:163], v155
	v_add_u32_e32 v155, s18, v145
	v_add_u32_e32 v199, v155, v151
	s_waitcnt lgkmcnt(2)
	v_mfma_f32_16x16x32_bf16 v[108:111], v[136:139], v[176:179], v[108:111]
	v_mfma_f32_16x16x32_bf16 v[104:107], v[156:159], v[176:179], v[104:107]
	v_mfma_f32_16x16x32_bf16 v[100:103], v[164:167], v[176:179], v[100:103]
	v_mfma_f32_16x16x32_bf16 v[96:99], v[172:175], v[176:179], v[96:99]
	ds_read_b128 v[176:179], v198 offset:8192
	ds_read_b128 v[190:193], v199 offset:32768
	s_waitcnt lgkmcnt(3)
	v_mfma_f32_16x16x32_bf16 v[92:95], v[136:139], v[180:183], v[92:95]
	v_mfma_f32_16x16x32_bf16 v[88:91], v[156:159], v[180:183], v[88:91]
	v_mfma_f32_16x16x32_bf16 v[84:87], v[164:167], v[180:183], v[84:87]
	v_mfma_f32_16x16x32_bf16 v[80:83], v[172:175], v[180:183], v[80:83]
	ds_read_b128 v[180:183], v198 offset:10240
	ds_read_b128 v[194:197], v199 offset:34816
	s_waitcnt lgkmcnt(4)
	v_mfma_f32_16x16x32_bf16 v[76:79], v[136:139], v[160:163], v[76:79]
	v_mfma_f32_16x16x32_bf16 v[72:75], v[156:159], v[160:163], v[72:75]
	v_mfma_f32_16x16x32_bf16 v[68:71], v[164:167], v[160:163], v[68:71]
	v_mfma_f32_16x16x32_bf16 v[64:67], v[172:175], v[160:163], v[64:67]
	ds_read_b128 v[160:163], v198 offset:12288
	ds_read_b128 v[198:201], v199 offset:36864
	s_waitcnt lgkmcnt(5)
	v_mfma_f32_16x16x32_bf16 v[60:63], v[136:139], v[176:179], v[60:63]
	v_mfma_f32_16x16x32_bf16 v[56:59], v[156:159], v[176:179], v[56:59]
	v_mfma_f32_16x16x32_bf16 v[52:55], v[164:167], v[176:179], v[52:55]
	v_mfma_f32_16x16x32_bf16 v[48:51], v[172:175], v[176:179], v[48:51]
	ds_read_b128 v[176:179], v146
	v_add_u32_e32 v146, v155, v153
	ds_read_b128 v[202:205], v146 offset:38912
	v_add_u32_e32 v146, v155, v144
	s_waitcnt lgkmcnt(5)
; #define MFMA16(a, b, c) __builtin_amdgcn_mfma_f32_16x16x32_bf16((a), (b), (c), 0, 0, 0)
; DI unsigned pk2(float a, float b) { f32x2 v = {a, b}; bf16x2_t r = __builtin_convertvector(v, bf16x2_t); return __builtin_bit_cast(unsigned, r); }
; DI bf16x8 ldfrag(const char* lds, int row, int chunk) { return *(const bf16x8*)(lds + swz(row, chunk)); }
; #define GEMM_SG1() do { __builtin_amdgcn_sched_group_barrier(0x100, 1, 0); __builtin_amdgcn_sched_group_barrier(0x008, 4, 0); } while (0)
; #define GEMM_SG2() do { __builtin_amdgcn_sched_group_barrier(0x100, 2, 0); __builtin_amdgcn_sched_group_barrier(0x008, 4, 0); } while (0)
; template <bool RSTD, bool SWAP>
; DI void gemm_tile(gacc_t& acc, const bf16_t* __restrict__ A, int lda, const bf16_t* __restrict__ Bt, int ldb, int K,
;                   char* lds, int tid, int wr, int wc, int lane, const float* ssq_row) {
;     ...
;         for (int idx = 0; idx < 16; ++idx) {
;             const int ks = idx >> 3, m = idx & 7;
;             if (idx < 14) afr[(idx + 2) % 3] = ldfrag(cur, wr * 128 + ((idx + 2) & 7) * 16 + fr, ((idx + 2) >> 3) * 4 + fq);
;             if (ks == 0 && m >= 2 && m < 6) bfr[1][m - 2] = ldfrag(cur + 32768, wc * 64 + (m - 2) * 16 + fr, 4 + fq);
; #pragma unroll
;             for (int n = 0; n < 4; ++n) acc[m][n] = SWAP ? MFMA16(bfr[ks][n], afr[idx % 3], acc[m][n]) : MFMA16(afr[idx % 3], bfr[ks][n], acc[m][n]);
;         }
;         __builtin_amdgcn_sched_group_barrier(0x100, 6, 0);
;     ...
;         GEMM_SG1(); GEMM_SG1(); GEMM_SG2(); GEMM_SG2(); GEMM_SG2(); GEMM_SG2(); GEMM_SG1(); GEMM_SG1();
;         GEMM_SG1(); GEMM_SG1(); GEMM_SG1(); GEMM_SG1(); GEMM_SG1(); GEMM_SG1();
;         __builtin_amdgcn_sched_group_barrier(0x008, 8, 0);
;         __builtin_amdgcn_sched_barrier(0);
;         asm volatile("s_waitcnt vmcnt(0)" ::: "memory");
;         __syncthreads();
;     DI void operator()(gacc_t& acc, int pm, int pn, char* lds, int tid, int wr, int wc, int lane) const {
;         asm volatile("" : "+v"(tid), "+v"(lane));
;         const int fr = lane & 15, fq = lane >> 4, wid = tid >> 6;
;         char* lbase = lds + (wr * 128 + fr) * 528 + (wc * 64 + 4 * fq) * 2;
; #pragma unroll
;         for (int m = 0; m < 8; ++m)
; #pragma unroll
;             for (int n = 0; n < 4; ++n) { u32x2 w; w.x = pk2(acc[m][n][0], acc[m][n][1]); w.y = pk2(acc[m][n][2], acc[m][n][3]); *(u32x2*)(lbase + m * 16 * 528 + n * 32) = w; }
	v_mfma_f32_16x16x32_bf16 v[44:47], v[136:139], v[180:183], v[44:47]
	v_mfma_f32_16x16x32_bf16 v[40:43], v[156:159], v[180:183], v[40:43]
	v_mfma_f32_16x16x32_bf16 v[36:39], v[164:167], v[180:183], v[36:39]
	v_mfma_f32_16x16x32_bf16 v[32:35], v[172:175], v[180:183], v[32:35]
	ds_read_b128 v[180:183], v146
	s_waitcnt lgkmcnt(4)
	v_mfma_f32_16x16x32_bf16 v[28:31], v[136:139], v[160:163], v[28:31]
	v_mfma_f32_16x16x32_bf16 v[24:27], v[156:159], v[160:163], v[24:27]
	v_mfma_f32_16x16x32_bf16 v[20:23], v[164:167], v[160:163], v[20:23]
	v_mfma_f32_16x16x32_bf16 v[16:19], v[172:175], v[160:163], v[16:19]
	ds_read_b128 v[160:163], v146 offset:2048
	s_waitcnt lgkmcnt(3)
	v_mfma_f32_16x16x32_bf16 v[8:11], v[156:159], v[176:179], v[8:11]
	v_add_u32_e32 v156, v155, v150
	v_mfma_f32_16x16x32_bf16 v[12:15], v[136:139], v[176:179], v[12:15]
	v_mfma_f32_16x16x32_bf16 v[4:7], v[164:167], v[176:179], v[4:7]
	v_mfma_f32_16x16x32_bf16 v[0:3], v[172:175], v[176:179], v[0:3]
	ds_read_b128 v[136:139], v146 offset:4096
	s_waitcnt lgkmcnt(2)
	v_mfma_f32_16x16x32_bf16 v[124:127], v[190:193], v[180:183], v[124:127]
	v_mfma_f32_16x16x32_bf16 v[120:123], v[194:197], v[180:183], v[120:123]
	v_mfma_f32_16x16x32_bf16 v[116:119], v[198:201], v[180:183], v[116:119]
	v_mfma_f32_16x16x32_bf16 v[112:115], v[202:205], v[180:183], v[112:115]
	ds_read_b128 v[156:159], v156
	s_waitcnt lgkmcnt(2)
	v_mfma_f32_16x16x32_bf16 v[108:111], v[190:193], v[160:163], v[108:111]
	v_mfma_f32_16x16x32_bf16 v[104:107], v[194:197], v[160:163], v[104:107]
	v_mfma_f32_16x16x32_bf16 v[100:103], v[198:201], v[160:163], v[100:103]
	v_mfma_f32_16x16x32_bf16 v[96:99], v[202:205], v[160:163], v[96:99]
	ds_read_b128 v[160:163], v146 offset:8192
	s_waitcnt lgkmcnt(2)
	v_mfma_f32_16x16x32_bf16 v[92:95], v[190:193], v[136:139], v[92:95]
	v_mfma_f32_16x16x32_bf16 v[88:91], v[194:197], v[136:139], v[88:91]
	v_mfma_f32_16x16x32_bf16 v[84:87], v[198:201], v[136:139], v[84:87]
	v_mfma_f32_16x16x32_bf16 v[80:83], v[202:205], v[136:139], v[80:83]
	ds_read_b128 v[136:139], v146 offset:10240
	s_waitcnt lgkmcnt(2)
	v_mfma_f32_16x16x32_bf16 v[76:79], v[190:193], v[156:159], v[76:79]
	v_mfma_f32_16x16x32_bf16 v[72:75], v[194:197], v[156:159], v[72:75]
	v_mfma_f32_16x16x32_bf16 v[68:71], v[198:201], v[156:159], v[68:71]
	v_mfma_f32_16x16x32_bf16 v[64:67], v[202:205], v[156:159], v[64:67]
	ds_read_b128 v[156:159], v146 offset:12288
	v_add_u32_e32 v146, v155, v152
	s_waitcnt lgkmcnt(2)
	v_mfma_f32_16x16x32_bf16 v[60:63], v[190:193], v[160:163], v[60:63]
	v_mfma_f32_16x16x32_bf16 v[56:59], v[194:197], v[160:163], v[56:59]
	v_mfma_f32_16x16x32_bf16 v[52:55], v[198:201], v[160:163], v[52:55]
	v_mfma_f32_16x16x32_bf16 v[48:51], v[202:205], v[160:163], v[48:51]
	ds_read_b128 v[160:163], v146
	s_waitcnt lgkmcnt(2)
	v_mfma_f32_16x16x32_bf16 v[44:47], v[190:193], v[136:139], v[44:47]
	v_mfma_f32_16x16x32_bf16 v[40:43], v[194:197], v[136:139], v[40:43]
	v_mfma_f32_16x16x32_bf16 v[36:39], v[198:201], v[136:139], v[36:39]
	v_mfma_f32_16x16x32_bf16 v[32:35], v[202:205], v[136:139], v[32:35]
	s_waitcnt lgkmcnt(1)
	v_mfma_f32_16x16x32_bf16 v[24:27], v[194:197], v[156:159], v[24:27]
	v_mfma_f32_16x16x32_bf16 v[20:23], v[198:201], v[156:159], v[20:23]
	v_mfma_f32_16x16x32_bf16 v[16:19], v[202:205], v[156:159], v[16:19]
	s_waitcnt lgkmcnt(0)
	v_mfma_f32_16x16x32_bf16 v[12:15], v[190:193], v[160:163], v[12:15]
	v_mfma_f32_16x16x32_bf16 v[8:11], v[194:197], v[160:163], v[8:11]
	v_mfma_f32_16x16x32_bf16 v[4:7], v[198:201], v[160:163], v[4:7]
	v_mfma_f32_16x16x32_bf16 v[0:3], v[202:205], v[160:163], v[0:3]
	v_mfma_f32_16x16x32_bf16 v[28:31], v[190:193], v[156:159], v[28:31]
	v_mov_b32_e32 v136, v141
	v_mov_b32_e32 v137, v140
	s_waitcnt vmcnt(0)
	s_barrier
	v_cvt_pk_bf16_f32 v124, v124, v125
	v_and_or_b32 v138, v136, 15, v143
	v_ashrrev_i32_e32 v139, 1, v136
	v_mul_lo_u32 v138, v138, s3
	v_and_b32_e32 v139, -8, v139
	v_add3_u32 v138, v154, v138, v139
	v_cvt_pk_bf16_f32 v125, v126, v127
	v_cvt_pk_bf16_f32 v120, v120, v121
	v_cvt_pk_bf16_f32 v121, v122, v123
	v_cvt_pk_bf16_f32 v116, v116, v117
	v_cvt_pk_bf16_f32 v117, v118, v119
	v_cvt_pk_bf16_f32 v112, v112, v113
	v_cvt_pk_bf16_f32 v113, v114, v115
	v_cvt_pk_bf16_f32 v108, v108, v109
	v_cvt_pk_bf16_f32 v109, v110, v111
	v_cvt_pk_bf16_f32 v104, v104, v105
	v_cvt_pk_bf16_f32 v105, v106, v107
	v_add_u32_e32 v106, 0x2000, v138
	v_cvt_pk_bf16_f32 v100, v100, v101
	v_cvt_pk_bf16_f32 v101, v102, v103
	v_cvt_pk_bf16_f32 v96, v96, v97
	v_cvt_pk_bf16_f32 v97, v98, v99
	v_cvt_pk_bf16_f32 v92, v92, v93
	v_cvt_pk_bf16_f32 v93, v94, v95
	v_cvt_pk_bf16_f32 v88, v88, v89
	v_cvt_pk_bf16_f32 v89, v90, v91
	v_add_u32_e32 v90, 0x4000, v138
	v_cvt_pk_bf16_f32 v84, v84, v85
	v_cvt_pk_bf16_f32 v85, v86, v87
	v_cvt_pk_bf16_f32 v80, v80, v81
	v_cvt_pk_bf16_f32 v81, v82, v83
	v_cvt_pk_bf16_f32 v76, v76, v77
	v_cvt_pk_bf16_f32 v77, v78, v79
	v_cvt_pk_bf16_f32 v72, v72, v73
	v_cvt_pk_bf16_f32 v73, v74, v75
	v_add_u32_e32 v74, 0x6000, v138
	v_cvt_pk_bf16_f32 v68, v68, v69
	v_cvt_pk_bf16_f32 v69, v70, v71
	v_cvt_pk_bf16_f32 v64, v64, v65
	v_cvt_pk_bf16_f32 v65, v66, v67
	v_cvt_pk_bf16_f32 v60, v60, v61
	v_cvt_pk_bf16_f32 v61, v62, v63
	v_cvt_pk_bf16_f32 v56, v56, v57
	v_cvt_pk_bf16_f32 v57, v58, v59
	v_add_u32_e32 v58, 0x8000, v138
	v_cvt_pk_bf16_f32 v52, v52, v53
	v_cvt_pk_bf16_f32 v53, v54, v55
	v_cvt_pk_bf16_f32 v48, v48, v49
	v_cvt_pk_bf16_f32 v49, v50, v51
	v_cvt_pk_bf16_f32 v44, v44, v45
	v_cvt_pk_bf16_f32 v45, v46, v47
	v_cvt_pk_bf16_f32 v40, v40, v41
	v_cvt_pk_bf16_f32 v41, v42, v43
	v_add_u32_e32 v42, 0xa000, v138
	v_cvt_pk_bf16_f32 v36, v36, v37
	v_cvt_pk_bf16_f32 v37, v38, v39
	v_cvt_pk_bf16_f32 v32, v32, v33
; DI unsigned pk2(float a, float b) { f32x2 v = {a, b}; bf16x2_t r = __builtin_convertvector(v, bf16x2_t); return __builtin_bit_cast(unsigned, r); }
; DI float bflo(unsigned w) { return __uint_as_float(w << 16); }
; DI float bfhi(unsigned w) { return __uint_as_float(w & 0xffff0000u); }
;     DI void operator()(gacc_t& acc, int pm, int pn, char* lds, int tid, int wr, int wc, int lane) const {
;     ...
; #pragma unroll
;         for (int m = 0; m < 8; ++m)
; #pragma unroll
;             for (int n = 0; n < 4; ++n) { u32x2 w; w.x = pk2(acc[m][n][0], acc[m][n][1]); w.y = pk2(acc[m][n][2], acc[m][n][3]); *(u32x2*)(lbase + m * 16 * 528 + n * 32) = w; }
;         __builtin_amdgcn_sched_barrier(0);
;         __syncthreads();
;         __builtin_amdgcn_sched_barrier(0);
;         const int g = lane >> 5, j32 = lane & 31;
; #pragma unroll
;         for (int ib = 0; ib < 4; ++ib) {
;             __builtin_amdgcn_sched_barrier(0);
;             u32x4 xv[4];
; #pragma unroll
;             for (int u = 0; u < 4; ++u) {
;                 const long row = (long)pm * 256 + (ib * 4 + u) * 16 + wid * 2 + g;
;                 xv[u] = *(const u32x4*)(xold + row * 1024 + pn * 256 + j32 * 8);
;             }
; #pragma unroll
;             for (int u = 0; u < 4; ++u) {
;                 const int rloc = (ib * 4 + u) * 16 + wid * 2 + g;
;                 const long row = (long)pm * 256 + rloc;
;                 const u32x4 a = *(const u32x4*)(lds + rloc * 528 + j32 * 16);
;                 u32x4 w; float ss = 0.f;
; #pragma unroll
;                 for (int e = 0; e < 4; ++e) {
;                     w[e] = pk2(bflo(xv[u][e]) + bflo(a[e]), bfhi(xv[u][e]) + bfhi(a[e]));
;                     const float b0 = bflo(w[e]), b1 = bfhi(w[e]);
;                     ss += b0 * b0 + b1 * b1;
;                 }
;                 *(u32x4*)(xnew + row * 1024 + pn * 256 + j32 * 8) = w;
; #pragma unroll
;                 for (int o = 1; o < 32; o <<= 1) ss += __shfl_xor(ss, o);
;                 if (j32 == 0) ssq[row * 4 + pn] = ss;
	v_cvt_pk_bf16_f32 v33, v34, v35
	v_cvt_pk_bf16_f32 v28, v28, v29
	v_cvt_pk_bf16_f32 v29, v30, v31
	v_cvt_pk_bf16_f32 v24, v24, v25
	v_cvt_pk_bf16_f32 v25, v26, v27
	v_add_u32_e32 v26, 0xc000, v138
	v_cvt_pk_bf16_f32 v20, v20, v21
	v_cvt_pk_bf16_f32 v21, v22, v23
	v_cvt_pk_bf16_f32 v16, v16, v17
	v_cvt_pk_bf16_f32 v17, v18, v19
	v_cvt_pk_bf16_f32 v12, v12, v13
	v_cvt_pk_bf16_f32 v13, v14, v15
	v_cvt_pk_bf16_f32 v8, v8, v9
	v_cvt_pk_bf16_f32 v9, v10, v11
	v_add_u32_e32 v10, 0xe000, v138
	v_cvt_pk_bf16_f32 v4, v4, v5
	v_cvt_pk_bf16_f32 v5, v6, v7
	v_cvt_pk_bf16_f32 v0, v0, v1
	v_cvt_pk_bf16_f32 v1, v2, v3
	ds_write2_b64 v138, v[124:125], v[120:121] offset1:4
	ds_write2_b64 v138, v[116:117], v[112:113] offset0:8 offset1:12
	ds_write2_b64 v106, v[108:109], v[104:105] offset0:32 offset1:36
	ds_write2_b64 v106, v[100:101], v[96:97] offset0:40 offset1:44
	ds_write2_b64 v90, v[92:93], v[88:89] offset0:64 offset1:68
	ds_write2_b64 v90, v[84:85], v[80:81] offset0:72 offset1:76
	ds_write2_b64 v74, v[76:77], v[72:73] offset0:96 offset1:100
	ds_write2_b64 v74, v[68:69], v[64:65] offset0:104 offset1:108
	ds_write2_b64 v58, v[60:61], v[56:57] offset0:128 offset1:132
	ds_write2_b64 v58, v[52:53], v[48:49] offset0:136 offset1:140
	ds_write2_b64 v42, v[44:45], v[40:41] offset0:160 offset1:164
	ds_write2_b64 v42, v[36:37], v[32:33] offset0:168 offset1:172
	ds_write2_b64 v26, v[28:29], v[24:25] offset0:192 offset1:196
	ds_write2_b64 v26, v[20:21], v[16:17] offset0:200 offset1:204
	ds_write2_b64 v10, v[12:13], v[8:9] offset0:224 offset1:228
	ds_write2_b64 v10, v[4:5], v[0:1] offset0:232 offset1:236
	s_waitcnt lgkmcnt(0)
	s_barrier
	v_ashrrev_i32_e32 v0, 5, v136
	v_ashrrev_i32_e32 v1, 5, v137
	v_and_b32_e32 v23, 31, v136
	v_and_b32_e32 v2, -2, v1
	v_ashrrev_i32_e32 v1, 31, v0
	v_ashrrev_i32_e32 v3, 31, v2
	v_lshl_add_u64 v[4:5], s[16:17], 0, v[0:1]
	s_lshl_b32 s18, s6, 8
	v_lshlrev_b32_e32 v146, 4, v23
	v_lshl_add_u64 v[4:5], v[4:5], 0, v[2:3]
	s_ashr_i32 s19, s18, 31
	v_add_u32_e32 v16, v2, v0
	v_add_u32_e32 v22, 0, v146
	v_cmp_eq_u32_e64 s[4:5], 0, v23
	v_cmp_eq_u32_e64 s[98:99], 16, v23
	s_lshl_b64 s[20:21], s[18:19], 1
	s_add_u32 s30, s10, s20
	s_addc_u32 s31, s11, s21
	v_lshl_add_u64 v[0:1], s[30:31], 0, v[146:147]
	v_lshlrev_b64 v[2:3], 11, v[4:5]
	v_lshl_add_u64 v[18:19], v[0:1], 0, v[2:3]
	flat_load_dwordx4 v[12:15], v[18:19]
	v_add_co_u32_e32 v0, vcc, s49, v18
	v_mul_lo_u32 v24, v16, s3
	s_nop 0
	v_addc_co_u32_e32 v1, vcc, 0, v19, vcc
	flat_load_dwordx4 v[8:11], v[0:1]
	v_add_co_u32_e32 v0, vcc, s48, v18
	v_add_u32_e32 v20, v22, v24
	s_nop 0
	v_addc_co_u32_e32 v1, vcc, 0, v19, vcc
	flat_load_dwordx4 v[4:7], v[0:1]
	v_add_co_u32_e32 v0, vcc, s47, v18
	ds_read_b128 v[26:29], v20
	s_nop 0
	v_addc_co_u32_e32 v1, vcc, 0, v19, vcc
	flat_load_dwordx4 v[0:3], v[0:1]
	v_ashrrev_i32_e32 v17, 31, v16
	s_waitcnt lgkmcnt(0)
	v_lshlrev_b32_e32 v30, 16, v26
	v_and_b32_e32 v31, 0xffff0000, v26
	v_lshlrev_b32_e32 v26, 16, v27
	v_and_b32_e32 v27, 0xffff0000, v27
	s_waitcnt vmcnt(0)
	v_lshlrev_b32_e32 v20, 16, v12
	v_and_b32_e32 v21, 0xffff0000, v12
	v_pk_add_f32 v[20:21], v[20:21], v[30:31]
	s_nop 0
	v_cvt_pk_bf16_f32 v12, v20, v21
	v_and_b32_e32 v21, 0xffff0000, v12
	v_lshlrev_b32_e32 v20, 16, v12
	v_mul_f32_e32 v25, v21, v21
	v_fmac_f32_e32 v25, v20, v20
	v_lshlrev_b32_e32 v20, 16, v13
	v_and_b32_e32 v21, 0xffff0000, v13
	v_pk_add_f32 v[20:21], v[20:21], v[26:27]
	v_lshlrev_b32_e32 v26, 16, v28
	v_cvt_pk_bf16_f32 v13, v20, v21
	v_and_b32_e32 v21, 0xffff0000, v13
	v_lshlrev_b32_e32 v20, 16, v13
	v_mul_f32_e32 v21, v21, v21
	v_fmac_f32_e32 v21, v20, v20
	v_add_f32_e32 v25, v25, v21
	v_lshlrev_b32_e32 v20, 16, v14
	v_and_b32_e32 v21, 0xffff0000, v14
	v_and_b32_e32 v27, 0xffff0000, v28
	v_pk_add_f32 v[20:21], v[20:21], v[26:27]
	v_lshlrev_b32_e32 v26, 16, v29
	v_cvt_pk_bf16_f32 v14, v20, v21
	v_and_b32_e32 v21, 0xffff0000, v14
	v_lshlrev_b32_e32 v20, 16, v14
	v_mul_f32_e32 v21, v21, v21
	v_fmac_f32_e32 v21, v20, v20
	v_add_f32_e32 v25, v21, v25
	v_lshlrev_b32_e32 v20, 16, v15
	v_and_b32_e32 v21, 0xffff0000, v15
	v_and_b32_e32 v27, 0xffff0000, v29
	v_pk_add_f32 v[20:21], v[20:21], v[26:27]
	s_nop 0
	v_cvt_pk_bf16_f32 v15, v20, v21
	v_and_b32_e32 v21, 0xffff0000, v15
	v_lshlrev_b32_e32 v20, 16, v15
	v_mul_f32_e32 v21, v21, v21
	v_fmac_f32_e32 v21, v20, v20
	v_add_f32_e32 v25, v21, v25
	v_lshl_add_u64 v[20:21], s[16:17], 0, v[16:17]
	v_lshlrev_b64 v[26:27], 11, v[20:21]
	v_lshl_add_u64 v[26:27], s[68:69], 0, v[26:27]
	v_lshl_add_u64 v[26:27], v[26:27], 0, s[20:21]
	v_lshl_add_u64 v[26:27], v[26:27], 0, v[146:147]
	flat_store_dwordx4 v[26:27], v[12:15]
	s_nop 1
	v_add_f32_dpp v86, v25, v25 quad_perm:[1,0,3,2] row_mask:0xf bank_mask:0xf
	s_nop 1
	v_add_f32_dpp v86, v86, v86 quad_perm:[2,3,0,1] row_mask:0xf bank_mask:0xf
	s_nop 1
	v_add_f32_dpp v86, v86, v86 row_half_mirror row_mask:0xf bank_mask:0xf
	s_nop 1
	v_add_f32_dpp v86, v86, v86 row_mirror row_mask:0xf bank_mask:0xf
	s_nop 1
	v_add_f32_dpp v86, v86, v86 row_bcast:15 row_mask:0xa bank_mask:0xf
	s_waitcnt lgkmcnt(0)
	s_waitcnt lgkmcnt(0)
	s_waitcnt lgkmcnt(0)
	s_waitcnt lgkmcnt(0)
	s_and_saveexec_b64 s[20:21], s[98:99]
	s_cbranch_execz .LBB0_284
	v_lshl_add_u64 v[14:15], v[20:21], 4, s[78:79]
	v_lshl_add_u64 v[14:15], s[6:7], 2, v[14:15]
	s_waitcnt lgkmcnt(0)
	v_mov_b32_e32 v12, v86
	flat_store_dword v[14:15], v12
; DI unsigned pk2(float a, float b) { f32x2 v = {a, b}; bf16x2_t r = __builtin_convertvector(v, bf16x2_t); return __builtin_bit_cast(unsigned, r); }
; DI float bflo(unsigned w) { return __uint_as_float(w << 16); }
; DI float bfhi(unsigned w) { return __uint_as_float(w & 0xffff0000u); }
;     DI void operator()(gacc_t& acc, int pm, int pn, char* lds, int tid, int wr, int wc, int lane) const {
;     ...
;         for (int ib = 0; ib < 4; ++ib) {
;             __builtin_amdgcn_sched_barrier(0);
;             u32x4 xv[4];
; #pragma unroll
;             for (int u = 0; u < 4; ++u) {
;                 const long row = (long)pm * 256 + (ib * 4 + u) * 16 + wid * 2 + g;
;                 xv[u] = *(const u32x4*)(xold + row * 1024 + pn * 256 + j32 * 8);
;             }
; #pragma unroll
;             for (int u = 0; u < 4; ++u) {
;                 const int rloc = (ib * 4 + u) * 16 + wid * 2 + g;
;                 const long row = (long)pm * 256 + rloc;
;                 const u32x4 a = *(const u32x4*)(lds + rloc * 528 + j32 * 16);
;                 u32x4 w; float ss = 0.f;
; #pragma unroll
;                 for (int e = 0; e < 4; ++e) {
;                     w[e] = pk2(bflo(xv[u][e]) + bflo(a[e]), bfhi(xv[u][e]) + bfhi(a[e]));
;                     const float b0 = bflo(w[e]), b1 = bfhi(w[e]);
;                     ss += b0 * b0 + b1 * b1;
;                 }
;                 *(u32x4*)(xnew + row * 1024 + pn * 256 + j32 * 8) = w;
; #pragma unroll
;                 for (int o = 1; o < 32; o <<= 1) ss += __shfl_xor(ss, o);
;                 if (j32 == 0) ssq[row * 4 + pn] = ss;
.LBB0_284:
	s_or_b64 exec, exec, s[20:21]
	v_add_u32_e32 v12, 0x2100, v24
	s_waitcnt lgkmcnt(0)
	v_add_u32_e32 v13, v22, v12
	ds_read_b128 v[24:27], v13
	v_lshlrev_b32_e32 v14, 16, v8
	v_and_b32_e32 v15, 0xffff0000, v8
	s_waitcnt lgkmcnt(0)
	v_lshlrev_b32_e32 v20, 16, v24
	v_and_b32_e32 v21, 0xffff0000, v24
	v_pk_add_f32 v[14:15], v[14:15], v[20:21]
	s_nop 0
	v_cvt_pk_bf16_f32 v24, v14, v15
	v_and_b32_e32 v13, 0xffff0000, v24
	v_lshlrev_b32_e32 v8, 16, v24
	v_mul_f32_e32 v13, v13, v13
	v_fmac_f32_e32 v13, v8, v8
	v_lshlrev_b32_e32 v8, 16, v9
	v_and_b32_e32 v9, 0xffff0000, v9
	v_lshlrev_b32_e32 v14, 16, v25
	v_and_b32_e32 v15, 0xffff0000, v25
	v_pk_add_f32 v[8:9], v[8:9], v[14:15]
	v_lshlrev_b32_e32 v14, 16, v26
	v_cvt_pk_bf16_f32 v25, v8, v9
	v_and_b32_e32 v9, 0xffff0000, v25
	v_lshlrev_b32_e32 v8, 16, v25
	v_mul_f32_e32 v9, v9, v9
	v_fmac_f32_e32 v9, v8, v8
	v_add_f32_e32 v13, v13, v9
	v_lshlrev_b32_e32 v8, 16, v10
	v_and_b32_e32 v9, 0xffff0000, v10
	v_and_b32_e32 v15, 0xffff0000, v26
	v_pk_add_f32 v[8:9], v[8:9], v[14:15]
	v_lshlrev_b32_e32 v10, 16, v27
	v_cvt_pk_bf16_f32 v26, v8, v9
	v_and_b32_e32 v9, 0xffff0000, v26
	v_lshlrev_b32_e32 v8, 16, v26
	v_mul_f32_e32 v9, v9, v9
	v_fmac_f32_e32 v9, v8, v8
	v_add_f32_e32 v13, v9, v13
	v_lshlrev_b32_e32 v8, 16, v11
	v_and_b32_e32 v9, 0xffff0000, v11
	v_and_b32_e32 v11, 0xffff0000, v27
	v_pk_add_f32 v[8:9], v[8:9], v[10:11]
	s_nop 0
	v_cvt_pk_bf16_f32 v27, v8, v9
	v_and_b32_e32 v9, 0xffff0000, v27
	v_lshlrev_b32_e32 v8, 16, v27
	v_mul_f32_e32 v9, v9, v9
	v_fmac_f32_e32 v9, v8, v8
	v_add_f32_e32 v8, v9, v13
	s_nop 1
	v_add_f32_dpp v86, v8, v8 quad_perm:[1,0,3,2] row_mask:0xf bank_mask:0xf
	s_nop 1
	v_add_f32_dpp v86, v86, v86 quad_perm:[2,3,0,1] row_mask:0xf bank_mask:0xf
	s_nop 1
	v_add_f32_dpp v86, v86, v86 row_half_mirror row_mask:0xf bank_mask:0xf
	s_nop 1
	v_add_f32_dpp v86, v86, v86 row_mirror row_mask:0xf bank_mask:0xf
	s_nop 1
	v_add_f32_dpp v86, v86, v86 row_bcast:15 row_mask:0xa bank_mask:0xf
	v_lshlrev_b32_e32 v13, 3, v23
	v_lshlrev_b32_e32 v146, 1, v13
	s_waitcnt lgkmcnt(0)
	s_waitcnt lgkmcnt(0)
	v_add_u32_e32 v8, 16, v16
	s_waitcnt lgkmcnt(0)
	v_ashrrev_i32_e32 v9, 31, v8
	v_lshl_add_u64 v[8:9], s[16:17], 0, v[8:9]
	v_lshlrev_b64 v[10:11], 11, v[8:9]
	v_lshl_add_u64 v[14:15], s[68:69], 0, v[10:11]
	s_waitcnt lgkmcnt(0)
	v_lshl_add_u64 v[14:15], s[18:19], 1, v[14:15]
	v_lshl_add_u64 v[14:15], v[14:15], 0, v[146:147]
	flat_store_dwordx4 v[14:15], v[24:27]
	s_and_saveexec_b64 s[20:21], s[98:99]
	s_cbranch_execz .LBB0_286
	v_lshl_add_u64 v[8:9], v[8:9], 4, s[78:79]
	v_lshl_add_u64 v[8:9], s[6:7], 2, v[8:9]
	s_waitcnt lgkmcnt(0)
	v_mov_b32_e32 v10, v86
	flat_store_dword v[8:9], v10
.LBB0_286:
	s_or_b64 exec, exec, s[20:21]
	v_add_u32_e32 v8, 0x2100, v12
	v_add_u32_e32 v9, v22, v8
	s_waitcnt lgkmcnt(0)
	ds_read_b128 v[10:13], v9
	v_lshlrev_b32_e32 v14, 16, v4
	v_and_b32_e32 v15, 0xffff0000, v4
	s_waitcnt lgkmcnt(0)
	v_lshlrev_b32_e32 v20, 16, v10
	v_and_b32_e32 v21, 0xffff0000, v10
	v_pk_add_f32 v[14:15], v[14:15], v[20:21]
	s_nop 0
	v_cvt_pk_bf16_f32 v10, v14, v15
	v_and_b32_e32 v9, 0xffff0000, v10
	v_lshlrev_b32_e32 v4, 16, v10
	v_mul_f32_e32 v9, v9, v9
	v_fmac_f32_e32 v9, v4, v4
	v_lshlrev_b32_e32 v4, 16, v5
	v_and_b32_e32 v5, 0xffff0000, v5
	v_lshlrev_b32_e32 v14, 16, v11
	v_and_b32_e32 v15, 0xffff0000, v11
	v_pk_add_f32 v[4:5], v[4:5], v[14:15]
	v_lshlrev_b32_e32 v14, 16, v12
	v_cvt_pk_bf16_f32 v11, v4, v5
	v_and_b32_e32 v5, 0xffff0000, v11
	v_lshlrev_b32_e32 v4, 16, v11
	v_mul_f32_e32 v5, v5, v5
	v_fmac_f32_e32 v5, v4, v4
	v_add_f32_e32 v9, v9, v5
	v_lshlrev_b32_e32 v4, 16, v6
	v_and_b32_e32 v5, 0xffff0000, v6
	v_and_b32_e32 v15, 0xffff0000, v12
	v_pk_add_f32 v[4:5], v[4:5], v[14:15]
	v_lshlrev_b32_e32 v6, 16, v13
	v_cvt_pk_bf16_f32 v12, v4, v5
	v_and_b32_e32 v5, 0xffff0000, v12
	v_lshlrev_b32_e32 v4, 16, v12
	v_mul_f32_e32 v5, v5, v5
	v_fmac_f32_e32 v5, v4, v4
	v_add_f32_e32 v9, v5, v9
	v_lshlrev_b32_e32 v4, 16, v7
	v_and_b32_e32 v5, 0xffff0000, v7
	v_and_b32_e32 v7, 0xffff0000, v13
	v_pk_add_f32 v[4:5], v[4:5], v[6:7]
	s_nop 0
	v_cvt_pk_bf16_f32 v13, v4, v5
	v_and_b32_e32 v5, 0xffff0000, v13
	v_lshlrev_b32_e32 v4, 16, v13
	v_mul_f32_e32 v5, v5, v5
	v_fmac_f32_e32 v5, v4, v4
	v_add_f32_e32 v4, v5, v9
	s_nop 1
	v_add_f32_dpp v86, v4, v4 quad_perm:[1,0,3,2] row_mask:0xf bank_mask:0xf
	s_nop 1
	v_add_f32_dpp v86, v86, v86 quad_perm:[2,3,0,1] row_mask:0xf bank_mask:0xf
	s_nop 1
	v_add_f32_dpp v86, v86, v86 row_half_mirror row_mask:0xf bank_mask:0xf
	s_nop 1
	v_add_f32_dpp v86, v86, v86 row_mirror row_mask:0xf bank_mask:0xf
	s_nop 1
	v_add_f32_dpp v86, v86, v86 row_bcast:15 row_mask:0xa bank_mask:0xf
	s_waitcnt lgkmcnt(0)
	s_waitcnt lgkmcnt(0)
	s_waitcnt lgkmcnt(0)
	v_add_u32_e32 v4, 32, v16
	v_ashrrev_i32_e32 v5, 31, v4
	v_lshl_add_u64 v[4:5], s[16:17], 0, v[4:5]
	v_lshlrev_b64 v[14:15], 11, v[4:5]
	s_waitcnt lgkmcnt(0)
	v_lshl_add_u64 v[14:15], s[68:69], 0, v[14:15]
	v_lshl_add_u64 v[14:15], s[18:19], 1, v[14:15]
	v_lshl_add_u64 v[14:15], v[14:15], 0, v[146:147]
	flat_store_dwordx4 v[14:15], v[10:13]
	s_and_saveexec_b64 s[20:21], s[98:99]
	s_cbranch_execz .LBB0_288
	v_lshl_add_u64 v[4:5], v[4:5], 4, s[78:79]
	v_lshl_add_u64 v[4:5], s[6:7], 2, v[4:5]
	s_waitcnt lgkmcnt(0)
	v_mov_b32_e32 v6, v86
	flat_store_dword v[4:5], v6
; DI unsigned pk2(float a, float b) { f32x2 v = {a, b}; bf16x2_t r = __builtin_convertvector(v, bf16x2_t); return __builtin_bit_cast(unsigned, r); }
; DI float bflo(unsigned w) { return __uint_as_float(w << 16); }
; DI float bfhi(unsigned w) { return __uint_as_float(w & 0xffff0000u); }
;     DI void operator()(gacc_t& acc, int pm, int pn, char* lds, int tid, int wr, int wc, int lane) const {
;     ...
;         for (int ib = 0; ib < 4; ++ib) {
;             __builtin_amdgcn_sched_barrier(0);
;             u32x4 xv[4];
; #pragma unroll
;             for (int u = 0; u < 4; ++u) {
;                 const long row = (long)pm * 256 + (ib * 4 + u) * 16 + wid * 2 + g;
;                 xv[u] = *(const u32x4*)(xold + row * 1024 + pn * 256 + j32 * 8);
;             }
; #pragma unroll
;             for (int u = 0; u < 4; ++u) {
;                 const int rloc = (ib * 4 + u) * 16 + wid * 2 + g;
;                 const long row = (long)pm * 256 + rloc;
;                 const u32x4 a = *(const u32x4*)(lds + rloc * 528 + j32 * 16);
;                 u32x4 w; float ss = 0.f;
; #pragma unroll
;                 for (int e = 0; e < 4; ++e) {
;                     w[e] = pk2(bflo(xv[u][e]) + bflo(a[e]), bfhi(xv[u][e]) + bfhi(a[e]));
;                     const float b0 = bflo(w[e]), b1 = bfhi(w[e]);
;                     ss += b0 * b0 + b1 * b1;
;                 }
;                 *(u32x4*)(xnew + row * 1024 + pn * 256 + j32 * 8) = w;
; #pragma unroll
;                 for (int o = 1; o < 32; o <<= 1) ss += __shfl_xor(ss, o);
;                 if (j32 == 0) ssq[row * 4 + pn] = ss;
.LBB0_288:
	s_or_b64 exec, exec, s[20:21]
	v_add_u32_e32 v12, 0x2100, v8
	v_add_u32_e32 v4, v22, v12
	s_waitcnt lgkmcnt(0)
	ds_read_b128 v[4:7], v4
	v_lshlrev_b32_e32 v8, 16, v0
	v_and_b32_e32 v9, 0xffff0000, v0
	s_waitcnt lgkmcnt(0)
	v_lshlrev_b32_e32 v10, 16, v4
	v_and_b32_e32 v11, 0xffff0000, v4
	v_pk_add_f32 v[8:9], v[8:9], v[10:11]
	s_nop 0
	v_cvt_pk_bf16_f32 v4, v8, v9
	v_and_b32_e32 v8, 0xffff0000, v4
	v_lshlrev_b32_e32 v0, 16, v4
	v_mul_f32_e32 v10, v8, v8
	v_fmac_f32_e32 v10, v0, v0
	v_lshlrev_b32_e32 v0, 16, v1
	v_and_b32_e32 v1, 0xffff0000, v1
	v_lshlrev_b32_e32 v8, 16, v5
	v_and_b32_e32 v9, 0xffff0000, v5
	v_pk_add_f32 v[0:1], v[0:1], v[8:9]
	v_lshlrev_b32_e32 v8, 16, v6
	v_cvt_pk_bf16_f32 v5, v0, v1
	v_and_b32_e32 v1, 0xffff0000, v5
	v_lshlrev_b32_e32 v0, 16, v5
	v_mul_f32_e32 v1, v1, v1
	v_fmac_f32_e32 v1, v0, v0
	v_add_f32_e32 v10, v10, v1
	v_lshlrev_b32_e32 v0, 16, v2
	v_and_b32_e32 v1, 0xffff0000, v2
	v_and_b32_e32 v9, 0xffff0000, v6
	v_pk_add_f32 v[0:1], v[0:1], v[8:9]
	v_lshlrev_b32_e32 v2, 16, v7
	v_cvt_pk_bf16_f32 v6, v0, v1
	v_and_b32_e32 v1, 0xffff0000, v6
	v_lshlrev_b32_e32 v0, 16, v6
	v_mul_f32_e32 v1, v1, v1
	v_fmac_f32_e32 v1, v0, v0
	v_add_f32_e32 v8, v1, v10
	v_lshlrev_b32_e32 v0, 16, v3
	v_and_b32_e32 v1, 0xffff0000, v3
	v_and_b32_e32 v3, 0xffff0000, v7
	v_pk_add_f32 v[0:1], v[0:1], v[2:3]
	s_nop 0
	v_cvt_pk_bf16_f32 v7, v0, v1
	v_and_b32_e32 v1, 0xffff0000, v7
	v_lshlrev_b32_e32 v0, 16, v7
	v_mul_f32_e32 v1, v1, v1
	v_fmac_f32_e32 v1, v0, v0
	v_add_f32_e32 v0, v1, v8
	s_nop 1
	v_add_f32_dpp v86, v0, v0 quad_perm:[1,0,3,2] row_mask:0xf bank_mask:0xf
	s_nop 1
	v_add_f32_dpp v86, v86, v86 quad_perm:[2,3,0,1] row_mask:0xf bank_mask:0xf
	s_nop 1
	v_add_f32_dpp v86, v86, v86 row_half_mirror row_mask:0xf bank_mask:0xf
	s_nop 1
	v_add_f32_dpp v86, v86, v86 row_mirror row_mask:0xf bank_mask:0xf
	s_nop 1
	v_add_f32_dpp v86, v86, v86 row_bcast:15 row_mask:0xa bank_mask:0xf
	s_waitcnt lgkmcnt(0)
	s_waitcnt lgkmcnt(0)
	s_waitcnt lgkmcnt(0)
	v_add_u32_e32 v0, 48, v16
	v_ashrrev_i32_e32 v1, 31, v0
	v_lshl_add_u64 v[0:1], s[16:17], 0, v[0:1]
	v_lshlrev_b64 v[8:9], 11, v[0:1]
	s_waitcnt lgkmcnt(0)
	v_lshl_add_u64 v[8:9], s[68:69], 0, v[8:9]
	v_lshl_add_u64 v[8:9], s[18:19], 1, v[8:9]
	v_lshl_add_u64 v[8:9], v[8:9], 0, v[146:147]
	flat_store_dwordx4 v[8:9], v[4:7]
	s_and_saveexec_b64 s[20:21], s[98:99]
	s_cbranch_execz .LBB0_290
	v_lshl_add_u64 v[0:1], v[0:1], 4, s[78:79]
	v_lshl_add_u64 v[0:1], s[6:7], 2, v[0:1]
	s_waitcnt lgkmcnt(0)
	v_mov_b32_e32 v2, v86
	flat_store_dword v[0:1], v2
.LBB0_290:
	s_or_b64 exec, exec, s[20:21]
	v_add_co_u32_e32 v0, vcc, 0x20000, v18
	v_add_u32_e32 v17, 0x2100, v12
	s_nop 0
	v_addc_co_u32_e32 v1, vcc, 0, v19, vcc
	flat_load_dwordx4 v[24:27], v[0:1]
	v_add_co_u32_e32 v0, vcc, 0x28000, v18
	v_add_u32_e32 v12, v22, v17
	s_nop 0
	v_addc_co_u32_e32 v1, vcc, 0, v19, vcc
	flat_load_dwordx4 v[8:11], v[0:1]
	v_add_co_u32_e32 v0, vcc, 0x30000, v18
	ds_read_b128 v[12:15], v12
	s_nop 0
	v_addc_co_u32_e32 v1, vcc, 0, v19, vcc
	flat_load_dwordx4 v[4:7], v[0:1]
	v_add_co_u32_e32 v0, vcc, 0x38000, v18
	s_waitcnt lgkmcnt(0)
	v_lshlrev_b32_e32 v30, 16, v12
	v_addc_co_u32_e32 v1, vcc, 0, v19, vcc
	flat_load_dwordx4 v[0:3], v[0:1]
	v_and_b32_e32 v31, 0xffff0000, v12
	v_add_u32_e32 v20, 64, v16
	v_ashrrev_i32_e32 v21, 31, v20
	v_lshl_add_u64 v[20:21], s[16:17], 0, v[20:21]
	s_waitcnt vmcnt(0)
	v_lshlrev_b32_e32 v28, 16, v24
	v_and_b32_e32 v29, 0xffff0000, v24
	v_pk_add_f32 v[28:29], v[28:29], v[30:31]
	s_nop 0
	v_cvt_pk_bf16_f32 v12, v28, v29
	v_and_b32_e32 v24, 0xffff0000, v12
	v_mul_f32_e32 v30, v24, v24
	v_lshlrev_b32_e32 v24, 16, v25
	v_and_b32_e32 v25, 0xffff0000, v25
	v_lshlrev_b32_e32 v28, 16, v13
	v_and_b32_e32 v29, 0xffff0000, v13
	v_pk_add_f32 v[24:25], v[24:25], v[28:29]
	v_lshlrev_b32_e32 v23, 16, v12
	v_cvt_pk_bf16_f32 v13, v24, v25
	v_and_b32_e32 v24, 0xffff0000, v13
	v_fmac_f32_e32 v30, v23, v23
	v_lshlrev_b32_e32 v23, 16, v13
	v_mul_f32_e32 v24, v24, v24
	v_fmac_f32_e32 v24, v23, v23
	v_add_f32_e32 v23, v30, v24
	v_lshlrev_b32_e32 v24, 16, v26
	v_and_b32_e32 v25, 0xffff0000, v26
	v_lshlrev_b32_e32 v28, 16, v14
	v_and_b32_e32 v29, 0xffff0000, v14
	v_pk_add_f32 v[24:25], v[24:25], v[28:29]
	v_lshlrev_b32_e32 v26, 16, v15
	v_cvt_pk_bf16_f32 v14, v24, v25
	v_and_b32_e32 v25, 0xffff0000, v14
	v_lshlrev_b32_e32 v24, 16, v14
	v_mul_f32_e32 v25, v25, v25
	v_fmac_f32_e32 v25, v24, v24
	v_add_f32_e32 v23, v25, v23
	v_lshlrev_b32_e32 v24, 16, v27
	v_and_b32_e32 v25, 0xffff0000, v27
	v_and_b32_e32 v27, 0xffff0000, v15
	v_pk_add_f32 v[24:25], v[24:25], v[26:27]
	s_nop 0
	v_cvt_pk_bf16_f32 v15, v24, v25
	v_and_b32_e32 v25, 0xffff0000, v15
	v_lshlrev_b32_e32 v24, 16, v15
	v_mul_f32_e32 v25, v25, v25
	v_fmac_f32_e32 v25, v24, v24
	v_add_f32_e32 v23, v25, v23
	v_lshlrev_b64 v[24:25], 11, v[20:21]
	v_lshl_add_u64 v[24:25], s[68:69], 0, v[24:25]
	v_lshl_add_u64 v[24:25], s[18:19], 1, v[24:25]
	v_lshl_add_u64 v[24:25], v[24:25], 0, v[146:147]
	flat_store_dwordx4 v[24:25], v[12:15]
	s_nop 1
	v_add_f32_dpp v86, v23, v23 quad_perm:[1,0,3,2] row_mask:0xf bank_mask:0xf
	s_nop 1
	v_add_f32_dpp v86, v86, v86 quad_perm:[2,3,0,1] row_mask:0xf bank_mask:0xf
	s_nop 1
	v_add_f32_dpp v86, v86, v86 row_half_mirror row_mask:0xf bank_mask:0xf
	s_nop 1
	v_add_f32_dpp v86, v86, v86 row_mirror row_mask:0xf bank_mask:0xf
	s_nop 1
	v_add_f32_dpp v86, v86, v86 row_bcast:15 row_mask:0xa bank_mask:0xf
	s_waitcnt lgkmcnt(0)
	s_waitcnt lgkmcnt(0)
	s_waitcnt lgkmcnt(0)
	s_waitcnt lgkmcnt(0)
	s_and_saveexec_b64 s[20:21], s[98:99]
	s_cbranch_execz .LBB0_292
	v_lshl_add_u64 v[14:15], v[20:21], 4, s[78:79]
	v_lshl_add_u64 v[14:15], s[6:7], 2, v[14:15]
	s_waitcnt lgkmcnt(0)
	v_mov_b32_e32 v12, v86
	flat_store_dword v[14:15], v12
; DI unsigned pk2(float a, float b) { f32x2 v = {a, b}; bf16x2_t r = __builtin_convertvector(v, bf16x2_t); return __builtin_bit_cast(unsigned, r); }
; DI float bflo(unsigned w) { return __uint_as_float(w << 16); }
; DI float bfhi(unsigned w) { return __uint_as_float(w & 0xffff0000u); }
;     DI void operator()(gacc_t& acc, int pm, int pn, char* lds, int tid, int wr, int wc, int lane) const {
;     ...
;             for (int u = 0; u < 4; ++u) {
;                 const int rloc = (ib * 4 + u) * 16 + wid * 2 + g;
;                 const long row = (long)pm * 256 + rloc;
;                 const u32x4 a = *(const u32x4*)(lds + rloc * 528 + j32 * 16);
;                 u32x4 w; float ss = 0.f;
; #pragma unroll
;                 for (int e = 0; e < 4; ++e) {
;                     w[e] = pk2(bflo(xv[u][e]) + bflo(a[e]), bfhi(xv[u][e]) + bfhi(a[e]));
;                     const float b0 = bflo(w[e]), b1 = bfhi(w[e]);
;                     ss += b0 * b0 + b1 * b1;
;                 }
;                 *(u32x4*)(xnew + row * 1024 + pn * 256 + j32 * 8) = w;
; #pragma unroll
;                 for (int o = 1; o < 32; o <<= 1) ss += __shfl_xor(ss, o);
;                 if (j32 == 0) ssq[row * 4 + pn] = ss;
.LBB0_292:
	s_or_b64 exec, exec, s[20:21]
	v_add_u32_e32 v12, 0x2100, v17
	s_waitcnt lgkmcnt(0)
	v_add_u32_e32 v13, v22, v12
	ds_read_b128 v[24:27], v13
	v_lshlrev_b32_e32 v14, 16, v8
	v_and_b32_e32 v15, 0xffff0000, v8
	s_waitcnt lgkmcnt(0)
	v_lshlrev_b32_e32 v20, 16, v24
	v_and_b32_e32 v21, 0xffff0000, v24
	v_pk_add_f32 v[14:15], v[14:15], v[20:21]
	s_nop 0
	v_cvt_pk_bf16_f32 v24, v14, v15
	v_and_b32_e32 v13, 0xffff0000, v24
	v_lshlrev_b32_e32 v8, 16, v24
	v_mul_f32_e32 v13, v13, v13
	v_fmac_f32_e32 v13, v8, v8
	v_lshlrev_b32_e32 v8, 16, v9
	v_and_b32_e32 v9, 0xffff0000, v9
	v_lshlrev_b32_e32 v14, 16, v25
	v_and_b32_e32 v15, 0xffff0000, v25
	v_pk_add_f32 v[8:9], v[8:9], v[14:15]
	v_lshlrev_b32_e32 v14, 16, v26
	v_cvt_pk_bf16_f32 v25, v8, v9
	v_and_b32_e32 v9, 0xffff0000, v25
	v_lshlrev_b32_e32 v8, 16, v25
	v_mul_f32_e32 v9, v9, v9
	v_fmac_f32_e32 v9, v8, v8
	v_add_f32_e32 v13, v13, v9
	v_lshlrev_b32_e32 v8, 16, v10
	v_and_b32_e32 v9, 0xffff0000, v10
	v_and_b32_e32 v15, 0xffff0000, v26
	v_pk_add_f32 v[8:9], v[8:9], v[14:15]
	v_lshlrev_b32_e32 v10, 16, v27
	v_cvt_pk_bf16_f32 v26, v8, v9
	v_and_b32_e32 v9, 0xffff0000, v26
	v_lshlrev_b32_e32 v8, 16, v26
	v_mul_f32_e32 v9, v9, v9
	v_fmac_f32_e32 v9, v8, v8
	v_add_f32_e32 v13, v9, v13
	v_lshlrev_b32_e32 v8, 16, v11
	v_and_b32_e32 v9, 0xffff0000, v11
	v_and_b32_e32 v11, 0xffff0000, v27
	v_pk_add_f32 v[8:9], v[8:9], v[10:11]
	s_nop 0
	v_cvt_pk_bf16_f32 v27, v8, v9
	v_and_b32_e32 v9, 0xffff0000, v27
	v_lshlrev_b32_e32 v8, 16, v27
	v_mul_f32_e32 v9, v9, v9
	v_fmac_f32_e32 v9, v8, v8
	v_add_f32_e32 v8, v9, v13
	s_nop 1
	v_add_f32_dpp v86, v8, v8 quad_perm:[1,0,3,2] row_mask:0xf bank_mask:0xf
	s_nop 1
	v_add_f32_dpp v86, v86, v86 quad_perm:[2,3,0,1] row_mask:0xf bank_mask:0xf
	s_nop 1
	v_add_f32_dpp v86, v86, v86 row_half_mirror row_mask:0xf bank_mask:0xf
	s_nop 1
	v_add_f32_dpp v86, v86, v86 row_mirror row_mask:0xf bank_mask:0xf
	s_nop 1
	v_add_f32_dpp v86, v86, v86 row_bcast:15 row_mask:0xa bank_mask:0xf
	s_waitcnt lgkmcnt(0)
	s_waitcnt lgkmcnt(0)
	s_waitcnt lgkmcnt(0)
	v_add_u32_e32 v8, 0x50, v16
	v_ashrrev_i32_e32 v9, 31, v8
	v_lshl_add_u64 v[8:9], s[16:17], 0, v[8:9]
	v_lshlrev_b64 v[14:15], 11, v[8:9]
	s_waitcnt lgkmcnt(0)
	v_lshl_add_u64 v[14:15], s[68:69], 0, v[14:15]
	v_lshl_add_u64 v[14:15], s[18:19], 1, v[14:15]
	v_lshl_add_u64 v[14:15], v[14:15], 0, v[146:147]
	flat_store_dwordx4 v[14:15], v[24:27]
	s_and_saveexec_b64 s[20:21], s[98:99]
	s_cbranch_execz .LBB0_294
	v_lshl_add_u64 v[8:9], v[8:9], 4, s[78:79]
	v_lshl_add_u64 v[8:9], s[6:7], 2, v[8:9]
	s_waitcnt lgkmcnt(0)
	v_mov_b32_e32 v10, v86
	flat_store_dword v[8:9], v10
.LBB0_294:
	s_or_b64 exec, exec, s[20:21]
	v_add_u32_e32 v8, 0x2100, v12
	v_add_u32_e32 v9, v22, v8
	s_waitcnt lgkmcnt(0)
	ds_read_b128 v[10:13], v9
	v_lshlrev_b32_e32 v14, 16, v4
	v_and_b32_e32 v15, 0xffff0000, v4
	s_waitcnt lgkmcnt(0)
	v_lshlrev_b32_e32 v20, 16, v10
	v_and_b32_e32 v21, 0xffff0000, v10
	v_pk_add_f32 v[14:15], v[14:15], v[20:21]
	s_nop 0
	v_cvt_pk_bf16_f32 v10, v14, v15
	v_and_b32_e32 v9, 0xffff0000, v10
	v_lshlrev_b32_e32 v4, 16, v10
	v_mul_f32_e32 v9, v9, v9
	v_fmac_f32_e32 v9, v4, v4
	v_lshlrev_b32_e32 v4, 16, v5
	v_and_b32_e32 v5, 0xffff0000, v5
	v_lshlrev_b32_e32 v14, 16, v11
	v_and_b32_e32 v15, 0xffff0000, v11
	v_pk_add_f32 v[4:5], v[4:5], v[14:15]
	v_lshlrev_b32_e32 v14, 16, v12
	v_cvt_pk_bf16_f32 v11, v4, v5
	v_and_b32_e32 v5, 0xffff0000, v11
	v_lshlrev_b32_e32 v4, 16, v11
	v_mul_f32_e32 v5, v5, v5
	v_fmac_f32_e32 v5, v4, v4
	v_add_f32_e32 v9, v9, v5
	v_lshlrev_b32_e32 v4, 16, v6
	v_and_b32_e32 v5, 0xffff0000, v6
	v_and_b32_e32 v15, 0xffff0000, v12
	v_pk_add_f32 v[4:5], v[4:5], v[14:15]
	v_lshlrev_b32_e32 v6, 16, v13
	v_cvt_pk_bf16_f32 v12, v4, v5
	v_and_b32_e32 v5, 0xffff0000, v12
	v_lshlrev_b32_e32 v4, 16, v12
	v_mul_f32_e32 v5, v5, v5
	v_fmac_f32_e32 v5, v4, v4
	v_add_f32_e32 v9, v5, v9
	v_lshlrev_b32_e32 v4, 16, v7
	v_and_b32_e32 v5, 0xffff0000, v7
	v_and_b32_e32 v7, 0xffff0000, v13
	v_pk_add_f32 v[4:5], v[4:5], v[6:7]
	s_nop 0
	v_cvt_pk_bf16_f32 v13, v4, v5
	v_and_b32_e32 v5, 0xffff0000, v13
	v_lshlrev_b32_e32 v4, 16, v13
	v_mul_f32_e32 v5, v5, v5
	v_fmac_f32_e32 v5, v4, v4
	v_add_f32_e32 v4, v5, v9
	s_nop 1
	v_add_f32_dpp v86, v4, v4 quad_perm:[1,0,3,2] row_mask:0xf bank_mask:0xf
	s_nop 1
	v_add_f32_dpp v86, v86, v86 quad_perm:[2,3,0,1] row_mask:0xf bank_mask:0xf
	s_nop 1
	v_add_f32_dpp v86, v86, v86 row_half_mirror row_mask:0xf bank_mask:0xf
	s_nop 1
	v_add_f32_dpp v86, v86, v86 row_mirror row_mask:0xf bank_mask:0xf
	s_nop 1
	v_add_f32_dpp v86, v86, v86 row_bcast:15 row_mask:0xa bank_mask:0xf
	s_waitcnt lgkmcnt(0)
	s_waitcnt lgkmcnt(0)
	s_waitcnt lgkmcnt(0)
	v_add_u32_e32 v4, 0x60, v16
	v_ashrrev_i32_e32 v5, 31, v4
	v_lshl_add_u64 v[4:5], s[16:17], 0, v[4:5]
	v_lshlrev_b64 v[14:15], 11, v[4:5]
	s_waitcnt lgkmcnt(0)
	v_lshl_add_u64 v[14:15], s[68:69], 0, v[14:15]
	v_lshl_add_u64 v[14:15], s[18:19], 1, v[14:15]
	v_lshl_add_u64 v[14:15], v[14:15], 0, v[146:147]
	flat_store_dwordx4 v[14:15], v[10:13]
	s_and_saveexec_b64 s[20:21], s[98:99]
	s_cbranch_execz .LBB0_296
	v_lshl_add_u64 v[4:5], v[4:5], 4, s[78:79]
	v_lshl_add_u64 v[4:5], s[6:7], 2, v[4:5]
	s_waitcnt lgkmcnt(0)
	v_mov_b32_e32 v6, v86
	flat_store_dword v[4:5], v6
; DI unsigned pk2(float a, float b) { f32x2 v = {a, b}; bf16x2_t r = __builtin_convertvector(v, bf16x2_t); return __builtin_bit_cast(unsigned, r); }
; DI float bflo(unsigned w) { return __uint_as_float(w << 16); }
; DI float bfhi(unsigned w) { return __uint_as_float(w & 0xffff0000u); }
;     DI void operator()(gacc_t& acc, int pm, int pn, char* lds, int tid, int wr, int wc, int lane) const {
;     ...
;         for (int ib = 0; ib < 4; ++ib) {
;             __builtin_amdgcn_sched_barrier(0);
;             u32x4 xv[4];
; #pragma unroll
;             for (int u = 0; u < 4; ++u) {
;                 const long row = (long)pm * 256 + (ib * 4 + u) * 16 + wid * 2 + g;
;                 xv[u] = *(const u32x4*)(xold + row * 1024 + pn * 256 + j32 * 8);
;             }
; #pragma unroll
;             for (int u = 0; u < 4; ++u) {
;                 const int rloc = (ib * 4 + u) * 16 + wid * 2 + g;
;                 const long row = (long)pm * 256 + rloc;
;                 const u32x4 a = *(const u32x4*)(lds + rloc * 528 + j32 * 16);
;                 u32x4 w; float ss = 0.f;
; #pragma unroll
;                 for (int e = 0; e < 4; ++e) {
;                     w[e] = pk2(bflo(xv[u][e]) + bflo(a[e]), bfhi(xv[u][e]) + bfhi(a[e]));
;                     const float b0 = bflo(w[e]), b1 = bfhi(w[e]);
;                     ss += b0 * b0 + b1 * b1;
;                 }
;                 *(u32x4*)(xnew + row * 1024 + pn * 256 + j32 * 8) = w;
; #pragma unroll
;                 for (int o = 1; o < 32; o <<= 1) ss += __shfl_xor(ss, o);
;                 if (j32 == 0) ssq[row * 4 + pn] = ss;
.LBB0_296:
	s_or_b64 exec, exec, s[20:21]
	v_add_u32_e32 v12, 0x2100, v8
	v_add_u32_e32 v4, v22, v12
	s_waitcnt lgkmcnt(0)
	ds_read_b128 v[4:7], v4
	v_lshlrev_b32_e32 v8, 16, v0
	v_and_b32_e32 v9, 0xffff0000, v0
	s_waitcnt lgkmcnt(0)
	v_lshlrev_b32_e32 v10, 16, v4
	v_and_b32_e32 v11, 0xffff0000, v4
	v_pk_add_f32 v[8:9], v[8:9], v[10:11]
	s_nop 0
	v_cvt_pk_bf16_f32 v4, v8, v9
	v_and_b32_e32 v8, 0xffff0000, v4
	v_lshlrev_b32_e32 v0, 16, v4
	v_mul_f32_e32 v10, v8, v8
	v_fmac_f32_e32 v10, v0, v0
	v_lshlrev_b32_e32 v0, 16, v1
	v_and_b32_e32 v1, 0xffff0000, v1
	v_lshlrev_b32_e32 v8, 16, v5
	v_and_b32_e32 v9, 0xffff0000, v5
	v_pk_add_f32 v[0:1], v[0:1], v[8:9]
	v_lshlrev_b32_e32 v8, 16, v6
	v_cvt_pk_bf16_f32 v5, v0, v1
	v_and_b32_e32 v1, 0xffff0000, v5
	v_lshlrev_b32_e32 v0, 16, v5
	v_mul_f32_e32 v1, v1, v1
	v_fmac_f32_e32 v1, v0, v0
	v_add_f32_e32 v10, v10, v1
	v_lshlrev_b32_e32 v0, 16, v2
	v_and_b32_e32 v1, 0xffff0000, v2
	v_and_b32_e32 v9, 0xffff0000, v6
	v_pk_add_f32 v[0:1], v[0:1], v[8:9]
	v_lshlrev_b32_e32 v2, 16, v7
	v_cvt_pk_bf16_f32 v6, v0, v1
	v_and_b32_e32 v1, 0xffff0000, v6
	v_lshlrev_b32_e32 v0, 16, v6
	v_mul_f32_e32 v1, v1, v1
	v_fmac_f32_e32 v1, v0, v0
	v_add_f32_e32 v8, v1, v10
	v_lshlrev_b32_e32 v0, 16, v3
	v_and_b32_e32 v1, 0xffff0000, v3
	v_and_b32_e32 v3, 0xffff0000, v7
	v_pk_add_f32 v[0:1], v[0:1], v[2:3]
	s_nop 0
	v_cvt_pk_bf16_f32 v7, v0, v1
	v_and_b32_e32 v1, 0xffff0000, v7
	v_lshlrev_b32_e32 v0, 16, v7
	v_mul_f32_e32 v1, v1, v1
	v_fmac_f32_e32 v1, v0, v0
	v_add_f32_e32 v0, v1, v8
	s_nop 1
	v_add_f32_dpp v86, v0, v0 quad_perm:[1,0,3,2] row_mask:0xf bank_mask:0xf
	s_nop 1
	v_add_f32_dpp v86, v86, v86 quad_perm:[2,3,0,1] row_mask:0xf bank_mask:0xf
	s_nop 1
	v_add_f32_dpp v86, v86, v86 row_half_mirror row_mask:0xf bank_mask:0xf
	s_nop 1
	v_add_f32_dpp v86, v86, v86 row_mirror row_mask:0xf bank_mask:0xf
	s_nop 1
	v_add_f32_dpp v86, v86, v86 row_bcast:15 row_mask:0xa bank_mask:0xf
	s_waitcnt lgkmcnt(0)
	s_waitcnt lgkmcnt(0)
	s_waitcnt lgkmcnt(0)
	v_add_u32_e32 v0, 0x70, v16
	v_ashrrev_i32_e32 v1, 31, v0
	v_lshl_add_u64 v[0:1], s[16:17], 0, v[0:1]
	v_lshlrev_b64 v[8:9], 11, v[0:1]
	s_waitcnt lgkmcnt(0)
	v_lshl_add_u64 v[8:9], s[68:69], 0, v[8:9]
	v_lshl_add_u64 v[8:9], s[18:19], 1, v[8:9]
	v_lshl_add_u64 v[8:9], v[8:9], 0, v[146:147]
	flat_store_dwordx4 v[8:9], v[4:7]
	s_and_saveexec_b64 s[20:21], s[98:99]
	s_cbranch_execz .LBB0_298
	v_lshl_add_u64 v[0:1], v[0:1], 4, s[78:79]
	v_lshl_add_u64 v[0:1], s[6:7], 2, v[0:1]
	s_waitcnt lgkmcnt(0)
	v_mov_b32_e32 v2, v86
	flat_store_dword v[0:1], v2
.LBB0_298:
	s_or_b64 exec, exec, s[20:21]
	v_add_co_u32_e32 v0, vcc, 0x40000, v18
	v_add_u32_e32 v12, 0x2100, v12
	s_nop 0
	v_addc_co_u32_e32 v1, vcc, 0, v19, vcc
	flat_load_dwordx4 v[24:27], v[0:1]
	v_add_co_u32_e32 v0, vcc, 0x48000, v18
	v_add_u32_e32 v17, v22, v12
	s_nop 0
	v_addc_co_u32_e32 v1, vcc, 0, v19, vcc
	flat_load_dwordx4 v[8:11], v[0:1]
	v_add_co_u32_e32 v0, vcc, 0x50000, v18
	ds_read_b128 v[12:15], v17
	s_nop 0
	v_addc_co_u32_e32 v1, vcc, 0, v19, vcc
	flat_load_dwordx4 v[4:7], v[0:1]
	v_add_co_u32_e32 v0, vcc, 0x58000, v18
	s_waitcnt lgkmcnt(0)
	v_lshlrev_b32_e32 v28, 16, v12
	v_addc_co_u32_e32 v1, vcc, 0, v19, vcc
	flat_load_dwordx4 v[0:3], v[0:1]
	v_and_b32_e32 v29, 0xffff0000, v12
	v_add_u32_e32 v20, 0x80, v16
	v_ashrrev_i32_e32 v21, 31, v20
	v_lshl_add_u64 v[20:21], s[16:17], 0, v[20:21]
	s_waitcnt vmcnt(0)
	v_lshlrev_b32_e32 v22, 16, v24
	v_and_b32_e32 v23, 0xffff0000, v24
	v_pk_add_f32 v[22:23], v[22:23], v[28:29]
	v_lshlrev_b32_e32 v24, 16, v13
	v_cvt_pk_bf16_f32 v12, v22, v23
	v_and_b32_e32 v23, 0xffff0000, v12
	v_lshlrev_b32_e32 v22, 16, v12
	v_mul_f32_e32 v28, v23, v23
	v_fmac_f32_e32 v28, v22, v22
	v_lshlrev_b32_e32 v22, 16, v25
	v_and_b32_e32 v23, 0xffff0000, v25
	v_and_b32_e32 v25, 0xffff0000, v13
	v_pk_add_f32 v[22:23], v[22:23], v[24:25]
	v_lshlrev_b32_e32 v24, 16, v14
	v_cvt_pk_bf16_f32 v13, v22, v23
	v_and_b32_e32 v23, 0xffff0000, v13
	v_lshlrev_b32_e32 v22, 16, v13
	v_mul_f32_e32 v23, v23, v23
	v_fmac_f32_e32 v23, v22, v22
	v_add_f32_e32 v28, v28, v23
	v_lshlrev_b32_e32 v22, 16, v26
	v_and_b32_e32 v23, 0xffff0000, v26
	v_and_b32_e32 v25, 0xffff0000, v14
	v_pk_add_f32 v[22:23], v[22:23], v[24:25]
	v_lshlrev_b32_e32 v24, 16, v15
	v_cvt_pk_bf16_f32 v14, v22, v23
	v_and_b32_e32 v23, 0xffff0000, v14
	v_lshlrev_b32_e32 v22, 16, v14
	v_mul_f32_e32 v23, v23, v23
	v_fmac_f32_e32 v23, v22, v22
	v_add_f32_e32 v26, v23, v28
	v_lshlrev_b32_e32 v22, 16, v27
	v_and_b32_e32 v23, 0xffff0000, v27
	v_and_b32_e32 v25, 0xffff0000, v15
	v_pk_add_f32 v[22:23], v[22:23], v[24:25]
	s_nop 0
	v_cvt_pk_bf16_f32 v15, v22, v23
	v_and_b32_e32 v23, 0xffff0000, v15
	v_lshlrev_b32_e32 v22, 16, v15
	v_mul_f32_e32 v23, v23, v23
	v_fmac_f32_e32 v23, v22, v22
	v_add_f32_e32 v24, v23, v26
	v_lshlrev_b64 v[22:23], 11, v[20:21]
	v_lshl_add_u64 v[22:23], s[68:69], 0, v[22:23]
	v_lshl_add_u64 v[22:23], s[18:19], 1, v[22:23]
	v_lshl_add_u64 v[22:23], v[22:23], 0, v[146:147]
	flat_store_dwordx4 v[22:23], v[12:15]
	s_nop 1
	v_add_f32_dpp v86, v24, v24 quad_perm:[1,0,3,2] row_mask:0xf bank_mask:0xf
	s_nop 1
	v_add_f32_dpp v86, v86, v86 quad_perm:[2,3,0,1] row_mask:0xf bank_mask:0xf
	s_nop 1
	v_add_f32_dpp v86, v86, v86 row_half_mirror row_mask:0xf bank_mask:0xf
	s_nop 1
	v_add_f32_dpp v86, v86, v86 row_mirror row_mask:0xf bank_mask:0xf
	s_nop 1
	v_add_f32_dpp v86, v86, v86 row_bcast:15 row_mask:0xa bank_mask:0xf
	s_waitcnt lgkmcnt(0)
	s_waitcnt lgkmcnt(0)
	s_waitcnt lgkmcnt(0)
	s_waitcnt lgkmcnt(0)
	s_and_saveexec_b64 s[20:21], s[98:99]
	s_cbranch_execz .LBB0_300
	v_lshl_add_u64 v[14:15], v[20:21], 4, s[78:79]
	v_lshl_add_u64 v[14:15], s[6:7], 2, v[14:15]
	s_waitcnt lgkmcnt(0)
	v_mov_b32_e32 v12, v86
	flat_store_dword v[14:15], v12
; DI unsigned pk2(float a, float b) { f32x2 v = {a, b}; bf16x2_t r = __builtin_convertvector(v, bf16x2_t); return __builtin_bit_cast(unsigned, r); }
; DI float bflo(unsigned w) { return __uint_as_float(w << 16); }
; DI float bfhi(unsigned w) { return __uint_as_float(w & 0xffff0000u); }
;     DI void operator()(gacc_t& acc, int pm, int pn, char* lds, int tid, int wr, int wc, int lane) const {
;     ...
;             for (int u = 0; u < 4; ++u) {
;                 const int rloc = (ib * 4 + u) * 16 + wid * 2 + g;
;                 const long row = (long)pm * 256 + rloc;
;                 const u32x4 a = *(const u32x4*)(lds + rloc * 528 + j32 * 16);
;                 u32x4 w; float ss = 0.f;
; #pragma unroll
;                 for (int e = 0; e < 4; ++e) {
;                     w[e] = pk2(bflo(xv[u][e]) + bflo(a[e]), bfhi(xv[u][e]) + bfhi(a[e]));
;                     const float b0 = bflo(w[e]), b1 = bfhi(w[e]);
;                     ss += b0 * b0 + b1 * b1;
;                 }
;                 *(u32x4*)(xnew + row * 1024 + pn * 256 + j32 * 8) = w;
; #pragma unroll
;                 for (int o = 1; o < 32; o <<= 1) ss += __shfl_xor(ss, o);
;                 if (j32 == 0) ssq[row * 4 + pn] = ss;
.LBB0_300:
	s_or_b64 exec, exec, s[20:21]
	s_waitcnt lgkmcnt(0)
	ds_read_b128 v[12:15], v17 offset:8448
	v_lshlrev_b32_e32 v20, 16, v8
	v_and_b32_e32 v21, 0xffff0000, v8
	s_waitcnt lgkmcnt(0)
	v_lshlrev_b32_e32 v22, 16, v12
	v_and_b32_e32 v23, 0xffff0000, v12
	v_pk_add_f32 v[20:21], v[20:21], v[22:23]
	s_nop 0
	v_cvt_pk_bf16_f32 v12, v20, v21
	v_and_b32_e32 v20, 0xffff0000, v12
	v_lshlrev_b32_e32 v8, 16, v12
	v_mul_f32_e32 v22, v20, v20
	v_fmac_f32_e32 v22, v8, v8
	v_lshlrev_b32_e32 v8, 16, v9
	v_and_b32_e32 v9, 0xffff0000, v9
	v_lshlrev_b32_e32 v20, 16, v13
	v_and_b32_e32 v21, 0xffff0000, v13
	v_pk_add_f32 v[8:9], v[8:9], v[20:21]
	v_lshlrev_b32_e32 v20, 16, v14
	v_cvt_pk_bf16_f32 v13, v8, v9
	v_and_b32_e32 v9, 0xffff0000, v13
	v_lshlrev_b32_e32 v8, 16, v13
	v_mul_f32_e32 v9, v9, v9
	v_fmac_f32_e32 v9, v8, v8
	v_add_f32_e32 v22, v22, v9
	v_lshlrev_b32_e32 v8, 16, v10
	v_and_b32_e32 v9, 0xffff0000, v10
	v_and_b32_e32 v21, 0xffff0000, v14
	v_pk_add_f32 v[8:9], v[8:9], v[20:21]
	v_lshlrev_b32_e32 v10, 16, v15
	v_cvt_pk_bf16_f32 v14, v8, v9
	v_and_b32_e32 v9, 0xffff0000, v14
	v_lshlrev_b32_e32 v8, 16, v14
	v_mul_f32_e32 v9, v9, v9
	v_fmac_f32_e32 v9, v8, v8
	v_add_f32_e32 v20, v9, v22
	v_lshlrev_b32_e32 v8, 16, v11
	v_and_b32_e32 v9, 0xffff0000, v11
	v_and_b32_e32 v11, 0xffff0000, v15
	v_pk_add_f32 v[8:9], v[8:9], v[10:11]
	s_nop 0
	v_cvt_pk_bf16_f32 v15, v8, v9
	v_and_b32_e32 v9, 0xffff0000, v15
	v_lshlrev_b32_e32 v8, 16, v15
	v_mul_f32_e32 v9, v9, v9
	v_fmac_f32_e32 v9, v8, v8
	v_add_f32_e32 v8, v9, v20
	s_nop 1
	v_add_f32_dpp v86, v8, v8 quad_perm:[1,0,3,2] row_mask:0xf bank_mask:0xf
	s_nop 1
	v_add_f32_dpp v86, v86, v86 quad_perm:[2,3,0,1] row_mask:0xf bank_mask:0xf
	s_nop 1
	v_add_f32_dpp v86, v86, v86 row_half_mirror row_mask:0xf bank_mask:0xf
	s_nop 1
	v_add_f32_dpp v86, v86, v86 row_mirror row_mask:0xf bank_mask:0xf
	s_nop 1
	v_add_f32_dpp v86, v86, v86 row_bcast:15 row_mask:0xa bank_mask:0xf
	s_waitcnt lgkmcnt(0)
	s_waitcnt lgkmcnt(0)
	s_waitcnt lgkmcnt(0)
	v_add_u32_e32 v8, 0x90, v16
	v_ashrrev_i32_e32 v9, 31, v8
	v_lshl_add_u64 v[8:9], s[16:17], 0, v[8:9]
	v_lshlrev_b64 v[20:21], 11, v[8:9]
	s_waitcnt lgkmcnt(0)
	v_lshl_add_u64 v[20:21], s[68:69], 0, v[20:21]
	v_lshl_add_u64 v[20:21], s[18:19], 1, v[20:21]
	v_lshl_add_u64 v[20:21], v[20:21], 0, v[146:147]
	flat_store_dwordx4 v[20:21], v[12:15]
	s_and_saveexec_b64 s[20:21], s[98:99]
	s_cbranch_execz .LBB0_302
	v_lshl_add_u64 v[8:9], v[8:9], 4, s[78:79]
	v_lshl_add_u64 v[8:9], s[6:7], 2, v[8:9]
	s_waitcnt lgkmcnt(0)
	v_mov_b32_e32 v10, v86
	flat_store_dword v[8:9], v10
.LBB0_302:
	s_or_b64 exec, exec, s[20:21]
	s_waitcnt lgkmcnt(0)
	ds_read_b128 v[8:11], v17 offset:16896
	v_lshlrev_b32_e32 v12, 16, v4
	v_and_b32_e32 v13, 0xffff0000, v4
	s_waitcnt lgkmcnt(0)
	v_lshlrev_b32_e32 v14, 16, v8
	v_and_b32_e32 v15, 0xffff0000, v8
	v_pk_add_f32 v[12:13], v[12:13], v[14:15]
	s_nop 0
	v_cvt_pk_bf16_f32 v8, v12, v13
	v_and_b32_e32 v12, 0xffff0000, v8
	v_lshlrev_b32_e32 v4, 16, v8
	v_mul_f32_e32 v14, v12, v12
	v_fmac_f32_e32 v14, v4, v4
	v_lshlrev_b32_e32 v4, 16, v5
	v_and_b32_e32 v5, 0xffff0000, v5
	v_lshlrev_b32_e32 v12, 16, v9
	v_and_b32_e32 v13, 0xffff0000, v9
	v_pk_add_f32 v[4:5], v[4:5], v[12:13]
	v_lshlrev_b32_e32 v12, 16, v10
	v_cvt_pk_bf16_f32 v9, v4, v5
	v_and_b32_e32 v5, 0xffff0000, v9
	v_lshlrev_b32_e32 v4, 16, v9
	v_mul_f32_e32 v5, v5, v5
	v_fmac_f32_e32 v5, v4, v4
	v_add_f32_e32 v14, v14, v5
	v_lshlrev_b32_e32 v4, 16, v6
	v_and_b32_e32 v5, 0xffff0000, v6
	v_and_b32_e32 v13, 0xffff0000, v10
	v_pk_add_f32 v[4:5], v[4:5], v[12:13]
	v_lshlrev_b32_e32 v6, 16, v11
	v_cvt_pk_bf16_f32 v10, v4, v5
	v_and_b32_e32 v5, 0xffff0000, v10
	v_lshlrev_b32_e32 v4, 16, v10
	v_mul_f32_e32 v5, v5, v5
	v_fmac_f32_e32 v5, v4, v4
	v_add_f32_e32 v12, v5, v14
	v_lshlrev_b32_e32 v4, 16, v7
	v_and_b32_e32 v5, 0xffff0000, v7
	v_and_b32_e32 v7, 0xffff0000, v11
	v_pk_add_f32 v[4:5], v[4:5], v[6:7]
	s_nop 0
	v_cvt_pk_bf16_f32 v11, v4, v5
	v_and_b32_e32 v5, 0xffff0000, v11
	v_lshlrev_b32_e32 v4, 16, v11
	v_mul_f32_e32 v5, v5, v5
	v_fmac_f32_e32 v5, v4, v4
	v_add_f32_e32 v4, v5, v12
	s_nop 1
	v_add_f32_dpp v86, v4, v4 quad_perm:[1,0,3,2] row_mask:0xf bank_mask:0xf
	s_nop 1
	v_add_f32_dpp v86, v86, v86 quad_perm:[2,3,0,1] row_mask:0xf bank_mask:0xf
	s_nop 1
	v_add_f32_dpp v86, v86, v86 row_half_mirror row_mask:0xf bank_mask:0xf
	s_nop 1
	v_add_f32_dpp v86, v86, v86 row_mirror row_mask:0xf bank_mask:0xf
	s_nop 1
	v_add_f32_dpp v86, v86, v86 row_bcast:15 row_mask:0xa bank_mask:0xf
	s_waitcnt lgkmcnt(0)
	s_waitcnt lgkmcnt(0)
	s_waitcnt lgkmcnt(0)
	v_add_u32_e32 v4, 0xa0, v16
	v_ashrrev_i32_e32 v5, 31, v4
	v_lshl_add_u64 v[4:5], s[16:17], 0, v[4:5]
	v_lshlrev_b64 v[12:13], 11, v[4:5]
	s_waitcnt lgkmcnt(0)
	v_lshl_add_u64 v[12:13], s[68:69], 0, v[12:13]
	v_lshl_add_u64 v[12:13], s[18:19], 1, v[12:13]
	v_lshl_add_u64 v[12:13], v[12:13], 0, v[146:147]
	flat_store_dwordx4 v[12:13], v[8:11]
	s_and_saveexec_b64 s[20:21], s[98:99]
	s_cbranch_execz .LBB0_304
	v_lshl_add_u64 v[4:5], v[4:5], 4, s[78:79]
	v_lshl_add_u64 v[4:5], s[6:7], 2, v[4:5]
	s_waitcnt lgkmcnt(0)
	v_mov_b32_e32 v6, v86
	flat_store_dword v[4:5], v6
; DI unsigned pk2(float a, float b) { f32x2 v = {a, b}; bf16x2_t r = __builtin_convertvector(v, bf16x2_t); return __builtin_bit_cast(unsigned, r); }
; DI float bflo(unsigned w) { return __uint_as_float(w << 16); }
; DI float bfhi(unsigned w) { return __uint_as_float(w & 0xffff0000u); }
;     DI void operator()(gacc_t& acc, int pm, int pn, char* lds, int tid, int wr, int wc, int lane) const {
;     ...
;         for (int ib = 0; ib < 4; ++ib) {
;             __builtin_amdgcn_sched_barrier(0);
;             u32x4 xv[4];
; #pragma unroll
;             for (int u = 0; u < 4; ++u) {
;                 const long row = (long)pm * 256 + (ib * 4 + u) * 16 + wid * 2 + g;
;                 xv[u] = *(const u32x4*)(xold + row * 1024 + pn * 256 + j32 * 8);
;             }
; #pragma unroll
;             for (int u = 0; u < 4; ++u) {
;                 const int rloc = (ib * 4 + u) * 16 + wid * 2 + g;
;                 const long row = (long)pm * 256 + rloc;
;                 const u32x4 a = *(const u32x4*)(lds + rloc * 528 + j32 * 16);
;                 u32x4 w; float ss = 0.f;
; #pragma unroll
;                 for (int e = 0; e < 4; ++e) {
;                     w[e] = pk2(bflo(xv[u][e]) + bflo(a[e]), bfhi(xv[u][e]) + bfhi(a[e]));
;                     const float b0 = bflo(w[e]), b1 = bfhi(w[e]);
;                     ss += b0 * b0 + b1 * b1;
;                 }
;                 *(u32x4*)(xnew + row * 1024 + pn * 256 + j32 * 8) = w;
; #pragma unroll
;                 for (int o = 1; o < 32; o <<= 1) ss += __shfl_xor(ss, o);
;                 if (j32 == 0) ssq[row * 4 + pn] = ss;
.LBB0_304:
	s_or_b64 exec, exec, s[20:21]
	s_waitcnt lgkmcnt(0)
	ds_read_b128 v[4:7], v17 offset:25344
	v_lshlrev_b32_e32 v8, 16, v0
	v_and_b32_e32 v9, 0xffff0000, v0
	s_waitcnt lgkmcnt(0)
	v_lshlrev_b32_e32 v10, 16, v4
	v_and_b32_e32 v11, 0xffff0000, v4
	v_pk_add_f32 v[8:9], v[8:9], v[10:11]
	s_nop 0
	v_cvt_pk_bf16_f32 v4, v8, v9
	v_and_b32_e32 v8, 0xffff0000, v4
	v_lshlrev_b32_e32 v0, 16, v4
	v_mul_f32_e32 v10, v8, v8
	v_fmac_f32_e32 v10, v0, v0
	v_lshlrev_b32_e32 v0, 16, v1
	v_and_b32_e32 v1, 0xffff0000, v1
	v_lshlrev_b32_e32 v8, 16, v5
	v_and_b32_e32 v9, 0xffff0000, v5
	v_pk_add_f32 v[0:1], v[0:1], v[8:9]
	v_lshlrev_b32_e32 v8, 16, v6
	v_cvt_pk_bf16_f32 v5, v0, v1
	v_and_b32_e32 v1, 0xffff0000, v5
	v_lshlrev_b32_e32 v0, 16, v5
	v_mul_f32_e32 v1, v1, v1
	v_fmac_f32_e32 v1, v0, v0
	v_add_f32_e32 v10, v10, v1
	v_lshlrev_b32_e32 v0, 16, v2
	v_and_b32_e32 v1, 0xffff0000, v2
	v_and_b32_e32 v9, 0xffff0000, v6
	v_pk_add_f32 v[0:1], v[0:1], v[8:9]
	v_lshlrev_b32_e32 v2, 16, v7
	v_cvt_pk_bf16_f32 v6, v0, v1
	v_and_b32_e32 v1, 0xffff0000, v6
	v_lshlrev_b32_e32 v0, 16, v6
	v_mul_f32_e32 v1, v1, v1
	v_fmac_f32_e32 v1, v0, v0
	v_add_f32_e32 v8, v1, v10
	v_lshlrev_b32_e32 v0, 16, v3
	v_and_b32_e32 v1, 0xffff0000, v3
	v_and_b32_e32 v3, 0xffff0000, v7
	v_pk_add_f32 v[0:1], v[0:1], v[2:3]
	s_nop 0
	v_cvt_pk_bf16_f32 v7, v0, v1
	v_and_b32_e32 v1, 0xffff0000, v7
	v_lshlrev_b32_e32 v0, 16, v7
	v_mul_f32_e32 v1, v1, v1
	v_fmac_f32_e32 v1, v0, v0
	v_add_f32_e32 v0, v1, v8
	s_nop 1
	v_add_f32_dpp v86, v0, v0 quad_perm:[1,0,3,2] row_mask:0xf bank_mask:0xf
	s_nop 1
	v_add_f32_dpp v86, v86, v86 quad_perm:[2,3,0,1] row_mask:0xf bank_mask:0xf
	s_nop 1
	v_add_f32_dpp v86, v86, v86 row_half_mirror row_mask:0xf bank_mask:0xf
	s_nop 1
	v_add_f32_dpp v86, v86, v86 row_mirror row_mask:0xf bank_mask:0xf
	s_nop 1
	v_add_f32_dpp v86, v86, v86 row_bcast:15 row_mask:0xa bank_mask:0xf
	s_waitcnt lgkmcnt(0)
	s_waitcnt lgkmcnt(0)
	s_waitcnt lgkmcnt(0)
	v_add_u32_e32 v0, 0xb0, v16
	v_ashrrev_i32_e32 v1, 31, v0
	v_lshl_add_u64 v[0:1], s[16:17], 0, v[0:1]
	v_lshlrev_b64 v[8:9], 11, v[0:1]
	s_waitcnt lgkmcnt(0)
	v_lshl_add_u64 v[8:9], s[68:69], 0, v[8:9]
	v_lshl_add_u64 v[8:9], s[18:19], 1, v[8:9]
	v_lshl_add_u64 v[8:9], v[8:9], 0, v[146:147]
	flat_store_dwordx4 v[8:9], v[4:7]
	s_and_saveexec_b64 s[20:21], s[98:99]
	s_cbranch_execz .LBB0_306
	v_lshl_add_u64 v[0:1], v[0:1], 4, s[78:79]
	v_lshl_add_u64 v[0:1], s[6:7], 2, v[0:1]
	s_waitcnt lgkmcnt(0)
	v_mov_b32_e32 v2, v86
	flat_store_dword v[0:1], v2
.LBB0_306:
	s_or_b64 exec, exec, s[20:21]
	v_add_co_u32_e32 v0, vcc, 0x60000, v18
	ds_read_b128 v[20:23], v17 offset:33792
	s_nop 0
	v_addc_co_u32_e32 v1, vcc, 0, v19, vcc
	flat_load_dwordx4 v[12:15], v[0:1]
	v_add_co_u32_e32 v0, vcc, 0x68000, v18
	s_waitcnt lgkmcnt(0)
	v_lshlrev_b32_e32 v26, 16, v20
	v_addc_co_u32_e32 v1, vcc, 0, v19, vcc
	flat_load_dwordx4 v[8:11], v[0:1]
	v_add_co_u32_e32 v0, vcc, 0x70000, v18
	v_and_b32_e32 v27, 0xffff0000, v20
	s_nop 0
	v_addc_co_u32_e32 v1, vcc, 0, v19, vcc
	flat_load_dwordx4 v[4:7], v[0:1]
	v_add_co_u32_e32 v0, vcc, 0x78000, v18
	v_add_u32_e32 v18, 0xc0, v16
	s_nop 0
	v_addc_co_u32_e32 v1, vcc, 0, v19, vcc
	flat_load_dwordx4 v[0:3], v[0:1]
	v_ashrrev_i32_e32 v19, 31, v18
	v_lshl_add_u64 v[18:19], s[16:17], 0, v[18:19]
	s_waitcnt vmcnt(0)
	v_lshlrev_b32_e32 v24, 16, v12
	v_and_b32_e32 v25, 0xffff0000, v12
	v_pk_add_f32 v[24:25], v[24:25], v[26:27]
	s_nop 0
	v_cvt_pk_bf16_f32 v12, v24, v25
	v_and_b32_e32 v24, 0xffff0000, v12
	v_lshlrev_b32_e32 v20, 16, v12
	v_mul_f32_e32 v26, v24, v24
	v_fmac_f32_e32 v26, v20, v20
	v_lshlrev_b32_e32 v24, 16, v13
	v_and_b32_e32 v25, 0xffff0000, v13
	v_lshlrev_b32_e32 v20, 16, v21
	v_and_b32_e32 v21, 0xffff0000, v21
	v_pk_add_f32 v[20:21], v[24:25], v[20:21]
	v_lshlrev_b32_e32 v24, 16, v22
	v_cvt_pk_bf16_f32 v13, v20, v21
	v_and_b32_e32 v21, 0xffff0000, v13
	v_lshlrev_b32_e32 v20, 16, v13
	v_mul_f32_e32 v21, v21, v21
	v_fmac_f32_e32 v21, v20, v20
	v_add_f32_e32 v26, v26, v21
	v_lshlrev_b32_e32 v20, 16, v14
	v_and_b32_e32 v21, 0xffff0000, v14
	v_and_b32_e32 v25, 0xffff0000, v22
	v_pk_add_f32 v[20:21], v[20:21], v[24:25]
	v_lshlrev_b32_e32 v22, 16, v23
	v_cvt_pk_bf16_f32 v14, v20, v21
	v_and_b32_e32 v21, 0xffff0000, v14
	v_lshlrev_b32_e32 v20, 16, v14
	v_mul_f32_e32 v21, v21, v21
	v_fmac_f32_e32 v21, v20, v20
	v_add_f32_e32 v24, v21, v26
	v_lshlrev_b32_e32 v20, 16, v15
	v_and_b32_e32 v21, 0xffff0000, v15
	v_and_b32_e32 v23, 0xffff0000, v23
	v_pk_add_f32 v[20:21], v[20:21], v[22:23]
	s_nop 0
	v_cvt_pk_bf16_f32 v15, v20, v21
	v_and_b32_e32 v21, 0xffff0000, v15
	v_lshlrev_b32_e32 v20, 16, v15
	v_mul_f32_e32 v21, v21, v21
	v_fmac_f32_e32 v21, v20, v20
	v_add_f32_e32 v22, v21, v24
	v_lshlrev_b64 v[20:21], 11, v[18:19]
	v_lshl_add_u64 v[20:21], s[68:69], 0, v[20:21]
	v_lshl_add_u64 v[20:21], s[18:19], 1, v[20:21]
	v_lshl_add_u64 v[20:21], v[20:21], 0, v[146:147]
	flat_store_dwordx4 v[20:21], v[12:15]
	s_nop 1
	v_add_f32_dpp v86, v22, v22 quad_perm:[1,0,3,2] row_mask:0xf bank_mask:0xf
	s_nop 1
	v_add_f32_dpp v86, v86, v86 quad_perm:[2,3,0,1] row_mask:0xf bank_mask:0xf
	s_nop 1
	v_add_f32_dpp v86, v86, v86 row_half_mirror row_mask:0xf bank_mask:0xf
	s_nop 1
	v_add_f32_dpp v86, v86, v86 row_mirror row_mask:0xf bank_mask:0xf
	s_nop 1
	v_add_f32_dpp v86, v86, v86 row_bcast:15 row_mask:0xa bank_mask:0xf
	s_waitcnt lgkmcnt(0)
	s_waitcnt lgkmcnt(0)
	s_waitcnt lgkmcnt(0)
	s_waitcnt lgkmcnt(0)
	s_and_saveexec_b64 s[20:21], s[98:99]
	s_cbranch_execz .LBB0_308
	v_lshl_add_u64 v[14:15], v[18:19], 4, s[78:79]
	v_lshl_add_u64 v[14:15], s[6:7], 2, v[14:15]
	s_waitcnt lgkmcnt(0)
	v_mov_b32_e32 v12, v86
	flat_store_dword v[14:15], v12
; DI unsigned pk2(float a, float b) { f32x2 v = {a, b}; bf16x2_t r = __builtin_convertvector(v, bf16x2_t); return __builtin_bit_cast(unsigned, r); }
; DI float bflo(unsigned w) { return __uint_as_float(w << 16); }
; DI float bfhi(unsigned w) { return __uint_as_float(w & 0xffff0000u); }
;     DI void operator()(gacc_t& acc, int pm, int pn, char* lds, int tid, int wr, int wc, int lane) const {
;     ...
;             for (int u = 0; u < 4; ++u) {
;                 const int rloc = (ib * 4 + u) * 16 + wid * 2 + g;
;                 const long row = (long)pm * 256 + rloc;
;                 const u32x4 a = *(const u32x4*)(lds + rloc * 528 + j32 * 16);
;                 u32x4 w; float ss = 0.f;
; #pragma unroll
;                 for (int e = 0; e < 4; ++e) {
;                     w[e] = pk2(bflo(xv[u][e]) + bflo(a[e]), bfhi(xv[u][e]) + bfhi(a[e]));
;                     const float b0 = bflo(w[e]), b1 = bfhi(w[e]);
;                     ss += b0 * b0 + b1 * b1;
;                 }
;                 *(u32x4*)(xnew + row * 1024 + pn * 256 + j32 * 8) = w;
; #pragma unroll
;                 for (int o = 1; o < 32; o <<= 1) ss += __shfl_xor(ss, o);
;                 if (j32 == 0) ssq[row * 4 + pn] = ss;
.LBB0_308:
	s_or_b64 exec, exec, s[20:21]
	s_waitcnt lgkmcnt(0)
	ds_read_b128 v[12:15], v17 offset:42240
	v_lshlrev_b32_e32 v18, 16, v8
	v_and_b32_e32 v19, 0xffff0000, v8
	s_waitcnt lgkmcnt(0)
	v_lshlrev_b32_e32 v20, 16, v12
	v_and_b32_e32 v21, 0xffff0000, v12
	v_pk_add_f32 v[18:19], v[18:19], v[20:21]
	s_nop 0
	v_cvt_pk_bf16_f32 v12, v18, v19
	v_and_b32_e32 v18, 0xffff0000, v12
	v_lshlrev_b32_e32 v8, 16, v12
	v_mul_f32_e32 v20, v18, v18
	v_fmac_f32_e32 v20, v8, v8
	v_lshlrev_b32_e32 v8, 16, v9
	v_and_b32_e32 v9, 0xffff0000, v9
	v_lshlrev_b32_e32 v18, 16, v13
	v_and_b32_e32 v19, 0xffff0000, v13
	v_pk_add_f32 v[8:9], v[8:9], v[18:19]
	v_lshlrev_b32_e32 v18, 16, v14
	v_cvt_pk_bf16_f32 v13, v8, v9
	v_and_b32_e32 v9, 0xffff0000, v13
	v_lshlrev_b32_e32 v8, 16, v13
	v_mul_f32_e32 v9, v9, v9
	v_fmac_f32_e32 v9, v8, v8
	v_add_f32_e32 v20, v20, v9
	v_lshlrev_b32_e32 v8, 16, v10
	v_and_b32_e32 v9, 0xffff0000, v10
	v_and_b32_e32 v19, 0xffff0000, v14
	v_pk_add_f32 v[8:9], v[8:9], v[18:19]
	v_lshlrev_b32_e32 v10, 16, v15
	v_cvt_pk_bf16_f32 v14, v8, v9
	v_and_b32_e32 v9, 0xffff0000, v14
	v_lshlrev_b32_e32 v8, 16, v14
	v_mul_f32_e32 v9, v9, v9
	v_fmac_f32_e32 v9, v8, v8
	v_add_f32_e32 v18, v9, v20
	v_lshlrev_b32_e32 v8, 16, v11
	v_and_b32_e32 v9, 0xffff0000, v11
	v_and_b32_e32 v11, 0xffff0000, v15
	v_pk_add_f32 v[8:9], v[8:9], v[10:11]
	s_nop 0
	v_cvt_pk_bf16_f32 v15, v8, v9
	v_and_b32_e32 v9, 0xffff0000, v15
	v_lshlrev_b32_e32 v8, 16, v15
	v_mul_f32_e32 v9, v9, v9
	v_fmac_f32_e32 v9, v8, v8
	v_add_f32_e32 v8, v9, v18
	s_nop 1
	v_add_f32_dpp v86, v8, v8 quad_perm:[1,0,3,2] row_mask:0xf bank_mask:0xf
	s_nop 1
	v_add_f32_dpp v86, v86, v86 quad_perm:[2,3,0,1] row_mask:0xf bank_mask:0xf
	s_nop 1
	v_add_f32_dpp v86, v86, v86 row_half_mirror row_mask:0xf bank_mask:0xf
	s_nop 1
	v_add_f32_dpp v86, v86, v86 row_mirror row_mask:0xf bank_mask:0xf
	s_nop 1
	v_add_f32_dpp v86, v86, v86 row_bcast:15 row_mask:0xa bank_mask:0xf
	s_waitcnt lgkmcnt(0)
	s_waitcnt lgkmcnt(0)
	s_waitcnt lgkmcnt(0)
	v_add_u32_e32 v8, 0xd0, v16
	v_ashrrev_i32_e32 v9, 31, v8
	v_lshl_add_u64 v[8:9], s[16:17], 0, v[8:9]
	v_lshlrev_b64 v[18:19], 11, v[8:9]
	s_waitcnt lgkmcnt(0)
	v_lshl_add_u64 v[18:19], s[68:69], 0, v[18:19]
	v_lshl_add_u64 v[18:19], s[18:19], 1, v[18:19]
	v_lshl_add_u64 v[18:19], v[18:19], 0, v[146:147]
	flat_store_dwordx4 v[18:19], v[12:15]
	s_and_saveexec_b64 s[20:21], s[98:99]
	s_cbranch_execz .LBB0_310
	v_lshl_add_u64 v[8:9], v[8:9], 4, s[78:79]
	v_lshl_add_u64 v[8:9], s[6:7], 2, v[8:9]
	s_waitcnt lgkmcnt(0)
	v_mov_b32_e32 v10, v86
	flat_store_dword v[8:9], v10
; DI unsigned pk2(float a, float b) { f32x2 v = {a, b}; bf16x2_t r = __builtin_convertvector(v, bf16x2_t); return __builtin_bit_cast(unsigned, r); }
; DI float bflo(unsigned w) { return __uint_as_float(w << 16); }
; DI float bfhi(unsigned w) { return __uint_as_float(w & 0xffff0000u); }
;     DI void operator()(gacc_t& acc, int pm, int pn, char* lds, int tid, int wr, int wc, int lane) const {
;     ...
;             for (int u = 0; u < 4; ++u) {
;                 const int rloc = (ib * 4 + u) * 16 + wid * 2 + g;
;                 const long row = (long)pm * 256 + rloc;
;                 const u32x4 a = *(const u32x4*)(lds + rloc * 528 + j32 * 16);
;                 u32x4 w; float ss = 0.f;
; #pragma unroll
;                 for (int e = 0; e < 4; ++e) {
;                     w[e] = pk2(bflo(xv[u][e]) + bflo(a[e]), bfhi(xv[u][e]) + bfhi(a[e]));
;                     const float b0 = bflo(w[e]), b1 = bfhi(w[e]);
;                     ss += b0 * b0 + b1 * b1;
;                 }
;                 *(u32x4*)(xnew + row * 1024 + pn * 256 + j32 * 8) = w;
; #pragma unroll
;                 for (int o = 1; o < 32; o <<= 1) ss += __shfl_xor(ss, o);
;                 if (j32 == 0) ssq[row * 4 + pn] = ss;
.LBB0_310:
	s_or_b64 exec, exec, s[20:21]
	s_waitcnt lgkmcnt(0)
	ds_read_b128 v[8:11], v17 offset:50688
	v_lshlrev_b32_e32 v12, 16, v4
	v_and_b32_e32 v13, 0xffff0000, v4
	s_waitcnt lgkmcnt(0)
	v_lshlrev_b32_e32 v14, 16, v8
	v_and_b32_e32 v15, 0xffff0000, v8
	v_pk_add_f32 v[12:13], v[12:13], v[14:15]
	s_nop 0
	v_cvt_pk_bf16_f32 v8, v12, v13
	v_and_b32_e32 v12, 0xffff0000, v8
	v_lshlrev_b32_e32 v4, 16, v8
	v_mul_f32_e32 v14, v12, v12
	v_fmac_f32_e32 v14, v4, v4
	v_lshlrev_b32_e32 v4, 16, v5
	v_and_b32_e32 v5, 0xffff0000, v5
	v_lshlrev_b32_e32 v12, 16, v9
	v_and_b32_e32 v13, 0xffff0000, v9
	v_pk_add_f32 v[4:5], v[4:5], v[12:13]
	v_lshlrev_b32_e32 v12, 16, v10
	v_cvt_pk_bf16_f32 v9, v4, v5
	v_and_b32_e32 v5, 0xffff0000, v9
	v_lshlrev_b32_e32 v4, 16, v9
	v_mul_f32_e32 v5, v5, v5
	v_fmac_f32_e32 v5, v4, v4
	v_add_f32_e32 v14, v14, v5
	v_lshlrev_b32_e32 v4, 16, v6
	v_and_b32_e32 v5, 0xffff0000, v6
	v_and_b32_e32 v13, 0xffff0000, v10
	v_pk_add_f32 v[4:5], v[4:5], v[12:13]
	v_lshlrev_b32_e32 v6, 16, v11
	v_cvt_pk_bf16_f32 v10, v4, v5
	v_and_b32_e32 v5, 0xffff0000, v10
	v_lshlrev_b32_e32 v4, 16, v10
	v_mul_f32_e32 v5, v5, v5
	v_fmac_f32_e32 v5, v4, v4
	v_add_f32_e32 v12, v5, v14
	v_lshlrev_b32_e32 v4, 16, v7
	v_and_b32_e32 v5, 0xffff0000, v7
	v_and_b32_e32 v7, 0xffff0000, v11
	v_pk_add_f32 v[4:5], v[4:5], v[6:7]
	s_nop 0
	v_cvt_pk_bf16_f32 v11, v4, v5
	v_and_b32_e32 v5, 0xffff0000, v11
	v_lshlrev_b32_e32 v4, 16, v11
	v_mul_f32_e32 v5, v5, v5
	v_fmac_f32_e32 v5, v4, v4
	v_add_f32_e32 v4, v5, v12
	s_nop 1
	v_add_f32_dpp v86, v4, v4 quad_perm:[1,0,3,2] row_mask:0xf bank_mask:0xf
	s_nop 1
	v_add_f32_dpp v86, v86, v86 quad_perm:[2,3,0,1] row_mask:0xf bank_mask:0xf
	s_nop 1
	v_add_f32_dpp v86, v86, v86 row_half_mirror row_mask:0xf bank_mask:0xf
	s_nop 1
	v_add_f32_dpp v86, v86, v86 row_mirror row_mask:0xf bank_mask:0xf
	s_nop 1
	v_add_f32_dpp v86, v86, v86 row_bcast:15 row_mask:0xa bank_mask:0xf
	s_waitcnt lgkmcnt(0)
	s_waitcnt lgkmcnt(0)
	s_waitcnt lgkmcnt(0)
	v_add_u32_e32 v4, 0xe0, v16
	v_ashrrev_i32_e32 v5, 31, v4
	v_lshl_add_u64 v[4:5], s[16:17], 0, v[4:5]
	v_lshlrev_b64 v[12:13], 11, v[4:5]
	s_waitcnt lgkmcnt(0)
	v_lshl_add_u64 v[12:13], s[68:69], 0, v[12:13]
	v_lshl_add_u64 v[12:13], s[18:19], 1, v[12:13]
	v_lshl_add_u64 v[12:13], v[12:13], 0, v[146:147]
	flat_store_dwordx4 v[12:13], v[8:11]
	s_and_saveexec_b64 s[20:21], s[98:99]
	s_cbranch_execz .LBB0_312
	v_lshl_add_u64 v[4:5], v[4:5], 4, s[78:79]
	v_lshl_add_u64 v[4:5], s[6:7], 2, v[4:5]
	s_waitcnt lgkmcnt(0)
	v_mov_b32_e32 v6, v86
	flat_store_dword v[4:5], v6
.LBB0_312:
	s_or_b64 exec, exec, s[20:21]
	s_waitcnt lgkmcnt(0)
	ds_read_b128 v[4:7], v17 offset:59136
	v_lshlrev_b32_e32 v10, 16, v0
	v_and_b32_e32 v11, 0xffff0000, v0
	v_add_u32_e32 v8, 0xf0, v16
	v_ashrrev_i32_e32 v9, 31, v8
	s_waitcnt lgkmcnt(0)
	v_lshlrev_b32_e32 v12, 16, v4
	v_and_b32_e32 v13, 0xffff0000, v4
	v_pk_add_f32 v[10:11], v[10:11], v[12:13]
	s_nop 0
	v_cvt_pk_bf16_f32 v4, v10, v11
	v_and_b32_e32 v10, 0xffff0000, v4
	v_lshlrev_b32_e32 v0, 16, v4
	v_mul_f32_e32 v12, v10, v10
	v_fmac_f32_e32 v12, v0, v0
	v_lshlrev_b32_e32 v0, 16, v1
	v_and_b32_e32 v1, 0xffff0000, v1
	v_lshlrev_b32_e32 v10, 16, v5
	v_and_b32_e32 v11, 0xffff0000, v5
	v_pk_add_f32 v[0:1], v[0:1], v[10:11]
	v_lshlrev_b32_e32 v10, 16, v6
	v_cvt_pk_bf16_f32 v5, v0, v1
	v_and_b32_e32 v1, 0xffff0000, v5
	v_lshlrev_b32_e32 v0, 16, v5
	v_mul_f32_e32 v1, v1, v1
	v_fmac_f32_e32 v1, v0, v0
	v_add_f32_e32 v12, v12, v1
	v_lshlrev_b32_e32 v0, 16, v2
	v_and_b32_e32 v1, 0xffff0000, v2
	v_and_b32_e32 v11, 0xffff0000, v6
	v_pk_add_f32 v[0:1], v[0:1], v[10:11]
	v_lshlrev_b32_e32 v2, 16, v7
	v_cvt_pk_bf16_f32 v6, v0, v1
	v_and_b32_e32 v1, 0xffff0000, v6
	v_lshlrev_b32_e32 v0, 16, v6
	v_mul_f32_e32 v1, v1, v1
	v_fmac_f32_e32 v1, v0, v0
	v_add_f32_e32 v10, v1, v12
	v_lshlrev_b32_e32 v0, 16, v3
	v_and_b32_e32 v1, 0xffff0000, v3
	v_and_b32_e32 v3, 0xffff0000, v7
	v_pk_add_f32 v[0:1], v[0:1], v[2:3]
	s_nop 0
	v_cvt_pk_bf16_f32 v7, v0, v1
	v_and_b32_e32 v1, 0xffff0000, v7
	v_lshlrev_b32_e32 v0, 16, v7
	v_mul_f32_e32 v1, v1, v1
	v_fmac_f32_e32 v1, v0, v0
	v_add_f32_e32 v10, v1, v10
	v_lshl_add_u64 v[0:1], s[16:17], 0, v[8:9]
	v_lshlrev_b64 v[2:3], 11, v[0:1]
	v_lshl_add_u64 v[2:3], s[68:69], 0, v[2:3]
	v_lshl_add_u64 v[2:3], s[18:19], 1, v[2:3]
	v_lshl_add_u64 v[2:3], v[2:3], 0, v[146:147]
	flat_store_dwordx4 v[2:3], v[4:7]
	s_nop 1
	v_add_f32_dpp v86, v10, v10 quad_perm:[1,0,3,2] row_mask:0xf bank_mask:0xf
	s_nop 1
	v_add_f32_dpp v86, v86, v86 quad_perm:[2,3,0,1] row_mask:0xf bank_mask:0xf
	s_nop 1
	v_add_f32_dpp v86, v86, v86 row_half_mirror row_mask:0xf bank_mask:0xf
	s_nop 1
	v_add_f32_dpp v86, v86, v86 row_mirror row_mask:0xf bank_mask:0xf
	s_nop 1
	v_add_f32_dpp v86, v86, v86 row_bcast:15 row_mask:0xa bank_mask:0xf
	s_waitcnt lgkmcnt(0)
	s_waitcnt lgkmcnt(0)
	s_waitcnt lgkmcnt(0)
	s_waitcnt lgkmcnt(0)
	s_and_saveexec_b64 s[16:17], s[98:99]
	s_cbranch_execz .LBB0_275
	v_lshl_add_u64 v[0:1], v[0:1], 4, s[78:79]
	v_lshl_add_u64 v[0:1], s[6:7], 2, v[0:1]
	s_waitcnt lgkmcnt(0)
	v_mov_b32_e32 v2, v86
	flat_store_dword v[0:1], v2
	s_branch .LBB0_275

; #define MFMA16(a, b, c) __builtin_amdgcn_mfma_f32_16x16x32_bf16((a), (b), (c), 0, 0, 0)
; DI bf16x8 ldfrag(const char* lds, int row, int chunk) { return *(const bf16x8*)(lds + swz(row, chunk)); }
; #define GEMM_SG1() do { __builtin_amdgcn_sched_group_barrier(0x100, 1, 0); __builtin_amdgcn_sched_group_barrier(0x008, 4, 0); } while (0)
; template <bool RSTD, bool SWAP>
; DI void gemm_tile(gacc_t& acc, const bf16_t* __restrict__ A, int lda, const bf16_t* __restrict__ Bt, int ldb, int K,
;                   char* lds, int tid, int wr, int wc, int lane, const float* ssq_row) {
;     ...
;     GEMM_ISSUE(0, 0);
;     if (RSTD && tid < 256) {
;         const f32x4 q = *(const f32x4*)ssq_row;
;         ((float*)(lds + RSTD_OFF))[tid] = 1.0f / sqrtf(((q.x + q.y) + (q.z + q.w)) * (1.0f / 1024.0f) + 1e-6f);
;     }
;     asm volatile("s_waitcnt vmcnt(0)" ::: "memory");
;     __syncthreads();
;     for (int kt = 0; kt < nk; ++kt) {
;         const char* cur = lds + (kt & 1) * 65536;
;         if (kt + 1 < nk) GEMM_ISSUE(kt + 1, (kt + 1) & 1);
;         bf16x8 bfr[2][4], afr[3];
; #pragma unroll
;         for (int n = 0; n < 4; ++n) bfr[0][n] = ldfrag(cur + 32768, wc * 64 + n * 16 + fr, fq);
;         afr[0] = ldfrag(cur, wr * 128 + fr, fq);
;         afr[1] = ldfrag(cur, wr * 128 + 16 + fr, fq);
; #pragma unroll
;         for (int idx = 0; idx < 16; ++idx) {
;             const int ks = idx >> 3, m = idx & 7;
;             if (idx < 14) afr[(idx + 2) % 3] = ldfrag(cur, wr * 128 + ((idx + 2) & 7) * 16 + fr, ((idx + 2) >> 3) * 4 + fq);
;             if (ks == 0 && m >= 2 && m < 6) bfr[1][m - 2] = ldfrag(cur + 32768, wc * 64 + (m - 2) * 16 + fr, 4 + fq);
; #pragma unroll
;             for (int n = 0; n < 4; ++n) acc[m][n] = SWAP ? MFMA16(bfr[ks][n], afr[idx % 3], acc[m][n]) : MFMA16(afr[idx % 3], bfr[ks][n], acc[m][n]);
;         }
;         __builtin_amdgcn_sched_group_barrier(0x100, 6, 0);
;     ...
;         GEMM_SG1(); GEMM_SG1(); GEMM_SG2(); GEMM_SG2(); GEMM_SG2(); GEMM_SG2(); GEMM_SG1(); GEMM_SG1();
;         GEMM_SG1(); GEMM_SG1(); GEMM_SG1(); GEMM_SG1(); GEMM_SG1(); GEMM_SG1();
;         __builtin_amdgcn_sched_group_barrier(0x008, 8, 0);
;         __builtin_amdgcn_sched_barrier(0);
;         asm volatile("s_waitcnt vmcnt(0)" ::: "memory");
;         __syncthreads();
.LBB0_523:
	v_lshl_add_u64 v[158:159], v[136:137], 0, s[4:5]
	s_mov_b64 s[18:19], 0x800080
	v_lshl_add_u64 v[162:163], v[158:159], 0, s[18:19]
	s_mov_b64 s[18:19], 0x820080
	s_add_i32 s16, s13, 0xffff0000
	s_and_b32 s17, s13, 0x10000
	v_lshl_add_u64 v[166:167], v[158:159], 0, s[18:19]
	s_mov_b64 s[18:19], 0x840080
	s_and_b32 s21, s16, 0x10000
	s_add_i32 s16, s17, 0
	v_lshl_add_u64 v[174:175], v[158:159], 0, s[18:19]
	s_mov_b64 s[18:19], 0x860080
	v_lshl_add_u64 v[156:157], v[138:139], 0, s[4:5]
	v_lshl_add_u64 v[158:159], v[158:159], 0, s[18:19]
	s_add_i32 s18, s16, s12
	v_lshl_add_u64 v[160:161], v[156:157], 0, s[14:15]
	s_add_i32 s19, s18, 0x8000
	s_mov_b32 m0, s18
	v_lshl_add_u64 v[164:165], v[156:157], 0, s[72:73]
	global_load_lds_dwordx4 v[160:161], off
	v_mfma_f32_16x16x32_bf16 v[60:63], v[202:205], v[236:239], v[60:63]
	s_mov_b32 m0, s19
	v_lshl_add_u64 v[172:173], v[156:157], 0, s[76:77]
	global_load_lds_dwordx4 v[162:163], off
	v_mfma_f32_16x16x32_bf16 v[56:59], v[206:209], v[236:239], v[56:59]
	s_add_i32 m0, s18, 0x2000
	v_lshl_add_u64 v[156:157], v[156:157], 0, s[0:1]
	global_load_lds_dwordx4 v[164:165], off
	v_mfma_f32_16x16x32_bf16 v[52:55], v[210:213], v[236:239], v[52:55]
	s_add_i32 m0, s18, 0xa000
	s_add_i32 s17, s21, 0
	global_load_lds_dwordx4 v[166:167], off
	v_mfma_f32_16x16x32_bf16 v[48:51], v[214:217], v[236:239], v[48:51]
	s_add_i32 m0, s18, 0x4000
	v_add_u32_e32 v146, s17, v142
	global_load_lds_dwordx4 v[172:173], off
	v_mfma_f32_16x16x32_bf16 v[44:47], v[202:205], v[240:243], v[44:47]
	s_add_i32 m0, s18, 0xc000
	v_add3_u32 v155, v146, v148, v149
	global_load_lds_dwordx4 v[174:175], off
	v_mfma_f32_16x16x32_bf16 v[40:43], v[206:209], v[240:243], v[40:43]
	s_add_i32 m0, s18, 0x6000
	v_add_u32_e32 v176, v146, v144
	global_load_lds_dwordx4 v[156:157], off
	v_mfma_f32_16x16x32_bf16 v[36:39], v[210:213], v[240:243], v[36:39]
	s_add_i32 m0, s18, 0xe000
	s_nop 0
	global_load_lds_dwordx4 v[158:159], off
	v_mfma_f32_16x16x32_bf16 v[32:35], v[214:217], v[240:243], v[32:35]
	ds_read_b128 v[156:159], v155 offset:32768
	ds_read_b128 v[160:163], v155 offset:34816
	ds_read_b128 v[186:189], v155 offset:36864
	ds_read_b128 v[190:193], v155 offset:38912
	ds_read_b128 v[164:167], v176
	ds_read_b128 v[194:197], v176 offset:2048
	v_add_u32_e32 v155, v146, v150
	ds_read_b128 v[198:201], v176 offset:4096
	v_mfma_f32_16x16x32_bf16 v[28:31], v[202:205], v[244:247], v[28:31]
	v_mfma_f32_16x16x32_bf16 v[24:27], v[206:209], v[244:247], v[24:27]
	v_mfma_f32_16x16x32_bf16 v[20:23], v[210:213], v[244:247], v[20:23]
	v_mfma_f32_16x16x32_bf16 v[16:19], v[214:217], v[244:247], v[16:19]
	v_mfma_f32_16x16x32_bf16 v[12:15], v[202:205], v[248:251], v[12:15]
	v_mfma_f32_16x16x32_bf16 v[8:11], v[206:209], v[248:251], v[8:11]
	v_mfma_f32_16x16x32_bf16 v[4:7], v[210:213], v[248:251], v[4:7]
	v_mfma_f32_16x16x32_bf16 v[0:3], v[214:217], v[248:251], v[0:3]
	s_waitcnt lgkmcnt(0)
	v_mfma_f32_16x16x32_bf16 v[124:127], v[156:159], v[164:167], v[124:127]
	v_add_u32_e32 v146, v146, v152
	v_mfma_f32_16x16x32_bf16 v[120:123], v[160:163], v[164:167], v[120:123]
	v_mfma_f32_16x16x32_bf16 v[116:119], v[186:189], v[164:167], v[116:119]
	v_mfma_f32_16x16x32_bf16 v[112:115], v[190:193], v[164:167], v[112:115]
	ds_read_b128 v[164:167], v155
	v_add_u32_e32 v155, s17, v145
	v_add_u32_e32 v172, v155, v151
	v_mfma_f32_16x16x32_bf16 v[108:111], v[156:159], v[194:197], v[108:111]
	v_mfma_f32_16x16x32_bf16 v[104:107], v[160:163], v[194:197], v[104:107]
	v_mfma_f32_16x16x32_bf16 v[100:103], v[186:189], v[194:197], v[100:103]
	v_mfma_f32_16x16x32_bf16 v[96:99], v[190:193], v[194:197], v[96:99]
	ds_read_b128 v[194:197], v176 offset:8192
	ds_read_b128 v[202:205], v172 offset:32768
	v_mfma_f32_16x16x32_bf16 v[92:95], v[156:159], v[198:201], v[92:95]
	v_mfma_f32_16x16x32_bf16 v[88:91], v[160:163], v[198:201], v[88:91]
	v_mfma_f32_16x16x32_bf16 v[84:87], v[186:189], v[198:201], v[84:87]
	v_mfma_f32_16x16x32_bf16 v[80:83], v[190:193], v[198:201], v[80:83]
	ds_read_b128 v[198:201], v176 offset:10240
	ds_read_b128 v[206:209], v172 offset:34816
	s_waitcnt lgkmcnt(0)
	v_mfma_f32_16x16x32_bf16 v[76:79], v[156:159], v[164:167], v[76:79]
	v_mfma_f32_16x16x32_bf16 v[72:75], v[160:163], v[164:167], v[72:75]
	v_mfma_f32_16x16x32_bf16 v[68:71], v[186:189], v[164:167], v[68:71]
	v_mfma_f32_16x16x32_bf16 v[64:67], v[190:193], v[164:167], v[64:67]
	ds_read_b128 v[210:213], v172 offset:36864
	v_add_u32_e32 v172, v155, v153
	ds_read_b128 v[164:167], v176 offset:12288
	v_mfma_f32_16x16x32_bf16 v[60:63], v[156:159], v[194:197], v[60:63]
	v_mfma_f32_16x16x32_bf16 v[56:59], v[160:163], v[194:197], v[56:59]
	v_mfma_f32_16x16x32_bf16 v[52:55], v[186:189], v[194:197], v[52:55]
	v_mfma_f32_16x16x32_bf16 v[48:51], v[190:193], v[194:197], v[48:51]
	ds_read_b128 v[214:217], v172 offset:38912
	ds_read_b128 v[194:197], v146
	v_add_u32_e32 v146, v155, v144
	v_mfma_f32_16x16x32_bf16 v[44:47], v[156:159], v[198:201], v[44:47]
	v_mfma_f32_16x16x32_bf16 v[40:43], v[160:163], v[198:201], v[40:43]
	v_mfma_f32_16x16x32_bf16 v[36:39], v[186:189], v[198:201], v[36:39]
	v_mfma_f32_16x16x32_bf16 v[32:35], v[190:193], v[198:201], v[32:35]
	ds_read_b128 v[198:201], v146
	s_waitcnt lgkmcnt(0)
; #define MFMA16(a, b, c) __builtin_amdgcn_mfma_f32_16x16x32_bf16((a), (b), (c), 0, 0, 0)
; DI bf16x8 ldfrag(const char* lds, int row, int chunk) { return *(const bf16x8*)(lds + swz(row, chunk)); }
; #define GEMM_SG1() do { __builtin_amdgcn_sched_group_barrier(0x100, 1, 0); __builtin_amdgcn_sched_group_barrier(0x008, 4, 0); } while (0)
; #define GEMM_SG2() do { __builtin_amdgcn_sched_group_barrier(0x100, 2, 0); __builtin_amdgcn_sched_group_barrier(0x008, 4, 0); } while (0)
; template <bool RSTD, bool SWAP>
; DI void gemm_tile(gacc_t& acc, const bf16_t* __restrict__ A, int lda, const bf16_t* __restrict__ Bt, int ldb, int K,
;                   char* lds, int tid, int wr, int wc, int lane, const float* ssq_row) {
;     ...
;     for (int kt = 0; kt < nk; ++kt) {
;         const char* cur = lds + (kt & 1) * 65536;
;         if (kt + 1 < nk) GEMM_ISSUE(kt + 1, (kt + 1) & 1);
;         bf16x8 bfr[2][4], afr[3];
; #pragma unroll
;         for (int n = 0; n < 4; ++n) bfr[0][n] = ldfrag(cur + 32768, wc * 64 + n * 16 + fr, fq);
;         afr[0] = ldfrag(cur, wr * 128 + fr, fq);
;         afr[1] = ldfrag(cur, wr * 128 + 16 + fr, fq);
; #pragma unroll
;         for (int idx = 0; idx < 16; ++idx) {
;             const int ks = idx >> 3, m = idx & 7;
;             if (idx < 14) afr[(idx + 2) % 3] = ldfrag(cur, wr * 128 + ((idx + 2) & 7) * 16 + fr, ((idx + 2) >> 3) * 4 + fq);
;             if (ks == 0 && m >= 2 && m < 6) bfr[1][m - 2] = ldfrag(cur + 32768, wc * 64 + (m - 2) * 16 + fr, 4 + fq);
; #pragma unroll
;             for (int n = 0; n < 4; ++n) acc[m][n] = SWAP ? MFMA16(bfr[ks][n], afr[idx % 3], acc[m][n]) : MFMA16(afr[idx % 3], bfr[ks][n], acc[m][n]);
;         }
;         __builtin_amdgcn_sched_group_barrier(0x100, 6, 0);
;     ...
;         GEMM_SG1(); GEMM_SG1(); GEMM_SG2(); GEMM_SG2(); GEMM_SG2(); GEMM_SG2(); GEMM_SG1(); GEMM_SG1();
;         GEMM_SG1(); GEMM_SG1(); GEMM_SG1(); GEMM_SG1(); GEMM_SG1(); GEMM_SG1();
;         __builtin_amdgcn_sched_group_barrier(0x008, 8, 0);
;         __builtin_amdgcn_sched_barrier(0);
;         asm volatile("s_waitcnt vmcnt(0)" ::: "memory");
;         __syncthreads();
	v_mfma_f32_16x16x32_bf16 v[28:31], v[156:159], v[164:167], v[28:31]
	v_mfma_f32_16x16x32_bf16 v[24:27], v[160:163], v[164:167], v[24:27]
	v_mfma_f32_16x16x32_bf16 v[20:23], v[186:189], v[164:167], v[20:23]
	v_mfma_f32_16x16x32_bf16 v[16:19], v[190:193], v[164:167], v[16:19]
	ds_read_b128 v[164:167], v146 offset:2048
	v_mfma_f32_16x16x32_bf16 v[8:11], v[160:163], v[194:197], v[8:11]
	v_add_u32_e32 v160, v155, v150
	v_mfma_f32_16x16x32_bf16 v[12:15], v[156:159], v[194:197], v[12:15]
	v_mfma_f32_16x16x32_bf16 v[4:7], v[186:189], v[194:197], v[4:7]
	v_mfma_f32_16x16x32_bf16 v[0:3], v[190:193], v[194:197], v[0:3]
	ds_read_b128 v[156:159], v146 offset:4096
	v_mfma_f32_16x16x32_bf16 v[124:127], v[202:205], v[198:201], v[124:127]
	v_mfma_f32_16x16x32_bf16 v[120:123], v[206:209], v[198:201], v[120:123]
	v_mfma_f32_16x16x32_bf16 v[116:119], v[210:213], v[198:201], v[116:119]
	v_mfma_f32_16x16x32_bf16 v[112:115], v[214:217], v[198:201], v[112:115]
	ds_read_b128 v[160:163], v160
	s_waitcnt lgkmcnt(0)
	v_mfma_f32_16x16x32_bf16 v[108:111], v[202:205], v[164:167], v[108:111]
	v_mfma_f32_16x16x32_bf16 v[104:107], v[206:209], v[164:167], v[104:107]
	v_mfma_f32_16x16x32_bf16 v[100:103], v[210:213], v[164:167], v[100:103]
	v_mfma_f32_16x16x32_bf16 v[96:99], v[214:217], v[164:167], v[96:99]
	ds_read_b128 v[236:239], v146 offset:8192
	v_mfma_f32_16x16x32_bf16 v[92:95], v[202:205], v[156:159], v[92:95]
	v_mfma_f32_16x16x32_bf16 v[88:91], v[206:209], v[156:159], v[88:91]
	v_mfma_f32_16x16x32_bf16 v[84:87], v[210:213], v[156:159], v[84:87]
	v_mfma_f32_16x16x32_bf16 v[80:83], v[214:217], v[156:159], v[80:83]
	ds_read_b128 v[240:243], v146 offset:10240
	ds_read_b128 v[244:247], v146 offset:12288
	v_add_u32_e32 v146, v155, v152
	ds_read_b128 v[248:251], v146
	v_mfma_f32_16x16x32_bf16 v[76:79], v[202:205], v[160:163], v[76:79]
	v_mfma_f32_16x16x32_bf16 v[72:75], v[206:209], v[160:163], v[72:75]
	v_mfma_f32_16x16x32_bf16 v[68:71], v[210:213], v[160:163], v[68:71]
	v_mfma_f32_16x16x32_bf16 v[64:67], v[214:217], v[160:163], v[64:67]
	s_waitcnt lgkmcnt(0)
	s_waitcnt vmcnt(0)
	s_add_u32 s4, s4, 0x80
	s_addc_u32 s5, s5, 0
	s_add_i32 s13, s13, 0x10000
	s_cmpk_eq_i32 s4, 0x780
	s_waitcnt vmcnt(0)
	s_barrier
	s_cbranch_scc0 .LBB0_523
	v_mfma_f32_16x16x32_bf16 v[60:63], v[202:205], v[236:239], v[60:63]
	v_mfma_f32_16x16x32_bf16 v[56:59], v[206:209], v[236:239], v[56:59]
	v_mfma_f32_16x16x32_bf16 v[52:55], v[210:213], v[236:239], v[52:55]
	v_mfma_f32_16x16x32_bf16 v[48:51], v[214:217], v[236:239], v[48:51]
	v_mfma_f32_16x16x32_bf16 v[44:47], v[202:205], v[240:243], v[44:47]
	v_mfma_f32_16x16x32_bf16 v[40:43], v[206:209], v[240:243], v[40:43]
	v_mfma_f32_16x16x32_bf16 v[36:39], v[210:213], v[240:243], v[36:39]
	v_mfma_f32_16x16x32_bf16 v[32:35], v[214:217], v[240:243], v[32:35]
	v_mfma_f32_16x16x32_bf16 v[28:31], v[202:205], v[244:247], v[28:31]
	v_mfma_f32_16x16x32_bf16 v[24:27], v[206:209], v[244:247], v[24:27]
	v_mfma_f32_16x16x32_bf16 v[20:23], v[210:213], v[244:247], v[20:23]
	v_mfma_f32_16x16x32_bf16 v[16:19], v[214:217], v[244:247], v[16:19]
	v_mfma_f32_16x16x32_bf16 v[12:15], v[202:205], v[248:251], v[12:15]
	v_mfma_f32_16x16x32_bf16 v[8:11], v[206:209], v[248:251], v[8:11]
	v_mfma_f32_16x16x32_bf16 v[4:7], v[210:213], v[248:251], v[4:7]
	v_mfma_f32_16x16x32_bf16 v[0:3], v[214:217], v[248:251], v[0:3]
	v_add_u32_e32 v146, s16, v142
	v_add3_u32 v155, v146, v148, v149
	ds_read_b128 v[136:139], v155 offset:32768
	ds_read_b128 v[156:159], v155 offset:34816
	ds_read_b128 v[164:167], v155 offset:36864
	ds_read_b128 v[186:189], v155 offset:38912
	v_add_u32_e32 v172, v146, v144
	ds_read_b128 v[160:163], v172
	ds_read_b128 v[190:193], v172 offset:2048
	v_add_u32_e32 v155, v146, v150
	ds_read_b128 v[194:197], v172 offset:4096
	s_waitcnt lgkmcnt(2)
	v_mfma_f32_16x16x32_bf16 v[124:127], v[136:139], v[160:163], v[124:127]
	v_add_u32_e32 v146, v146, v152
	s_lshl_b64 s[12:13], s[8:9], 8
	v_mfma_f32_16x16x32_bf16 v[120:123], v[156:159], v[160:163], v[120:123]
	v_mfma_f32_16x16x32_bf16 v[116:119], v[164:167], v[160:163], v[116:119]
	v_mfma_f32_16x16x32_bf16 v[112:115], v[186:189], v[160:163], v[112:115]
	ds_read_b128 v[160:163], v155
	v_add_u32_e32 v155, s16, v145
	v_add_u32_e32 v173, v155, v151
	s_waitcnt lgkmcnt(2)
	v_mfma_f32_16x16x32_bf16 v[108:111], v[136:139], v[190:193], v[108:111]
	v_mfma_f32_16x16x32_bf16 v[104:107], v[156:159], v[190:193], v[104:107]
	v_mfma_f32_16x16x32_bf16 v[100:103], v[164:167], v[190:193], v[100:103]
	v_mfma_f32_16x16x32_bf16 v[96:99], v[186:189], v[190:193], v[96:99]
	ds_read_b128 v[190:193], v172 offset:8192
	ds_read_b128 v[198:201], v173 offset:32768
	s_waitcnt lgkmcnt(3)
	v_mfma_f32_16x16x32_bf16 v[92:95], v[136:139], v[194:197], v[92:95]
	v_mfma_f32_16x16x32_bf16 v[88:91], v[156:159], v[194:197], v[88:91]
	v_mfma_f32_16x16x32_bf16 v[84:87], v[164:167], v[194:197], v[84:87]
	v_mfma_f32_16x16x32_bf16 v[80:83], v[186:189], v[194:197], v[80:83]
	ds_read_b128 v[194:197], v172 offset:10240
	ds_read_b128 v[202:205], v173 offset:34816
	s_waitcnt lgkmcnt(4)
	v_mfma_f32_16x16x32_bf16 v[76:79], v[136:139], v[160:163], v[76:79]
	v_mfma_f32_16x16x32_bf16 v[72:75], v[156:159], v[160:163], v[72:75]
	v_mfma_f32_16x16x32_bf16 v[68:71], v[164:167], v[160:163], v[68:71]
	v_mfma_f32_16x16x32_bf16 v[64:67], v[186:189], v[160:163], v[64:67]
	ds_read_b128 v[160:163], v172 offset:12288
	ds_read_b128 v[206:209], v173 offset:36864
	s_waitcnt lgkmcnt(5)
	v_mfma_f32_16x16x32_bf16 v[60:63], v[136:139], v[190:193], v[60:63]
	v_mfma_f32_16x16x32_bf16 v[56:59], v[156:159], v[190:193], v[56:59]
	v_mfma_f32_16x16x32_bf16 v[52:55], v[164:167], v[190:193], v[52:55]
	v_mfma_f32_16x16x32_bf16 v[48:51], v[186:189], v[190:193], v[48:51]
	ds_read_b128 v[190:193], v146
	v_add_u32_e32 v146, v155, v153
	ds_read_b128 v[210:213], v146 offset:38912
	v_add_u32_e32 v146, v155, v144
	s_waitcnt lgkmcnt(5)
; #define MFMA16(a, b, c) __builtin_amdgcn_mfma_f32_16x16x32_bf16((a), (b), (c), 0, 0, 0)
; DI unsigned pk2(float a, float b) { f32x2 v = {a, b}; bf16x2_t r = __builtin_convertvector(v, bf16x2_t); return __builtin_bit_cast(unsigned, r); }
; DI bf16x8 ldfrag(const char* lds, int row, int chunk) { return *(const bf16x8*)(lds + swz(row, chunk)); }
; #define GEMM_SG1() do { __builtin_amdgcn_sched_group_barrier(0x100, 1, 0); __builtin_amdgcn_sched_group_barrier(0x008, 4, 0); } while (0)
; #define GEMM_SG2() do { __builtin_amdgcn_sched_group_barrier(0x100, 2, 0); __builtin_amdgcn_sched_group_barrier(0x008, 4, 0); } while (0)
; template <bool RSTD, bool SWAP>
; DI void gemm_tile(gacc_t& acc, const bf16_t* __restrict__ A, int lda, const bf16_t* __restrict__ Bt, int ldb, int K,
;                   char* lds, int tid, int wr, int wc, int lane, const float* ssq_row) {
;     ...
;         for (int idx = 0; idx < 16; ++idx) {
;             const int ks = idx >> 3, m = idx & 7;
;             if (idx < 14) afr[(idx + 2) % 3] = ldfrag(cur, wr * 128 + ((idx + 2) & 7) * 16 + fr, ((idx + 2) >> 3) * 4 + fq);
;             if (ks == 0 && m >= 2 && m < 6) bfr[1][m - 2] = ldfrag(cur + 32768, wc * 64 + (m - 2) * 16 + fr, 4 + fq);
; #pragma unroll
;             for (int n = 0; n < 4; ++n) acc[m][n] = SWAP ? MFMA16(bfr[ks][n], afr[idx % 3], acc[m][n]) : MFMA16(afr[idx % 3], bfr[ks][n], acc[m][n]);
;         }
;         __builtin_amdgcn_sched_group_barrier(0x100, 6, 0);
;     ...
;         GEMM_SG1(); GEMM_SG1(); GEMM_SG2(); GEMM_SG2(); GEMM_SG2(); GEMM_SG2(); GEMM_SG1(); GEMM_SG1();
;         GEMM_SG1(); GEMM_SG1(); GEMM_SG1(); GEMM_SG1(); GEMM_SG1(); GEMM_SG1();
;         __builtin_amdgcn_sched_group_barrier(0x008, 8, 0);
;         __builtin_amdgcn_sched_barrier(0);
;         asm volatile("s_waitcnt vmcnt(0)" ::: "memory");
;         __syncthreads();
;     DI void operator()(gacc_t& acc, int pm, int pn, char* lds, int tid, int wr, int wc, int lane) const {
;         asm volatile("" : "+v"(tid), "+v"(lane));
;         const int fr = lane & 15, fq = lane >> 4, wid = tid >> 6;
;         char* lbase = lds + (wr * 128 + fr) * 528 + (wc * 64 + 4 * fq) * 2;
; #pragma unroll
;         for (int m = 0; m < 8; ++m)
; #pragma unroll
;             for (int n = 0; n < 4; ++n) { u32x2 w; w.x = pk2(acc[m][n][0], acc[m][n][1]); w.y = pk2(acc[m][n][2], acc[m][n][3]); *(u32x2*)(lbase + m * 16 * 528 + n * 32) = w; }
	v_mfma_f32_16x16x32_bf16 v[44:47], v[136:139], v[194:197], v[44:47]
	v_mfma_f32_16x16x32_bf16 v[40:43], v[156:159], v[194:197], v[40:43]
	v_mfma_f32_16x16x32_bf16 v[36:39], v[164:167], v[194:197], v[36:39]
	v_mfma_f32_16x16x32_bf16 v[32:35], v[186:189], v[194:197], v[32:35]
	ds_read_b128 v[194:197], v146
	s_waitcnt lgkmcnt(4)
	v_mfma_f32_16x16x32_bf16 v[28:31], v[136:139], v[160:163], v[28:31]
	v_mfma_f32_16x16x32_bf16 v[24:27], v[156:159], v[160:163], v[24:27]
	v_mfma_f32_16x16x32_bf16 v[20:23], v[164:167], v[160:163], v[20:23]
	v_mfma_f32_16x16x32_bf16 v[16:19], v[186:189], v[160:163], v[16:19]
	ds_read_b128 v[160:163], v146 offset:2048
	s_waitcnt lgkmcnt(3)
	v_mfma_f32_16x16x32_bf16 v[8:11], v[156:159], v[190:193], v[8:11]
	v_add_u32_e32 v156, v155, v150
	v_mfma_f32_16x16x32_bf16 v[12:15], v[136:139], v[190:193], v[12:15]
	v_mfma_f32_16x16x32_bf16 v[4:7], v[164:167], v[190:193], v[4:7]
	v_mfma_f32_16x16x32_bf16 v[0:3], v[186:189], v[190:193], v[0:3]
	ds_read_b128 v[136:139], v146 offset:4096
	s_waitcnt lgkmcnt(2)
	v_mfma_f32_16x16x32_bf16 v[124:127], v[198:201], v[194:197], v[124:127]
	v_mfma_f32_16x16x32_bf16 v[120:123], v[202:205], v[194:197], v[120:123]
	v_mfma_f32_16x16x32_bf16 v[116:119], v[206:209], v[194:197], v[116:119]
	v_mfma_f32_16x16x32_bf16 v[112:115], v[210:213], v[194:197], v[112:115]
	ds_read_b128 v[156:159], v156
	s_waitcnt lgkmcnt(2)
	v_mfma_f32_16x16x32_bf16 v[108:111], v[198:201], v[160:163], v[108:111]
	v_mfma_f32_16x16x32_bf16 v[104:107], v[202:205], v[160:163], v[104:107]
	v_mfma_f32_16x16x32_bf16 v[100:103], v[206:209], v[160:163], v[100:103]
	v_mfma_f32_16x16x32_bf16 v[96:99], v[210:213], v[160:163], v[96:99]
	ds_read_b128 v[160:163], v146 offset:8192
	s_waitcnt lgkmcnt(2)
	v_mfma_f32_16x16x32_bf16 v[92:95], v[198:201], v[136:139], v[92:95]
	v_mfma_f32_16x16x32_bf16 v[88:91], v[202:205], v[136:139], v[88:91]
	v_mfma_f32_16x16x32_bf16 v[84:87], v[206:209], v[136:139], v[84:87]
	v_mfma_f32_16x16x32_bf16 v[80:83], v[210:213], v[136:139], v[80:83]
	ds_read_b128 v[136:139], v146 offset:10240
	s_waitcnt lgkmcnt(2)
	v_mfma_f32_16x16x32_bf16 v[76:79], v[198:201], v[156:159], v[76:79]
	v_mfma_f32_16x16x32_bf16 v[72:75], v[202:205], v[156:159], v[72:75]
	v_mfma_f32_16x16x32_bf16 v[68:71], v[206:209], v[156:159], v[68:71]
	v_mfma_f32_16x16x32_bf16 v[64:67], v[210:213], v[156:159], v[64:67]
	ds_read_b128 v[156:159], v146 offset:12288
	v_add_u32_e32 v146, v155, v152
	s_waitcnt lgkmcnt(2)
	v_mfma_f32_16x16x32_bf16 v[60:63], v[198:201], v[160:163], v[60:63]
	v_mfma_f32_16x16x32_bf16 v[56:59], v[202:205], v[160:163], v[56:59]
	v_mfma_f32_16x16x32_bf16 v[52:55], v[206:209], v[160:163], v[52:55]
	v_mfma_f32_16x16x32_bf16 v[48:51], v[210:213], v[160:163], v[48:51]
	ds_read_b128 v[160:163], v146
	s_waitcnt lgkmcnt(2)
	v_mfma_f32_16x16x32_bf16 v[44:47], v[198:201], v[136:139], v[44:47]
	v_mfma_f32_16x16x32_bf16 v[40:43], v[202:205], v[136:139], v[40:43]
	v_mfma_f32_16x16x32_bf16 v[36:39], v[206:209], v[136:139], v[36:39]
	v_mfma_f32_16x16x32_bf16 v[32:35], v[210:213], v[136:139], v[32:35]
	s_waitcnt lgkmcnt(1)
	v_mfma_f32_16x16x32_bf16 v[24:27], v[202:205], v[156:159], v[24:27]
	v_mfma_f32_16x16x32_bf16 v[20:23], v[206:209], v[156:159], v[20:23]
	v_mfma_f32_16x16x32_bf16 v[16:19], v[210:213], v[156:159], v[16:19]
	s_waitcnt lgkmcnt(0)
	v_mfma_f32_16x16x32_bf16 v[12:15], v[198:201], v[160:163], v[12:15]
	v_mfma_f32_16x16x32_bf16 v[8:11], v[202:205], v[160:163], v[8:11]
	v_mfma_f32_16x16x32_bf16 v[4:7], v[206:209], v[160:163], v[4:7]
	v_mfma_f32_16x16x32_bf16 v[0:3], v[210:213], v[160:163], v[0:3]
	v_mfma_f32_16x16x32_bf16 v[28:31], v[198:201], v[156:159], v[28:31]
	v_mov_b32_e32 v136, v141
	v_mov_b32_e32 v137, v140
	s_waitcnt vmcnt(0)
	s_barrier
	v_cvt_pk_bf16_f32 v124, v124, v125
	v_and_or_b32 v138, v136, 15, v143
	v_ashrrev_i32_e32 v139, 1, v136
	v_mul_lo_u32 v138, v138, s3
	v_and_b32_e32 v139, -8, v139
	v_add3_u32 v138, v154, v138, v139
	v_cvt_pk_bf16_f32 v125, v126, v127
	v_cvt_pk_bf16_f32 v120, v120, v121
	v_cvt_pk_bf16_f32 v121, v122, v123
	v_cvt_pk_bf16_f32 v116, v116, v117
	v_cvt_pk_bf16_f32 v117, v118, v119
	v_cvt_pk_bf16_f32 v112, v112, v113
	v_cvt_pk_bf16_f32 v113, v114, v115
	v_cvt_pk_bf16_f32 v108, v108, v109
	v_cvt_pk_bf16_f32 v109, v110, v111
	v_cvt_pk_bf16_f32 v104, v104, v105
	v_cvt_pk_bf16_f32 v105, v106, v107
	v_add_u32_e32 v106, 0x2000, v138
	v_cvt_pk_bf16_f32 v100, v100, v101
	v_cvt_pk_bf16_f32 v101, v102, v103
	v_cvt_pk_bf16_f32 v96, v96, v97
	v_cvt_pk_bf16_f32 v97, v98, v99
	v_cvt_pk_bf16_f32 v92, v92, v93
	v_cvt_pk_bf16_f32 v93, v94, v95
	v_cvt_pk_bf16_f32 v88, v88, v89
	v_cvt_pk_bf16_f32 v89, v90, v91
	v_add_u32_e32 v90, 0x4000, v138
	v_cvt_pk_bf16_f32 v84, v84, v85
	v_cvt_pk_bf16_f32 v85, v86, v87
	v_cvt_pk_bf16_f32 v80, v80, v81
	v_cvt_pk_bf16_f32 v81, v82, v83
	v_cvt_pk_bf16_f32 v76, v76, v77
	v_cvt_pk_bf16_f32 v77, v78, v79
	v_cvt_pk_bf16_f32 v72, v72, v73
	v_cvt_pk_bf16_f32 v73, v74, v75
	v_add_u32_e32 v74, 0x6000, v138
	v_cvt_pk_bf16_f32 v68, v68, v69
	v_cvt_pk_bf16_f32 v69, v70, v71
	v_cvt_pk_bf16_f32 v64, v64, v65
	v_cvt_pk_bf16_f32 v65, v66, v67
	v_cvt_pk_bf16_f32 v60, v60, v61
	v_cvt_pk_bf16_f32 v61, v62, v63
	v_cvt_pk_bf16_f32 v56, v56, v57
	v_cvt_pk_bf16_f32 v57, v58, v59
	v_add_u32_e32 v58, 0x8000, v138
	v_cvt_pk_bf16_f32 v52, v52, v53
	v_cvt_pk_bf16_f32 v53, v54, v55
	v_cvt_pk_bf16_f32 v48, v48, v49
	v_cvt_pk_bf16_f32 v49, v50, v51
	v_cvt_pk_bf16_f32 v44, v44, v45
	v_cvt_pk_bf16_f32 v45, v46, v47
	v_cvt_pk_bf16_f32 v40, v40, v41
	v_cvt_pk_bf16_f32 v41, v42, v43
	v_add_u32_e32 v42, 0xa000, v138
	v_cvt_pk_bf16_f32 v36, v36, v37
	v_cvt_pk_bf16_f32 v37, v38, v39
	v_cvt_pk_bf16_f32 v32, v32, v33
; DI unsigned pk2(float a, float b) { f32x2 v = {a, b}; bf16x2_t r = __builtin_convertvector(v, bf16x2_t); return __builtin_bit_cast(unsigned, r); }
; DI float bflo(unsigned w) { return __uint_as_float(w << 16); }
; DI float bfhi(unsigned w) { return __uint_as_float(w & 0xffff0000u); }
;     DI void operator()(gacc_t& acc, int pm, int pn, char* lds, int tid, int wr, int wc, int lane) const {
;     ...
; #pragma unroll
;         for (int m = 0; m < 8; ++m)
; #pragma unroll
;             for (int n = 0; n < 4; ++n) { u32x2 w; w.x = pk2(acc[m][n][0], acc[m][n][1]); w.y = pk2(acc[m][n][2], acc[m][n][3]); *(u32x2*)(lbase + m * 16 * 528 + n * 32) = w; }
;         __builtin_amdgcn_sched_barrier(0);
;         __syncthreads();
;         __builtin_amdgcn_sched_barrier(0);
;         const int g = lane >> 5, j32 = lane & 31;
; #pragma unroll
;         for (int ib = 0; ib < 4; ++ib) {
;             __builtin_amdgcn_sched_barrier(0);
;             u32x4 xv[4];
; #pragma unroll
;             for (int u = 0; u < 4; ++u) {
;                 const long row = (long)pm * 256 + (ib * 4 + u) * 16 + wid * 2 + g;
;                 xv[u] = *(const u32x4*)(xold + row * 1024 + pn * 256 + j32 * 8);
;             }
; #pragma unroll
;             for (int u = 0; u < 4; ++u) {
;                 const int rloc = (ib * 4 + u) * 16 + wid * 2 + g;
;                 const long row = (long)pm * 256 + rloc;
;                 const u32x4 a = *(const u32x4*)(lds + rloc * 528 + j32 * 16);
;                 u32x4 w; float ss = 0.f;
; #pragma unroll
;                 for (int e = 0; e < 4; ++e) {
;                     w[e] = pk2(bflo(xv[u][e]) + bflo(a[e]), bfhi(xv[u][e]) + bfhi(a[e]));
;                     const float b0 = bflo(w[e]), b1 = bfhi(w[e]);
;                     ss += b0 * b0 + b1 * b1;
;                 }
;                 *(u32x4*)(xnew + row * 1024 + pn * 256 + j32 * 8) = w;
; #pragma unroll
;                 for (int o = 1; o < 32; o <<= 1) ss += __shfl_xor(ss, o);
;                 if (j32 == 0) ssq[row * 4 + pn] = ss;
	v_cvt_pk_bf16_f32 v33, v34, v35
	v_cvt_pk_bf16_f32 v28, v28, v29
	v_cvt_pk_bf16_f32 v29, v30, v31
	v_cvt_pk_bf16_f32 v24, v24, v25
	v_cvt_pk_bf16_f32 v25, v26, v27
	v_add_u32_e32 v26, 0xc000, v138
	v_cvt_pk_bf16_f32 v20, v20, v21
	v_cvt_pk_bf16_f32 v21, v22, v23
	v_cvt_pk_bf16_f32 v16, v16, v17
	v_cvt_pk_bf16_f32 v17, v18, v19
	v_cvt_pk_bf16_f32 v12, v12, v13
	v_cvt_pk_bf16_f32 v13, v14, v15
	v_cvt_pk_bf16_f32 v8, v8, v9
	v_cvt_pk_bf16_f32 v9, v10, v11
	v_add_u32_e32 v10, 0xe000, v138
	v_cvt_pk_bf16_f32 v4, v4, v5
	v_cvt_pk_bf16_f32 v5, v6, v7
	v_cvt_pk_bf16_f32 v0, v0, v1
	v_cvt_pk_bf16_f32 v1, v2, v3
	ds_write2_b64 v138, v[124:125], v[120:121] offset1:4
	ds_write2_b64 v138, v[116:117], v[112:113] offset0:8 offset1:12
	ds_write2_b64 v106, v[108:109], v[104:105] offset0:32 offset1:36
	ds_write2_b64 v106, v[100:101], v[96:97] offset0:40 offset1:44
	ds_write2_b64 v90, v[92:93], v[88:89] offset0:64 offset1:68
	ds_write2_b64 v90, v[84:85], v[80:81] offset0:72 offset1:76
	ds_write2_b64 v74, v[76:77], v[72:73] offset0:96 offset1:100
	ds_write2_b64 v74, v[68:69], v[64:65] offset0:104 offset1:108
	ds_write2_b64 v58, v[60:61], v[56:57] offset0:128 offset1:132
	ds_write2_b64 v58, v[52:53], v[48:49] offset0:136 offset1:140
	ds_write2_b64 v42, v[44:45], v[40:41] offset0:160 offset1:164
	ds_write2_b64 v42, v[36:37], v[32:33] offset0:168 offset1:172
	ds_write2_b64 v26, v[28:29], v[24:25] offset0:192 offset1:196
	ds_write2_b64 v26, v[20:21], v[16:17] offset0:200 offset1:204
	ds_write2_b64 v10, v[12:13], v[8:9] offset0:224 offset1:228
	ds_write2_b64 v10, v[4:5], v[0:1] offset0:232 offset1:236
	s_waitcnt lgkmcnt(0)
	s_barrier
	v_ashrrev_i32_e32 v0, 5, v136
	v_ashrrev_i32_e32 v1, 5, v137
	v_and_b32_e32 v14, 31, v136
	v_and_b32_e32 v2, -2, v1
	v_ashrrev_i32_e32 v1, 31, v0
	v_ashrrev_i32_e32 v3, 31, v2
	v_lshl_add_u64 v[4:5], s[12:13], 0, v[0:1]
	s_lshl_b32 s16, s6, 8
	v_add_u32_e32 v16, v2, v0
	v_lshlrev_b32_e32 v146, 4, v14
	v_and_b32_e32 v0, 64, v169
	v_lshl_add_u64 v[4:5], v[4:5], 0, v[2:3]
	s_ashr_i32 s17, s16, 31
	v_add_u32_e32 v26, 0, v146
	v_add_u32_e32 v15, 64, v0
	v_cmp_eq_u32_e64 s[4:5], 0, v14
	v_cmp_eq_u32_e64 s[98:99], 16, v14
	s_lshl_b64 s[18:19], s[16:17], 1
	s_add_u32 s22, s10, s18
	s_addc_u32 s23, s11, s19
	v_lshl_add_u64 v[0:1], s[22:23], 0, v[146:147]
	v_lshlrev_b64 v[2:3], 11, v[4:5]
	v_lshl_add_u64 v[18:19], v[0:1], 0, v[2:3]
	flat_load_dwordx4 v[22:25], v[18:19]
	v_add_co_u32_e32 v0, vcc, s49, v18
	v_mul_lo_u32 v20, v16, s3
	s_nop 0
	v_addc_co_u32_e32 v1, vcc, 0, v19, vcc
	flat_load_dwordx4 v[8:11], v[0:1]
	v_add_co_u32_e32 v0, vcc, s48, v18
	v_add_u32_e32 v12, v26, v20
	s_nop 0
	v_addc_co_u32_e32 v1, vcc, 0, v19, vcc
	flat_load_dwordx4 v[4:7], v[0:1]
	v_add_co_u32_e32 v0, vcc, s47, v18
	ds_read_b128 v[28:31], v12
	s_nop 0
	v_addc_co_u32_e32 v1, vcc, 0, v19, vcc
	flat_load_dwordx4 v[0:3], v[0:1]
	v_ashrrev_i32_e32 v17, 31, v16
	s_waitcnt lgkmcnt(0)
	v_lshlrev_b32_e32 v32, 16, v28
	v_and_b32_e32 v33, 0xffff0000, v28
	v_lshlrev_b32_e32 v28, 16, v29
	v_and_b32_e32 v29, 0xffff0000, v29
	s_waitcnt vmcnt(0)
	v_lshlrev_b32_e32 v12, 16, v22
	v_and_b32_e32 v13, 0xffff0000, v22
	v_pk_add_f32 v[12:13], v[12:13], v[32:33]
	s_nop 0
	v_cvt_pk_bf16_f32 v22, v12, v13
	v_and_b32_e32 v13, 0xffff0000, v22
	v_lshlrev_b32_e32 v12, 16, v22
	v_mul_f32_e32 v21, v13, v13
	v_fmac_f32_e32 v21, v12, v12
	v_lshlrev_b32_e32 v12, 16, v23
	v_and_b32_e32 v13, 0xffff0000, v23
	v_pk_add_f32 v[12:13], v[12:13], v[28:29]
	v_lshlrev_b32_e32 v28, 16, v30
	v_cvt_pk_bf16_f32 v23, v12, v13
	v_and_b32_e32 v13, 0xffff0000, v23
	v_lshlrev_b32_e32 v12, 16, v23
	v_mul_f32_e32 v13, v13, v13
	v_fmac_f32_e32 v13, v12, v12
	v_add_f32_e32 v21, v21, v13
	v_lshlrev_b32_e32 v12, 16, v24
	v_and_b32_e32 v13, 0xffff0000, v24
	v_and_b32_e32 v29, 0xffff0000, v30
	v_pk_add_f32 v[12:13], v[12:13], v[28:29]
	v_lshlrev_b32_e32 v28, 16, v31
	v_cvt_pk_bf16_f32 v24, v12, v13
	v_and_b32_e32 v13, 0xffff0000, v24
	v_lshlrev_b32_e32 v12, 16, v24
	v_mul_f32_e32 v13, v13, v13
	v_fmac_f32_e32 v13, v12, v12
	v_add_f32_e32 v21, v13, v21
	v_lshlrev_b32_e32 v12, 16, v25
	v_and_b32_e32 v13, 0xffff0000, v25
	v_and_b32_e32 v29, 0xffff0000, v31
	v_pk_add_f32 v[12:13], v[12:13], v[28:29]
	s_nop 0
	v_cvt_pk_bf16_f32 v25, v12, v13
	v_and_b32_e32 v13, 0xffff0000, v25
	v_lshlrev_b32_e32 v12, 16, v25
	v_mul_f32_e32 v13, v13, v13
	v_fmac_f32_e32 v13, v12, v12
	v_add_f32_e32 v21, v13, v21
	v_lshl_add_u64 v[12:13], s[12:13], 0, v[16:17]
	v_lshlrev_b64 v[28:29], 11, v[12:13]
	v_xor_b32_e32 v17, 1, v169
	v_lshl_add_u64 v[28:29], s[68:69], 0, v[28:29]
	v_cmp_lt_i32_e32 vcc, v17, v15
	v_lshl_add_u64 v[28:29], v[28:29], 0, s[18:19]
	v_lshl_add_u64 v[28:29], v[28:29], 0, v[146:147]
	v_cndmask_b32_e32 v17, v169, v17, vcc
	v_lshlrev_b32_e32 v17, 2, v17
	flat_store_dwordx4 v[28:29], v[22:25]
	s_nop 1
	v_add_f32_dpp v86, v21, v21 quad_perm:[1,0,3,2] row_mask:0xf bank_mask:0xf
	s_nop 1
	v_add_f32_dpp v86, v86, v86 quad_perm:[2,3,0,1] row_mask:0xf bank_mask:0xf
	s_nop 1
	v_add_f32_dpp v86, v86, v86 row_half_mirror row_mask:0xf bank_mask:0xf
	s_nop 1
	v_add_f32_dpp v86, v86, v86 row_mirror row_mask:0xf bank_mask:0xf
	s_nop 1
	v_add_f32_dpp v86, v86, v86 row_bcast:15 row_mask:0xa bank_mask:0xf
	s_waitcnt lgkmcnt(0)
	v_xor_b32_e32 v22, 2, v169
	v_cmp_lt_i32_e32 vcc, v22, v15
	s_nop 1
	v_cndmask_b32_e32 v22, v169, v22, vcc
	v_lshlrev_b32_e32 v22, 2, v22
	s_waitcnt lgkmcnt(0)
	v_xor_b32_e32 v23, 4, v169
	v_cmp_lt_i32_e32 vcc, v23, v15
	s_nop 1
	v_cndmask_b32_e32 v23, v169, v23, vcc
	v_lshlrev_b32_e32 v23, 2, v23
	s_waitcnt lgkmcnt(0)
	v_xor_b32_e32 v24, 8, v169
	v_cmp_lt_i32_e32 vcc, v24, v15
	s_nop 1
	v_cndmask_b32_e32 v24, v169, v24, vcc
	v_lshlrev_b32_e32 v24, 2, v24
	s_waitcnt lgkmcnt(0)
	v_xor_b32_e32 v25, 16, v169
	v_cmp_lt_i32_e32 vcc, v25, v15
	s_nop 1
	v_cndmask_b32_e32 v15, v169, v25, vcc
	v_lshlrev_b32_e32 v25, 2, v15
	s_and_saveexec_b64 s[18:19], s[98:99]
	s_cbranch_execz .LBB0_526
	v_lshl_add_u64 v[12:13], v[12:13], 4, s[78:79]
	v_lshl_add_u64 v[12:13], s[6:7], 2, v[12:13]
	s_waitcnt lgkmcnt(0)
	v_mov_b32_e32 v15, v86
	flat_store_dword v[12:13], v15
; DI unsigned pk2(float a, float b) { f32x2 v = {a, b}; bf16x2_t r = __builtin_convertvector(v, bf16x2_t); return __builtin_bit_cast(unsigned, r); }
; DI float bflo(unsigned w) { return __uint_as_float(w << 16); }
; DI float bfhi(unsigned w) { return __uint_as_float(w & 0xffff0000u); }
;     DI void operator()(gacc_t& acc, int pm, int pn, char* lds, int tid, int wr, int wc, int lane) const {
;     ...
;             for (int u = 0; u < 4; ++u) {
;                 const int rloc = (ib * 4 + u) * 16 + wid * 2 + g;
;                 const long row = (long)pm * 256 + rloc;
;                 const u32x4 a = *(const u32x4*)(lds + rloc * 528 + j32 * 16);
;                 u32x4 w; float ss = 0.f;
; #pragma unroll
;                 for (int e = 0; e < 4; ++e) {
;                     w[e] = pk2(bflo(xv[u][e]) + bflo(a[e]), bfhi(xv[u][e]) + bfhi(a[e]));
;                     const float b0 = bflo(w[e]), b1 = bfhi(w[e]);
;                     ss += b0 * b0 + b1 * b1;
;                 }
;                 *(u32x4*)(xnew + row * 1024 + pn * 256 + j32 * 8) = w;
; #pragma unroll
;                 for (int o = 1; o < 32; o <<= 1) ss += __shfl_xor(ss, o);
;                 if (j32 == 0) ssq[row * 4 + pn] = ss;
.LBB0_526:
	s_or_b64 exec, exec, s[18:19]
	v_add_u32_e32 v12, 0x2100, v20
	v_add_u32_e32 v13, v26, v12
	ds_read_b128 v[28:31], v13
	v_lshlrev_b32_e32 v20, 16, v8
	v_and_b32_e32 v21, 0xffff0000, v8
	s_waitcnt lgkmcnt(0)
	v_lshlrev_b32_e32 v32, 16, v28
	v_and_b32_e32 v33, 0xffff0000, v28
	v_pk_add_f32 v[20:21], v[20:21], v[32:33]
	s_nop 0
	v_cvt_pk_bf16_f32 v28, v20, v21
	v_and_b32_e32 v13, 0xffff0000, v28
	v_lshlrev_b32_e32 v8, 16, v28
	v_mul_f32_e32 v13, v13, v13
	v_fmac_f32_e32 v13, v8, v8
	v_lshlrev_b32_e32 v8, 16, v9
	v_and_b32_e32 v9, 0xffff0000, v9
	v_lshlrev_b32_e32 v20, 16, v29
	v_and_b32_e32 v21, 0xffff0000, v29
	v_pk_add_f32 v[8:9], v[8:9], v[20:21]
	v_lshlrev_b32_e32 v20, 16, v30
	v_cvt_pk_bf16_f32 v29, v8, v9
	v_and_b32_e32 v9, 0xffff0000, v29
	v_lshlrev_b32_e32 v8, 16, v29
	v_mul_f32_e32 v9, v9, v9
	v_fmac_f32_e32 v9, v8, v8
	v_add_f32_e32 v13, v13, v9
	v_lshlrev_b32_e32 v8, 16, v10
	v_and_b32_e32 v9, 0xffff0000, v10
	v_and_b32_e32 v21, 0xffff0000, v30
	v_pk_add_f32 v[8:9], v[8:9], v[20:21]
	v_lshlrev_b32_e32 v10, 16, v31
	v_cvt_pk_bf16_f32 v30, v8, v9
	v_and_b32_e32 v9, 0xffff0000, v30
	v_lshlrev_b32_e32 v8, 16, v30
	v_mul_f32_e32 v9, v9, v9
	v_fmac_f32_e32 v9, v8, v8
	v_add_f32_e32 v13, v9, v13
	v_lshlrev_b32_e32 v8, 16, v11
	v_and_b32_e32 v9, 0xffff0000, v11
	v_and_b32_e32 v11, 0xffff0000, v31
	v_pk_add_f32 v[8:9], v[8:9], v[10:11]
	s_nop 0
	v_cvt_pk_bf16_f32 v31, v8, v9
	v_and_b32_e32 v9, 0xffff0000, v31
	v_lshlrev_b32_e32 v8, 16, v31
	v_mul_f32_e32 v9, v9, v9
	v_fmac_f32_e32 v9, v8, v8
	v_add_f32_e32 v8, v9, v13
	s_nop 1
	v_add_f32_dpp v86, v8, v8 quad_perm:[1,0,3,2] row_mask:0xf bank_mask:0xf
	s_nop 1
	v_add_f32_dpp v86, v86, v86 quad_perm:[2,3,0,1] row_mask:0xf bank_mask:0xf
	s_nop 1
	v_add_f32_dpp v86, v86, v86 row_half_mirror row_mask:0xf bank_mask:0xf
	s_nop 1
	v_add_f32_dpp v86, v86, v86 row_mirror row_mask:0xf bank_mask:0xf
	s_nop 1
	v_add_f32_dpp v86, v86, v86 row_bcast:15 row_mask:0xa bank_mask:0xf
	v_lshlrev_b32_e32 v13, 3, v14
	v_lshlrev_b32_e32 v146, 1, v13
	s_waitcnt lgkmcnt(0)
	s_waitcnt lgkmcnt(0)
	v_add_u32_e32 v8, 16, v16
	s_waitcnt lgkmcnt(0)
	v_ashrrev_i32_e32 v9, 31, v8
	v_lshl_add_u64 v[8:9], s[12:13], 0, v[8:9]
	v_lshlrev_b64 v[10:11], 11, v[8:9]
	v_lshl_add_u64 v[14:15], s[68:69], 0, v[10:11]
	s_waitcnt lgkmcnt(0)
	v_lshl_add_u64 v[14:15], s[16:17], 1, v[14:15]
	v_lshl_add_u64 v[14:15], v[14:15], 0, v[146:147]
	flat_store_dwordx4 v[14:15], v[28:31]
	s_and_saveexec_b64 s[18:19], s[98:99]
	s_cbranch_execz .LBB0_528
	v_lshl_add_u64 v[8:9], v[8:9], 4, s[78:79]
	v_lshl_add_u64 v[8:9], s[6:7], 2, v[8:9]
	s_waitcnt lgkmcnt(0)
	v_mov_b32_e32 v10, v86
	flat_store_dword v[8:9], v10
.LBB0_528:
	s_or_b64 exec, exec, s[18:19]
	v_add_u32_e32 v8, 0x2100, v12
	v_add_u32_e32 v9, v26, v8
	s_waitcnt lgkmcnt(0)
	ds_read_b128 v[10:13], v9
	v_lshlrev_b32_e32 v14, 16, v4
	v_and_b32_e32 v15, 0xffff0000, v4
	s_waitcnt lgkmcnt(0)
	v_lshlrev_b32_e32 v20, 16, v10
	v_and_b32_e32 v21, 0xffff0000, v10
	v_pk_add_f32 v[14:15], v[14:15], v[20:21]
	s_nop 0
	v_cvt_pk_bf16_f32 v10, v14, v15
	v_and_b32_e32 v9, 0xffff0000, v10
	v_lshlrev_b32_e32 v4, 16, v10
	v_mul_f32_e32 v9, v9, v9
	v_fmac_f32_e32 v9, v4, v4
	v_lshlrev_b32_e32 v4, 16, v5
	v_and_b32_e32 v5, 0xffff0000, v5
	v_lshlrev_b32_e32 v14, 16, v11
	v_and_b32_e32 v15, 0xffff0000, v11
	v_pk_add_f32 v[4:5], v[4:5], v[14:15]
	v_lshlrev_b32_e32 v14, 16, v12
	v_cvt_pk_bf16_f32 v11, v4, v5
	v_and_b32_e32 v5, 0xffff0000, v11
	v_lshlrev_b32_e32 v4, 16, v11
	v_mul_f32_e32 v5, v5, v5
	v_fmac_f32_e32 v5, v4, v4
	v_add_f32_e32 v9, v9, v5
	v_lshlrev_b32_e32 v4, 16, v6
	v_and_b32_e32 v5, 0xffff0000, v6
	v_and_b32_e32 v15, 0xffff0000, v12
	v_pk_add_f32 v[4:5], v[4:5], v[14:15]
	v_lshlrev_b32_e32 v6, 16, v13
	v_cvt_pk_bf16_f32 v12, v4, v5
	v_and_b32_e32 v5, 0xffff0000, v12
	v_lshlrev_b32_e32 v4, 16, v12
	v_mul_f32_e32 v5, v5, v5
	v_fmac_f32_e32 v5, v4, v4
	v_add_f32_e32 v9, v5, v9
	v_lshlrev_b32_e32 v4, 16, v7
	v_and_b32_e32 v5, 0xffff0000, v7
	v_and_b32_e32 v7, 0xffff0000, v13
	v_pk_add_f32 v[4:5], v[4:5], v[6:7]
	s_nop 0
	v_cvt_pk_bf16_f32 v13, v4, v5
	v_and_b32_e32 v5, 0xffff0000, v13
	v_lshlrev_b32_e32 v4, 16, v13
	v_mul_f32_e32 v5, v5, v5
	v_fmac_f32_e32 v5, v4, v4
	v_add_f32_e32 v4, v5, v9
	s_nop 1
	v_add_f32_dpp v86, v4, v4 quad_perm:[1,0,3,2] row_mask:0xf bank_mask:0xf
	s_nop 1
	v_add_f32_dpp v86, v86, v86 quad_perm:[2,3,0,1] row_mask:0xf bank_mask:0xf
	s_nop 1
	v_add_f32_dpp v86, v86, v86 row_half_mirror row_mask:0xf bank_mask:0xf
	s_nop 1
	v_add_f32_dpp v86, v86, v86 row_mirror row_mask:0xf bank_mask:0xf
	s_nop 1
	v_add_f32_dpp v86, v86, v86 row_bcast:15 row_mask:0xa bank_mask:0xf
	s_waitcnt lgkmcnt(0)
	s_waitcnt lgkmcnt(0)
	s_waitcnt lgkmcnt(0)
	v_add_u32_e32 v4, 32, v16
	v_ashrrev_i32_e32 v5, 31, v4
	v_lshl_add_u64 v[4:5], s[12:13], 0, v[4:5]
	v_lshlrev_b64 v[14:15], 11, v[4:5]
	s_waitcnt lgkmcnt(0)
	v_lshl_add_u64 v[14:15], s[68:69], 0, v[14:15]
	v_lshl_add_u64 v[14:15], s[16:17], 1, v[14:15]
	v_lshl_add_u64 v[14:15], v[14:15], 0, v[146:147]
	flat_store_dwordx4 v[14:15], v[10:13]
	s_and_saveexec_b64 s[18:19], s[98:99]
	s_cbranch_execz .LBB0_530
	v_lshl_add_u64 v[4:5], v[4:5], 4, s[78:79]
	v_lshl_add_u64 v[4:5], s[6:7], 2, v[4:5]
	s_waitcnt lgkmcnt(0)
	v_mov_b32_e32 v6, v86
	flat_store_dword v[4:5], v6
; DI unsigned pk2(float a, float b) { f32x2 v = {a, b}; bf16x2_t r = __builtin_convertvector(v, bf16x2_t); return __builtin_bit_cast(unsigned, r); }
; DI float bflo(unsigned w) { return __uint_as_float(w << 16); }
; DI float bfhi(unsigned w) { return __uint_as_float(w & 0xffff0000u); }
;     DI void operator()(gacc_t& acc, int pm, int pn, char* lds, int tid, int wr, int wc, int lane) const {
;     ...
;         for (int ib = 0; ib < 4; ++ib) {
;             __builtin_amdgcn_sched_barrier(0);
;             u32x4 xv[4];
; #pragma unroll
;             for (int u = 0; u < 4; ++u) {
;                 const long row = (long)pm * 256 + (ib * 4 + u) * 16 + wid * 2 + g;
;                 xv[u] = *(const u32x4*)(xold + row * 1024 + pn * 256 + j32 * 8);
;             }
; #pragma unroll
;             for (int u = 0; u < 4; ++u) {
;                 const int rloc = (ib * 4 + u) * 16 + wid * 2 + g;
;                 const long row = (long)pm * 256 + rloc;
;                 const u32x4 a = *(const u32x4*)(lds + rloc * 528 + j32 * 16);
;                 u32x4 w; float ss = 0.f;
; #pragma unroll
;                 for (int e = 0; e < 4; ++e) {
;                     w[e] = pk2(bflo(xv[u][e]) + bflo(a[e]), bfhi(xv[u][e]) + bfhi(a[e]));
;                     const float b0 = bflo(w[e]), b1 = bfhi(w[e]);
;                     ss += b0 * b0 + b1 * b1;
;                 }
;                 *(u32x4*)(xnew + row * 1024 + pn * 256 + j32 * 8) = w;
; #pragma unroll
;                 for (int o = 1; o < 32; o <<= 1) ss += __shfl_xor(ss, o);
;                 if (j32 == 0) ssq[row * 4 + pn] = ss;
.LBB0_530:
	s_or_b64 exec, exec, s[18:19]
	v_add_u32_e32 v12, 0x2100, v8
	v_add_u32_e32 v4, v26, v12
	s_waitcnt lgkmcnt(0)
	ds_read_b128 v[4:7], v4
	v_lshlrev_b32_e32 v8, 16, v0
	v_and_b32_e32 v9, 0xffff0000, v0
	s_waitcnt lgkmcnt(0)
	v_lshlrev_b32_e32 v10, 16, v4
	v_and_b32_e32 v11, 0xffff0000, v4
	v_pk_add_f32 v[8:9], v[8:9], v[10:11]
	s_nop 0
	v_cvt_pk_bf16_f32 v4, v8, v9
	v_and_b32_e32 v8, 0xffff0000, v4
	v_lshlrev_b32_e32 v0, 16, v4
	v_mul_f32_e32 v10, v8, v8
	v_fmac_f32_e32 v10, v0, v0
	v_lshlrev_b32_e32 v0, 16, v1
	v_and_b32_e32 v1, 0xffff0000, v1
	v_lshlrev_b32_e32 v8, 16, v5
	v_and_b32_e32 v9, 0xffff0000, v5
	v_pk_add_f32 v[0:1], v[0:1], v[8:9]
	v_lshlrev_b32_e32 v8, 16, v6
	v_cvt_pk_bf16_f32 v5, v0, v1
	v_and_b32_e32 v1, 0xffff0000, v5
	v_lshlrev_b32_e32 v0, 16, v5
	v_mul_f32_e32 v1, v1, v1
	v_fmac_f32_e32 v1, v0, v0
	v_add_f32_e32 v10, v10, v1
	v_lshlrev_b32_e32 v0, 16, v2
	v_and_b32_e32 v1, 0xffff0000, v2
	v_and_b32_e32 v9, 0xffff0000, v6
	v_pk_add_f32 v[0:1], v[0:1], v[8:9]
	v_lshlrev_b32_e32 v2, 16, v7
	v_cvt_pk_bf16_f32 v6, v0, v1
	v_and_b32_e32 v1, 0xffff0000, v6
	v_lshlrev_b32_e32 v0, 16, v6
	v_mul_f32_e32 v1, v1, v1
	v_fmac_f32_e32 v1, v0, v0
	v_add_f32_e32 v8, v1, v10
	v_lshlrev_b32_e32 v0, 16, v3
	v_and_b32_e32 v1, 0xffff0000, v3
	v_and_b32_e32 v3, 0xffff0000, v7
	v_pk_add_f32 v[0:1], v[0:1], v[2:3]
	s_nop 0
	v_cvt_pk_bf16_f32 v7, v0, v1
	v_and_b32_e32 v1, 0xffff0000, v7
	v_lshlrev_b32_e32 v0, 16, v7
	v_mul_f32_e32 v1, v1, v1
	v_fmac_f32_e32 v1, v0, v0
	v_add_f32_e32 v0, v1, v8
	s_nop 1
	v_add_f32_dpp v86, v0, v0 quad_perm:[1,0,3,2] row_mask:0xf bank_mask:0xf
	s_nop 1
	v_add_f32_dpp v86, v86, v86 quad_perm:[2,3,0,1] row_mask:0xf bank_mask:0xf
	s_nop 1
	v_add_f32_dpp v86, v86, v86 row_half_mirror row_mask:0xf bank_mask:0xf
	s_nop 1
	v_add_f32_dpp v86, v86, v86 row_mirror row_mask:0xf bank_mask:0xf
	s_nop 1
	v_add_f32_dpp v86, v86, v86 row_bcast:15 row_mask:0xa bank_mask:0xf
	s_waitcnt lgkmcnt(0)
	s_waitcnt lgkmcnt(0)
	s_waitcnt lgkmcnt(0)
	v_add_u32_e32 v0, 48, v16
	v_ashrrev_i32_e32 v1, 31, v0
	v_lshl_add_u64 v[0:1], s[12:13], 0, v[0:1]
	v_lshlrev_b64 v[8:9], 11, v[0:1]
	s_waitcnt lgkmcnt(0)
	v_lshl_add_u64 v[8:9], s[68:69], 0, v[8:9]
	v_lshl_add_u64 v[8:9], s[16:17], 1, v[8:9]
	v_lshl_add_u64 v[8:9], v[8:9], 0, v[146:147]
	flat_store_dwordx4 v[8:9], v[4:7]
	s_and_saveexec_b64 s[18:19], s[98:99]
	s_cbranch_execz .LBB0_532
	v_lshl_add_u64 v[0:1], v[0:1], 4, s[78:79]
	v_lshl_add_u64 v[0:1], s[6:7], 2, v[0:1]
	s_waitcnt lgkmcnt(0)
	v_mov_b32_e32 v2, v86
	flat_store_dword v[0:1], v2
.LBB0_532:
	s_or_b64 exec, exec, s[18:19]
	v_add_co_u32_e32 v0, vcc, 0x20000, v18
	v_add_u32_e32 v27, 0x2100, v12
	s_nop 0
	v_addc_co_u32_e32 v1, vcc, 0, v19, vcc
	flat_load_dwordx4 v[28:31], v[0:1]
	v_add_co_u32_e32 v0, vcc, 0x28000, v18
	v_add_u32_e32 v12, v26, v27
	s_nop 0
	v_addc_co_u32_e32 v1, vcc, 0, v19, vcc
	flat_load_dwordx4 v[8:11], v[0:1]
	v_add_co_u32_e32 v0, vcc, 0x30000, v18
	ds_read_b128 v[12:15], v12
	s_nop 0
	v_addc_co_u32_e32 v1, vcc, 0, v19, vcc
	flat_load_dwordx4 v[4:7], v[0:1]
	v_add_co_u32_e32 v0, vcc, 0x38000, v18
	s_waitcnt lgkmcnt(0)
	v_lshlrev_b32_e32 v34, 16, v12
	v_addc_co_u32_e32 v1, vcc, 0, v19, vcc
	flat_load_dwordx4 v[0:3], v[0:1]
	v_and_b32_e32 v35, 0xffff0000, v12
	v_add_u32_e32 v20, 64, v16
	v_ashrrev_i32_e32 v21, 31, v20
	v_lshl_add_u64 v[20:21], s[12:13], 0, v[20:21]
	s_waitcnt vmcnt(0)
	v_lshlrev_b32_e32 v32, 16, v28
	v_and_b32_e32 v33, 0xffff0000, v28
	v_pk_add_f32 v[32:33], v[32:33], v[34:35]
	s_nop 0
	v_cvt_pk_bf16_f32 v12, v32, v33
	v_and_b32_e32 v32, 0xffff0000, v12
	v_lshlrev_b32_e32 v28, 16, v12
	v_mul_f32_e32 v34, v32, v32
	v_fmac_f32_e32 v34, v28, v28
	v_lshlrev_b32_e32 v28, 16, v29
	v_and_b32_e32 v29, 0xffff0000, v29
	v_lshlrev_b32_e32 v32, 16, v13
	v_and_b32_e32 v33, 0xffff0000, v13
	v_pk_add_f32 v[28:29], v[28:29], v[32:33]
	v_lshlrev_b32_e32 v32, 16, v14
	v_cvt_pk_bf16_f32 v13, v28, v29
	v_and_b32_e32 v29, 0xffff0000, v13
	v_lshlrev_b32_e32 v28, 16, v13
	v_mul_f32_e32 v29, v29, v29
	v_fmac_f32_e32 v29, v28, v28
	v_add_f32_e32 v34, v34, v29
	v_lshlrev_b32_e32 v28, 16, v30
	v_and_b32_e32 v29, 0xffff0000, v30
	v_and_b32_e32 v33, 0xffff0000, v14
	v_pk_add_f32 v[28:29], v[28:29], v[32:33]
	v_lshlrev_b32_e32 v30, 16, v15
	v_cvt_pk_bf16_f32 v14, v28, v29
	v_and_b32_e32 v29, 0xffff0000, v14
	v_lshlrev_b32_e32 v28, 16, v14
	v_mul_f32_e32 v29, v29, v29
	v_fmac_f32_e32 v29, v28, v28
	v_add_f32_e32 v32, v29, v34
	v_lshlrev_b32_e32 v28, 16, v31
	v_and_b32_e32 v29, 0xffff0000, v31
	v_and_b32_e32 v31, 0xffff0000, v15
	v_pk_add_f32 v[28:29], v[28:29], v[30:31]
	s_nop 0
	v_cvt_pk_bf16_f32 v15, v28, v29
	v_and_b32_e32 v29, 0xffff0000, v15
	v_lshlrev_b32_e32 v28, 16, v15
	v_mul_f32_e32 v29, v29, v29
	v_fmac_f32_e32 v29, v28, v28
	v_add_f32_e32 v30, v29, v32
	v_lshlrev_b64 v[28:29], 11, v[20:21]
	v_lshl_add_u64 v[28:29], s[68:69], 0, v[28:29]
	v_lshl_add_u64 v[28:29], s[16:17], 1, v[28:29]
	v_lshl_add_u64 v[28:29], v[28:29], 0, v[146:147]
	flat_store_dwordx4 v[28:29], v[12:15]
	s_nop 1
	v_add_f32_dpp v86, v30, v30 quad_perm:[1,0,3,2] row_mask:0xf bank_mask:0xf
	s_nop 1
	v_add_f32_dpp v86, v86, v86 quad_perm:[2,3,0,1] row_mask:0xf bank_mask:0xf
	s_nop 1
	v_add_f32_dpp v86, v86, v86 row_half_mirror row_mask:0xf bank_mask:0xf
	s_nop 1
	v_add_f32_dpp v86, v86, v86 row_mirror row_mask:0xf bank_mask:0xf
	s_nop 1
	v_add_f32_dpp v86, v86, v86 row_bcast:15 row_mask:0xa bank_mask:0xf
	s_waitcnt lgkmcnt(0)
	s_waitcnt lgkmcnt(0)
	s_waitcnt lgkmcnt(0)
	s_waitcnt lgkmcnt(0)
	s_and_saveexec_b64 s[18:19], s[98:99]
	s_cbranch_execz .LBB0_534
	v_lshl_add_u64 v[14:15], v[20:21], 4, s[78:79]
	v_lshl_add_u64 v[14:15], s[6:7], 2, v[14:15]
	s_waitcnt lgkmcnt(0)
	v_mov_b32_e32 v12, v86
	flat_store_dword v[14:15], v12
; DI unsigned pk2(float a, float b) { f32x2 v = {a, b}; bf16x2_t r = __builtin_convertvector(v, bf16x2_t); return __builtin_bit_cast(unsigned, r); }
; DI float bflo(unsigned w) { return __uint_as_float(w << 16); }
; DI float bfhi(unsigned w) { return __uint_as_float(w & 0xffff0000u); }
;     DI void operator()(gacc_t& acc, int pm, int pn, char* lds, int tid, int wr, int wc, int lane) const {
;     ...
;             for (int u = 0; u < 4; ++u) {
;                 const int rloc = (ib * 4 + u) * 16 + wid * 2 + g;
;                 const long row = (long)pm * 256 + rloc;
;                 const u32x4 a = *(const u32x4*)(lds + rloc * 528 + j32 * 16);
;                 u32x4 w; float ss = 0.f;
; #pragma unroll
;                 for (int e = 0; e < 4; ++e) {
;                     w[e] = pk2(bflo(xv[u][e]) + bflo(a[e]), bfhi(xv[u][e]) + bfhi(a[e]));
;                     const float b0 = bflo(w[e]), b1 = bfhi(w[e]);
;                     ss += b0 * b0 + b1 * b1;
;                 }
;                 *(u32x4*)(xnew + row * 1024 + pn * 256 + j32 * 8) = w;
; #pragma unroll
;                 for (int o = 1; o < 32; o <<= 1) ss += __shfl_xor(ss, o);
;                 if (j32 == 0) ssq[row * 4 + pn] = ss;
.LBB0_534:
	s_or_b64 exec, exec, s[18:19]
	v_add_u32_e32 v12, 0x2100, v27
	s_waitcnt lgkmcnt(0)
	v_add_u32_e32 v13, v26, v12
	ds_read_b128 v[28:31], v13
	v_lshlrev_b32_e32 v14, 16, v8
	v_and_b32_e32 v15, 0xffff0000, v8
	s_waitcnt lgkmcnt(0)
	v_lshlrev_b32_e32 v20, 16, v28
	v_and_b32_e32 v21, 0xffff0000, v28
	v_pk_add_f32 v[14:15], v[14:15], v[20:21]
	s_nop 0
	v_cvt_pk_bf16_f32 v28, v14, v15
	v_and_b32_e32 v13, 0xffff0000, v28
	v_lshlrev_b32_e32 v8, 16, v28
	v_mul_f32_e32 v13, v13, v13
	v_fmac_f32_e32 v13, v8, v8
	v_lshlrev_b32_e32 v8, 16, v9
	v_and_b32_e32 v9, 0xffff0000, v9
	v_lshlrev_b32_e32 v14, 16, v29
	v_and_b32_e32 v15, 0xffff0000, v29
	v_pk_add_f32 v[8:9], v[8:9], v[14:15]
	v_lshlrev_b32_e32 v14, 16, v30
	v_cvt_pk_bf16_f32 v29, v8, v9
	v_and_b32_e32 v9, 0xffff0000, v29
	v_lshlrev_b32_e32 v8, 16, v29
	v_mul_f32_e32 v9, v9, v9
	v_fmac_f32_e32 v9, v8, v8
	v_add_f32_e32 v13, v13, v9
	v_lshlrev_b32_e32 v8, 16, v10
	v_and_b32_e32 v9, 0xffff0000, v10
	v_and_b32_e32 v15, 0xffff0000, v30
	v_pk_add_f32 v[8:9], v[8:9], v[14:15]
	v_lshlrev_b32_e32 v10, 16, v31
	v_cvt_pk_bf16_f32 v30, v8, v9
	v_and_b32_e32 v9, 0xffff0000, v30
	v_lshlrev_b32_e32 v8, 16, v30
	v_mul_f32_e32 v9, v9, v9
	v_fmac_f32_e32 v9, v8, v8
	v_add_f32_e32 v13, v9, v13
	v_lshlrev_b32_e32 v8, 16, v11
	v_and_b32_e32 v9, 0xffff0000, v11
	v_and_b32_e32 v11, 0xffff0000, v31
	v_pk_add_f32 v[8:9], v[8:9], v[10:11]
	s_nop 0
	v_cvt_pk_bf16_f32 v31, v8, v9
	v_and_b32_e32 v9, 0xffff0000, v31
	v_lshlrev_b32_e32 v8, 16, v31
	v_mul_f32_e32 v9, v9, v9
	v_fmac_f32_e32 v9, v8, v8
	v_add_f32_e32 v8, v9, v13
	s_nop 1
	v_add_f32_dpp v86, v8, v8 quad_perm:[1,0,3,2] row_mask:0xf bank_mask:0xf
	s_nop 1
	v_add_f32_dpp v86, v86, v86 quad_perm:[2,3,0,1] row_mask:0xf bank_mask:0xf
	s_nop 1
	v_add_f32_dpp v86, v86, v86 row_half_mirror row_mask:0xf bank_mask:0xf
	s_nop 1
	v_add_f32_dpp v86, v86, v86 row_mirror row_mask:0xf bank_mask:0xf
	s_nop 1
	v_add_f32_dpp v86, v86, v86 row_bcast:15 row_mask:0xa bank_mask:0xf
	s_waitcnt lgkmcnt(0)
	s_waitcnt lgkmcnt(0)
	s_waitcnt lgkmcnt(0)
	v_add_u32_e32 v8, 0x50, v16
	v_ashrrev_i32_e32 v9, 31, v8
	v_lshl_add_u64 v[8:9], s[12:13], 0, v[8:9]
	v_lshlrev_b64 v[14:15], 11, v[8:9]
	s_waitcnt lgkmcnt(0)
	v_lshl_add_u64 v[14:15], s[68:69], 0, v[14:15]
	v_lshl_add_u64 v[14:15], s[16:17], 1, v[14:15]
	v_lshl_add_u64 v[14:15], v[14:15], 0, v[146:147]
	flat_store_dwordx4 v[14:15], v[28:31]
	s_and_saveexec_b64 s[18:19], s[98:99]
	s_cbranch_execz .LBB0_536
	v_lshl_add_u64 v[8:9], v[8:9], 4, s[78:79]
	v_lshl_add_u64 v[8:9], s[6:7], 2, v[8:9]
	s_waitcnt lgkmcnt(0)
	v_mov_b32_e32 v10, v86
	flat_store_dword v[8:9], v10
.LBB0_536:
	s_or_b64 exec, exec, s[18:19]
	v_add_u32_e32 v8, 0x2100, v12
	v_add_u32_e32 v9, v26, v8
	s_waitcnt lgkmcnt(0)
	ds_read_b128 v[10:13], v9
	v_lshlrev_b32_e32 v14, 16, v4
	v_and_b32_e32 v15, 0xffff0000, v4
	s_waitcnt lgkmcnt(0)
	v_lshlrev_b32_e32 v20, 16, v10
	v_and_b32_e32 v21, 0xffff0000, v10
	v_pk_add_f32 v[14:15], v[14:15], v[20:21]
	s_nop 0
	v_cvt_pk_bf16_f32 v10, v14, v15
	v_and_b32_e32 v9, 0xffff0000, v10
	v_lshlrev_b32_e32 v4, 16, v10
	v_mul_f32_e32 v9, v9, v9
	v_fmac_f32_e32 v9, v4, v4
	v_lshlrev_b32_e32 v4, 16, v5
	v_and_b32_e32 v5, 0xffff0000, v5
	v_lshlrev_b32_e32 v14, 16, v11
	v_and_b32_e32 v15, 0xffff0000, v11
	v_pk_add_f32 v[4:5], v[4:5], v[14:15]
	v_lshlrev_b32_e32 v14, 16, v12
	v_cvt_pk_bf16_f32 v11, v4, v5
	v_and_b32_e32 v5, 0xffff0000, v11
	v_lshlrev_b32_e32 v4, 16, v11
	v_mul_f32_e32 v5, v5, v5
	v_fmac_f32_e32 v5, v4, v4
	v_add_f32_e32 v9, v9, v5
	v_lshlrev_b32_e32 v4, 16, v6
	v_and_b32_e32 v5, 0xffff0000, v6
	v_and_b32_e32 v15, 0xffff0000, v12
	v_pk_add_f32 v[4:5], v[4:5], v[14:15]
	v_lshlrev_b32_e32 v6, 16, v13
	v_cvt_pk_bf16_f32 v12, v4, v5
	v_and_b32_e32 v5, 0xffff0000, v12
	v_lshlrev_b32_e32 v4, 16, v12
	v_mul_f32_e32 v5, v5, v5
	v_fmac_f32_e32 v5, v4, v4
	v_add_f32_e32 v9, v5, v9
	v_lshlrev_b32_e32 v4, 16, v7
	v_and_b32_e32 v5, 0xffff0000, v7
	v_and_b32_e32 v7, 0xffff0000, v13
	v_pk_add_f32 v[4:5], v[4:5], v[6:7]
	s_nop 0
	v_cvt_pk_bf16_f32 v13, v4, v5
	v_and_b32_e32 v5, 0xffff0000, v13
	v_lshlrev_b32_e32 v4, 16, v13
	v_mul_f32_e32 v5, v5, v5
	v_fmac_f32_e32 v5, v4, v4
	v_add_f32_e32 v4, v5, v9
	s_nop 1
	v_add_f32_dpp v86, v4, v4 quad_perm:[1,0,3,2] row_mask:0xf bank_mask:0xf
	s_nop 1
	v_add_f32_dpp v86, v86, v86 quad_perm:[2,3,0,1] row_mask:0xf bank_mask:0xf
	s_nop 1
	v_add_f32_dpp v86, v86, v86 row_half_mirror row_mask:0xf bank_mask:0xf
	s_nop 1
	v_add_f32_dpp v86, v86, v86 row_mirror row_mask:0xf bank_mask:0xf
	s_nop 1
	v_add_f32_dpp v86, v86, v86 row_bcast:15 row_mask:0xa bank_mask:0xf
	s_waitcnt lgkmcnt(0)
	s_waitcnt lgkmcnt(0)
	s_waitcnt lgkmcnt(0)
	v_add_u32_e32 v4, 0x60, v16
	v_ashrrev_i32_e32 v5, 31, v4
	v_lshl_add_u64 v[4:5], s[12:13], 0, v[4:5]
	v_lshlrev_b64 v[14:15], 11, v[4:5]
	s_waitcnt lgkmcnt(0)
	v_lshl_add_u64 v[14:15], s[68:69], 0, v[14:15]
	v_lshl_add_u64 v[14:15], s[16:17], 1, v[14:15]
	v_lshl_add_u64 v[14:15], v[14:15], 0, v[146:147]
	flat_store_dwordx4 v[14:15], v[10:13]
	s_and_saveexec_b64 s[18:19], s[98:99]
	s_cbranch_execz .LBB0_538
	v_lshl_add_u64 v[4:5], v[4:5], 4, s[78:79]
	v_lshl_add_u64 v[4:5], s[6:7], 2, v[4:5]
	s_waitcnt lgkmcnt(0)
	v_mov_b32_e32 v6, v86
	flat_store_dword v[4:5], v6
; DI unsigned pk2(float a, float b) { f32x2 v = {a, b}; bf16x2_t r = __builtin_convertvector(v, bf16x2_t); return __builtin_bit_cast(unsigned, r); }
; DI float bflo(unsigned w) { return __uint_as_float(w << 16); }
; DI float bfhi(unsigned w) { return __uint_as_float(w & 0xffff0000u); }
;     DI void operator()(gacc_t& acc, int pm, int pn, char* lds, int tid, int wr, int wc, int lane) const {
;     ...
;         for (int ib = 0; ib < 4; ++ib) {
;             __builtin_amdgcn_sched_barrier(0);
;             u32x4 xv[4];
; #pragma unroll
;             for (int u = 0; u < 4; ++u) {
;                 const long row = (long)pm * 256 + (ib * 4 + u) * 16 + wid * 2 + g;
;                 xv[u] = *(const u32x4*)(xold + row * 1024 + pn * 256 + j32 * 8);
;             }
; #pragma unroll
;             for (int u = 0; u < 4; ++u) {
;                 const int rloc = (ib * 4 + u) * 16 + wid * 2 + g;
;                 const long row = (long)pm * 256 + rloc;
;                 const u32x4 a = *(const u32x4*)(lds + rloc * 528 + j32 * 16);
;                 u32x4 w; float ss = 0.f;
; #pragma unroll
;                 for (int e = 0; e < 4; ++e) {
;                     w[e] = pk2(bflo(xv[u][e]) + bflo(a[e]), bfhi(xv[u][e]) + bfhi(a[e]));
;                     const float b0 = bflo(w[e]), b1 = bfhi(w[e]);
;                     ss += b0 * b0 + b1 * b1;
;                 }
;                 *(u32x4*)(xnew + row * 1024 + pn * 256 + j32 * 8) = w;
; #pragma unroll
;                 for (int o = 1; o < 32; o <<= 1) ss += __shfl_xor(ss, o);
;                 if (j32 == 0) ssq[row * 4 + pn] = ss;
.LBB0_538:
	s_or_b64 exec, exec, s[18:19]
	v_add_u32_e32 v12, 0x2100, v8
	v_add_u32_e32 v4, v26, v12
	s_waitcnt lgkmcnt(0)
	ds_read_b128 v[4:7], v4
	v_lshlrev_b32_e32 v8, 16, v0
	v_and_b32_e32 v9, 0xffff0000, v0
	s_waitcnt lgkmcnt(0)
	v_lshlrev_b32_e32 v10, 16, v4
	v_and_b32_e32 v11, 0xffff0000, v4
	v_pk_add_f32 v[8:9], v[8:9], v[10:11]
	s_nop 0
	v_cvt_pk_bf16_f32 v4, v8, v9
	v_and_b32_e32 v8, 0xffff0000, v4
	v_lshlrev_b32_e32 v0, 16, v4
	v_mul_f32_e32 v10, v8, v8
	v_fmac_f32_e32 v10, v0, v0
	v_lshlrev_b32_e32 v0, 16, v1
	v_and_b32_e32 v1, 0xffff0000, v1
	v_lshlrev_b32_e32 v8, 16, v5
	v_and_b32_e32 v9, 0xffff0000, v5
	v_pk_add_f32 v[0:1], v[0:1], v[8:9]
	v_lshlrev_b32_e32 v8, 16, v6
	v_cvt_pk_bf16_f32 v5, v0, v1
	v_and_b32_e32 v1, 0xffff0000, v5
	v_lshlrev_b32_e32 v0, 16, v5
	v_mul_f32_e32 v1, v1, v1
	v_fmac_f32_e32 v1, v0, v0
	v_add_f32_e32 v10, v10, v1
	v_lshlrev_b32_e32 v0, 16, v2
	v_and_b32_e32 v1, 0xffff0000, v2
	v_and_b32_e32 v9, 0xffff0000, v6
	v_pk_add_f32 v[0:1], v[0:1], v[8:9]
	v_lshlrev_b32_e32 v2, 16, v7
	v_cvt_pk_bf16_f32 v6, v0, v1
	v_and_b32_e32 v1, 0xffff0000, v6
	v_lshlrev_b32_e32 v0, 16, v6
	v_mul_f32_e32 v1, v1, v1
	v_fmac_f32_e32 v1, v0, v0
	v_add_f32_e32 v8, v1, v10
	v_lshlrev_b32_e32 v0, 16, v3
	v_and_b32_e32 v1, 0xffff0000, v3
	v_and_b32_e32 v3, 0xffff0000, v7
	v_pk_add_f32 v[0:1], v[0:1], v[2:3]
	s_nop 0
	v_cvt_pk_bf16_f32 v7, v0, v1
	v_and_b32_e32 v1, 0xffff0000, v7
	v_lshlrev_b32_e32 v0, 16, v7
	v_mul_f32_e32 v1, v1, v1
	v_fmac_f32_e32 v1, v0, v0
	v_add_f32_e32 v0, v1, v8
	s_nop 1
	v_add_f32_dpp v86, v0, v0 quad_perm:[1,0,3,2] row_mask:0xf bank_mask:0xf
	s_nop 1
	v_add_f32_dpp v86, v86, v86 quad_perm:[2,3,0,1] row_mask:0xf bank_mask:0xf
	s_nop 1
	v_add_f32_dpp v86, v86, v86 row_half_mirror row_mask:0xf bank_mask:0xf
	s_nop 1
	v_add_f32_dpp v86, v86, v86 row_mirror row_mask:0xf bank_mask:0xf
	s_nop 1
	v_add_f32_dpp v86, v86, v86 row_bcast:15 row_mask:0xa bank_mask:0xf
	s_waitcnt lgkmcnt(0)
	s_waitcnt lgkmcnt(0)
	s_waitcnt lgkmcnt(0)
	v_add_u32_e32 v0, 0x70, v16
	v_ashrrev_i32_e32 v1, 31, v0
	v_lshl_add_u64 v[0:1], s[12:13], 0, v[0:1]
	v_lshlrev_b64 v[8:9], 11, v[0:1]
	s_waitcnt lgkmcnt(0)
	v_lshl_add_u64 v[8:9], s[68:69], 0, v[8:9]
	v_lshl_add_u64 v[8:9], s[16:17], 1, v[8:9]
	v_lshl_add_u64 v[8:9], v[8:9], 0, v[146:147]
	flat_store_dwordx4 v[8:9], v[4:7]
	s_and_saveexec_b64 s[18:19], s[98:99]
	s_cbranch_execz .LBB0_540
	v_lshl_add_u64 v[0:1], v[0:1], 4, s[78:79]
	v_lshl_add_u64 v[0:1], s[6:7], 2, v[0:1]
	s_waitcnt lgkmcnt(0)
	v_mov_b32_e32 v2, v86
	flat_store_dword v[0:1], v2
.LBB0_540:
	s_or_b64 exec, exec, s[18:19]
	v_add_co_u32_e32 v0, vcc, 0x40000, v18
	v_add_u32_e32 v12, 0x2100, v12
	s_nop 0
	v_addc_co_u32_e32 v1, vcc, 0, v19, vcc
	flat_load_dwordx4 v[28:31], v[0:1]
	v_add_co_u32_e32 v0, vcc, 0x48000, v18
	v_add_u32_e32 v26, v26, v12
	s_nop 0
	v_addc_co_u32_e32 v1, vcc, 0, v19, vcc
	flat_load_dwordx4 v[8:11], v[0:1]
	v_add_co_u32_e32 v0, vcc, 0x50000, v18
	ds_read_b128 v[12:15], v26
	s_nop 0
	v_addc_co_u32_e32 v1, vcc, 0, v19, vcc
	flat_load_dwordx4 v[4:7], v[0:1]
	v_add_co_u32_e32 v0, vcc, 0x58000, v18
	s_waitcnt lgkmcnt(0)
	v_lshlrev_b32_e32 v34, 16, v12
	v_addc_co_u32_e32 v1, vcc, 0, v19, vcc
	flat_load_dwordx4 v[0:3], v[0:1]
	v_and_b32_e32 v35, 0xffff0000, v12
	v_add_u32_e32 v20, 0x80, v16
	v_ashrrev_i32_e32 v21, 31, v20
	v_lshl_add_u64 v[20:21], s[12:13], 0, v[20:21]
	s_waitcnt vmcnt(0)
	v_lshlrev_b32_e32 v32, 16, v28
	v_and_b32_e32 v33, 0xffff0000, v28
	v_pk_add_f32 v[32:33], v[32:33], v[34:35]
	s_nop 0
	v_cvt_pk_bf16_f32 v12, v32, v33
	v_and_b32_e32 v28, 0xffff0000, v12
	v_mul_f32_e32 v34, v28, v28
	v_lshlrev_b32_e32 v28, 16, v29
	v_and_b32_e32 v29, 0xffff0000, v29
	v_lshlrev_b32_e32 v32, 16, v13
	v_and_b32_e32 v33, 0xffff0000, v13
	v_pk_add_f32 v[28:29], v[28:29], v[32:33]
	v_lshlrev_b32_e32 v27, 16, v12
	v_cvt_pk_bf16_f32 v13, v28, v29
	v_and_b32_e32 v28, 0xffff0000, v13
	v_fmac_f32_e32 v34, v27, v27
	v_lshlrev_b32_e32 v27, 16, v13
	v_mul_f32_e32 v28, v28, v28
	v_fmac_f32_e32 v28, v27, v27
	v_add_f32_e32 v27, v34, v28
	v_lshlrev_b32_e32 v28, 16, v30
	v_and_b32_e32 v29, 0xffff0000, v30
	v_lshlrev_b32_e32 v32, 16, v14
	v_and_b32_e32 v33, 0xffff0000, v14
	v_pk_add_f32 v[28:29], v[28:29], v[32:33]
	v_lshlrev_b32_e32 v30, 16, v15
	v_cvt_pk_bf16_f32 v14, v28, v29
	v_and_b32_e32 v29, 0xffff0000, v14
	v_lshlrev_b32_e32 v28, 16, v14
	v_mul_f32_e32 v29, v29, v29
	v_fmac_f32_e32 v29, v28, v28
	v_add_f32_e32 v27, v29, v27
	v_lshlrev_b32_e32 v28, 16, v31
	v_and_b32_e32 v29, 0xffff0000, v31
	v_and_b32_e32 v31, 0xffff0000, v15
	v_pk_add_f32 v[28:29], v[28:29], v[30:31]
	s_nop 0
	v_cvt_pk_bf16_f32 v15, v28, v29
	v_and_b32_e32 v29, 0xffff0000, v15
	v_lshlrev_b32_e32 v28, 16, v15
	v_mul_f32_e32 v29, v29, v29
	v_fmac_f32_e32 v29, v28, v28
	v_add_f32_e32 v27, v29, v27
	v_lshlrev_b64 v[28:29], 11, v[20:21]
	v_lshl_add_u64 v[28:29], s[68:69], 0, v[28:29]
	v_lshl_add_u64 v[28:29], s[16:17], 1, v[28:29]
	v_lshl_add_u64 v[28:29], v[28:29], 0, v[146:147]
	flat_store_dwordx4 v[28:29], v[12:15]
	s_nop 1
	v_add_f32_dpp v86, v27, v27 quad_perm:[1,0,3,2] row_mask:0xf bank_mask:0xf
	s_nop 1
	v_add_f32_dpp v86, v86, v86 quad_perm:[2,3,0,1] row_mask:0xf bank_mask:0xf
	s_nop 1
	v_add_f32_dpp v86, v86, v86 row_half_mirror row_mask:0xf bank_mask:0xf
	s_nop 1
	v_add_f32_dpp v86, v86, v86 row_mirror row_mask:0xf bank_mask:0xf
	s_nop 1
	v_add_f32_dpp v86, v86, v86 row_bcast:15 row_mask:0xa bank_mask:0xf
	s_waitcnt lgkmcnt(0)
	s_waitcnt lgkmcnt(0)
	s_waitcnt lgkmcnt(0)
	s_waitcnt lgkmcnt(0)
	s_and_saveexec_b64 s[18:19], s[98:99]
	s_cbranch_execz .LBB0_542
	v_lshl_add_u64 v[14:15], v[20:21], 4, s[78:79]
	v_lshl_add_u64 v[14:15], s[6:7], 2, v[14:15]
	s_waitcnt lgkmcnt(0)
	v_mov_b32_e32 v12, v86
	flat_store_dword v[14:15], v12
; DI unsigned pk2(float a, float b) { f32x2 v = {a, b}; bf16x2_t r = __builtin_convertvector(v, bf16x2_t); return __builtin_bit_cast(unsigned, r); }
; DI float bflo(unsigned w) { return __uint_as_float(w << 16); }
; DI float bfhi(unsigned w) { return __uint_as_float(w & 0xffff0000u); }
;     DI void operator()(gacc_t& acc, int pm, int pn, char* lds, int tid, int wr, int wc, int lane) const {
;     ...
;         const int g = lane >> 5, j32 = lane & 31;
; #pragma unroll
;         for (int ib = 0; ib < 4; ++ib) {
;             __builtin_amdgcn_sched_barrier(0);
;             u32x4 xv[4];
; #pragma unroll
;             for (int u = 0; u < 4; ++u) {
;                 const long row = (long)pm * 256 + (ib * 4 + u) * 16 + wid * 2 + g;
;                 xv[u] = *(const u32x4*)(xold + row * 1024 + pn * 256 + j32 * 8);
;             }
; #pragma unroll
;             for (int u = 0; u < 4; ++u) {
;                 const int rloc = (ib * 4 + u) * 16 + wid * 2 + g;
;                 const long row = (long)pm * 256 + rloc;
;                 const u32x4 a = *(const u32x4*)(lds + rloc * 528 + j32 * 16);
;                 u32x4 w; float ss = 0.f;
; #pragma unroll
;                 for (int e = 0; e < 4; ++e) {
;                     w[e] = pk2(bflo(xv[u][e]) + bflo(a[e]), bfhi(xv[u][e]) + bfhi(a[e]));
;                     const float b0 = bflo(w[e]), b1 = bfhi(w[e]);
;                     ss += b0 * b0 + b1 * b1;
;                 }
;                 *(u32x4*)(xnew + row * 1024 + pn * 256 + j32 * 8) = w;
; #pragma unroll
;                 for (int o = 1; o < 32; o <<= 1) ss += __shfl_xor(ss, o);
;                 if (j32 == 0) ssq[row * 4 + pn] = ss;
;             }
.LBB0_542:
	s_or_b64 exec, exec, s[18:19]
	s_waitcnt lgkmcnt(0)
	ds_read_b128 v[12:15], v26 offset:8448
	v_lshlrev_b32_e32 v20, 16, v8
	v_and_b32_e32 v21, 0xffff0000, v8
	s_waitcnt lgkmcnt(0)
	v_lshlrev_b32_e32 v28, 16, v12
	v_and_b32_e32 v29, 0xffff0000, v12
	v_pk_add_f32 v[20:21], v[20:21], v[28:29]
	s_nop 0
	v_cvt_pk_bf16_f32 v12, v20, v21
	v_and_b32_e32 v20, 0xffff0000, v12
	v_lshlrev_b32_e32 v8, 16, v12
	v_mul_f32_e32 v27, v20, v20
	v_fmac_f32_e32 v27, v8, v8
	v_lshlrev_b32_e32 v8, 16, v9
	v_and_b32_e32 v9, 0xffff0000, v9
	v_lshlrev_b32_e32 v20, 16, v13
	v_and_b32_e32 v21, 0xffff0000, v13
	v_pk_add_f32 v[8:9], v[8:9], v[20:21]
	v_lshlrev_b32_e32 v20, 16, v14
	v_cvt_pk_bf16_f32 v13, v8, v9
	v_and_b32_e32 v9, 0xffff0000, v13
	v_lshlrev_b32_e32 v8, 16, v13
	v_mul_f32_e32 v9, v9, v9
	v_fmac_f32_e32 v9, v8, v8
	v_add_f32_e32 v27, v27, v9
	v_lshlrev_b32_e32 v8, 16, v10
	v_and_b32_e32 v9, 0xffff0000, v10
	v_and_b32_e32 v21, 0xffff0000, v14
	v_pk_add_f32 v[8:9], v[8:9], v[20:21]
	v_lshlrev_b32_e32 v10, 16, v15
	v_cvt_pk_bf16_f32 v14, v8, v9
	v_and_b32_e32 v9, 0xffff0000, v14
	v_lshlrev_b32_e32 v8, 16, v14
	v_mul_f32_e32 v9, v9, v9
	v_fmac_f32_e32 v9, v8, v8
	v_add_f32_e32 v20, v9, v27
	v_lshlrev_b32_e32 v8, 16, v11
	v_and_b32_e32 v9, 0xffff0000, v11
	v_and_b32_e32 v11, 0xffff0000, v15
	v_pk_add_f32 v[8:9], v[8:9], v[10:11]
	s_nop 0
	v_cvt_pk_bf16_f32 v15, v8, v9
	v_and_b32_e32 v9, 0xffff0000, v15
	v_lshlrev_b32_e32 v8, 16, v15
	v_mul_f32_e32 v9, v9, v9
	v_fmac_f32_e32 v9, v8, v8
	v_add_f32_e32 v8, v9, v20
	s_nop 1
	v_add_f32_dpp v86, v8, v8 quad_perm:[1,0,3,2] row_mask:0xf bank_mask:0xf
	s_nop 1
	v_add_f32_dpp v86, v86, v86 quad_perm:[2,3,0,1] row_mask:0xf bank_mask:0xf
	s_nop 1
	v_add_f32_dpp v86, v86, v86 row_half_mirror row_mask:0xf bank_mask:0xf
	s_nop 1
	v_add_f32_dpp v86, v86, v86 row_mirror row_mask:0xf bank_mask:0xf
	s_nop 1
	v_add_f32_dpp v86, v86, v86 row_bcast:15 row_mask:0xa bank_mask:0xf
	s_waitcnt lgkmcnt(0)
	s_waitcnt lgkmcnt(0)
	s_waitcnt lgkmcnt(0)
	v_add_u32_e32 v8, 0x90, v16
	v_ashrrev_i32_e32 v9, 31, v8
	v_lshl_add_u64 v[8:9], s[12:13], 0, v[8:9]
	v_lshlrev_b64 v[20:21], 11, v[8:9]
	s_waitcnt lgkmcnt(0)
	v_lshl_add_u64 v[20:21], s[68:69], 0, v[20:21]
	v_lshl_add_u64 v[20:21], s[16:17], 1, v[20:21]
	v_lshl_add_u64 v[20:21], v[20:21], 0, v[146:147]
	flat_store_dwordx4 v[20:21], v[12:15]
	s_and_saveexec_b64 s[18:19], s[98:99]
	s_cbranch_execz .LBB0_544
	v_lshl_add_u64 v[8:9], v[8:9], 4, s[78:79]
	v_lshl_add_u64 v[8:9], s[6:7], 2, v[8:9]
	s_waitcnt lgkmcnt(0)
	v_mov_b32_e32 v10, v86
	flat_store_dword v[8:9], v10
.LBB0_544:
	s_or_b64 exec, exec, s[18:19]
	s_waitcnt lgkmcnt(0)
	ds_read_b128 v[8:11], v26 offset:16896
	v_lshlrev_b32_e32 v12, 16, v4
	v_and_b32_e32 v13, 0xffff0000, v4
	s_waitcnt lgkmcnt(0)
	v_lshlrev_b32_e32 v14, 16, v8
	v_and_b32_e32 v15, 0xffff0000, v8
	v_pk_add_f32 v[12:13], v[12:13], v[14:15]
	s_nop 0
	v_cvt_pk_bf16_f32 v8, v12, v13
	v_and_b32_e32 v12, 0xffff0000, v8
	v_lshlrev_b32_e32 v4, 16, v8
	v_mul_f32_e32 v14, v12, v12
	v_fmac_f32_e32 v14, v4, v4
	v_lshlrev_b32_e32 v4, 16, v5
	v_and_b32_e32 v5, 0xffff0000, v5
	v_lshlrev_b32_e32 v12, 16, v9
	v_and_b32_e32 v13, 0xffff0000, v9
	v_pk_add_f32 v[4:5], v[4:5], v[12:13]
	v_lshlrev_b32_e32 v12, 16, v10
	v_cvt_pk_bf16_f32 v9, v4, v5
	v_and_b32_e32 v5, 0xffff0000, v9
	v_lshlrev_b32_e32 v4, 16, v9
	v_mul_f32_e32 v5, v5, v5
	v_fmac_f32_e32 v5, v4, v4
	v_add_f32_e32 v14, v14, v5
	v_lshlrev_b32_e32 v4, 16, v6
	v_and_b32_e32 v5, 0xffff0000, v6
	v_and_b32_e32 v13, 0xffff0000, v10
	v_pk_add_f32 v[4:5], v[4:5], v[12:13]
	v_lshlrev_b32_e32 v6, 16, v11
	v_cvt_pk_bf16_f32 v10, v4, v5
	v_and_b32_e32 v5, 0xffff0000, v10
	v_lshlrev_b32_e32 v4, 16, v10
	v_mul_f32_e32 v5, v5, v5
	v_fmac_f32_e32 v5, v4, v4
	v_add_f32_e32 v12, v5, v14
	v_lshlrev_b32_e32 v4, 16, v7
	v_and_b32_e32 v5, 0xffff0000, v7
	v_and_b32_e32 v7, 0xffff0000, v11
	v_pk_add_f32 v[4:5], v[4:5], v[6:7]
	s_nop 0
	v_cvt_pk_bf16_f32 v11, v4, v5
	v_and_b32_e32 v5, 0xffff0000, v11
	v_lshlrev_b32_e32 v4, 16, v11
	v_mul_f32_e32 v5, v5, v5
	v_fmac_f32_e32 v5, v4, v4
	v_add_f32_e32 v4, v5, v12
	s_nop 1
	v_add_f32_dpp v86, v4, v4 quad_perm:[1,0,3,2] row_mask:0xf bank_mask:0xf
	s_nop 1
	v_add_f32_dpp v86, v86, v86 quad_perm:[2,3,0,1] row_mask:0xf bank_mask:0xf
	s_nop 1
	v_add_f32_dpp v86, v86, v86 row_half_mirror row_mask:0xf bank_mask:0xf
	s_nop 1
	v_add_f32_dpp v86, v86, v86 row_mirror row_mask:0xf bank_mask:0xf
	s_nop 1
	v_add_f32_dpp v86, v86, v86 row_bcast:15 row_mask:0xa bank_mask:0xf
	s_waitcnt lgkmcnt(0)
	s_waitcnt lgkmcnt(0)
	s_waitcnt lgkmcnt(0)
	v_add_u32_e32 v4, 0xa0, v16
	v_ashrrev_i32_e32 v5, 31, v4
	v_lshl_add_u64 v[4:5], s[12:13], 0, v[4:5]
	v_lshlrev_b64 v[12:13], 11, v[4:5]
	s_waitcnt lgkmcnt(0)
	v_lshl_add_u64 v[12:13], s[68:69], 0, v[12:13]
	v_lshl_add_u64 v[12:13], s[16:17], 1, v[12:13]
	v_lshl_add_u64 v[12:13], v[12:13], 0, v[146:147]
	flat_store_dwordx4 v[12:13], v[8:11]
	s_and_saveexec_b64 s[18:19], s[98:99]
	s_cbranch_execz .LBB0_546
	v_lshl_add_u64 v[4:5], v[4:5], 4, s[78:79]
	v_lshl_add_u64 v[4:5], s[6:7], 2, v[4:5]
	s_waitcnt lgkmcnt(0)
	v_mov_b32_e32 v6, v86
	flat_store_dword v[4:5], v6
; DI unsigned pk2(float a, float b) { f32x2 v = {a, b}; bf16x2_t r = __builtin_convertvector(v, bf16x2_t); return __builtin_bit_cast(unsigned, r); }
; DI float bflo(unsigned w) { return __uint_as_float(w << 16); }
; DI float bfhi(unsigned w) { return __uint_as_float(w & 0xffff0000u); }
;     DI void operator()(gacc_t& acc, int pm, int pn, char* lds, int tid, int wr, int wc, int lane) const {
;     ...
;         for (int ib = 0; ib < 4; ++ib) {
;             __builtin_amdgcn_sched_barrier(0);
;             u32x4 xv[4];
; #pragma unroll
;             for (int u = 0; u < 4; ++u) {
;                 const long row = (long)pm * 256 + (ib * 4 + u) * 16 + wid * 2 + g;
;                 xv[u] = *(const u32x4*)(xold + row * 1024 + pn * 256 + j32 * 8);
;             }
; #pragma unroll
;             for (int u = 0; u < 4; ++u) {
;                 const int rloc = (ib * 4 + u) * 16 + wid * 2 + g;
;                 const long row = (long)pm * 256 + rloc;
;                 const u32x4 a = *(const u32x4*)(lds + rloc * 528 + j32 * 16);
;                 u32x4 w; float ss = 0.f;
; #pragma unroll
;                 for (int e = 0; e < 4; ++e) {
;                     w[e] = pk2(bflo(xv[u][e]) + bflo(a[e]), bfhi(xv[u][e]) + bfhi(a[e]));
;                     const float b0 = bflo(w[e]), b1 = bfhi(w[e]);
;                     ss += b0 * b0 + b1 * b1;
;                 }
;                 *(u32x4*)(xnew + row * 1024 + pn * 256 + j32 * 8) = w;
; #pragma unroll
;                 for (int o = 1; o < 32; o <<= 1) ss += __shfl_xor(ss, o);
;                 if (j32 == 0) ssq[row * 4 + pn] = ss;
;             }
.LBB0_546:
	s_or_b64 exec, exec, s[18:19]
	s_waitcnt lgkmcnt(0)
	ds_read_b128 v[4:7], v26 offset:25344
	v_lshlrev_b32_e32 v8, 16, v0
	v_and_b32_e32 v9, 0xffff0000, v0
	s_waitcnt lgkmcnt(0)
	v_lshlrev_b32_e32 v10, 16, v4
	v_and_b32_e32 v11, 0xffff0000, v4
	v_pk_add_f32 v[8:9], v[8:9], v[10:11]
	s_nop 0
	v_cvt_pk_bf16_f32 v4, v8, v9
	v_and_b32_e32 v8, 0xffff0000, v4
	v_lshlrev_b32_e32 v0, 16, v4
	v_mul_f32_e32 v10, v8, v8
	v_fmac_f32_e32 v10, v0, v0
	v_lshlrev_b32_e32 v0, 16, v1
	v_and_b32_e32 v1, 0xffff0000, v1
	v_lshlrev_b32_e32 v8, 16, v5
	v_and_b32_e32 v9, 0xffff0000, v5
	v_pk_add_f32 v[0:1], v[0:1], v[8:9]
	v_lshlrev_b32_e32 v8, 16, v6
	v_cvt_pk_bf16_f32 v5, v0, v1
	v_and_b32_e32 v1, 0xffff0000, v5
	v_lshlrev_b32_e32 v0, 16, v5
	v_mul_f32_e32 v1, v1, v1
	v_fmac_f32_e32 v1, v0, v0
	v_add_f32_e32 v10, v10, v1
	v_lshlrev_b32_e32 v0, 16, v2
	v_and_b32_e32 v1, 0xffff0000, v2
	v_and_b32_e32 v9, 0xffff0000, v6
	v_pk_add_f32 v[0:1], v[0:1], v[8:9]
	v_lshlrev_b32_e32 v2, 16, v7
	v_cvt_pk_bf16_f32 v6, v0, v1
	v_and_b32_e32 v1, 0xffff0000, v6
	v_lshlrev_b32_e32 v0, 16, v6
	v_mul_f32_e32 v1, v1, v1
	v_fmac_f32_e32 v1, v0, v0
	v_add_f32_e32 v8, v1, v10
	v_lshlrev_b32_e32 v0, 16, v3
	v_and_b32_e32 v1, 0xffff0000, v3
	v_and_b32_e32 v3, 0xffff0000, v7
	v_pk_add_f32 v[0:1], v[0:1], v[2:3]
	s_nop 0
	v_cvt_pk_bf16_f32 v7, v0, v1
	v_and_b32_e32 v1, 0xffff0000, v7
	v_lshlrev_b32_e32 v0, 16, v7
	v_mul_f32_e32 v1, v1, v1
	v_fmac_f32_e32 v1, v0, v0
	v_add_f32_e32 v0, v1, v8
	s_nop 1
	v_add_f32_dpp v86, v0, v0 quad_perm:[1,0,3,2] row_mask:0xf bank_mask:0xf
	s_nop 1
	v_add_f32_dpp v86, v86, v86 quad_perm:[2,3,0,1] row_mask:0xf bank_mask:0xf
	s_nop 1
	v_add_f32_dpp v86, v86, v86 row_half_mirror row_mask:0xf bank_mask:0xf
	s_nop 1
	v_add_f32_dpp v86, v86, v86 row_mirror row_mask:0xf bank_mask:0xf
	s_nop 1
	v_add_f32_dpp v86, v86, v86 row_bcast:15 row_mask:0xa bank_mask:0xf
	s_waitcnt lgkmcnt(0)
	s_waitcnt lgkmcnt(0)
	s_waitcnt lgkmcnt(0)
	v_add_u32_e32 v0, 0xb0, v16
	v_ashrrev_i32_e32 v1, 31, v0
	v_lshl_add_u64 v[0:1], s[12:13], 0, v[0:1]
	v_lshlrev_b64 v[8:9], 11, v[0:1]
	s_waitcnt lgkmcnt(0)
	v_lshl_add_u64 v[8:9], s[68:69], 0, v[8:9]
	v_lshl_add_u64 v[8:9], s[16:17], 1, v[8:9]
	v_lshl_add_u64 v[8:9], v[8:9], 0, v[146:147]
	flat_store_dwordx4 v[8:9], v[4:7]
	s_and_saveexec_b64 s[18:19], s[98:99]
	s_cbranch_execz .LBB0_548
	v_lshl_add_u64 v[0:1], v[0:1], 4, s[78:79]
	v_lshl_add_u64 v[0:1], s[6:7], 2, v[0:1]
	s_waitcnt lgkmcnt(0)
	v_mov_b32_e32 v2, v86
	flat_store_dword v[0:1], v2
.LBB0_548:
	s_or_b64 exec, exec, s[18:19]
	v_add_co_u32_e32 v0, vcc, 0x60000, v18
	ds_read_b128 v[28:31], v26 offset:33792
	s_nop 0
	v_addc_co_u32_e32 v1, vcc, 0, v19, vcc
	flat_load_dwordx4 v[12:15], v[0:1]
	v_add_co_u32_e32 v0, vcc, 0x68000, v18
	s_waitcnt lgkmcnt(0)
	v_lshlrev_b32_e32 v32, 16, v28
	v_addc_co_u32_e32 v1, vcc, 0, v19, vcc
	flat_load_dwordx4 v[8:11], v[0:1]
	v_add_co_u32_e32 v0, vcc, 0x70000, v18
	v_and_b32_e32 v33, 0xffff0000, v28
	s_nop 0
	v_addc_co_u32_e32 v1, vcc, 0, v19, vcc
	flat_load_dwordx4 v[4:7], v[0:1]
	v_add_co_u32_e32 v0, vcc, 0x78000, v18
	v_lshlrev_b32_e32 v28, 16, v29
	s_nop 0
	v_addc_co_u32_e32 v1, vcc, 0, v19, vcc
	flat_load_dwordx4 v[0:3], v[0:1]
	v_and_b32_e32 v29, 0xffff0000, v29
	v_add_u32_e32 v18, 0xc0, v16
	v_ashrrev_i32_e32 v19, 31, v18
	v_lshl_add_u64 v[18:19], s[12:13], 0, v[18:19]
	s_waitcnt vmcnt(0)
	v_lshlrev_b32_e32 v20, 16, v12
	v_and_b32_e32 v21, 0xffff0000, v12
	v_pk_add_f32 v[20:21], v[20:21], v[32:33]
	s_nop 0
	v_cvt_pk_bf16_f32 v12, v20, v21
	v_and_b32_e32 v21, 0xffff0000, v12
	v_lshlrev_b32_e32 v20, 16, v12
	v_mul_f32_e32 v27, v21, v21
	v_fmac_f32_e32 v27, v20, v20
	v_lshlrev_b32_e32 v20, 16, v13
	v_and_b32_e32 v21, 0xffff0000, v13
	v_pk_add_f32 v[20:21], v[20:21], v[28:29]
	v_lshlrev_b32_e32 v28, 16, v30
	v_cvt_pk_bf16_f32 v13, v20, v21
	v_and_b32_e32 v21, 0xffff0000, v13
	v_lshlrev_b32_e32 v20, 16, v13
	v_mul_f32_e32 v21, v21, v21
	v_fmac_f32_e32 v21, v20, v20
	v_add_f32_e32 v27, v27, v21
	v_lshlrev_b32_e32 v20, 16, v14
	v_and_b32_e32 v21, 0xffff0000, v14
	v_and_b32_e32 v29, 0xffff0000, v30
	v_pk_add_f32 v[20:21], v[20:21], v[28:29]
	v_lshlrev_b32_e32 v28, 16, v31
	v_cvt_pk_bf16_f32 v14, v20, v21
	v_and_b32_e32 v21, 0xffff0000, v14
	v_lshlrev_b32_e32 v20, 16, v14
	v_mul_f32_e32 v21, v21, v21
	v_fmac_f32_e32 v21, v20, v20
	v_add_f32_e32 v27, v21, v27
	v_lshlrev_b32_e32 v20, 16, v15
	v_and_b32_e32 v21, 0xffff0000, v15
	v_and_b32_e32 v29, 0xffff0000, v31
	v_pk_add_f32 v[20:21], v[20:21], v[28:29]
	s_nop 0
	v_cvt_pk_bf16_f32 v15, v20, v21
	v_and_b32_e32 v21, 0xffff0000, v15
	v_lshlrev_b32_e32 v20, 16, v15
	v_mul_f32_e32 v21, v21, v21
	v_fmac_f32_e32 v21, v20, v20
	v_add_f32_e32 v27, v21, v27
	v_lshlrev_b64 v[20:21], 11, v[18:19]
	v_lshl_add_u64 v[20:21], s[68:69], 0, v[20:21]
	v_lshl_add_u64 v[20:21], s[16:17], 1, v[20:21]
	v_lshl_add_u64 v[20:21], v[20:21], 0, v[146:147]
	flat_store_dwordx4 v[20:21], v[12:15]
	s_nop 1
	v_add_f32_dpp v86, v27, v27 quad_perm:[1,0,3,2] row_mask:0xf bank_mask:0xf
	s_nop 1
	v_add_f32_dpp v86, v86, v86 quad_perm:[2,3,0,1] row_mask:0xf bank_mask:0xf
	s_nop 1
	v_add_f32_dpp v86, v86, v86 row_half_mirror row_mask:0xf bank_mask:0xf
	s_nop 1
	v_add_f32_dpp v86, v86, v86 row_mirror row_mask:0xf bank_mask:0xf
	s_nop 1
	v_add_f32_dpp v86, v86, v86 row_bcast:15 row_mask:0xa bank_mask:0xf
	s_waitcnt lgkmcnt(0)
	s_waitcnt lgkmcnt(0)
	s_waitcnt lgkmcnt(0)
	s_waitcnt lgkmcnt(0)
	s_and_saveexec_b64 s[18:19], s[98:99]
	s_cbranch_execz .LBB0_550
	v_lshl_add_u64 v[14:15], v[18:19], 4, s[78:79]
	v_lshl_add_u64 v[14:15], s[6:7], 2, v[14:15]
	s_waitcnt lgkmcnt(0)
	v_mov_b32_e32 v12, v86
	flat_store_dword v[14:15], v12
; DI unsigned pk2(float a, float b) { f32x2 v = {a, b}; bf16x2_t r = __builtin_convertvector(v, bf16x2_t); return __builtin_bit_cast(unsigned, r); }
; DI float bflo(unsigned w) { return __uint_as_float(w << 16); }
; DI float bfhi(unsigned w) { return __uint_as_float(w & 0xffff0000u); }
;     DI void operator()(gacc_t& acc, int pm, int pn, char* lds, int tid, int wr, int wc, int lane) const {
;     ...
;             for (int u = 0; u < 4; ++u) {
;                 const int rloc = (ib * 4 + u) * 16 + wid * 2 + g;
;                 const long row = (long)pm * 256 + rloc;
;                 const u32x4 a = *(const u32x4*)(lds + rloc * 528 + j32 * 16);
;                 u32x4 w; float ss = 0.f;
; #pragma unroll
;                 for (int e = 0; e < 4; ++e) {
;                     w[e] = pk2(bflo(xv[u][e]) + bflo(a[e]), bfhi(xv[u][e]) + bfhi(a[e]));
;                     const float b0 = bflo(w[e]), b1 = bfhi(w[e]);
;                     ss += b0 * b0 + b1 * b1;
;                 }
;                 *(u32x4*)(xnew + row * 1024 + pn * 256 + j32 * 8) = w;
; #pragma unroll
;                 for (int o = 1; o < 32; o <<= 1) ss += __shfl_xor(ss, o);
;                 if (j32 == 0) ssq[row * 4 + pn] = ss;
;             }
.LBB0_550:
	s_or_b64 exec, exec, s[18:19]
	s_waitcnt lgkmcnt(0)
	ds_read_b128 v[12:15], v26 offset:42240
	v_lshlrev_b32_e32 v18, 16, v8
	v_and_b32_e32 v19, 0xffff0000, v8
	s_waitcnt lgkmcnt(0)
	v_lshlrev_b32_e32 v20, 16, v12
	v_and_b32_e32 v21, 0xffff0000, v12
	v_pk_add_f32 v[18:19], v[18:19], v[20:21]
	s_nop 0
	v_cvt_pk_bf16_f32 v12, v18, v19
	v_and_b32_e32 v18, 0xffff0000, v12
	v_lshlrev_b32_e32 v8, 16, v12
	v_mul_f32_e32 v20, v18, v18
	v_fmac_f32_e32 v20, v8, v8
	v_lshlrev_b32_e32 v8, 16, v9
	v_and_b32_e32 v9, 0xffff0000, v9
	v_lshlrev_b32_e32 v18, 16, v13
	v_and_b32_e32 v19, 0xffff0000, v13
	v_pk_add_f32 v[8:9], v[8:9], v[18:19]
	v_lshlrev_b32_e32 v18, 16, v14
	v_cvt_pk_bf16_f32 v13, v8, v9
	v_and_b32_e32 v9, 0xffff0000, v13
	v_lshlrev_b32_e32 v8, 16, v13
	v_mul_f32_e32 v9, v9, v9
	v_fmac_f32_e32 v9, v8, v8
	v_add_f32_e32 v20, v20, v9
	v_lshlrev_b32_e32 v8, 16, v10
	v_and_b32_e32 v9, 0xffff0000, v10
	v_and_b32_e32 v19, 0xffff0000, v14
	v_pk_add_f32 v[8:9], v[8:9], v[18:19]
	v_lshlrev_b32_e32 v10, 16, v15
	v_cvt_pk_bf16_f32 v14, v8, v9
	v_and_b32_e32 v9, 0xffff0000, v14
	v_lshlrev_b32_e32 v8, 16, v14
	v_mul_f32_e32 v9, v9, v9
	v_fmac_f32_e32 v9, v8, v8
	v_add_f32_e32 v18, v9, v20
	v_lshlrev_b32_e32 v8, 16, v11
	v_and_b32_e32 v9, 0xffff0000, v11
	v_and_b32_e32 v11, 0xffff0000, v15
	v_pk_add_f32 v[8:9], v[8:9], v[10:11]
	s_nop 0
	v_cvt_pk_bf16_f32 v15, v8, v9
	v_and_b32_e32 v9, 0xffff0000, v15
	v_lshlrev_b32_e32 v8, 16, v15
	v_mul_f32_e32 v9, v9, v9
	v_fmac_f32_e32 v9, v8, v8
	v_add_f32_e32 v8, v9, v18
	s_nop 1
	v_add_f32_dpp v86, v8, v8 quad_perm:[1,0,3,2] row_mask:0xf bank_mask:0xf
	s_nop 1
	v_add_f32_dpp v86, v86, v86 quad_perm:[2,3,0,1] row_mask:0xf bank_mask:0xf
	s_nop 1
	v_add_f32_dpp v86, v86, v86 row_half_mirror row_mask:0xf bank_mask:0xf
	s_nop 1
	v_add_f32_dpp v86, v86, v86 row_mirror row_mask:0xf bank_mask:0xf
	s_nop 1
	v_add_f32_dpp v86, v86, v86 row_bcast:15 row_mask:0xa bank_mask:0xf
	s_waitcnt lgkmcnt(0)
	s_waitcnt lgkmcnt(0)
	s_waitcnt lgkmcnt(0)
	v_add_u32_e32 v8, 0xd0, v16
	v_ashrrev_i32_e32 v9, 31, v8
	v_lshl_add_u64 v[8:9], s[12:13], 0, v[8:9]
	v_lshlrev_b64 v[18:19], 11, v[8:9]
	s_waitcnt lgkmcnt(0)
	v_lshl_add_u64 v[18:19], s[68:69], 0, v[18:19]
	v_lshl_add_u64 v[18:19], s[16:17], 1, v[18:19]
	v_lshl_add_u64 v[18:19], v[18:19], 0, v[146:147]
	flat_store_dwordx4 v[18:19], v[12:15]
	s_and_saveexec_b64 s[18:19], s[98:99]
	s_cbranch_execz .LBB0_552
	v_lshl_add_u64 v[8:9], v[8:9], 4, s[78:79]
	v_lshl_add_u64 v[8:9], s[6:7], 2, v[8:9]
	s_waitcnt lgkmcnt(0)
	v_mov_b32_e32 v10, v86
	flat_store_dword v[8:9], v10
; DI unsigned pk2(float a, float b) { f32x2 v = {a, b}; bf16x2_t r = __builtin_convertvector(v, bf16x2_t); return __builtin_bit_cast(unsigned, r); }
; DI float bflo(unsigned w) { return __uint_as_float(w << 16); }
; DI float bfhi(unsigned w) { return __uint_as_float(w & 0xffff0000u); }
;     DI void operator()(gacc_t& acc, int pm, int pn, char* lds, int tid, int wr, int wc, int lane) const {
;     ...
;             for (int u = 0; u < 4; ++u) {
;                 const int rloc = (ib * 4 + u) * 16 + wid * 2 + g;
;                 const long row = (long)pm * 256 + rloc;
;                 const u32x4 a = *(const u32x4*)(lds + rloc * 528 + j32 * 16);
;                 u32x4 w; float ss = 0.f;
; #pragma unroll
;                 for (int e = 0; e < 4; ++e) {
;                     w[e] = pk2(bflo(xv[u][e]) + bflo(a[e]), bfhi(xv[u][e]) + bfhi(a[e]));
;                     const float b0 = bflo(w[e]), b1 = bfhi(w[e]);
;                     ss += b0 * b0 + b1 * b1;
;                 }
;                 *(u32x4*)(xnew + row * 1024 + pn * 256 + j32 * 8) = w;
; #pragma unroll
;                 for (int o = 1; o < 32; o <<= 1) ss += __shfl_xor(ss, o);
;                 if (j32 == 0) ssq[row * 4 + pn] = ss;
;             }
;         }
;         __syncthreads();
.LBB0_552:
	s_or_b64 exec, exec, s[18:19]
	s_waitcnt lgkmcnt(0)
	ds_read_b128 v[8:11], v26 offset:50688
	v_lshlrev_b32_e32 v12, 16, v4
	v_and_b32_e32 v13, 0xffff0000, v4
	s_waitcnt lgkmcnt(0)
	v_lshlrev_b32_e32 v14, 16, v8
	v_and_b32_e32 v15, 0xffff0000, v8
	v_pk_add_f32 v[12:13], v[12:13], v[14:15]
	s_nop 0
	v_cvt_pk_bf16_f32 v8, v12, v13
	v_and_b32_e32 v12, 0xffff0000, v8
	v_lshlrev_b32_e32 v4, 16, v8
	v_mul_f32_e32 v14, v12, v12
	v_fmac_f32_e32 v14, v4, v4
	v_lshlrev_b32_e32 v4, 16, v5
	v_and_b32_e32 v5, 0xffff0000, v5
	v_lshlrev_b32_e32 v12, 16, v9
	v_and_b32_e32 v13, 0xffff0000, v9
	v_pk_add_f32 v[4:5], v[4:5], v[12:13]
	v_lshlrev_b32_e32 v12, 16, v10
	v_cvt_pk_bf16_f32 v9, v4, v5
	v_and_b32_e32 v5, 0xffff0000, v9
	v_lshlrev_b32_e32 v4, 16, v9
	v_mul_f32_e32 v5, v5, v5
	v_fmac_f32_e32 v5, v4, v4
	v_add_f32_e32 v14, v14, v5
	v_lshlrev_b32_e32 v4, 16, v6
	v_and_b32_e32 v5, 0xffff0000, v6
	v_and_b32_e32 v13, 0xffff0000, v10
	v_pk_add_f32 v[4:5], v[4:5], v[12:13]
	v_lshlrev_b32_e32 v6, 16, v11
	v_cvt_pk_bf16_f32 v10, v4, v5
	v_and_b32_e32 v5, 0xffff0000, v10
	v_lshlrev_b32_e32 v4, 16, v10
	v_mul_f32_e32 v5, v5, v5
	v_fmac_f32_e32 v5, v4, v4
	v_add_f32_e32 v12, v5, v14
	v_lshlrev_b32_e32 v4, 16, v7
	v_and_b32_e32 v5, 0xffff0000, v7
	v_and_b32_e32 v7, 0xffff0000, v11
	v_pk_add_f32 v[4:5], v[4:5], v[6:7]
	s_nop 0
	v_cvt_pk_bf16_f32 v11, v4, v5
	v_and_b32_e32 v5, 0xffff0000, v11
	v_lshlrev_b32_e32 v4, 16, v11
	v_mul_f32_e32 v5, v5, v5
	v_fmac_f32_e32 v5, v4, v4
	v_add_f32_e32 v4, v5, v12
	s_nop 1
	v_add_f32_dpp v86, v4, v4 quad_perm:[1,0,3,2] row_mask:0xf bank_mask:0xf
	s_nop 1
	v_add_f32_dpp v86, v86, v86 quad_perm:[2,3,0,1] row_mask:0xf bank_mask:0xf
	s_nop 1
	v_add_f32_dpp v86, v86, v86 row_half_mirror row_mask:0xf bank_mask:0xf
	s_nop 1
	v_add_f32_dpp v86, v86, v86 row_mirror row_mask:0xf bank_mask:0xf
	s_nop 1
	v_add_f32_dpp v86, v86, v86 row_bcast:15 row_mask:0xa bank_mask:0xf
	s_waitcnt lgkmcnt(0)
	s_waitcnt lgkmcnt(0)
	s_waitcnt lgkmcnt(0)
	v_add_u32_e32 v4, 0xe0, v16
	v_ashrrev_i32_e32 v5, 31, v4
	v_lshl_add_u64 v[4:5], s[12:13], 0, v[4:5]
	v_lshlrev_b64 v[12:13], 11, v[4:5]
	s_waitcnt lgkmcnt(0)
	v_lshl_add_u64 v[12:13], s[68:69], 0, v[12:13]
	v_lshl_add_u64 v[12:13], s[16:17], 1, v[12:13]
	v_lshl_add_u64 v[12:13], v[12:13], 0, v[146:147]
	flat_store_dwordx4 v[12:13], v[8:11]
	s_and_saveexec_b64 s[18:19], s[98:99]
	s_cbranch_execz .LBB0_554
	v_lshl_add_u64 v[4:5], v[4:5], 4, s[78:79]
	v_lshl_add_u64 v[4:5], s[6:7], 2, v[4:5]
	s_waitcnt lgkmcnt(0)
	v_mov_b32_e32 v6, v86
	flat_store_dword v[4:5], v6
.LBB0_554:
	s_or_b64 exec, exec, s[18:19]
	s_waitcnt lgkmcnt(0)
	ds_read_b128 v[4:7], v26 offset:59136
	v_lshlrev_b32_e32 v10, 16, v0
	v_and_b32_e32 v11, 0xffff0000, v0
	v_add_u32_e32 v8, 0xf0, v16
	v_ashrrev_i32_e32 v9, 31, v8
	s_waitcnt lgkmcnt(0)
	v_lshlrev_b32_e32 v12, 16, v4
	v_and_b32_e32 v13, 0xffff0000, v4
	v_pk_add_f32 v[10:11], v[10:11], v[12:13]
	s_nop 0
	v_cvt_pk_bf16_f32 v4, v10, v11
	v_and_b32_e32 v10, 0xffff0000, v4
	v_lshlrev_b32_e32 v0, 16, v4
	v_mul_f32_e32 v12, v10, v10
	v_fmac_f32_e32 v12, v0, v0
	v_lshlrev_b32_e32 v0, 16, v1
	v_and_b32_e32 v1, 0xffff0000, v1
	v_lshlrev_b32_e32 v10, 16, v5
	v_and_b32_e32 v11, 0xffff0000, v5
	v_pk_add_f32 v[0:1], v[0:1], v[10:11]
	v_lshlrev_b32_e32 v10, 16, v6
	v_cvt_pk_bf16_f32 v5, v0, v1
	v_and_b32_e32 v1, 0xffff0000, v5
	v_lshlrev_b32_e32 v0, 16, v5
	v_mul_f32_e32 v1, v1, v1
	v_fmac_f32_e32 v1, v0, v0
	v_add_f32_e32 v12, v12, v1
	v_lshlrev_b32_e32 v0, 16, v2
	v_and_b32_e32 v1, 0xffff0000, v2
	v_and_b32_e32 v11, 0xffff0000, v6
	v_pk_add_f32 v[0:1], v[0:1], v[10:11]
	v_lshlrev_b32_e32 v2, 16, v7
	v_cvt_pk_bf16_f32 v6, v0, v1
	v_and_b32_e32 v1, 0xffff0000, v6
	v_lshlrev_b32_e32 v0, 16, v6
	v_mul_f32_e32 v1, v1, v1
	v_fmac_f32_e32 v1, v0, v0
	v_add_f32_e32 v10, v1, v12
	v_lshlrev_b32_e32 v0, 16, v3
	v_and_b32_e32 v1, 0xffff0000, v3
	v_and_b32_e32 v3, 0xffff0000, v7
	v_pk_add_f32 v[0:1], v[0:1], v[2:3]
	s_nop 0
	v_cvt_pk_bf16_f32 v7, v0, v1
	v_and_b32_e32 v1, 0xffff0000, v7
	v_lshlrev_b32_e32 v0, 16, v7
	v_mul_f32_e32 v1, v1, v1
	v_fmac_f32_e32 v1, v0, v0
	v_add_f32_e32 v10, v1, v10
	v_lshl_add_u64 v[0:1], s[12:13], 0, v[8:9]
	v_lshlrev_b64 v[2:3], 11, v[0:1]
	v_lshl_add_u64 v[2:3], s[68:69], 0, v[2:3]
	v_lshl_add_u64 v[2:3], s[16:17], 1, v[2:3]
	v_lshl_add_u64 v[2:3], v[2:3], 0, v[146:147]
	flat_store_dwordx4 v[2:3], v[4:7]
	s_nop 1
	v_add_f32_dpp v86, v10, v10 quad_perm:[1,0,3,2] row_mask:0xf bank_mask:0xf
	s_nop 1
	v_add_f32_dpp v86, v86, v86 quad_perm:[2,3,0,1] row_mask:0xf bank_mask:0xf
	s_nop 1
	v_add_f32_dpp v86, v86, v86 row_half_mirror row_mask:0xf bank_mask:0xf
	s_nop 1
	v_add_f32_dpp v86, v86, v86 row_mirror row_mask:0xf bank_mask:0xf
	s_nop 1
	v_add_f32_dpp v86, v86, v86 row_bcast:15 row_mask:0xa bank_mask:0xf
	s_waitcnt lgkmcnt(0)
	s_waitcnt lgkmcnt(0)
	s_waitcnt lgkmcnt(0)
	s_waitcnt lgkmcnt(0)
	s_and_saveexec_b64 s[12:13], s[98:99]
	s_cbranch_execz .LBB0_517
	v_lshl_add_u64 v[0:1], v[0:1], 4, s[78:79]
	v_lshl_add_u64 v[0:1], s[6:7], 2, v[0:1]
	s_waitcnt lgkmcnt(0)
	v_mov_b32_e32 v2, v86
	flat_store_dword v[0:1], v2
	s_branch .LBB0_517

; #define MFMA16(a, b, c) __builtin_amdgcn_mfma_f32_16x16x32_bf16((a), (b), (c), 0, 0, 0)
; DI bf16x8 ldfrag(const char* lds, int row, int chunk) { return *(const bf16x8*)(lds + swz(row, chunk)); }
; #define GEMM_SG1() do { __builtin_amdgcn_sched_group_barrier(0x100, 1, 0); __builtin_amdgcn_sched_group_barrier(0x008, 4, 0); } while (0)
; template <bool RSTD, bool SWAP>
; DI void gemm_tile(gacc_t& acc, const bf16_t* __restrict__ A, int lda, const bf16_t* __restrict__ Bt, int ldb, int K,
;                   char* lds, int tid, int wr, int wc, int lane, const float* ssq_row) {
;     ...
;     GEMM_ISSUE(0, 0);
;     if (RSTD && tid < 256) {
;         const f32x4 q = *(const f32x4*)ssq_row;
;         ((float*)(lds + RSTD_OFF))[tid] = 1.0f / sqrtf(((q.x + q.y) + (q.z + q.w)) * (1.0f / 1024.0f) + 1e-6f);
;     }
;     asm volatile("s_waitcnt vmcnt(0)" ::: "memory");
;     __syncthreads();
;     for (int kt = 0; kt < nk; ++kt) {
;         const char* cur = lds + (kt & 1) * 65536;
;         if (kt + 1 < nk) GEMM_ISSUE(kt + 1, (kt + 1) & 1);
;         bf16x8 bfr[2][4], afr[3];
; #pragma unroll
;         for (int n = 0; n < 4; ++n) bfr[0][n] = ldfrag(cur + 32768, wc * 64 + n * 16 + fr, fq);
;         afr[0] = ldfrag(cur, wr * 128 + fr, fq);
;         afr[1] = ldfrag(cur, wr * 128 + 16 + fr, fq);
; #pragma unroll
;         for (int idx = 0; idx < 16; ++idx) {
;             const int ks = idx >> 3, m = idx & 7;
;             if (idx < 14) afr[(idx + 2) % 3] = ldfrag(cur, wr * 128 + ((idx + 2) & 7) * 16 + fr, ((idx + 2) >> 3) * 4 + fq);
;             if (ks == 0 && m >= 2 && m < 6) bfr[1][m - 2] = ldfrag(cur + 32768, wc * 64 + (m - 2) * 16 + fr, 4 + fq);
; #pragma unroll
;             for (int n = 0; n < 4; ++n) acc[m][n] = SWAP ? MFMA16(bfr[ks][n], afr[idx % 3], acc[m][n]) : MFMA16(afr[idx % 3], bfr[ks][n], acc[m][n]);
;         }
;         __builtin_amdgcn_sched_group_barrier(0x100, 6, 0);
;     ...
;         GEMM_SG1(); GEMM_SG1(); GEMM_SG2(); GEMM_SG2(); GEMM_SG2(); GEMM_SG2(); GEMM_SG1(); GEMM_SG1();
;         GEMM_SG1(); GEMM_SG1(); GEMM_SG1(); GEMM_SG1(); GEMM_SG1(); GEMM_SG1();
;         __builtin_amdgcn_sched_group_barrier(0x008, 8, 0);
;         __builtin_amdgcn_sched_barrier(0);
;         asm volatile("s_waitcnt vmcnt(0)" ::: "memory");
;         __syncthreads();
.LBB0_775:
	s_add_i32 s16, s13, 0xffff0000
	v_lshl_add_u64 v[156:157], v[138:139], 0, s[4:5]
	s_and_b32 s18, s13, 0x10000
	s_and_b32 s21, s16, 0x10000
	s_mov_b64 s[16:17], 0x10080080
	v_lshl_add_u64 v[158:159], v[136:137], 0, s[4:5]
	v_lshl_add_u64 v[160:161], v[156:157], 0, s[16:17]
	s_add_i32 s16, s18, 0
	s_mov_b64 s[18:19], 0x4880080
	v_lshl_add_u64 v[162:163], v[158:159], 0, s[18:19]
	s_mov_b64 s[18:19], 0x100d8080
	v_lshl_add_u64 v[164:165], v[156:157], 0, s[18:19]
	s_mov_b64 s[18:19], 0x48d8080
	v_lshl_add_u64 v[166:167], v[158:159], 0, s[18:19]
	s_mov_b64 s[18:19], 0x10130080
	v_lshl_add_u64 v[172:173], v[156:157], 0, s[18:19]
	s_mov_b64 s[18:19], 0x4930080
	v_lshl_add_u64 v[174:175], v[158:159], 0, s[18:19]
	s_mov_b64 s[18:19], 0x10188080
	v_lshl_add_u64 v[156:157], v[156:157], 0, s[18:19]
	s_mov_b64 s[18:19], 0x4988080
	v_lshl_add_u64 v[158:159], v[158:159], 0, s[18:19]
	s_add_i32 s18, s16, s12
	s_add_i32 s19, s18, 0x8000
	s_mov_b32 m0, s18
	s_add_i32 s17, s21, 0
	global_load_lds_dwordx4 v[160:161], off
	v_mfma_f32_16x16x32_bf16 v[60:63], v[190:193], v[236:239], v[60:63]
	s_mov_b32 m0, s19
	v_add_u32_e32 v146, s17, v142
	global_load_lds_dwordx4 v[162:163], off
	v_mfma_f32_16x16x32_bf16 v[56:59], v[194:197], v[236:239], v[56:59]
	s_add_i32 m0, s18, 0x2000
	v_add3_u32 v155, v146, v148, v149
	global_load_lds_dwordx4 v[164:165], off
	v_mfma_f32_16x16x32_bf16 v[52:55], v[198:201], v[236:239], v[52:55]
	s_add_i32 m0, s18, 0xa000
	v_add_u32_e32 v185, v146, v144
	global_load_lds_dwordx4 v[166:167], off
	v_mfma_f32_16x16x32_bf16 v[48:51], v[202:205], v[236:239], v[48:51]
	s_add_i32 m0, s18, 0x4000
	s_nop 0
	global_load_lds_dwordx4 v[172:173], off
	v_mfma_f32_16x16x32_bf16 v[44:47], v[190:193], v[240:243], v[44:47]
	s_add_i32 m0, s18, 0xc000
	s_nop 0
	global_load_lds_dwordx4 v[174:175], off
	v_mfma_f32_16x16x32_bf16 v[40:43], v[194:197], v[240:243], v[40:43]
	s_add_i32 m0, s18, 0x6000
	s_nop 0
	global_load_lds_dwordx4 v[156:157], off
	v_mfma_f32_16x16x32_bf16 v[36:39], v[198:201], v[240:243], v[36:39]
	s_add_i32 m0, s18, 0xe000
	s_nop 0
	global_load_lds_dwordx4 v[158:159], off
	v_mfma_f32_16x16x32_bf16 v[32:35], v[202:205], v[240:243], v[32:35]
	ds_read_b128 v[156:159], v155 offset:32768
	ds_read_b128 v[160:163], v155 offset:34816
	ds_read_b128 v[172:175], v155 offset:36864
	ds_read_b128 v[176:179], v155 offset:38912
	ds_read_b128 v[164:167], v185
	ds_read_b128 v[180:183], v185 offset:2048
	v_add_u32_e32 v155, v146, v150
	ds_read_b128 v[186:189], v185 offset:4096
	v_mfma_f32_16x16x32_bf16 v[28:31], v[190:193], v[244:247], v[28:31]
	v_mfma_f32_16x16x32_bf16 v[24:27], v[194:197], v[244:247], v[24:27]
	v_mfma_f32_16x16x32_bf16 v[20:23], v[198:201], v[244:247], v[20:23]
	v_mfma_f32_16x16x32_bf16 v[16:19], v[202:205], v[244:247], v[16:19]
	v_mfma_f32_16x16x32_bf16 v[12:15], v[190:193], v[248:251], v[12:15]
	v_mfma_f32_16x16x32_bf16 v[8:11], v[194:197], v[248:251], v[8:11]
	v_mfma_f32_16x16x32_bf16 v[4:7], v[198:201], v[248:251], v[4:7]
	v_mfma_f32_16x16x32_bf16 v[0:3], v[202:205], v[248:251], v[0:3]
	s_waitcnt lgkmcnt(0)
	v_mfma_f32_16x16x32_bf16 v[124:127], v[156:159], v[164:167], v[124:127]
	v_add_u32_e32 v146, v146, v152
	v_mfma_f32_16x16x32_bf16 v[120:123], v[160:163], v[164:167], v[120:123]
	v_mfma_f32_16x16x32_bf16 v[116:119], v[172:175], v[164:167], v[116:119]
	v_mfma_f32_16x16x32_bf16 v[112:115], v[176:179], v[164:167], v[112:115]
	ds_read_b128 v[164:167], v155
	v_add_u32_e32 v155, s17, v145
	v_add_u32_e32 v198, v155, v151
	v_mfma_f32_16x16x32_bf16 v[108:111], v[156:159], v[180:183], v[108:111]
	v_mfma_f32_16x16x32_bf16 v[104:107], v[160:163], v[180:183], v[104:107]
	v_mfma_f32_16x16x32_bf16 v[100:103], v[172:175], v[180:183], v[100:103]
	v_mfma_f32_16x16x32_bf16 v[96:99], v[176:179], v[180:183], v[96:99]
	ds_read_b128 v[180:183], v185 offset:8192
	ds_read_b128 v[190:193], v198 offset:32768
	v_mfma_f32_16x16x32_bf16 v[92:95], v[156:159], v[186:189], v[92:95]
	v_mfma_f32_16x16x32_bf16 v[88:91], v[160:163], v[186:189], v[88:91]
	v_mfma_f32_16x16x32_bf16 v[84:87], v[172:175], v[186:189], v[84:87]
	v_mfma_f32_16x16x32_bf16 v[80:83], v[176:179], v[186:189], v[80:83]
	ds_read_b128 v[186:189], v185 offset:10240
	ds_read_b128 v[194:197], v198 offset:34816
	s_waitcnt lgkmcnt(0)
	v_mfma_f32_16x16x32_bf16 v[76:79], v[156:159], v[164:167], v[76:79]
	v_mfma_f32_16x16x32_bf16 v[72:75], v[160:163], v[164:167], v[72:75]
	v_mfma_f32_16x16x32_bf16 v[68:71], v[172:175], v[164:167], v[68:71]
	v_mfma_f32_16x16x32_bf16 v[64:67], v[176:179], v[164:167], v[64:67]
	ds_read_b128 v[164:167], v185 offset:12288
	v_add_u32_e32 v185, v155, v153
	ds_read_b128 v[198:201], v198 offset:36864
	v_mfma_f32_16x16x32_bf16 v[60:63], v[156:159], v[180:183], v[60:63]
	v_mfma_f32_16x16x32_bf16 v[56:59], v[160:163], v[180:183], v[56:59]
	v_mfma_f32_16x16x32_bf16 v[52:55], v[172:175], v[180:183], v[52:55]
	v_mfma_f32_16x16x32_bf16 v[48:51], v[176:179], v[180:183], v[48:51]
	ds_read_b128 v[202:205], v185 offset:38912
	ds_read_b128 v[180:183], v146
	v_add_u32_e32 v146, v155, v144
	v_mfma_f32_16x16x32_bf16 v[44:47], v[156:159], v[186:189], v[44:47]
	v_mfma_f32_16x16x32_bf16 v[40:43], v[160:163], v[186:189], v[40:43]
	v_mfma_f32_16x16x32_bf16 v[36:39], v[172:175], v[186:189], v[36:39]
	v_mfma_f32_16x16x32_bf16 v[32:35], v[176:179], v[186:189], v[32:35]
	ds_read_b128 v[186:189], v146
	s_waitcnt lgkmcnt(0)
; #define MFMA16(a, b, c) __builtin_amdgcn_mfma_f32_16x16x32_bf16((a), (b), (c), 0, 0, 0)
; DI bf16x8 ldfrag(const char* lds, int row, int chunk) { return *(const bf16x8*)(lds + swz(row, chunk)); }
; #define GEMM_SG1() do { __builtin_amdgcn_sched_group_barrier(0x100, 1, 0); __builtin_amdgcn_sched_group_barrier(0x008, 4, 0); } while (0)
; #define GEMM_SG2() do { __builtin_amdgcn_sched_group_barrier(0x100, 2, 0); __builtin_amdgcn_sched_group_barrier(0x008, 4, 0); } while (0)
; template <bool RSTD, bool SWAP>
; DI void gemm_tile(gacc_t& acc, const bf16_t* __restrict__ A, int lda, const bf16_t* __restrict__ Bt, int ldb, int K,
;                   char* lds, int tid, int wr, int wc, int lane, const float* ssq_row) {
;     ...
;     for (int kt = 0; kt < nk; ++kt) {
;         const char* cur = lds + (kt & 1) * 65536;
;         if (kt + 1 < nk) GEMM_ISSUE(kt + 1, (kt + 1) & 1);
;         bf16x8 bfr[2][4], afr[3];
; #pragma unroll
;         for (int n = 0; n < 4; ++n) bfr[0][n] = ldfrag(cur + 32768, wc * 64 + n * 16 + fr, fq);
;         afr[0] = ldfrag(cur, wr * 128 + fr, fq);
;         afr[1] = ldfrag(cur, wr * 128 + 16 + fr, fq);
; #pragma unroll
;         for (int idx = 0; idx < 16; ++idx) {
;             const int ks = idx >> 3, m = idx & 7;
;             if (idx < 14) afr[(idx + 2) % 3] = ldfrag(cur, wr * 128 + ((idx + 2) & 7) * 16 + fr, ((idx + 2) >> 3) * 4 + fq);
;             if (ks == 0 && m >= 2 && m < 6) bfr[1][m - 2] = ldfrag(cur + 32768, wc * 64 + (m - 2) * 16 + fr, 4 + fq);
; #pragma unroll
;             for (int n = 0; n < 4; ++n) acc[m][n] = SWAP ? MFMA16(bfr[ks][n], afr[idx % 3], acc[m][n]) : MFMA16(afr[idx % 3], bfr[ks][n], acc[m][n]);
;         }
;         __builtin_amdgcn_sched_group_barrier(0x100, 6, 0);
;     ...
;         GEMM_SG1(); GEMM_SG1(); GEMM_SG2(); GEMM_SG2(); GEMM_SG2(); GEMM_SG2(); GEMM_SG1(); GEMM_SG1();
;         GEMM_SG1(); GEMM_SG1(); GEMM_SG1(); GEMM_SG1(); GEMM_SG1(); GEMM_SG1();
;         __builtin_amdgcn_sched_group_barrier(0x008, 8, 0);
;         __builtin_amdgcn_sched_barrier(0);
;         asm volatile("s_waitcnt vmcnt(0)" ::: "memory");
;         __syncthreads();
	v_mfma_f32_16x16x32_bf16 v[28:31], v[156:159], v[164:167], v[28:31]
	v_mfma_f32_16x16x32_bf16 v[24:27], v[160:163], v[164:167], v[24:27]
	v_mfma_f32_16x16x32_bf16 v[20:23], v[172:175], v[164:167], v[20:23]
	v_mfma_f32_16x16x32_bf16 v[16:19], v[176:179], v[164:167], v[16:19]
	ds_read_b128 v[164:167], v146 offset:2048
	v_mfma_f32_16x16x32_bf16 v[8:11], v[160:163], v[180:183], v[8:11]
	v_add_u32_e32 v160, v155, v150
	v_mfma_f32_16x16x32_bf16 v[12:15], v[156:159], v[180:183], v[12:15]
	v_mfma_f32_16x16x32_bf16 v[4:7], v[172:175], v[180:183], v[4:7]
	v_mfma_f32_16x16x32_bf16 v[0:3], v[176:179], v[180:183], v[0:3]
	ds_read_b128 v[156:159], v146 offset:4096
	v_mfma_f32_16x16x32_bf16 v[124:127], v[190:193], v[186:189], v[124:127]
	v_mfma_f32_16x16x32_bf16 v[120:123], v[194:197], v[186:189], v[120:123]
	v_mfma_f32_16x16x32_bf16 v[116:119], v[198:201], v[186:189], v[116:119]
	v_mfma_f32_16x16x32_bf16 v[112:115], v[202:205], v[186:189], v[112:115]
	ds_read_b128 v[160:163], v160
	s_waitcnt lgkmcnt(0)
	v_mfma_f32_16x16x32_bf16 v[108:111], v[190:193], v[164:167], v[108:111]
	v_mfma_f32_16x16x32_bf16 v[104:107], v[194:197], v[164:167], v[104:107]
	v_mfma_f32_16x16x32_bf16 v[100:103], v[198:201], v[164:167], v[100:103]
	v_mfma_f32_16x16x32_bf16 v[96:99], v[202:205], v[164:167], v[96:99]
	ds_read_b128 v[236:239], v146 offset:8192
	v_mfma_f32_16x16x32_bf16 v[92:95], v[190:193], v[156:159], v[92:95]
	v_mfma_f32_16x16x32_bf16 v[88:91], v[194:197], v[156:159], v[88:91]
	v_mfma_f32_16x16x32_bf16 v[84:87], v[198:201], v[156:159], v[84:87]
	v_mfma_f32_16x16x32_bf16 v[80:83], v[202:205], v[156:159], v[80:83]
	ds_read_b128 v[240:243], v146 offset:10240
	ds_read_b128 v[244:247], v146 offset:12288
	v_add_u32_e32 v146, v155, v152
	ds_read_b128 v[248:251], v146
	v_mfma_f32_16x16x32_bf16 v[76:79], v[190:193], v[160:163], v[76:79]
	v_mfma_f32_16x16x32_bf16 v[72:75], v[194:197], v[160:163], v[72:75]
	v_mfma_f32_16x16x32_bf16 v[68:71], v[198:201], v[160:163], v[68:71]
	v_mfma_f32_16x16x32_bf16 v[64:67], v[202:205], v[160:163], v[64:67]
	s_waitcnt lgkmcnt(0)
	s_waitcnt vmcnt(0)
	s_add_u32 s4, s4, 0x80
	s_addc_u32 s5, s5, 0
	s_add_i32 s13, s13, 0x10000
	s_cmpk_eq_i32 s4, 0x1580
	s_waitcnt vmcnt(0)
	s_barrier
	s_cbranch_scc0 .LBB0_775
	v_mfma_f32_16x16x32_bf16 v[60:63], v[190:193], v[236:239], v[60:63]
	v_mfma_f32_16x16x32_bf16 v[56:59], v[194:197], v[236:239], v[56:59]
	v_mfma_f32_16x16x32_bf16 v[52:55], v[198:201], v[236:239], v[52:55]
	v_mfma_f32_16x16x32_bf16 v[48:51], v[202:205], v[236:239], v[48:51]
	v_mfma_f32_16x16x32_bf16 v[44:47], v[190:193], v[240:243], v[44:47]
	v_mfma_f32_16x16x32_bf16 v[40:43], v[194:197], v[240:243], v[40:43]
	v_mfma_f32_16x16x32_bf16 v[36:39], v[198:201], v[240:243], v[36:39]
	v_mfma_f32_16x16x32_bf16 v[32:35], v[202:205], v[240:243], v[32:35]
	v_mfma_f32_16x16x32_bf16 v[28:31], v[190:193], v[244:247], v[28:31]
	v_mfma_f32_16x16x32_bf16 v[24:27], v[194:197], v[244:247], v[24:27]
	v_mfma_f32_16x16x32_bf16 v[20:23], v[198:201], v[244:247], v[20:23]
	v_mfma_f32_16x16x32_bf16 v[16:19], v[202:205], v[244:247], v[16:19]
	v_mfma_f32_16x16x32_bf16 v[12:15], v[190:193], v[248:251], v[12:15]
	v_mfma_f32_16x16x32_bf16 v[8:11], v[194:197], v[248:251], v[8:11]
	v_mfma_f32_16x16x32_bf16 v[4:7], v[198:201], v[248:251], v[4:7]
	v_mfma_f32_16x16x32_bf16 v[0:3], v[202:205], v[248:251], v[0:3]
	v_add_u32_e32 v146, s16, v142
	v_add3_u32 v155, v146, v148, v149
	ds_read_b128 v[136:139], v155 offset:32768
	ds_read_b128 v[156:159], v155 offset:34816
	ds_read_b128 v[164:167], v155 offset:36864
	ds_read_b128 v[172:175], v155 offset:38912
	v_add_u32_e32 v185, v146, v144
	ds_read_b128 v[160:163], v185
	ds_read_b128 v[176:179], v185 offset:2048
	v_add_u32_e32 v155, v146, v150
	ds_read_b128 v[180:183], v185 offset:4096
	s_waitcnt lgkmcnt(2)
	v_mfma_f32_16x16x32_bf16 v[124:127], v[136:139], v[160:163], v[124:127]
	v_add_u32_e32 v146, v146, v152
	s_lshl_b64 s[12:13], s[8:9], 8
	v_mfma_f32_16x16x32_bf16 v[120:123], v[156:159], v[160:163], v[120:123]
	v_mfma_f32_16x16x32_bf16 v[116:119], v[164:167], v[160:163], v[116:119]
	v_mfma_f32_16x16x32_bf16 v[112:115], v[172:175], v[160:163], v[112:115]
	ds_read_b128 v[160:163], v155
	v_add_u32_e32 v155, s16, v145
	v_add_u32_e32 v194, v155, v151
	s_waitcnt lgkmcnt(2)
	v_mfma_f32_16x16x32_bf16 v[108:111], v[136:139], v[176:179], v[108:111]
	v_mfma_f32_16x16x32_bf16 v[104:107], v[156:159], v[176:179], v[104:107]
	v_mfma_f32_16x16x32_bf16 v[100:103], v[164:167], v[176:179], v[100:103]
	v_mfma_f32_16x16x32_bf16 v[96:99], v[172:175], v[176:179], v[96:99]
	ds_read_b128 v[176:179], v185 offset:8192
	ds_read_b128 v[186:189], v194 offset:32768
	s_waitcnt lgkmcnt(3)
	v_mfma_f32_16x16x32_bf16 v[92:95], v[136:139], v[180:183], v[92:95]
	v_mfma_f32_16x16x32_bf16 v[88:91], v[156:159], v[180:183], v[88:91]
	v_mfma_f32_16x16x32_bf16 v[84:87], v[164:167], v[180:183], v[84:87]
	v_mfma_f32_16x16x32_bf16 v[80:83], v[172:175], v[180:183], v[80:83]
	ds_read_b128 v[180:183], v185 offset:10240
	ds_read_b128 v[190:193], v194 offset:34816
	s_waitcnt lgkmcnt(4)
	v_mfma_f32_16x16x32_bf16 v[76:79], v[136:139], v[160:163], v[76:79]
	v_mfma_f32_16x16x32_bf16 v[72:75], v[156:159], v[160:163], v[72:75]
	v_mfma_f32_16x16x32_bf16 v[68:71], v[164:167], v[160:163], v[68:71]
	v_mfma_f32_16x16x32_bf16 v[64:67], v[172:175], v[160:163], v[64:67]
	ds_read_b128 v[160:163], v185 offset:12288
	ds_read_b128 v[194:197], v194 offset:36864
	s_waitcnt lgkmcnt(5)
	v_mfma_f32_16x16x32_bf16 v[60:63], v[136:139], v[176:179], v[60:63]
	v_mfma_f32_16x16x32_bf16 v[56:59], v[156:159], v[176:179], v[56:59]
	v_mfma_f32_16x16x32_bf16 v[52:55], v[164:167], v[176:179], v[52:55]
	v_mfma_f32_16x16x32_bf16 v[48:51], v[172:175], v[176:179], v[48:51]
	ds_read_b128 v[176:179], v146
	v_add_u32_e32 v146, v155, v153
	ds_read_b128 v[198:201], v146 offset:38912
	v_add_u32_e32 v146, v155, v144
	s_waitcnt lgkmcnt(5)
; #define MFMA16(a, b, c) __builtin_amdgcn_mfma_f32_16x16x32_bf16((a), (b), (c), 0, 0, 0)
; DI unsigned pk2(float a, float b) { f32x2 v = {a, b}; bf16x2_t r = __builtin_convertvector(v, bf16x2_t); return __builtin_bit_cast(unsigned, r); }
; DI bf16x8 ldfrag(const char* lds, int row, int chunk) { return *(const bf16x8*)(lds + swz(row, chunk)); }
; template <bool RSTD, bool SWAP>
; DI void gemm_tile(gacc_t& acc, const bf16_t* __restrict__ A, int lda, const bf16_t* __restrict__ Bt, int ldb, int K,
;                   char* lds, int tid, int wr, int wc, int lane, const float* ssq_row) {
;     ...
;         for (int idx = 0; idx < 16; ++idx) {
;             const int ks = idx >> 3, m = idx & 7;
;             if (idx < 14) afr[(idx + 2) % 3] = ldfrag(cur, wr * 128 + ((idx + 2) & 7) * 16 + fr, ((idx + 2) >> 3) * 4 + fq);
;             if (ks == 0 && m >= 2 && m < 6) bfr[1][m - 2] = ldfrag(cur + 32768, wc * 64 + (m - 2) * 16 + fr, 4 + fq);
; #pragma unroll
;             for (int n = 0; n < 4; ++n) acc[m][n] = SWAP ? MFMA16(bfr[ks][n], afr[idx % 3], acc[m][n]) : MFMA16(afr[idx % 3], bfr[ks][n], acc[m][n]);
;     DI void operator()(gacc_t& acc, int pm, int pn, char* lds, int tid, int wr, int wc, int lane) const {
;     ...
; #pragma unroll
;         for (int m = 0; m < 8; ++m)
; #pragma unroll
;             for (int n = 0; n < 4; ++n) { u32x2 w; w.x = pk2(acc[m][n][0], acc[m][n][1]); w.y = pk2(acc[m][n][2], acc[m][n][3]); *(u32x2*)(lbase + m * 16 * 528 + n * 32) = w; }
	v_mfma_f32_16x16x32_bf16 v[44:47], v[136:139], v[180:183], v[44:47]
	v_mfma_f32_16x16x32_bf16 v[40:43], v[156:159], v[180:183], v[40:43]
	v_mfma_f32_16x16x32_bf16 v[36:39], v[164:167], v[180:183], v[36:39]
	v_mfma_f32_16x16x32_bf16 v[32:35], v[172:175], v[180:183], v[32:35]
	ds_read_b128 v[180:183], v146
	s_waitcnt lgkmcnt(4)
	v_mfma_f32_16x16x32_bf16 v[28:31], v[136:139], v[160:163], v[28:31]
	v_mfma_f32_16x16x32_bf16 v[24:27], v[156:159], v[160:163], v[24:27]
	v_mfma_f32_16x16x32_bf16 v[20:23], v[164:167], v[160:163], v[20:23]
	v_mfma_f32_16x16x32_bf16 v[16:19], v[172:175], v[160:163], v[16:19]
	ds_read_b128 v[160:163], v146 offset:2048
	s_waitcnt lgkmcnt(3)
	v_mfma_f32_16x16x32_bf16 v[8:11], v[156:159], v[176:179], v[8:11]
	v_add_u32_e32 v156, v155, v150
	v_mfma_f32_16x16x32_bf16 v[12:15], v[136:139], v[176:179], v[12:15]
	v_mfma_f32_16x16x32_bf16 v[4:7], v[164:167], v[176:179], v[4:7]
	v_mfma_f32_16x16x32_bf16 v[0:3], v[172:175], v[176:179], v[0:3]
	ds_read_b128 v[136:139], v146 offset:4096
	s_waitcnt lgkmcnt(2)
	v_mfma_f32_16x16x32_bf16 v[124:127], v[186:189], v[180:183], v[124:127]
	v_mfma_f32_16x16x32_bf16 v[120:123], v[190:193], v[180:183], v[120:123]
	v_mfma_f32_16x16x32_bf16 v[116:119], v[194:197], v[180:183], v[116:119]
	v_mfma_f32_16x16x32_bf16 v[112:115], v[198:201], v[180:183], v[112:115]
	ds_read_b128 v[156:159], v156
	s_waitcnt lgkmcnt(2)
	v_mfma_f32_16x16x32_bf16 v[108:111], v[186:189], v[160:163], v[108:111]
	v_mfma_f32_16x16x32_bf16 v[104:107], v[190:193], v[160:163], v[104:107]
	v_mfma_f32_16x16x32_bf16 v[100:103], v[194:197], v[160:163], v[100:103]
	v_mfma_f32_16x16x32_bf16 v[96:99], v[198:201], v[160:163], v[96:99]
	ds_read_b128 v[160:163], v146 offset:8192
	s_waitcnt lgkmcnt(2)
	v_mfma_f32_16x16x32_bf16 v[92:95], v[186:189], v[136:139], v[92:95]
	v_mfma_f32_16x16x32_bf16 v[88:91], v[190:193], v[136:139], v[88:91]
	v_mfma_f32_16x16x32_bf16 v[84:87], v[194:197], v[136:139], v[84:87]
	v_mfma_f32_16x16x32_bf16 v[80:83], v[198:201], v[136:139], v[80:83]
	ds_read_b128 v[136:139], v146 offset:10240
	s_waitcnt lgkmcnt(2)
	v_mfma_f32_16x16x32_bf16 v[76:79], v[186:189], v[156:159], v[76:79]
	v_mfma_f32_16x16x32_bf16 v[72:75], v[190:193], v[156:159], v[72:75]
	v_mfma_f32_16x16x32_bf16 v[68:71], v[194:197], v[156:159], v[68:71]
	v_mfma_f32_16x16x32_bf16 v[64:67], v[198:201], v[156:159], v[64:67]
	ds_read_b128 v[156:159], v146 offset:12288
	v_add_u32_e32 v146, v155, v152
	s_waitcnt lgkmcnt(2)
	v_mfma_f32_16x16x32_bf16 v[60:63], v[186:189], v[160:163], v[60:63]
	v_mfma_f32_16x16x32_bf16 v[56:59], v[190:193], v[160:163], v[56:59]
	v_mfma_f32_16x16x32_bf16 v[52:55], v[194:197], v[160:163], v[52:55]
	v_mfma_f32_16x16x32_bf16 v[48:51], v[198:201], v[160:163], v[48:51]
	ds_read_b128 v[160:163], v146
	s_waitcnt lgkmcnt(2)
	v_mfma_f32_16x16x32_bf16 v[44:47], v[186:189], v[136:139], v[44:47]
	v_mfma_f32_16x16x32_bf16 v[40:43], v[190:193], v[136:139], v[40:43]
	v_mfma_f32_16x16x32_bf16 v[36:39], v[194:197], v[136:139], v[36:39]
	v_mfma_f32_16x16x32_bf16 v[32:35], v[198:201], v[136:139], v[32:35]
	s_waitcnt lgkmcnt(1)
	v_mfma_f32_16x16x32_bf16 v[24:27], v[190:193], v[156:159], v[24:27]
	v_mfma_f32_16x16x32_bf16 v[20:23], v[194:197], v[156:159], v[20:23]
	v_mfma_f32_16x16x32_bf16 v[16:19], v[198:201], v[156:159], v[16:19]
	s_waitcnt lgkmcnt(0)
	v_mfma_f32_16x16x32_bf16 v[12:15], v[186:189], v[160:163], v[12:15]
	v_mfma_f32_16x16x32_bf16 v[8:11], v[190:193], v[160:163], v[8:11]
	v_mfma_f32_16x16x32_bf16 v[4:7], v[194:197], v[160:163], v[4:7]
	v_mfma_f32_16x16x32_bf16 v[0:3], v[198:201], v[160:163], v[0:3]
	v_mfma_f32_16x16x32_bf16 v[28:31], v[186:189], v[156:159], v[28:31]
	v_mov_b32_e32 v136, v140
	v_mov_b32_e32 v137, v141
	s_waitcnt vmcnt(0)
	s_barrier
	v_cvt_pk_bf16_f32 v124, v124, v125
	v_and_or_b32 v138, v137, 15, v143
	v_ashrrev_i32_e32 v139, 1, v137
	v_mul_lo_u32 v138, v138, s3
	v_and_b32_e32 v139, -8, v139
	v_add3_u32 v138, v154, v138, v139
	v_cvt_pk_bf16_f32 v125, v126, v127
	v_cvt_pk_bf16_f32 v120, v120, v121
	v_cvt_pk_bf16_f32 v121, v122, v123
	v_cvt_pk_bf16_f32 v116, v116, v117
	v_cvt_pk_bf16_f32 v117, v118, v119
	v_cvt_pk_bf16_f32 v112, v112, v113
	v_cvt_pk_bf16_f32 v113, v114, v115
	v_cvt_pk_bf16_f32 v108, v108, v109
	v_cvt_pk_bf16_f32 v109, v110, v111
	v_cvt_pk_bf16_f32 v104, v104, v105
	v_cvt_pk_bf16_f32 v105, v106, v107
	v_add_u32_e32 v106, 0x2000, v138
	v_cvt_pk_bf16_f32 v100, v100, v101
	v_cvt_pk_bf16_f32 v101, v102, v103
	v_cvt_pk_bf16_f32 v96, v96, v97
	v_cvt_pk_bf16_f32 v97, v98, v99
	v_cvt_pk_bf16_f32 v92, v92, v93
	v_cvt_pk_bf16_f32 v93, v94, v95
	v_cvt_pk_bf16_f32 v88, v88, v89
	v_cvt_pk_bf16_f32 v89, v90, v91
	v_add_u32_e32 v90, 0x4000, v138
	v_cvt_pk_bf16_f32 v84, v84, v85
	v_cvt_pk_bf16_f32 v85, v86, v87
	v_cvt_pk_bf16_f32 v80, v80, v81
	v_cvt_pk_bf16_f32 v81, v82, v83
	v_cvt_pk_bf16_f32 v76, v76, v77
	v_cvt_pk_bf16_f32 v77, v78, v79
	v_cvt_pk_bf16_f32 v72, v72, v73
	v_cvt_pk_bf16_f32 v73, v74, v75
	v_add_u32_e32 v74, 0x6000, v138
	v_cvt_pk_bf16_f32 v68, v68, v69
	v_cvt_pk_bf16_f32 v69, v70, v71
	v_cvt_pk_bf16_f32 v64, v64, v65
	v_cvt_pk_bf16_f32 v65, v66, v67
	v_cvt_pk_bf16_f32 v60, v60, v61
	v_cvt_pk_bf16_f32 v61, v62, v63
	v_cvt_pk_bf16_f32 v56, v56, v57
	v_cvt_pk_bf16_f32 v57, v58, v59
	v_add_u32_e32 v58, 0x8000, v138
	v_cvt_pk_bf16_f32 v52, v52, v53
	v_cvt_pk_bf16_f32 v53, v54, v55
	v_cvt_pk_bf16_f32 v48, v48, v49
	v_cvt_pk_bf16_f32 v49, v50, v51
	v_cvt_pk_bf16_f32 v44, v44, v45
	v_cvt_pk_bf16_f32 v45, v46, v47
	v_cvt_pk_bf16_f32 v40, v40, v41
	v_cvt_pk_bf16_f32 v41, v42, v43
	v_add_u32_e32 v42, 0xa000, v138
	v_cvt_pk_bf16_f32 v36, v36, v37
	v_cvt_pk_bf16_f32 v37, v38, v39
	v_cvt_pk_bf16_f32 v32, v32, v33
; DI unsigned pk2(float a, float b) { f32x2 v = {a, b}; bf16x2_t r = __builtin_convertvector(v, bf16x2_t); return __builtin_bit_cast(unsigned, r); }
; DI float bflo(unsigned w) { return __uint_as_float(w << 16); }
; DI float bfhi(unsigned w) { return __uint_as_float(w & 0xffff0000u); }
;     DI void operator()(gacc_t& acc, int pm, int pn, char* lds, int tid, int wr, int wc, int lane) const {
;     ...
; #pragma unroll
;         for (int m = 0; m < 8; ++m)
; #pragma unroll
;             for (int n = 0; n < 4; ++n) { u32x2 w; w.x = pk2(acc[m][n][0], acc[m][n][1]); w.y = pk2(acc[m][n][2], acc[m][n][3]); *(u32x2*)(lbase + m * 16 * 528 + n * 32) = w; }
;         __builtin_amdgcn_sched_barrier(0);
;         __syncthreads();
;         __builtin_amdgcn_sched_barrier(0);
;         const int g = lane >> 5, j32 = lane & 31;
; #pragma unroll
;         for (int ib = 0; ib < 4; ++ib) {
;             __builtin_amdgcn_sched_barrier(0);
;             u32x4 xv[4];
; #pragma unroll
;             for (int u = 0; u < 4; ++u) {
;                 const long row = (long)pm * 256 + (ib * 4 + u) * 16 + wid * 2 + g;
;                 xv[u] = *(const u32x4*)(xold + row * 1024 + pn * 256 + j32 * 8);
;             }
; #pragma unroll
;             for (int u = 0; u < 4; ++u) {
;                 const int rloc = (ib * 4 + u) * 16 + wid * 2 + g;
;                 const long row = (long)pm * 256 + rloc;
;                 const u32x4 a = *(const u32x4*)(lds + rloc * 528 + j32 * 16);
;                 u32x4 w; float ss = 0.f;
; #pragma unroll
;                 for (int e = 0; e < 4; ++e) {
;                     w[e] = pk2(bflo(xv[u][e]) + bflo(a[e]), bfhi(xv[u][e]) + bfhi(a[e]));
;                     const float b0 = bflo(w[e]), b1 = bfhi(w[e]);
;                     ss += b0 * b0 + b1 * b1;
;                 }
;                 *(u32x4*)(xnew + row * 1024 + pn * 256 + j32 * 8) = w;
; #pragma unroll
;                 for (int o = 1; o < 32; o <<= 1) ss += __shfl_xor(ss, o);
;                 if (j32 == 0) ssq[row * 4 + pn] = ss;
;             }
	v_cvt_pk_bf16_f32 v33, v34, v35
	v_cvt_pk_bf16_f32 v28, v28, v29
	v_cvt_pk_bf16_f32 v29, v30, v31
	v_cvt_pk_bf16_f32 v24, v24, v25
	v_cvt_pk_bf16_f32 v25, v26, v27
	v_add_u32_e32 v26, 0xc000, v138
	v_cvt_pk_bf16_f32 v20, v20, v21
	v_cvt_pk_bf16_f32 v21, v22, v23
	v_cvt_pk_bf16_f32 v16, v16, v17
	v_cvt_pk_bf16_f32 v17, v18, v19
	v_cvt_pk_bf16_f32 v12, v12, v13
	v_cvt_pk_bf16_f32 v13, v14, v15
	v_cvt_pk_bf16_f32 v8, v8, v9
	v_cvt_pk_bf16_f32 v9, v10, v11
	v_add_u32_e32 v10, 0xe000, v138
	v_cvt_pk_bf16_f32 v4, v4, v5
	v_cvt_pk_bf16_f32 v5, v6, v7
	v_cvt_pk_bf16_f32 v0, v0, v1
	v_cvt_pk_bf16_f32 v1, v2, v3
	ds_write2_b64 v138, v[124:125], v[120:121] offset1:4
	ds_write2_b64 v138, v[116:117], v[112:113] offset0:8 offset1:12
	ds_write2_b64 v106, v[108:109], v[104:105] offset0:32 offset1:36
	ds_write2_b64 v106, v[100:101], v[96:97] offset0:40 offset1:44
	ds_write2_b64 v90, v[92:93], v[88:89] offset0:64 offset1:68
	ds_write2_b64 v90, v[84:85], v[80:81] offset0:72 offset1:76
	ds_write2_b64 v74, v[76:77], v[72:73] offset0:96 offset1:100
	ds_write2_b64 v74, v[68:69], v[64:65] offset0:104 offset1:108
	ds_write2_b64 v58, v[60:61], v[56:57] offset0:128 offset1:132
	ds_write2_b64 v58, v[52:53], v[48:49] offset0:136 offset1:140
	ds_write2_b64 v42, v[44:45], v[40:41] offset0:160 offset1:164
	ds_write2_b64 v42, v[36:37], v[32:33] offset0:168 offset1:172
	ds_write2_b64 v26, v[28:29], v[24:25] offset0:192 offset1:196
	ds_write2_b64 v26, v[20:21], v[16:17] offset0:200 offset1:204
	ds_write2_b64 v10, v[12:13], v[8:9] offset0:224 offset1:228
	ds_write2_b64 v10, v[4:5], v[0:1] offset0:232 offset1:236
	s_waitcnt lgkmcnt(0)
	s_barrier
	v_ashrrev_i32_e32 v0, 5, v137
	v_ashrrev_i32_e32 v1, 5, v136
	v_and_b32_e32 v14, 31, v137
	v_and_b32_e32 v2, -2, v1
	v_ashrrev_i32_e32 v1, 31, v0
	v_ashrrev_i32_e32 v3, 31, v2
	v_lshl_add_u64 v[4:5], s[12:13], 0, v[0:1]
	s_lshl_b32 s16, s6, 8
	v_add_u32_e32 v16, v2, v0
	v_lshlrev_b32_e32 v146, 4, v14
	v_and_b32_e32 v0, 64, v169
	v_lshl_add_u64 v[4:5], v[4:5], 0, v[2:3]
	s_ashr_i32 s17, s16, 31
	v_add_u32_e32 v26, 0, v146
	v_add_u32_e32 v15, 64, v0
	v_cmp_eq_u32_e64 s[4:5], 0, v14
	v_cmp_eq_u32_e64 s[98:99], 16, v14
	s_lshl_b64 s[18:19], s[16:17], 1
	s_add_u32 s22, s68, s18
	s_addc_u32 s23, s69, s19
	v_lshl_add_u64 v[0:1], s[22:23], 0, v[146:147]
	v_lshlrev_b64 v[2:3], 11, v[4:5]
	v_lshl_add_u64 v[18:19], v[0:1], 0, v[2:3]
	flat_load_dwordx4 v[22:25], v[18:19]
	v_add_co_u32_e32 v0, vcc, s49, v18
	v_mul_lo_u32 v20, v16, s3
	s_nop 0
	v_addc_co_u32_e32 v1, vcc, 0, v19, vcc
	flat_load_dwordx4 v[8:11], v[0:1]
	v_add_co_u32_e32 v0, vcc, s48, v18
	v_add_u32_e32 v12, v26, v20
	s_nop 0
	v_addc_co_u32_e32 v1, vcc, 0, v19, vcc
	flat_load_dwordx4 v[4:7], v[0:1]
	v_add_co_u32_e32 v0, vcc, s47, v18
	ds_read_b128 v[28:31], v12
	s_nop 0
	v_addc_co_u32_e32 v1, vcc, 0, v19, vcc
	flat_load_dwordx4 v[0:3], v[0:1]
	v_ashrrev_i32_e32 v17, 31, v16
	s_waitcnt lgkmcnt(0)
	v_lshlrev_b32_e32 v32, 16, v28
	v_and_b32_e32 v33, 0xffff0000, v28
	v_lshlrev_b32_e32 v28, 16, v29
	v_and_b32_e32 v29, 0xffff0000, v29
	s_waitcnt vmcnt(0)
	v_lshlrev_b32_e32 v12, 16, v22
	v_and_b32_e32 v13, 0xffff0000, v22
	v_pk_add_f32 v[12:13], v[12:13], v[32:33]
	s_nop 0
	v_cvt_pk_bf16_f32 v22, v12, v13
	v_and_b32_e32 v13, 0xffff0000, v22
	v_lshlrev_b32_e32 v12, 16, v22
	v_mul_f32_e32 v21, v13, v13
	v_fmac_f32_e32 v21, v12, v12
	v_lshlrev_b32_e32 v12, 16, v23
	v_and_b32_e32 v13, 0xffff0000, v23
	v_pk_add_f32 v[12:13], v[12:13], v[28:29]
	v_lshlrev_b32_e32 v28, 16, v30
	v_cvt_pk_bf16_f32 v23, v12, v13
	v_and_b32_e32 v13, 0xffff0000, v23
	v_lshlrev_b32_e32 v12, 16, v23
	v_mul_f32_e32 v13, v13, v13
	v_fmac_f32_e32 v13, v12, v12
	v_add_f32_e32 v21, v21, v13
	v_lshlrev_b32_e32 v12, 16, v24
	v_and_b32_e32 v13, 0xffff0000, v24
	v_and_b32_e32 v29, 0xffff0000, v30
	v_pk_add_f32 v[12:13], v[12:13], v[28:29]
	v_lshlrev_b32_e32 v28, 16, v31
	v_cvt_pk_bf16_f32 v24, v12, v13
	v_and_b32_e32 v13, 0xffff0000, v24
	v_lshlrev_b32_e32 v12, 16, v24
	v_mul_f32_e32 v13, v13, v13
	v_fmac_f32_e32 v13, v12, v12
	v_add_f32_e32 v21, v13, v21
	v_lshlrev_b32_e32 v12, 16, v25
	v_and_b32_e32 v13, 0xffff0000, v25
	v_and_b32_e32 v29, 0xffff0000, v31
	v_pk_add_f32 v[12:13], v[12:13], v[28:29]
	s_nop 0
	v_cvt_pk_bf16_f32 v25, v12, v13
	v_and_b32_e32 v13, 0xffff0000, v25
	v_lshlrev_b32_e32 v12, 16, v25
	v_mul_f32_e32 v13, v13, v13
	v_fmac_f32_e32 v13, v12, v12
	v_add_f32_e32 v21, v13, v21
	v_lshl_add_u64 v[12:13], s[12:13], 0, v[16:17]
	v_lshlrev_b64 v[28:29], 11, v[12:13]
	v_xor_b32_e32 v17, 1, v169
	v_lshl_add_u64 v[28:29], s[10:11], 0, v[28:29]
	v_cmp_lt_i32_e32 vcc, v17, v15
	v_lshl_add_u64 v[28:29], v[28:29], 0, s[18:19]
	v_lshl_add_u64 v[28:29], v[28:29], 0, v[146:147]
	v_cndmask_b32_e32 v17, v169, v17, vcc
	v_lshlrev_b32_e32 v17, 2, v17
	flat_store_dwordx4 v[28:29], v[22:25]
	s_nop 1
	v_add_f32_dpp v86, v21, v21 quad_perm:[1,0,3,2] row_mask:0xf bank_mask:0xf
	s_nop 1
	v_add_f32_dpp v86, v86, v86 quad_perm:[2,3,0,1] row_mask:0xf bank_mask:0xf
	s_nop 1
	v_add_f32_dpp v86, v86, v86 row_half_mirror row_mask:0xf bank_mask:0xf
	s_nop 1
	v_add_f32_dpp v86, v86, v86 row_mirror row_mask:0xf bank_mask:0xf
	s_nop 1
	v_add_f32_dpp v86, v86, v86 row_bcast:15 row_mask:0xa bank_mask:0xf
	s_waitcnt lgkmcnt(0)
	v_xor_b32_e32 v22, 2, v169
	v_cmp_lt_i32_e32 vcc, v22, v15
	s_nop 1
	v_cndmask_b32_e32 v22, v169, v22, vcc
	v_lshlrev_b32_e32 v22, 2, v22
	s_waitcnt lgkmcnt(0)
	v_xor_b32_e32 v23, 4, v169
	v_cmp_lt_i32_e32 vcc, v23, v15
	s_nop 1
	v_cndmask_b32_e32 v23, v169, v23, vcc
	v_lshlrev_b32_e32 v23, 2, v23
	s_waitcnt lgkmcnt(0)
	v_xor_b32_e32 v24, 8, v169
	v_cmp_lt_i32_e32 vcc, v24, v15
	s_nop 1
	v_cndmask_b32_e32 v24, v169, v24, vcc
	v_lshlrev_b32_e32 v24, 2, v24
	s_waitcnt lgkmcnt(0)
	v_xor_b32_e32 v25, 16, v169
	v_cmp_lt_i32_e32 vcc, v25, v15
	s_nop 1
	v_cndmask_b32_e32 v15, v169, v25, vcc
	v_lshlrev_b32_e32 v25, 2, v15
	s_and_saveexec_b64 s[18:19], s[98:99]
	s_cbranch_execz .LBB0_778
	v_lshl_add_u64 v[12:13], v[12:13], 4, s[78:79]
	v_lshl_add_u64 v[12:13], s[6:7], 2, v[12:13]
	s_waitcnt lgkmcnt(0)
	v_mov_b32_e32 v15, v86
	flat_store_dword v[12:13], v15
; DI unsigned pk2(float a, float b) { f32x2 v = {a, b}; bf16x2_t r = __builtin_convertvector(v, bf16x2_t); return __builtin_bit_cast(unsigned, r); }
; DI float bflo(unsigned w) { return __uint_as_float(w << 16); }
; DI float bfhi(unsigned w) { return __uint_as_float(w & 0xffff0000u); }
;     DI void operator()(gacc_t& acc, int pm, int pn, char* lds, int tid, int wr, int wc, int lane) const {
;     ...
;             for (int u = 0; u < 4; ++u) {
;                 const int rloc = (ib * 4 + u) * 16 + wid * 2 + g;
;                 const long row = (long)pm * 256 + rloc;
;                 const u32x4 a = *(const u32x4*)(lds + rloc * 528 + j32 * 16);
;                 u32x4 w; float ss = 0.f;
; #pragma unroll
;                 for (int e = 0; e < 4; ++e) {
;                     w[e] = pk2(bflo(xv[u][e]) + bflo(a[e]), bfhi(xv[u][e]) + bfhi(a[e]));
;                     const float b0 = bflo(w[e]), b1 = bfhi(w[e]);
;                     ss += b0 * b0 + b1 * b1;
;                 }
;                 *(u32x4*)(xnew + row * 1024 + pn * 256 + j32 * 8) = w;
; #pragma unroll
;                 for (int o = 1; o < 32; o <<= 1) ss += __shfl_xor(ss, o);
;                 if (j32 == 0) ssq[row * 4 + pn] = ss;
;             }
.LBB0_778:
	s_or_b64 exec, exec, s[18:19]
	v_add_u32_e32 v12, 0x2100, v20
	v_add_u32_e32 v13, v26, v12
	ds_read_b128 v[28:31], v13
	v_lshlrev_b32_e32 v20, 16, v8
	v_and_b32_e32 v21, 0xffff0000, v8
	s_waitcnt lgkmcnt(0)
	v_lshlrev_b32_e32 v32, 16, v28
	v_and_b32_e32 v33, 0xffff0000, v28
	v_pk_add_f32 v[20:21], v[20:21], v[32:33]
	s_nop 0
	v_cvt_pk_bf16_f32 v28, v20, v21
	v_and_b32_e32 v13, 0xffff0000, v28
	v_lshlrev_b32_e32 v8, 16, v28
	v_mul_f32_e32 v13, v13, v13
	v_fmac_f32_e32 v13, v8, v8
	v_lshlrev_b32_e32 v8, 16, v9
	v_and_b32_e32 v9, 0xffff0000, v9
	v_lshlrev_b32_e32 v20, 16, v29
	v_and_b32_e32 v21, 0xffff0000, v29
	v_pk_add_f32 v[8:9], v[8:9], v[20:21]
	v_lshlrev_b32_e32 v20, 16, v30
	v_cvt_pk_bf16_f32 v29, v8, v9
	v_and_b32_e32 v9, 0xffff0000, v29
	v_lshlrev_b32_e32 v8, 16, v29
	v_mul_f32_e32 v9, v9, v9
	v_fmac_f32_e32 v9, v8, v8
	v_add_f32_e32 v13, v13, v9
	v_lshlrev_b32_e32 v8, 16, v10
	v_and_b32_e32 v9, 0xffff0000, v10
	v_and_b32_e32 v21, 0xffff0000, v30
	v_pk_add_f32 v[8:9], v[8:9], v[20:21]
	v_lshlrev_b32_e32 v10, 16, v31
	v_cvt_pk_bf16_f32 v30, v8, v9
	v_and_b32_e32 v9, 0xffff0000, v30
	v_lshlrev_b32_e32 v8, 16, v30
	v_mul_f32_e32 v9, v9, v9
	v_fmac_f32_e32 v9, v8, v8
	v_add_f32_e32 v13, v9, v13
	v_lshlrev_b32_e32 v8, 16, v11
	v_and_b32_e32 v9, 0xffff0000, v11
	v_and_b32_e32 v11, 0xffff0000, v31
	v_pk_add_f32 v[8:9], v[8:9], v[10:11]
	s_nop 0
	v_cvt_pk_bf16_f32 v31, v8, v9
	v_and_b32_e32 v9, 0xffff0000, v31
	v_lshlrev_b32_e32 v8, 16, v31
	v_mul_f32_e32 v9, v9, v9
	v_fmac_f32_e32 v9, v8, v8
	v_add_f32_e32 v8, v9, v13
	s_nop 1
	v_add_f32_dpp v86, v8, v8 quad_perm:[1,0,3,2] row_mask:0xf bank_mask:0xf
	s_nop 1
	v_add_f32_dpp v86, v86, v86 quad_perm:[2,3,0,1] row_mask:0xf bank_mask:0xf
	s_nop 1
	v_add_f32_dpp v86, v86, v86 row_half_mirror row_mask:0xf bank_mask:0xf
	s_nop 1
	v_add_f32_dpp v86, v86, v86 row_mirror row_mask:0xf bank_mask:0xf
	s_nop 1
	v_add_f32_dpp v86, v86, v86 row_bcast:15 row_mask:0xa bank_mask:0xf
	v_lshlrev_b32_e32 v13, 3, v14
	v_lshlrev_b32_e32 v146, 1, v13
	s_waitcnt lgkmcnt(0)
	s_waitcnt lgkmcnt(0)
	v_add_u32_e32 v8, 16, v16
	s_waitcnt lgkmcnt(0)
	v_ashrrev_i32_e32 v9, 31, v8
	v_lshl_add_u64 v[8:9], s[12:13], 0, v[8:9]
	v_lshlrev_b64 v[10:11], 11, v[8:9]
	v_lshl_add_u64 v[14:15], s[10:11], 0, v[10:11]
	s_waitcnt lgkmcnt(0)
	v_lshl_add_u64 v[14:15], s[16:17], 1, v[14:15]
	v_lshl_add_u64 v[14:15], v[14:15], 0, v[146:147]
	flat_store_dwordx4 v[14:15], v[28:31]
	s_and_saveexec_b64 s[18:19], s[98:99]
	s_cbranch_execz .LBB0_780
	v_lshl_add_u64 v[8:9], v[8:9], 4, s[78:79]
	v_lshl_add_u64 v[8:9], s[6:7], 2, v[8:9]
	s_waitcnt lgkmcnt(0)
	v_mov_b32_e32 v10, v86
	flat_store_dword v[8:9], v10
.LBB0_780:
	s_or_b64 exec, exec, s[18:19]
	v_add_u32_e32 v8, 0x2100, v12
	v_add_u32_e32 v9, v26, v8
	s_waitcnt lgkmcnt(0)
	ds_read_b128 v[10:13], v9
	v_lshlrev_b32_e32 v14, 16, v4
	v_and_b32_e32 v15, 0xffff0000, v4
	s_waitcnt lgkmcnt(0)
	v_lshlrev_b32_e32 v20, 16, v10
	v_and_b32_e32 v21, 0xffff0000, v10
	v_pk_add_f32 v[14:15], v[14:15], v[20:21]
	s_nop 0
	v_cvt_pk_bf16_f32 v10, v14, v15
	v_and_b32_e32 v9, 0xffff0000, v10
	v_lshlrev_b32_e32 v4, 16, v10
	v_mul_f32_e32 v9, v9, v9
	v_fmac_f32_e32 v9, v4, v4
	v_lshlrev_b32_e32 v4, 16, v5
	v_and_b32_e32 v5, 0xffff0000, v5
	v_lshlrev_b32_e32 v14, 16, v11
	v_and_b32_e32 v15, 0xffff0000, v11
	v_pk_add_f32 v[4:5], v[4:5], v[14:15]
	v_lshlrev_b32_e32 v14, 16, v12
	v_cvt_pk_bf16_f32 v11, v4, v5
	v_and_b32_e32 v5, 0xffff0000, v11
	v_lshlrev_b32_e32 v4, 16, v11
	v_mul_f32_e32 v5, v5, v5
	v_fmac_f32_e32 v5, v4, v4
	v_add_f32_e32 v9, v9, v5
	v_lshlrev_b32_e32 v4, 16, v6
	v_and_b32_e32 v5, 0xffff0000, v6
	v_and_b32_e32 v15, 0xffff0000, v12
	v_pk_add_f32 v[4:5], v[4:5], v[14:15]
	v_lshlrev_b32_e32 v6, 16, v13
	v_cvt_pk_bf16_f32 v12, v4, v5
	v_and_b32_e32 v5, 0xffff0000, v12
	v_lshlrev_b32_e32 v4, 16, v12
	v_mul_f32_e32 v5, v5, v5
	v_fmac_f32_e32 v5, v4, v4
	v_add_f32_e32 v9, v5, v9
	v_lshlrev_b32_e32 v4, 16, v7
	v_and_b32_e32 v5, 0xffff0000, v7
	v_and_b32_e32 v7, 0xffff0000, v13
	v_pk_add_f32 v[4:5], v[4:5], v[6:7]
	s_nop 0
	v_cvt_pk_bf16_f32 v13, v4, v5
	v_and_b32_e32 v5, 0xffff0000, v13
	v_lshlrev_b32_e32 v4, 16, v13
	v_mul_f32_e32 v5, v5, v5
	v_fmac_f32_e32 v5, v4, v4
	v_add_f32_e32 v4, v5, v9
	s_nop 1
	v_add_f32_dpp v86, v4, v4 quad_perm:[1,0,3,2] row_mask:0xf bank_mask:0xf
	s_nop 1
	v_add_f32_dpp v86, v86, v86 quad_perm:[2,3,0,1] row_mask:0xf bank_mask:0xf
	s_nop 1
	v_add_f32_dpp v86, v86, v86 row_half_mirror row_mask:0xf bank_mask:0xf
	s_nop 1
	v_add_f32_dpp v86, v86, v86 row_mirror row_mask:0xf bank_mask:0xf
	s_nop 1
	v_add_f32_dpp v86, v86, v86 row_bcast:15 row_mask:0xa bank_mask:0xf
	s_waitcnt lgkmcnt(0)
	s_waitcnt lgkmcnt(0)
	s_waitcnt lgkmcnt(0)
	v_add_u32_e32 v4, 32, v16
	v_ashrrev_i32_e32 v5, 31, v4
	v_lshl_add_u64 v[4:5], s[12:13], 0, v[4:5]
	v_lshlrev_b64 v[14:15], 11, v[4:5]
	s_waitcnt lgkmcnt(0)
	v_lshl_add_u64 v[14:15], s[10:11], 0, v[14:15]
	v_lshl_add_u64 v[14:15], s[16:17], 1, v[14:15]
	v_lshl_add_u64 v[14:15], v[14:15], 0, v[146:147]
	flat_store_dwordx4 v[14:15], v[10:13]
	s_and_saveexec_b64 s[18:19], s[98:99]
	s_cbranch_execz .LBB0_782
	v_lshl_add_u64 v[4:5], v[4:5], 4, s[78:79]
	v_lshl_add_u64 v[4:5], s[6:7], 2, v[4:5]
	s_waitcnt lgkmcnt(0)
	v_mov_b32_e32 v6, v86
	flat_store_dword v[4:5], v6
; DI unsigned pk2(float a, float b) { f32x2 v = {a, b}; bf16x2_t r = __builtin_convertvector(v, bf16x2_t); return __builtin_bit_cast(unsigned, r); }
; DI float bflo(unsigned w) { return __uint_as_float(w << 16); }
; DI float bfhi(unsigned w) { return __uint_as_float(w & 0xffff0000u); }
;     DI void operator()(gacc_t& acc, int pm, int pn, char* lds, int tid, int wr, int wc, int lane) const {
;     ...
;         for (int ib = 0; ib < 4; ++ib) {
;             __builtin_amdgcn_sched_barrier(0);
;             u32x4 xv[4];
; #pragma unroll
;             for (int u = 0; u < 4; ++u) {
;                 const long row = (long)pm * 256 + (ib * 4 + u) * 16 + wid * 2 + g;
;                 xv[u] = *(const u32x4*)(xold + row * 1024 + pn * 256 + j32 * 8);
;             }
; #pragma unroll
;             for (int u = 0; u < 4; ++u) {
;                 const int rloc = (ib * 4 + u) * 16 + wid * 2 + g;
;                 const long row = (long)pm * 256 + rloc;
;                 const u32x4 a = *(const u32x4*)(lds + rloc * 528 + j32 * 16);
;                 u32x4 w; float ss = 0.f;
; #pragma unroll
;                 for (int e = 0; e < 4; ++e) {
;                     w[e] = pk2(bflo(xv[u][e]) + bflo(a[e]), bfhi(xv[u][e]) + bfhi(a[e]));
;                     const float b0 = bflo(w[e]), b1 = bfhi(w[e]);
;                     ss += b0 * b0 + b1 * b1;
;                 }
;                 *(u32x4*)(xnew + row * 1024 + pn * 256 + j32 * 8) = w;
; #pragma unroll
;                 for (int o = 1; o < 32; o <<= 1) ss += __shfl_xor(ss, o);
;                 if (j32 == 0) ssq[row * 4 + pn] = ss;
;             }
.LBB0_782:
	s_or_b64 exec, exec, s[18:19]
	v_add_u32_e32 v12, 0x2100, v8
	v_add_u32_e32 v4, v26, v12
	s_waitcnt lgkmcnt(0)
	ds_read_b128 v[4:7], v4
	v_lshlrev_b32_e32 v8, 16, v0
	v_and_b32_e32 v9, 0xffff0000, v0
	s_waitcnt lgkmcnt(0)
	v_lshlrev_b32_e32 v10, 16, v4
	v_and_b32_e32 v11, 0xffff0000, v4
	v_pk_add_f32 v[8:9], v[8:9], v[10:11]
	s_nop 0
	v_cvt_pk_bf16_f32 v4, v8, v9
	v_and_b32_e32 v8, 0xffff0000, v4
	v_lshlrev_b32_e32 v0, 16, v4
	v_mul_f32_e32 v10, v8, v8
	v_fmac_f32_e32 v10, v0, v0
	v_lshlrev_b32_e32 v0, 16, v1
	v_and_b32_e32 v1, 0xffff0000, v1
	v_lshlrev_b32_e32 v8, 16, v5
	v_and_b32_e32 v9, 0xffff0000, v5
	v_pk_add_f32 v[0:1], v[0:1], v[8:9]
	v_lshlrev_b32_e32 v8, 16, v6
	v_cvt_pk_bf16_f32 v5, v0, v1
	v_and_b32_e32 v1, 0xffff0000, v5
	v_lshlrev_b32_e32 v0, 16, v5
	v_mul_f32_e32 v1, v1, v1
	v_fmac_f32_e32 v1, v0, v0
	v_add_f32_e32 v10, v10, v1
	v_lshlrev_b32_e32 v0, 16, v2
	v_and_b32_e32 v1, 0xffff0000, v2
	v_and_b32_e32 v9, 0xffff0000, v6
	v_pk_add_f32 v[0:1], v[0:1], v[8:9]
	v_lshlrev_b32_e32 v2, 16, v7
	v_cvt_pk_bf16_f32 v6, v0, v1
	v_and_b32_e32 v1, 0xffff0000, v6
	v_lshlrev_b32_e32 v0, 16, v6
	v_mul_f32_e32 v1, v1, v1
	v_fmac_f32_e32 v1, v0, v0
	v_add_f32_e32 v8, v1, v10
	v_lshlrev_b32_e32 v0, 16, v3
	v_and_b32_e32 v1, 0xffff0000, v3
	v_and_b32_e32 v3, 0xffff0000, v7
	v_pk_add_f32 v[0:1], v[0:1], v[2:3]
	s_nop 0
	v_cvt_pk_bf16_f32 v7, v0, v1
	v_and_b32_e32 v1, 0xffff0000, v7
	v_lshlrev_b32_e32 v0, 16, v7
	v_mul_f32_e32 v1, v1, v1
	v_fmac_f32_e32 v1, v0, v0
	v_add_f32_e32 v0, v1, v8
	s_nop 1
	v_add_f32_dpp v86, v0, v0 quad_perm:[1,0,3,2] row_mask:0xf bank_mask:0xf
	s_nop 1
	v_add_f32_dpp v86, v86, v86 quad_perm:[2,3,0,1] row_mask:0xf bank_mask:0xf
	s_nop 1
	v_add_f32_dpp v86, v86, v86 row_half_mirror row_mask:0xf bank_mask:0xf
	s_nop 1
	v_add_f32_dpp v86, v86, v86 row_mirror row_mask:0xf bank_mask:0xf
	s_nop 1
	v_add_f32_dpp v86, v86, v86 row_bcast:15 row_mask:0xa bank_mask:0xf
	s_waitcnt lgkmcnt(0)
	s_waitcnt lgkmcnt(0)
	s_waitcnt lgkmcnt(0)
	v_add_u32_e32 v0, 48, v16
	v_ashrrev_i32_e32 v1, 31, v0
	v_lshl_add_u64 v[0:1], s[12:13], 0, v[0:1]
	v_lshlrev_b64 v[8:9], 11, v[0:1]
	s_waitcnt lgkmcnt(0)
	v_lshl_add_u64 v[8:9], s[10:11], 0, v[8:9]
	v_lshl_add_u64 v[8:9], s[16:17], 1, v[8:9]
	v_lshl_add_u64 v[8:9], v[8:9], 0, v[146:147]
	flat_store_dwordx4 v[8:9], v[4:7]
	s_and_saveexec_b64 s[18:19], s[98:99]
	s_cbranch_execz .LBB0_784
	v_lshl_add_u64 v[0:1], v[0:1], 4, s[78:79]
	v_lshl_add_u64 v[0:1], s[6:7], 2, v[0:1]
	s_waitcnt lgkmcnt(0)
	v_mov_b32_e32 v2, v86
	flat_store_dword v[0:1], v2
.LBB0_784:
	s_or_b64 exec, exec, s[18:19]
	v_add_co_u32_e32 v0, vcc, 0x20000, v18
	v_add_u32_e32 v27, 0x2100, v12
	s_nop 0
	v_addc_co_u32_e32 v1, vcc, 0, v19, vcc
	flat_load_dwordx4 v[28:31], v[0:1]
	v_add_co_u32_e32 v0, vcc, 0x28000, v18
	v_add_u32_e32 v12, v26, v27
	s_nop 0
	v_addc_co_u32_e32 v1, vcc, 0, v19, vcc
	flat_load_dwordx4 v[8:11], v[0:1]
	v_add_co_u32_e32 v0, vcc, 0x30000, v18
	ds_read_b128 v[12:15], v12
	s_nop 0
	v_addc_co_u32_e32 v1, vcc, 0, v19, vcc
	flat_load_dwordx4 v[4:7], v[0:1]
	v_add_co_u32_e32 v0, vcc, 0x38000, v18
	s_waitcnt lgkmcnt(0)
	v_lshlrev_b32_e32 v34, 16, v12
	v_addc_co_u32_e32 v1, vcc, 0, v19, vcc
	flat_load_dwordx4 v[0:3], v[0:1]
	v_and_b32_e32 v35, 0xffff0000, v12
	v_add_u32_e32 v20, 64, v16
	v_ashrrev_i32_e32 v21, 31, v20
	v_lshl_add_u64 v[20:21], s[12:13], 0, v[20:21]
	s_waitcnt vmcnt(0)
	v_lshlrev_b32_e32 v32, 16, v28
	v_and_b32_e32 v33, 0xffff0000, v28
	v_pk_add_f32 v[32:33], v[32:33], v[34:35]
	s_nop 0
	v_cvt_pk_bf16_f32 v12, v32, v33
	v_and_b32_e32 v32, 0xffff0000, v12
	v_lshlrev_b32_e32 v28, 16, v12
	v_mul_f32_e32 v34, v32, v32
	v_fmac_f32_e32 v34, v28, v28
	v_lshlrev_b32_e32 v28, 16, v29
	v_and_b32_e32 v29, 0xffff0000, v29
	v_lshlrev_b32_e32 v32, 16, v13
	v_and_b32_e32 v33, 0xffff0000, v13
	v_pk_add_f32 v[28:29], v[28:29], v[32:33]
	v_lshlrev_b32_e32 v32, 16, v14
	v_cvt_pk_bf16_f32 v13, v28, v29
	v_and_b32_e32 v29, 0xffff0000, v13
	v_lshlrev_b32_e32 v28, 16, v13
	v_mul_f32_e32 v29, v29, v29
	v_fmac_f32_e32 v29, v28, v28
	v_add_f32_e32 v34, v34, v29
	v_lshlrev_b32_e32 v28, 16, v30
	v_and_b32_e32 v29, 0xffff0000, v30
	v_and_b32_e32 v33, 0xffff0000, v14
	v_pk_add_f32 v[28:29], v[28:29], v[32:33]
	v_lshlrev_b32_e32 v30, 16, v15
	v_cvt_pk_bf16_f32 v14, v28, v29
	v_and_b32_e32 v29, 0xffff0000, v14
	v_lshlrev_b32_e32 v28, 16, v14
	v_mul_f32_e32 v29, v29, v29
	v_fmac_f32_e32 v29, v28, v28
	v_add_f32_e32 v32, v29, v34
	v_lshlrev_b32_e32 v28, 16, v31
	v_and_b32_e32 v29, 0xffff0000, v31
	v_and_b32_e32 v31, 0xffff0000, v15
	v_pk_add_f32 v[28:29], v[28:29], v[30:31]
	s_nop 0
	v_cvt_pk_bf16_f32 v15, v28, v29
	v_and_b32_e32 v29, 0xffff0000, v15
	v_lshlrev_b32_e32 v28, 16, v15
	v_mul_f32_e32 v29, v29, v29
	v_fmac_f32_e32 v29, v28, v28
	v_add_f32_e32 v30, v29, v32
	v_lshlrev_b64 v[28:29], 11, v[20:21]
	v_lshl_add_u64 v[28:29], s[10:11], 0, v[28:29]
	v_lshl_add_u64 v[28:29], s[16:17], 1, v[28:29]
	v_lshl_add_u64 v[28:29], v[28:29], 0, v[146:147]
	flat_store_dwordx4 v[28:29], v[12:15]
	s_nop 1
	v_add_f32_dpp v86, v30, v30 quad_perm:[1,0,3,2] row_mask:0xf bank_mask:0xf
	s_nop 1
	v_add_f32_dpp v86, v86, v86 quad_perm:[2,3,0,1] row_mask:0xf bank_mask:0xf
	s_nop 1
	v_add_f32_dpp v86, v86, v86 row_half_mirror row_mask:0xf bank_mask:0xf
	s_nop 1
	v_add_f32_dpp v86, v86, v86 row_mirror row_mask:0xf bank_mask:0xf
	s_nop 1
	v_add_f32_dpp v86, v86, v86 row_bcast:15 row_mask:0xa bank_mask:0xf
	s_waitcnt lgkmcnt(0)
	s_waitcnt lgkmcnt(0)
	s_waitcnt lgkmcnt(0)
	s_waitcnt lgkmcnt(0)
	s_and_saveexec_b64 s[18:19], s[98:99]
	s_cbranch_execz .LBB0_786
	v_lshl_add_u64 v[14:15], v[20:21], 4, s[78:79]
	v_lshl_add_u64 v[14:15], s[6:7], 2, v[14:15]
	s_waitcnt lgkmcnt(0)
	v_mov_b32_e32 v12, v86
	flat_store_dword v[14:15], v12
; DI unsigned pk2(float a, float b) { f32x2 v = {a, b}; bf16x2_t r = __builtin_convertvector(v, bf16x2_t); return __builtin_bit_cast(unsigned, r); }
; DI float bflo(unsigned w) { return __uint_as_float(w << 16); }
; DI float bfhi(unsigned w) { return __uint_as_float(w & 0xffff0000u); }
;     DI void operator()(gacc_t& acc, int pm, int pn, char* lds, int tid, int wr, int wc, int lane) const {
;     ...
;             for (int u = 0; u < 4; ++u) {
;                 const int rloc = (ib * 4 + u) * 16 + wid * 2 + g;
;                 const long row = (long)pm * 256 + rloc;
;                 const u32x4 a = *(const u32x4*)(lds + rloc * 528 + j32 * 16);
;                 u32x4 w; float ss = 0.f;
; #pragma unroll
;                 for (int e = 0; e < 4; ++e) {
;                     w[e] = pk2(bflo(xv[u][e]) + bflo(a[e]), bfhi(xv[u][e]) + bfhi(a[e]));
;                     const float b0 = bflo(w[e]), b1 = bfhi(w[e]);
;                     ss += b0 * b0 + b1 * b1;
;                 }
;                 *(u32x4*)(xnew + row * 1024 + pn * 256 + j32 * 8) = w;
; #pragma unroll
;                 for (int o = 1; o < 32; o <<= 1) ss += __shfl_xor(ss, o);
;                 if (j32 == 0) ssq[row * 4 + pn] = ss;
;             }
.LBB0_786:
	s_or_b64 exec, exec, s[18:19]
	v_add_u32_e32 v12, 0x2100, v27
	s_waitcnt lgkmcnt(0)
	v_add_u32_e32 v13, v26, v12
	ds_read_b128 v[28:31], v13
	v_lshlrev_b32_e32 v14, 16, v8
	v_and_b32_e32 v15, 0xffff0000, v8
	s_waitcnt lgkmcnt(0)
	v_lshlrev_b32_e32 v20, 16, v28
	v_and_b32_e32 v21, 0xffff0000, v28
	v_pk_add_f32 v[14:15], v[14:15], v[20:21]
	s_nop 0
	v_cvt_pk_bf16_f32 v28, v14, v15
	v_and_b32_e32 v13, 0xffff0000, v28
	v_lshlrev_b32_e32 v8, 16, v28
	v_mul_f32_e32 v13, v13, v13
	v_fmac_f32_e32 v13, v8, v8
	v_lshlrev_b32_e32 v8, 16, v9
	v_and_b32_e32 v9, 0xffff0000, v9
	v_lshlrev_b32_e32 v14, 16, v29
	v_and_b32_e32 v15, 0xffff0000, v29
	v_pk_add_f32 v[8:9], v[8:9], v[14:15]
	v_lshlrev_b32_e32 v14, 16, v30
	v_cvt_pk_bf16_f32 v29, v8, v9
	v_and_b32_e32 v9, 0xffff0000, v29
	v_lshlrev_b32_e32 v8, 16, v29
	v_mul_f32_e32 v9, v9, v9
	v_fmac_f32_e32 v9, v8, v8
	v_add_f32_e32 v13, v13, v9
	v_lshlrev_b32_e32 v8, 16, v10
	v_and_b32_e32 v9, 0xffff0000, v10
	v_and_b32_e32 v15, 0xffff0000, v30
	v_pk_add_f32 v[8:9], v[8:9], v[14:15]
	v_lshlrev_b32_e32 v10, 16, v31
	v_cvt_pk_bf16_f32 v30, v8, v9
	v_and_b32_e32 v9, 0xffff0000, v30
	v_lshlrev_b32_e32 v8, 16, v30
	v_mul_f32_e32 v9, v9, v9
	v_fmac_f32_e32 v9, v8, v8
	v_add_f32_e32 v13, v9, v13
	v_lshlrev_b32_e32 v8, 16, v11
	v_and_b32_e32 v9, 0xffff0000, v11
	v_and_b32_e32 v11, 0xffff0000, v31
	v_pk_add_f32 v[8:9], v[8:9], v[10:11]
	s_nop 0
	v_cvt_pk_bf16_f32 v31, v8, v9
	v_and_b32_e32 v9, 0xffff0000, v31
	v_lshlrev_b32_e32 v8, 16, v31
	v_mul_f32_e32 v9, v9, v9
	v_fmac_f32_e32 v9, v8, v8
	v_add_f32_e32 v8, v9, v13
	s_nop 1
	v_add_f32_dpp v86, v8, v8 quad_perm:[1,0,3,2] row_mask:0xf bank_mask:0xf
	s_nop 1
	v_add_f32_dpp v86, v86, v86 quad_perm:[2,3,0,1] row_mask:0xf bank_mask:0xf
	s_nop 1
	v_add_f32_dpp v86, v86, v86 row_half_mirror row_mask:0xf bank_mask:0xf
	s_nop 1
	v_add_f32_dpp v86, v86, v86 row_mirror row_mask:0xf bank_mask:0xf
	s_nop 1
	v_add_f32_dpp v86, v86, v86 row_bcast:15 row_mask:0xa bank_mask:0xf
	s_waitcnt lgkmcnt(0)
	s_waitcnt lgkmcnt(0)
	s_waitcnt lgkmcnt(0)
	v_add_u32_e32 v8, 0x50, v16
	v_ashrrev_i32_e32 v9, 31, v8
	v_lshl_add_u64 v[8:9], s[12:13], 0, v[8:9]
	v_lshlrev_b64 v[14:15], 11, v[8:9]
	s_waitcnt lgkmcnt(0)
	v_lshl_add_u64 v[14:15], s[10:11], 0, v[14:15]
	v_lshl_add_u64 v[14:15], s[16:17], 1, v[14:15]
	v_lshl_add_u64 v[14:15], v[14:15], 0, v[146:147]
	flat_store_dwordx4 v[14:15], v[28:31]
	s_and_saveexec_b64 s[18:19], s[98:99]
	s_cbranch_execz .LBB0_788
	v_lshl_add_u64 v[8:9], v[8:9], 4, s[78:79]
	v_lshl_add_u64 v[8:9], s[6:7], 2, v[8:9]
	s_waitcnt lgkmcnt(0)
	v_mov_b32_e32 v10, v86
	flat_store_dword v[8:9], v10
.LBB0_788:
	s_or_b64 exec, exec, s[18:19]
	v_add_u32_e32 v8, 0x2100, v12
	v_add_u32_e32 v9, v26, v8
	s_waitcnt lgkmcnt(0)
	ds_read_b128 v[10:13], v9
	v_lshlrev_b32_e32 v14, 16, v4
	v_and_b32_e32 v15, 0xffff0000, v4
	s_waitcnt lgkmcnt(0)
	v_lshlrev_b32_e32 v20, 16, v10
	v_and_b32_e32 v21, 0xffff0000, v10
	v_pk_add_f32 v[14:15], v[14:15], v[20:21]
	s_nop 0
	v_cvt_pk_bf16_f32 v10, v14, v15
	v_and_b32_e32 v9, 0xffff0000, v10
	v_lshlrev_b32_e32 v4, 16, v10
	v_mul_f32_e32 v9, v9, v9
	v_fmac_f32_e32 v9, v4, v4
	v_lshlrev_b32_e32 v4, 16, v5
	v_and_b32_e32 v5, 0xffff0000, v5
	v_lshlrev_b32_e32 v14, 16, v11
	v_and_b32_e32 v15, 0xffff0000, v11
	v_pk_add_f32 v[4:5], v[4:5], v[14:15]
	v_lshlrev_b32_e32 v14, 16, v12
	v_cvt_pk_bf16_f32 v11, v4, v5
	v_and_b32_e32 v5, 0xffff0000, v11
	v_lshlrev_b32_e32 v4, 16, v11
	v_mul_f32_e32 v5, v5, v5
	v_fmac_f32_e32 v5, v4, v4
	v_add_f32_e32 v9, v9, v5
	v_lshlrev_b32_e32 v4, 16, v6
	v_and_b32_e32 v5, 0xffff0000, v6
	v_and_b32_e32 v15, 0xffff0000, v12
	v_pk_add_f32 v[4:5], v[4:5], v[14:15]
	v_lshlrev_b32_e32 v6, 16, v13
	v_cvt_pk_bf16_f32 v12, v4, v5
	v_and_b32_e32 v5, 0xffff0000, v12
	v_lshlrev_b32_e32 v4, 16, v12
	v_mul_f32_e32 v5, v5, v5
	v_fmac_f32_e32 v5, v4, v4
	v_add_f32_e32 v9, v5, v9
	v_lshlrev_b32_e32 v4, 16, v7
	v_and_b32_e32 v5, 0xffff0000, v7
	v_and_b32_e32 v7, 0xffff0000, v13
	v_pk_add_f32 v[4:5], v[4:5], v[6:7]
	s_nop 0
	v_cvt_pk_bf16_f32 v13, v4, v5
	v_and_b32_e32 v5, 0xffff0000, v13
	v_lshlrev_b32_e32 v4, 16, v13
	v_mul_f32_e32 v5, v5, v5
	v_fmac_f32_e32 v5, v4, v4
	v_add_f32_e32 v4, v5, v9
	s_nop 1
	v_add_f32_dpp v86, v4, v4 quad_perm:[1,0,3,2] row_mask:0xf bank_mask:0xf
	s_nop 1
	v_add_f32_dpp v86, v86, v86 quad_perm:[2,3,0,1] row_mask:0xf bank_mask:0xf
	s_nop 1
	v_add_f32_dpp v86, v86, v86 row_half_mirror row_mask:0xf bank_mask:0xf
	s_nop 1
	v_add_f32_dpp v86, v86, v86 row_mirror row_mask:0xf bank_mask:0xf
	s_nop 1
	v_add_f32_dpp v86, v86, v86 row_bcast:15 row_mask:0xa bank_mask:0xf
	s_waitcnt lgkmcnt(0)
	s_waitcnt lgkmcnt(0)
	s_waitcnt lgkmcnt(0)
	v_add_u32_e32 v4, 0x60, v16
	v_ashrrev_i32_e32 v5, 31, v4
	v_lshl_add_u64 v[4:5], s[12:13], 0, v[4:5]
	v_lshlrev_b64 v[14:15], 11, v[4:5]
	s_waitcnt lgkmcnt(0)
	v_lshl_add_u64 v[14:15], s[10:11], 0, v[14:15]
	v_lshl_add_u64 v[14:15], s[16:17], 1, v[14:15]
	v_lshl_add_u64 v[14:15], v[14:15], 0, v[146:147]
	flat_store_dwordx4 v[14:15], v[10:13]
	s_and_saveexec_b64 s[18:19], s[98:99]
	s_cbranch_execz .LBB0_790
	v_lshl_add_u64 v[4:5], v[4:5], 4, s[78:79]
	v_lshl_add_u64 v[4:5], s[6:7], 2, v[4:5]
	s_waitcnt lgkmcnt(0)
	v_mov_b32_e32 v6, v86
	flat_store_dword v[4:5], v6
; DI unsigned pk2(float a, float b) { f32x2 v = {a, b}; bf16x2_t r = __builtin_convertvector(v, bf16x2_t); return __builtin_bit_cast(unsigned, r); }
; DI float bflo(unsigned w) { return __uint_as_float(w << 16); }
; DI float bfhi(unsigned w) { return __uint_as_float(w & 0xffff0000u); }
;     DI void operator()(gacc_t& acc, int pm, int pn, char* lds, int tid, int wr, int wc, int lane) const {
;     ...
;         for (int ib = 0; ib < 4; ++ib) {
;             __builtin_amdgcn_sched_barrier(0);
;             u32x4 xv[4];
; #pragma unroll
;             for (int u = 0; u < 4; ++u) {
;                 const long row = (long)pm * 256 + (ib * 4 + u) * 16 + wid * 2 + g;
;                 xv[u] = *(const u32x4*)(xold + row * 1024 + pn * 256 + j32 * 8);
;             }
; #pragma unroll
;             for (int u = 0; u < 4; ++u) {
;                 const int rloc = (ib * 4 + u) * 16 + wid * 2 + g;
;                 const long row = (long)pm * 256 + rloc;
;                 const u32x4 a = *(const u32x4*)(lds + rloc * 528 + j32 * 16);
;                 u32x4 w; float ss = 0.f;
; #pragma unroll
;                 for (int e = 0; e < 4; ++e) {
;                     w[e] = pk2(bflo(xv[u][e]) + bflo(a[e]), bfhi(xv[u][e]) + bfhi(a[e]));
;                     const float b0 = bflo(w[e]), b1 = bfhi(w[e]);
;                     ss += b0 * b0 + b1 * b1;
;                 }
;                 *(u32x4*)(xnew + row * 1024 + pn * 256 + j32 * 8) = w;
; #pragma unroll
;                 for (int o = 1; o < 32; o <<= 1) ss += __shfl_xor(ss, o);
;                 if (j32 == 0) ssq[row * 4 + pn] = ss;
;             }
.LBB0_790:
	s_or_b64 exec, exec, s[18:19]
	v_add_u32_e32 v12, 0x2100, v8
	v_add_u32_e32 v4, v26, v12
	s_waitcnt lgkmcnt(0)
	ds_read_b128 v[4:7], v4
	v_lshlrev_b32_e32 v8, 16, v0
	v_and_b32_e32 v9, 0xffff0000, v0
	s_waitcnt lgkmcnt(0)
	v_lshlrev_b32_e32 v10, 16, v4
	v_and_b32_e32 v11, 0xffff0000, v4
	v_pk_add_f32 v[8:9], v[8:9], v[10:11]
	s_nop 0
	v_cvt_pk_bf16_f32 v4, v8, v9
	v_and_b32_e32 v8, 0xffff0000, v4
	v_lshlrev_b32_e32 v0, 16, v4
	v_mul_f32_e32 v10, v8, v8
	v_fmac_f32_e32 v10, v0, v0
	v_lshlrev_b32_e32 v0, 16, v1
	v_and_b32_e32 v1, 0xffff0000, v1
	v_lshlrev_b32_e32 v8, 16, v5
	v_and_b32_e32 v9, 0xffff0000, v5
	v_pk_add_f32 v[0:1], v[0:1], v[8:9]
	v_lshlrev_b32_e32 v8, 16, v6
	v_cvt_pk_bf16_f32 v5, v0, v1
	v_and_b32_e32 v1, 0xffff0000, v5
	v_lshlrev_b32_e32 v0, 16, v5
	v_mul_f32_e32 v1, v1, v1
	v_fmac_f32_e32 v1, v0, v0
	v_add_f32_e32 v10, v10, v1
	v_lshlrev_b32_e32 v0, 16, v2
	v_and_b32_e32 v1, 0xffff0000, v2
	v_and_b32_e32 v9, 0xffff0000, v6
	v_pk_add_f32 v[0:1], v[0:1], v[8:9]
	v_lshlrev_b32_e32 v2, 16, v7
	v_cvt_pk_bf16_f32 v6, v0, v1
	v_and_b32_e32 v1, 0xffff0000, v6
	v_lshlrev_b32_e32 v0, 16, v6
	v_mul_f32_e32 v1, v1, v1
	v_fmac_f32_e32 v1, v0, v0
	v_add_f32_e32 v8, v1, v10
	v_lshlrev_b32_e32 v0, 16, v3
	v_and_b32_e32 v1, 0xffff0000, v3
	v_and_b32_e32 v3, 0xffff0000, v7
	v_pk_add_f32 v[0:1], v[0:1], v[2:3]
	s_nop 0
	v_cvt_pk_bf16_f32 v7, v0, v1
	v_and_b32_e32 v1, 0xffff0000, v7
	v_lshlrev_b32_e32 v0, 16, v7
	v_mul_f32_e32 v1, v1, v1
	v_fmac_f32_e32 v1, v0, v0
	v_add_f32_e32 v0, v1, v8
	s_nop 1
	v_add_f32_dpp v86, v0, v0 quad_perm:[1,0,3,2] row_mask:0xf bank_mask:0xf
	s_nop 1
	v_add_f32_dpp v86, v86, v86 quad_perm:[2,3,0,1] row_mask:0xf bank_mask:0xf
	s_nop 1
	v_add_f32_dpp v86, v86, v86 row_half_mirror row_mask:0xf bank_mask:0xf
	s_nop 1
	v_add_f32_dpp v86, v86, v86 row_mirror row_mask:0xf bank_mask:0xf
	s_nop 1
	v_add_f32_dpp v86, v86, v86 row_bcast:15 row_mask:0xa bank_mask:0xf
	s_waitcnt lgkmcnt(0)
	s_waitcnt lgkmcnt(0)
	s_waitcnt lgkmcnt(0)
	v_add_u32_e32 v0, 0x70, v16
	v_ashrrev_i32_e32 v1, 31, v0
	v_lshl_add_u64 v[0:1], s[12:13], 0, v[0:1]
	v_lshlrev_b64 v[8:9], 11, v[0:1]
	s_waitcnt lgkmcnt(0)
	v_lshl_add_u64 v[8:9], s[10:11], 0, v[8:9]
	v_lshl_add_u64 v[8:9], s[16:17], 1, v[8:9]
	v_lshl_add_u64 v[8:9], v[8:9], 0, v[146:147]
	flat_store_dwordx4 v[8:9], v[4:7]
	s_and_saveexec_b64 s[18:19], s[98:99]
	s_cbranch_execz .LBB0_792
	v_lshl_add_u64 v[0:1], v[0:1], 4, s[78:79]
	v_lshl_add_u64 v[0:1], s[6:7], 2, v[0:1]
	s_waitcnt lgkmcnt(0)
	v_mov_b32_e32 v2, v86
	flat_store_dword v[0:1], v2
.LBB0_792:
	s_or_b64 exec, exec, s[18:19]
	v_add_co_u32_e32 v0, vcc, 0x40000, v18
	v_add_u32_e32 v12, 0x2100, v12
	s_nop 0
	v_addc_co_u32_e32 v1, vcc, 0, v19, vcc
	flat_load_dwordx4 v[28:31], v[0:1]
	v_add_co_u32_e32 v0, vcc, 0x48000, v18
	v_add_u32_e32 v26, v26, v12
	s_nop 0
	v_addc_co_u32_e32 v1, vcc, 0, v19, vcc
	flat_load_dwordx4 v[8:11], v[0:1]
	v_add_co_u32_e32 v0, vcc, 0x50000, v18
	ds_read_b128 v[12:15], v26
	s_nop 0
	v_addc_co_u32_e32 v1, vcc, 0, v19, vcc
	flat_load_dwordx4 v[4:7], v[0:1]
	v_add_co_u32_e32 v0, vcc, 0x58000, v18
	s_waitcnt lgkmcnt(0)
	v_lshlrev_b32_e32 v34, 16, v12
	v_addc_co_u32_e32 v1, vcc, 0, v19, vcc
	flat_load_dwordx4 v[0:3], v[0:1]
	v_and_b32_e32 v35, 0xffff0000, v12
	v_add_u32_e32 v20, 0x80, v16
	v_ashrrev_i32_e32 v21, 31, v20
	v_lshl_add_u64 v[20:21], s[12:13], 0, v[20:21]
	s_waitcnt vmcnt(0)
	v_lshlrev_b32_e32 v32, 16, v28
	v_and_b32_e32 v33, 0xffff0000, v28
	v_pk_add_f32 v[32:33], v[32:33], v[34:35]
	s_nop 0
	v_cvt_pk_bf16_f32 v12, v32, v33
	v_and_b32_e32 v28, 0xffff0000, v12
	v_mul_f32_e32 v34, v28, v28
	v_lshlrev_b32_e32 v28, 16, v29
	v_and_b32_e32 v29, 0xffff0000, v29
	v_lshlrev_b32_e32 v32, 16, v13
	v_and_b32_e32 v33, 0xffff0000, v13
	v_pk_add_f32 v[28:29], v[28:29], v[32:33]
	v_lshlrev_b32_e32 v27, 16, v12
	v_cvt_pk_bf16_f32 v13, v28, v29
	v_and_b32_e32 v28, 0xffff0000, v13
	v_fmac_f32_e32 v34, v27, v27
	v_lshlrev_b32_e32 v27, 16, v13
	v_mul_f32_e32 v28, v28, v28
	v_fmac_f32_e32 v28, v27, v27
	v_add_f32_e32 v27, v34, v28
	v_lshlrev_b32_e32 v28, 16, v30
	v_and_b32_e32 v29, 0xffff0000, v30
	v_lshlrev_b32_e32 v32, 16, v14
	v_and_b32_e32 v33, 0xffff0000, v14
	v_pk_add_f32 v[28:29], v[28:29], v[32:33]
	v_lshlrev_b32_e32 v30, 16, v15
	v_cvt_pk_bf16_f32 v14, v28, v29
	v_and_b32_e32 v29, 0xffff0000, v14
	v_lshlrev_b32_e32 v28, 16, v14
	v_mul_f32_e32 v29, v29, v29
	v_fmac_f32_e32 v29, v28, v28
	v_add_f32_e32 v27, v29, v27
	v_lshlrev_b32_e32 v28, 16, v31
	v_and_b32_e32 v29, 0xffff0000, v31
	v_and_b32_e32 v31, 0xffff0000, v15
	v_pk_add_f32 v[28:29], v[28:29], v[30:31]
	s_nop 0
	v_cvt_pk_bf16_f32 v15, v28, v29
	v_and_b32_e32 v29, 0xffff0000, v15
	v_lshlrev_b32_e32 v28, 16, v15
	v_mul_f32_e32 v29, v29, v29
	v_fmac_f32_e32 v29, v28, v28
	v_add_f32_e32 v27, v29, v27
	v_lshlrev_b64 v[28:29], 11, v[20:21]
	v_lshl_add_u64 v[28:29], s[10:11], 0, v[28:29]
	v_lshl_add_u64 v[28:29], s[16:17], 1, v[28:29]
	v_lshl_add_u64 v[28:29], v[28:29], 0, v[146:147]
	flat_store_dwordx4 v[28:29], v[12:15]
	s_nop 1
	v_add_f32_dpp v86, v27, v27 quad_perm:[1,0,3,2] row_mask:0xf bank_mask:0xf
	s_nop 1
	v_add_f32_dpp v86, v86, v86 quad_perm:[2,3,0,1] row_mask:0xf bank_mask:0xf
	s_nop 1
	v_add_f32_dpp v86, v86, v86 row_half_mirror row_mask:0xf bank_mask:0xf
	s_nop 1
	v_add_f32_dpp v86, v86, v86 row_mirror row_mask:0xf bank_mask:0xf
	s_nop 1
	v_add_f32_dpp v86, v86, v86 row_bcast:15 row_mask:0xa bank_mask:0xf
	s_waitcnt lgkmcnt(0)
	s_waitcnt lgkmcnt(0)
	s_waitcnt lgkmcnt(0)
	s_waitcnt lgkmcnt(0)
	s_and_saveexec_b64 s[18:19], s[98:99]
	s_cbranch_execz .LBB0_794
	v_lshl_add_u64 v[14:15], v[20:21], 4, s[78:79]
	v_lshl_add_u64 v[14:15], s[6:7], 2, v[14:15]
	s_waitcnt lgkmcnt(0)
	v_mov_b32_e32 v12, v86
	flat_store_dword v[14:15], v12
; DI unsigned pk2(float a, float b) { f32x2 v = {a, b}; bf16x2_t r = __builtin_convertvector(v, bf16x2_t); return __builtin_bit_cast(unsigned, r); }
; DI float bflo(unsigned w) { return __uint_as_float(w << 16); }
; DI float bfhi(unsigned w) { return __uint_as_float(w & 0xffff0000u); }
;     DI void operator()(gacc_t& acc, int pm, int pn, char* lds, int tid, int wr, int wc, int lane) const {
;     ...
;             for (int u = 0; u < 4; ++u) {
;                 const int rloc = (ib * 4 + u) * 16 + wid * 2 + g;
;                 const long row = (long)pm * 256 + rloc;
;                 const u32x4 a = *(const u32x4*)(lds + rloc * 528 + j32 * 16);
;                 u32x4 w; float ss = 0.f;
; #pragma unroll
;                 for (int e = 0; e < 4; ++e) {
;                     w[e] = pk2(bflo(xv[u][e]) + bflo(a[e]), bfhi(xv[u][e]) + bfhi(a[e]));
;                     const float b0 = bflo(w[e]), b1 = bfhi(w[e]);
;                     ss += b0 * b0 + b1 * b1;
;                 }
;                 *(u32x4*)(xnew + row * 1024 + pn * 256 + j32 * 8) = w;
; #pragma unroll
;                 for (int o = 1; o < 32; o <<= 1) ss += __shfl_xor(ss, o);
;                 if (j32 == 0) ssq[row * 4 + pn] = ss;
;             }
.LBB0_794:
	s_or_b64 exec, exec, s[18:19]
	s_waitcnt lgkmcnt(0)
	ds_read_b128 v[12:15], v26 offset:8448
	v_lshlrev_b32_e32 v20, 16, v8
	v_and_b32_e32 v21, 0xffff0000, v8
	s_waitcnt lgkmcnt(0)
	v_lshlrev_b32_e32 v28, 16, v12
	v_and_b32_e32 v29, 0xffff0000, v12
	v_pk_add_f32 v[20:21], v[20:21], v[28:29]
	s_nop 0
	v_cvt_pk_bf16_f32 v12, v20, v21
	v_and_b32_e32 v20, 0xffff0000, v12
	v_lshlrev_b32_e32 v8, 16, v12
	v_mul_f32_e32 v27, v20, v20
	v_fmac_f32_e32 v27, v8, v8
	v_lshlrev_b32_e32 v8, 16, v9
	v_and_b32_e32 v9, 0xffff0000, v9
	v_lshlrev_b32_e32 v20, 16, v13
	v_and_b32_e32 v21, 0xffff0000, v13
	v_pk_add_f32 v[8:9], v[8:9], v[20:21]
	v_lshlrev_b32_e32 v20, 16, v14
	v_cvt_pk_bf16_f32 v13, v8, v9
	v_and_b32_e32 v9, 0xffff0000, v13
	v_lshlrev_b32_e32 v8, 16, v13
	v_mul_f32_e32 v9, v9, v9
	v_fmac_f32_e32 v9, v8, v8
	v_add_f32_e32 v27, v27, v9
	v_lshlrev_b32_e32 v8, 16, v10
	v_and_b32_e32 v9, 0xffff0000, v10
	v_and_b32_e32 v21, 0xffff0000, v14
	v_pk_add_f32 v[8:9], v[8:9], v[20:21]
	v_lshlrev_b32_e32 v10, 16, v15
	v_cvt_pk_bf16_f32 v14, v8, v9
	v_and_b32_e32 v9, 0xffff0000, v14
	v_lshlrev_b32_e32 v8, 16, v14
	v_mul_f32_e32 v9, v9, v9
	v_fmac_f32_e32 v9, v8, v8
	v_add_f32_e32 v20, v9, v27
	v_lshlrev_b32_e32 v8, 16, v11
	v_and_b32_e32 v9, 0xffff0000, v11
	v_and_b32_e32 v11, 0xffff0000, v15
	v_pk_add_f32 v[8:9], v[8:9], v[10:11]
	s_nop 0
	v_cvt_pk_bf16_f32 v15, v8, v9
	v_and_b32_e32 v9, 0xffff0000, v15
	v_lshlrev_b32_e32 v8, 16, v15
	v_mul_f32_e32 v9, v9, v9
	v_fmac_f32_e32 v9, v8, v8
	v_add_f32_e32 v8, v9, v20
	s_nop 1
	v_add_f32_dpp v86, v8, v8 quad_perm:[1,0,3,2] row_mask:0xf bank_mask:0xf
	s_nop 1
	v_add_f32_dpp v86, v86, v86 quad_perm:[2,3,0,1] row_mask:0xf bank_mask:0xf
	s_nop 1
	v_add_f32_dpp v86, v86, v86 row_half_mirror row_mask:0xf bank_mask:0xf
	s_nop 1
	v_add_f32_dpp v86, v86, v86 row_mirror row_mask:0xf bank_mask:0xf
	s_nop 1
	v_add_f32_dpp v86, v86, v86 row_bcast:15 row_mask:0xa bank_mask:0xf
	s_waitcnt lgkmcnt(0)
	s_waitcnt lgkmcnt(0)
	s_waitcnt lgkmcnt(0)
	v_add_u32_e32 v8, 0x90, v16
	v_ashrrev_i32_e32 v9, 31, v8
	v_lshl_add_u64 v[8:9], s[12:13], 0, v[8:9]
	v_lshlrev_b64 v[20:21], 11, v[8:9]
	s_waitcnt lgkmcnt(0)
	v_lshl_add_u64 v[20:21], s[10:11], 0, v[20:21]
	v_lshl_add_u64 v[20:21], s[16:17], 1, v[20:21]
	v_lshl_add_u64 v[20:21], v[20:21], 0, v[146:147]
	flat_store_dwordx4 v[20:21], v[12:15]
	s_and_saveexec_b64 s[18:19], s[98:99]
	s_cbranch_execz .LBB0_796
	v_lshl_add_u64 v[8:9], v[8:9], 4, s[78:79]
	v_lshl_add_u64 v[8:9], s[6:7], 2, v[8:9]
	s_waitcnt lgkmcnt(0)
	v_mov_b32_e32 v10, v86
	flat_store_dword v[8:9], v10
.LBB0_796:
	s_or_b64 exec, exec, s[18:19]
	s_waitcnt lgkmcnt(0)
	ds_read_b128 v[8:11], v26 offset:16896
	v_lshlrev_b32_e32 v12, 16, v4
	v_and_b32_e32 v13, 0xffff0000, v4
	s_waitcnt lgkmcnt(0)
	v_lshlrev_b32_e32 v14, 16, v8
	v_and_b32_e32 v15, 0xffff0000, v8
	v_pk_add_f32 v[12:13], v[12:13], v[14:15]
	s_nop 0
	v_cvt_pk_bf16_f32 v8, v12, v13
	v_and_b32_e32 v12, 0xffff0000, v8
	v_lshlrev_b32_e32 v4, 16, v8
	v_mul_f32_e32 v14, v12, v12
	v_fmac_f32_e32 v14, v4, v4
	v_lshlrev_b32_e32 v4, 16, v5
	v_and_b32_e32 v5, 0xffff0000, v5
	v_lshlrev_b32_e32 v12, 16, v9
	v_and_b32_e32 v13, 0xffff0000, v9
	v_pk_add_f32 v[4:5], v[4:5], v[12:13]
	v_lshlrev_b32_e32 v12, 16, v10
	v_cvt_pk_bf16_f32 v9, v4, v5
	v_and_b32_e32 v5, 0xffff0000, v9
	v_lshlrev_b32_e32 v4, 16, v9
	v_mul_f32_e32 v5, v5, v5
	v_fmac_f32_e32 v5, v4, v4
	v_add_f32_e32 v14, v14, v5
	v_lshlrev_b32_e32 v4, 16, v6
	v_and_b32_e32 v5, 0xffff0000, v6
	v_and_b32_e32 v13, 0xffff0000, v10
	v_pk_add_f32 v[4:5], v[4:5], v[12:13]
	v_lshlrev_b32_e32 v6, 16, v11
	v_cvt_pk_bf16_f32 v10, v4, v5
	v_and_b32_e32 v5, 0xffff0000, v10
	v_lshlrev_b32_e32 v4, 16, v10
	v_mul_f32_e32 v5, v5, v5
	v_fmac_f32_e32 v5, v4, v4
	v_add_f32_e32 v12, v5, v14
	v_lshlrev_b32_e32 v4, 16, v7
	v_and_b32_e32 v5, 0xffff0000, v7
	v_and_b32_e32 v7, 0xffff0000, v11
	v_pk_add_f32 v[4:5], v[4:5], v[6:7]
	s_nop 0
	v_cvt_pk_bf16_f32 v11, v4, v5
	v_and_b32_e32 v5, 0xffff0000, v11
	v_lshlrev_b32_e32 v4, 16, v11
	v_mul_f32_e32 v5, v5, v5
	v_fmac_f32_e32 v5, v4, v4
	v_add_f32_e32 v4, v5, v12
	s_nop 1
	v_add_f32_dpp v86, v4, v4 quad_perm:[1,0,3,2] row_mask:0xf bank_mask:0xf
	s_nop 1
	v_add_f32_dpp v86, v86, v86 quad_perm:[2,3,0,1] row_mask:0xf bank_mask:0xf
	s_nop 1
	v_add_f32_dpp v86, v86, v86 row_half_mirror row_mask:0xf bank_mask:0xf
	s_nop 1
	v_add_f32_dpp v86, v86, v86 row_mirror row_mask:0xf bank_mask:0xf
	s_nop 1
	v_add_f32_dpp v86, v86, v86 row_bcast:15 row_mask:0xa bank_mask:0xf
	s_waitcnt lgkmcnt(0)
	s_waitcnt lgkmcnt(0)
	s_waitcnt lgkmcnt(0)
	v_add_u32_e32 v4, 0xa0, v16
	v_ashrrev_i32_e32 v5, 31, v4
	v_lshl_add_u64 v[4:5], s[12:13], 0, v[4:5]
	v_lshlrev_b64 v[12:13], 11, v[4:5]
	s_waitcnt lgkmcnt(0)
	v_lshl_add_u64 v[12:13], s[10:11], 0, v[12:13]
	v_lshl_add_u64 v[12:13], s[16:17], 1, v[12:13]
	v_lshl_add_u64 v[12:13], v[12:13], 0, v[146:147]
	flat_store_dwordx4 v[12:13], v[8:11]
	s_and_saveexec_b64 s[18:19], s[98:99]
	s_cbranch_execz .LBB0_798
	v_lshl_add_u64 v[4:5], v[4:5], 4, s[78:79]
	v_lshl_add_u64 v[4:5], s[6:7], 2, v[4:5]
	s_waitcnt lgkmcnt(0)
	v_mov_b32_e32 v6, v86
	flat_store_dword v[4:5], v6
; DI unsigned pk2(float a, float b) { f32x2 v = {a, b}; bf16x2_t r = __builtin_convertvector(v, bf16x2_t); return __builtin_bit_cast(unsigned, r); }
; DI float bflo(unsigned w) { return __uint_as_float(w << 16); }
; DI float bfhi(unsigned w) { return __uint_as_float(w & 0xffff0000u); }
;     DI void operator()(gacc_t& acc, int pm, int pn, char* lds, int tid, int wr, int wc, int lane) const {
;     ...
;         for (int ib = 0; ib < 4; ++ib) {
;             __builtin_amdgcn_sched_barrier(0);
;             u32x4 xv[4];
; #pragma unroll
;             for (int u = 0; u < 4; ++u) {
;                 const long row = (long)pm * 256 + (ib * 4 + u) * 16 + wid * 2 + g;
;                 xv[u] = *(const u32x4*)(xold + row * 1024 + pn * 256 + j32 * 8);
;             }
; #pragma unroll
;             for (int u = 0; u < 4; ++u) {
;                 const int rloc = (ib * 4 + u) * 16 + wid * 2 + g;
;                 const long row = (long)pm * 256 + rloc;
;                 const u32x4 a = *(const u32x4*)(lds + rloc * 528 + j32 * 16);
;                 u32x4 w; float ss = 0.f;
; #pragma unroll
;                 for (int e = 0; e < 4; ++e) {
;                     w[e] = pk2(bflo(xv[u][e]) + bflo(a[e]), bfhi(xv[u][e]) + bfhi(a[e]));
;                     const float b0 = bflo(w[e]), b1 = bfhi(w[e]);
;                     ss += b0 * b0 + b1 * b1;
;                 }
;                 *(u32x4*)(xnew + row * 1024 + pn * 256 + j32 * 8) = w;
; #pragma unroll
;                 for (int o = 1; o < 32; o <<= 1) ss += __shfl_xor(ss, o);
;                 if (j32 == 0) ssq[row * 4 + pn] = ss;
;             }
.LBB0_798:
	s_or_b64 exec, exec, s[18:19]
	s_waitcnt lgkmcnt(0)
	ds_read_b128 v[4:7], v26 offset:25344
	v_lshlrev_b32_e32 v8, 16, v0
	v_and_b32_e32 v9, 0xffff0000, v0
	s_waitcnt lgkmcnt(0)
	v_lshlrev_b32_e32 v10, 16, v4
	v_and_b32_e32 v11, 0xffff0000, v4
	v_pk_add_f32 v[8:9], v[8:9], v[10:11]
	s_nop 0
	v_cvt_pk_bf16_f32 v4, v8, v9
	v_and_b32_e32 v8, 0xffff0000, v4
	v_lshlrev_b32_e32 v0, 16, v4
	v_mul_f32_e32 v10, v8, v8
	v_fmac_f32_e32 v10, v0, v0
	v_lshlrev_b32_e32 v0, 16, v1
	v_and_b32_e32 v1, 0xffff0000, v1
	v_lshlrev_b32_e32 v8, 16, v5
	v_and_b32_e32 v9, 0xffff0000, v5
	v_pk_add_f32 v[0:1], v[0:1], v[8:9]
	v_lshlrev_b32_e32 v8, 16, v6
	v_cvt_pk_bf16_f32 v5, v0, v1
	v_and_b32_e32 v1, 0xffff0000, v5
	v_lshlrev_b32_e32 v0, 16, v5
	v_mul_f32_e32 v1, v1, v1
	v_fmac_f32_e32 v1, v0, v0
	v_add_f32_e32 v10, v10, v1
	v_lshlrev_b32_e32 v0, 16, v2
	v_and_b32_e32 v1, 0xffff0000, v2
	v_and_b32_e32 v9, 0xffff0000, v6
	v_pk_add_f32 v[0:1], v[0:1], v[8:9]
	v_lshlrev_b32_e32 v2, 16, v7
	v_cvt_pk_bf16_f32 v6, v0, v1
	v_and_b32_e32 v1, 0xffff0000, v6
	v_lshlrev_b32_e32 v0, 16, v6
	v_mul_f32_e32 v1, v1, v1
	v_fmac_f32_e32 v1, v0, v0
	v_add_f32_e32 v8, v1, v10
	v_lshlrev_b32_e32 v0, 16, v3
	v_and_b32_e32 v1, 0xffff0000, v3
	v_and_b32_e32 v3, 0xffff0000, v7
	v_pk_add_f32 v[0:1], v[0:1], v[2:3]
	s_nop 0
	v_cvt_pk_bf16_f32 v7, v0, v1
	v_and_b32_e32 v1, 0xffff0000, v7
	v_lshlrev_b32_e32 v0, 16, v7
	v_mul_f32_e32 v1, v1, v1
	v_fmac_f32_e32 v1, v0, v0
	v_add_f32_e32 v0, v1, v8
	s_nop 1
	v_add_f32_dpp v86, v0, v0 quad_perm:[1,0,3,2] row_mask:0xf bank_mask:0xf
	s_nop 1
	v_add_f32_dpp v86, v86, v86 quad_perm:[2,3,0,1] row_mask:0xf bank_mask:0xf
	s_nop 1
	v_add_f32_dpp v86, v86, v86 row_half_mirror row_mask:0xf bank_mask:0xf
	s_nop 1
	v_add_f32_dpp v86, v86, v86 row_mirror row_mask:0xf bank_mask:0xf
	s_nop 1
	v_add_f32_dpp v86, v86, v86 row_bcast:15 row_mask:0xa bank_mask:0xf
	s_waitcnt lgkmcnt(0)
	s_waitcnt lgkmcnt(0)
	s_waitcnt lgkmcnt(0)
	v_add_u32_e32 v0, 0xb0, v16
	v_ashrrev_i32_e32 v1, 31, v0
	v_lshl_add_u64 v[0:1], s[12:13], 0, v[0:1]
	v_lshlrev_b64 v[8:9], 11, v[0:1]
	s_waitcnt lgkmcnt(0)
	v_lshl_add_u64 v[8:9], s[10:11], 0, v[8:9]
	v_lshl_add_u64 v[8:9], s[16:17], 1, v[8:9]
	v_lshl_add_u64 v[8:9], v[8:9], 0, v[146:147]
	flat_store_dwordx4 v[8:9], v[4:7]
	s_and_saveexec_b64 s[18:19], s[98:99]
	s_cbranch_execz .LBB0_800
	v_lshl_add_u64 v[0:1], v[0:1], 4, s[78:79]
	v_lshl_add_u64 v[0:1], s[6:7], 2, v[0:1]
	s_waitcnt lgkmcnt(0)
	v_mov_b32_e32 v2, v86
	flat_store_dword v[0:1], v2
.LBB0_800:
	s_or_b64 exec, exec, s[18:19]
	v_add_co_u32_e32 v0, vcc, 0x60000, v18
	ds_read_b128 v[28:31], v26 offset:33792
	s_nop 0
	v_addc_co_u32_e32 v1, vcc, 0, v19, vcc
	flat_load_dwordx4 v[12:15], v[0:1]
	v_add_co_u32_e32 v0, vcc, 0x68000, v18
	s_waitcnt lgkmcnt(0)
	v_lshlrev_b32_e32 v32, 16, v28
	v_addc_co_u32_e32 v1, vcc, 0, v19, vcc
	flat_load_dwordx4 v[8:11], v[0:1]
	v_add_co_u32_e32 v0, vcc, 0x70000, v18
	v_and_b32_e32 v33, 0xffff0000, v28
	s_nop 0
	v_addc_co_u32_e32 v1, vcc, 0, v19, vcc
	flat_load_dwordx4 v[4:7], v[0:1]
	v_add_co_u32_e32 v0, vcc, 0x78000, v18
	v_lshlrev_b32_e32 v28, 16, v29
	s_nop 0
	v_addc_co_u32_e32 v1, vcc, 0, v19, vcc
	flat_load_dwordx4 v[0:3], v[0:1]
	v_and_b32_e32 v29, 0xffff0000, v29
	v_add_u32_e32 v18, 0xc0, v16
	v_ashrrev_i32_e32 v19, 31, v18
	v_lshl_add_u64 v[18:19], s[12:13], 0, v[18:19]
	s_waitcnt vmcnt(0)
	v_lshlrev_b32_e32 v20, 16, v12
	v_and_b32_e32 v21, 0xffff0000, v12
	v_pk_add_f32 v[20:21], v[20:21], v[32:33]
	s_nop 0
	v_cvt_pk_bf16_f32 v12, v20, v21
	v_and_b32_e32 v21, 0xffff0000, v12
	v_lshlrev_b32_e32 v20, 16, v12
	v_mul_f32_e32 v27, v21, v21
	v_fmac_f32_e32 v27, v20, v20
	v_lshlrev_b32_e32 v20, 16, v13
	v_and_b32_e32 v21, 0xffff0000, v13
	v_pk_add_f32 v[20:21], v[20:21], v[28:29]
	v_lshlrev_b32_e32 v28, 16, v30
	v_cvt_pk_bf16_f32 v13, v20, v21
	v_and_b32_e32 v21, 0xffff0000, v13
	v_lshlrev_b32_e32 v20, 16, v13
	v_mul_f32_e32 v21, v21, v21
	v_fmac_f32_e32 v21, v20, v20
	v_add_f32_e32 v27, v27, v21
	v_lshlrev_b32_e32 v20, 16, v14
	v_and_b32_e32 v21, 0xffff0000, v14
	v_and_b32_e32 v29, 0xffff0000, v30
	v_pk_add_f32 v[20:21], v[20:21], v[28:29]
	v_lshlrev_b32_e32 v28, 16, v31
	v_cvt_pk_bf16_f32 v14, v20, v21
	v_and_b32_e32 v21, 0xffff0000, v14
	v_lshlrev_b32_e32 v20, 16, v14
	v_mul_f32_e32 v21, v21, v21
	v_fmac_f32_e32 v21, v20, v20
	v_add_f32_e32 v27, v21, v27
	v_lshlrev_b32_e32 v20, 16, v15
	v_and_b32_e32 v21, 0xffff0000, v15
	v_and_b32_e32 v29, 0xffff0000, v31
	v_pk_add_f32 v[20:21], v[20:21], v[28:29]
	s_nop 0
	v_cvt_pk_bf16_f32 v15, v20, v21
	v_and_b32_e32 v21, 0xffff0000, v15
	v_lshlrev_b32_e32 v20, 16, v15
	v_mul_f32_e32 v21, v21, v21
	v_fmac_f32_e32 v21, v20, v20
	v_add_f32_e32 v27, v21, v27
	v_lshlrev_b64 v[20:21], 11, v[18:19]
	v_lshl_add_u64 v[20:21], s[10:11], 0, v[20:21]
	v_lshl_add_u64 v[20:21], s[16:17], 1, v[20:21]
	v_lshl_add_u64 v[20:21], v[20:21], 0, v[146:147]
	flat_store_dwordx4 v[20:21], v[12:15]
	s_nop 1
	v_add_f32_dpp v86, v27, v27 quad_perm:[1,0,3,2] row_mask:0xf bank_mask:0xf
	s_nop 1
	v_add_f32_dpp v86, v86, v86 quad_perm:[2,3,0,1] row_mask:0xf bank_mask:0xf
	s_nop 1
	v_add_f32_dpp v86, v86, v86 row_half_mirror row_mask:0xf bank_mask:0xf
	s_nop 1
	v_add_f32_dpp v86, v86, v86 row_mirror row_mask:0xf bank_mask:0xf
	s_nop 1
	v_add_f32_dpp v86, v86, v86 row_bcast:15 row_mask:0xa bank_mask:0xf
	s_waitcnt lgkmcnt(0)
	s_waitcnt lgkmcnt(0)
	s_waitcnt lgkmcnt(0)
	s_waitcnt lgkmcnt(0)
	s_and_saveexec_b64 s[18:19], s[98:99]
	s_cbranch_execz .LBB0_802
	v_lshl_add_u64 v[14:15], v[18:19], 4, s[78:79]
	v_lshl_add_u64 v[14:15], s[6:7], 2, v[14:15]
	s_waitcnt lgkmcnt(0)
	v_mov_b32_e32 v12, v86
	flat_store_dword v[14:15], v12
; DI unsigned pk2(float a, float b) { f32x2 v = {a, b}; bf16x2_t r = __builtin_convertvector(v, bf16x2_t); return __builtin_bit_cast(unsigned, r); }
; DI float bflo(unsigned w) { return __uint_as_float(w << 16); }
; DI float bfhi(unsigned w) { return __uint_as_float(w & 0xffff0000u); }
;     DI void operator()(gacc_t& acc, int pm, int pn, char* lds, int tid, int wr, int wc, int lane) const {
;     ...
;             for (int u = 0; u < 4; ++u) {
;                 const int rloc = (ib * 4 + u) * 16 + wid * 2 + g;
;                 const long row = (long)pm * 256 + rloc;
;                 const u32x4 a = *(const u32x4*)(lds + rloc * 528 + j32 * 16);
;                 u32x4 w; float ss = 0.f;
; #pragma unroll
;                 for (int e = 0; e < 4; ++e) {
;                     w[e] = pk2(bflo(xv[u][e]) + bflo(a[e]), bfhi(xv[u][e]) + bfhi(a[e]));
;                     const float b0 = bflo(w[e]), b1 = bfhi(w[e]);
;                     ss += b0 * b0 + b1 * b1;
;                 }
;                 *(u32x4*)(xnew + row * 1024 + pn * 256 + j32 * 8) = w;
; #pragma unroll
;                 for (int o = 1; o < 32; o <<= 1) ss += __shfl_xor(ss, o);
;                 if (j32 == 0) ssq[row * 4 + pn] = ss;
;             }
.LBB0_802:
	s_or_b64 exec, exec, s[18:19]
	s_waitcnt lgkmcnt(0)
	ds_read_b128 v[12:15], v26 offset:42240
	v_lshlrev_b32_e32 v18, 16, v8
	v_and_b32_e32 v19, 0xffff0000, v8
	s_waitcnt lgkmcnt(0)
	v_lshlrev_b32_e32 v20, 16, v12
	v_and_b32_e32 v21, 0xffff0000, v12
	v_pk_add_f32 v[18:19], v[18:19], v[20:21]
	s_nop 0
	v_cvt_pk_bf16_f32 v12, v18, v19
	v_and_b32_e32 v18, 0xffff0000, v12
	v_lshlrev_b32_e32 v8, 16, v12
	v_mul_f32_e32 v20, v18, v18
	v_fmac_f32_e32 v20, v8, v8
	v_lshlrev_b32_e32 v8, 16, v9
	v_and_b32_e32 v9, 0xffff0000, v9
	v_lshlrev_b32_e32 v18, 16, v13
	v_and_b32_e32 v19, 0xffff0000, v13
	v_pk_add_f32 v[8:9], v[8:9], v[18:19]
	v_lshlrev_b32_e32 v18, 16, v14
	v_cvt_pk_bf16_f32 v13, v8, v9
	v_and_b32_e32 v9, 0xffff0000, v13
	v_lshlrev_b32_e32 v8, 16, v13
	v_mul_f32_e32 v9, v9, v9
	v_fmac_f32_e32 v9, v8, v8
	v_add_f32_e32 v20, v20, v9
	v_lshlrev_b32_e32 v8, 16, v10
	v_and_b32_e32 v9, 0xffff0000, v10
	v_and_b32_e32 v19, 0xffff0000, v14
	v_pk_add_f32 v[8:9], v[8:9], v[18:19]
	v_lshlrev_b32_e32 v10, 16, v15
	v_cvt_pk_bf16_f32 v14, v8, v9
	v_and_b32_e32 v9, 0xffff0000, v14
	v_lshlrev_b32_e32 v8, 16, v14
	v_mul_f32_e32 v9, v9, v9
	v_fmac_f32_e32 v9, v8, v8
	v_add_f32_e32 v18, v9, v20
	v_lshlrev_b32_e32 v8, 16, v11
	v_and_b32_e32 v9, 0xffff0000, v11
	v_and_b32_e32 v11, 0xffff0000, v15
	v_pk_add_f32 v[8:9], v[8:9], v[10:11]
	s_nop 0
	v_cvt_pk_bf16_f32 v15, v8, v9
	v_and_b32_e32 v9, 0xffff0000, v15
	v_lshlrev_b32_e32 v8, 16, v15
	v_mul_f32_e32 v9, v9, v9
	v_fmac_f32_e32 v9, v8, v8
	v_add_f32_e32 v8, v9, v18
	s_nop 1
	v_add_f32_dpp v86, v8, v8 quad_perm:[1,0,3,2] row_mask:0xf bank_mask:0xf
	s_nop 1
	v_add_f32_dpp v86, v86, v86 quad_perm:[2,3,0,1] row_mask:0xf bank_mask:0xf
	s_nop 1
	v_add_f32_dpp v86, v86, v86 row_half_mirror row_mask:0xf bank_mask:0xf
	s_nop 1
	v_add_f32_dpp v86, v86, v86 row_mirror row_mask:0xf bank_mask:0xf
	s_nop 1
	v_add_f32_dpp v86, v86, v86 row_bcast:15 row_mask:0xa bank_mask:0xf
	s_waitcnt lgkmcnt(0)
	s_waitcnt lgkmcnt(0)
	s_waitcnt lgkmcnt(0)
	v_add_u32_e32 v8, 0xd0, v16
	v_ashrrev_i32_e32 v9, 31, v8
	v_lshl_add_u64 v[8:9], s[12:13], 0, v[8:9]
	v_lshlrev_b64 v[18:19], 11, v[8:9]
	s_waitcnt lgkmcnt(0)
	v_lshl_add_u64 v[18:19], s[10:11], 0, v[18:19]
	v_lshl_add_u64 v[18:19], s[16:17], 1, v[18:19]
	v_lshl_add_u64 v[18:19], v[18:19], 0, v[146:147]
	flat_store_dwordx4 v[18:19], v[12:15]
	s_and_saveexec_b64 s[18:19], s[98:99]
	s_cbranch_execz .LBB0_804
	v_lshl_add_u64 v[8:9], v[8:9], 4, s[78:79]
	v_lshl_add_u64 v[8:9], s[6:7], 2, v[8:9]
	s_waitcnt lgkmcnt(0)
	v_mov_b32_e32 v10, v86
	flat_store_dword v[8:9], v10
; DI unsigned pk2(float a, float b) { f32x2 v = {a, b}; bf16x2_t r = __builtin_convertvector(v, bf16x2_t); return __builtin_bit_cast(unsigned, r); }
; DI float bflo(unsigned w) { return __uint_as_float(w << 16); }
; DI float bfhi(unsigned w) { return __uint_as_float(w & 0xffff0000u); }
;     DI void operator()(gacc_t& acc, int pm, int pn, char* lds, int tid, int wr, int wc, int lane) const {
;     ...
;             for (int u = 0; u < 4; ++u) {
;                 const int rloc = (ib * 4 + u) * 16 + wid * 2 + g;
;                 const long row = (long)pm * 256 + rloc;
;                 const u32x4 a = *(const u32x4*)(lds + rloc * 528 + j32 * 16);
;                 u32x4 w; float ss = 0.f;
; #pragma unroll
;                 for (int e = 0; e < 4; ++e) {
;                     w[e] = pk2(bflo(xv[u][e]) + bflo(a[e]), bfhi(xv[u][e]) + bfhi(a[e]));
;                     const float b0 = bflo(w[e]), b1 = bfhi(w[e]);
;                     ss += b0 * b0 + b1 * b1;
;                 }
;                 *(u32x4*)(xnew + row * 1024 + pn * 256 + j32 * 8) = w;
; #pragma unroll
;                 for (int o = 1; o < 32; o <<= 1) ss += __shfl_xor(ss, o);
;                 if (j32 == 0) ssq[row * 4 + pn] = ss;
;             }
;         }
;         __syncthreads();
.LBB0_804:
	s_or_b64 exec, exec, s[18:19]
	s_waitcnt lgkmcnt(0)
	ds_read_b128 v[8:11], v26 offset:50688
	v_lshlrev_b32_e32 v12, 16, v4
	v_and_b32_e32 v13, 0xffff0000, v4
	s_waitcnt lgkmcnt(0)
	v_lshlrev_b32_e32 v14, 16, v8
	v_and_b32_e32 v15, 0xffff0000, v8
	v_pk_add_f32 v[12:13], v[12:13], v[14:15]
	s_nop 0
	v_cvt_pk_bf16_f32 v8, v12, v13
	v_and_b32_e32 v12, 0xffff0000, v8
	v_lshlrev_b32_e32 v4, 16, v8
	v_mul_f32_e32 v14, v12, v12
	v_fmac_f32_e32 v14, v4, v4
	v_lshlrev_b32_e32 v4, 16, v5
	v_and_b32_e32 v5, 0xffff0000, v5
	v_lshlrev_b32_e32 v12, 16, v9
	v_and_b32_e32 v13, 0xffff0000, v9
	v_pk_add_f32 v[4:5], v[4:5], v[12:13]
	v_lshlrev_b32_e32 v12, 16, v10
	v_cvt_pk_bf16_f32 v9, v4, v5
	v_and_b32_e32 v5, 0xffff0000, v9
	v_lshlrev_b32_e32 v4, 16, v9
	v_mul_f32_e32 v5, v5, v5
	v_fmac_f32_e32 v5, v4, v4
	v_add_f32_e32 v14, v14, v5
	v_lshlrev_b32_e32 v4, 16, v6
	v_and_b32_e32 v5, 0xffff0000, v6
	v_and_b32_e32 v13, 0xffff0000, v10
	v_pk_add_f32 v[4:5], v[4:5], v[12:13]
	v_lshlrev_b32_e32 v6, 16, v11
	v_cvt_pk_bf16_f32 v10, v4, v5
	v_and_b32_e32 v5, 0xffff0000, v10
	v_lshlrev_b32_e32 v4, 16, v10
	v_mul_f32_e32 v5, v5, v5
	v_fmac_f32_e32 v5, v4, v4
	v_add_f32_e32 v12, v5, v14
	v_lshlrev_b32_e32 v4, 16, v7
	v_and_b32_e32 v5, 0xffff0000, v7
	v_and_b32_e32 v7, 0xffff0000, v11
	v_pk_add_f32 v[4:5], v[4:5], v[6:7]
	s_nop 0
	v_cvt_pk_bf16_f32 v11, v4, v5
	v_and_b32_e32 v5, 0xffff0000, v11
	v_lshlrev_b32_e32 v4, 16, v11
	v_mul_f32_e32 v5, v5, v5
	v_fmac_f32_e32 v5, v4, v4
	v_add_f32_e32 v4, v5, v12
	s_nop 1
	v_add_f32_dpp v86, v4, v4 quad_perm:[1,0,3,2] row_mask:0xf bank_mask:0xf
	s_nop 1
	v_add_f32_dpp v86, v86, v86 quad_perm:[2,3,0,1] row_mask:0xf bank_mask:0xf
	s_nop 1
	v_add_f32_dpp v86, v86, v86 row_half_mirror row_mask:0xf bank_mask:0xf
	s_nop 1
	v_add_f32_dpp v86, v86, v86 row_mirror row_mask:0xf bank_mask:0xf
	s_nop 1
	v_add_f32_dpp v86, v86, v86 row_bcast:15 row_mask:0xa bank_mask:0xf
	s_waitcnt lgkmcnt(0)
	s_waitcnt lgkmcnt(0)
	s_waitcnt lgkmcnt(0)
	v_add_u32_e32 v4, 0xe0, v16
	v_ashrrev_i32_e32 v5, 31, v4
	v_lshl_add_u64 v[4:5], s[12:13], 0, v[4:5]
	v_lshlrev_b64 v[12:13], 11, v[4:5]
	s_waitcnt lgkmcnt(0)
	v_lshl_add_u64 v[12:13], s[10:11], 0, v[12:13]
	v_lshl_add_u64 v[12:13], s[16:17], 1, v[12:13]
	v_lshl_add_u64 v[12:13], v[12:13], 0, v[146:147]
	flat_store_dwordx4 v[12:13], v[8:11]
	s_and_saveexec_b64 s[18:19], s[98:99]
	s_cbranch_execz .LBB0_806
	v_lshl_add_u64 v[4:5], v[4:5], 4, s[78:79]
	v_lshl_add_u64 v[4:5], s[6:7], 2, v[4:5]
	s_waitcnt lgkmcnt(0)
	v_mov_b32_e32 v6, v86
	flat_store_dword v[4:5], v6
.LBB0_806:
	s_or_b64 exec, exec, s[18:19]
	s_waitcnt lgkmcnt(0)
	ds_read_b128 v[4:7], v26 offset:59136
	v_lshlrev_b32_e32 v10, 16, v0
	v_and_b32_e32 v11, 0xffff0000, v0
	v_add_u32_e32 v8, 0xf0, v16
	v_ashrrev_i32_e32 v9, 31, v8
	s_waitcnt lgkmcnt(0)
	v_lshlrev_b32_e32 v12, 16, v4
	v_and_b32_e32 v13, 0xffff0000, v4
	v_pk_add_f32 v[10:11], v[10:11], v[12:13]
	s_nop 0
	v_cvt_pk_bf16_f32 v4, v10, v11
	v_and_b32_e32 v10, 0xffff0000, v4
	v_lshlrev_b32_e32 v0, 16, v4
	v_mul_f32_e32 v12, v10, v10
	v_fmac_f32_e32 v12, v0, v0
	v_lshlrev_b32_e32 v0, 16, v1
	v_and_b32_e32 v1, 0xffff0000, v1
	v_lshlrev_b32_e32 v10, 16, v5
	v_and_b32_e32 v11, 0xffff0000, v5
	v_pk_add_f32 v[0:1], v[0:1], v[10:11]
	v_lshlrev_b32_e32 v10, 16, v6
	v_cvt_pk_bf16_f32 v5, v0, v1
	v_and_b32_e32 v1, 0xffff0000, v5
	v_lshlrev_b32_e32 v0, 16, v5
	v_mul_f32_e32 v1, v1, v1
	v_fmac_f32_e32 v1, v0, v0
	v_add_f32_e32 v12, v12, v1
	v_lshlrev_b32_e32 v0, 16, v2
	v_and_b32_e32 v1, 0xffff0000, v2
	v_and_b32_e32 v11, 0xffff0000, v6
	v_pk_add_f32 v[0:1], v[0:1], v[10:11]
	v_lshlrev_b32_e32 v2, 16, v7
	v_cvt_pk_bf16_f32 v6, v0, v1
	v_and_b32_e32 v1, 0xffff0000, v6
	v_lshlrev_b32_e32 v0, 16, v6
	v_mul_f32_e32 v1, v1, v1
	v_fmac_f32_e32 v1, v0, v0
	v_add_f32_e32 v10, v1, v12
	v_lshlrev_b32_e32 v0, 16, v3
	v_and_b32_e32 v1, 0xffff0000, v3
	v_and_b32_e32 v3, 0xffff0000, v7
	v_pk_add_f32 v[0:1], v[0:1], v[2:3]
	s_nop 0
	v_cvt_pk_bf16_f32 v7, v0, v1
	v_and_b32_e32 v1, 0xffff0000, v7
	v_lshlrev_b32_e32 v0, 16, v7
	v_mul_f32_e32 v1, v1, v1
	v_fmac_f32_e32 v1, v0, v0
	v_add_f32_e32 v10, v1, v10
	v_lshl_add_u64 v[0:1], s[12:13], 0, v[8:9]
	v_lshlrev_b64 v[2:3], 11, v[0:1]
	v_lshl_add_u64 v[2:3], s[10:11], 0, v[2:3]
	v_lshl_add_u64 v[2:3], s[16:17], 1, v[2:3]
	v_lshl_add_u64 v[2:3], v[2:3], 0, v[146:147]
	flat_store_dwordx4 v[2:3], v[4:7]
	s_nop 1
	v_add_f32_dpp v86, v10, v10 quad_perm:[1,0,3,2] row_mask:0xf bank_mask:0xf
	s_nop 1
	v_add_f32_dpp v86, v86, v86 quad_perm:[2,3,0,1] row_mask:0xf bank_mask:0xf
	s_nop 1
	v_add_f32_dpp v86, v86, v86 row_half_mirror row_mask:0xf bank_mask:0xf
	s_nop 1
	v_add_f32_dpp v86, v86, v86 row_mirror row_mask:0xf bank_mask:0xf
	s_nop 1
	v_add_f32_dpp v86, v86, v86 row_bcast:15 row_mask:0xa bank_mask:0xf
	s_waitcnt lgkmcnt(0)
	s_waitcnt lgkmcnt(0)
	s_waitcnt lgkmcnt(0)
	s_waitcnt lgkmcnt(0)
	s_and_saveexec_b64 s[12:13], s[98:99]
	s_cbranch_execz .LBB0_769
	v_lshl_add_u64 v[0:1], v[0:1], 4, s[78:79]
	v_lshl_add_u64 v[0:1], s[6:7], 2, v[0:1]
	s_waitcnt lgkmcnt(0)
	v_mov_b32_e32 v2, v86
	flat_store_dword v[0:1], v2
	s_branch .LBB0_769

; __global__ void __launch_bounds__(512) mega(Params p) {
;     extern __shared__ __attribute__((aligned(16))) char lds[];
;     cg::grid_group grid = cg::this_grid();
;     const int tid = threadIdx.x, wid = tid >> 6, lane = tid & 63;
	.amdhsa_kernel _Z4mega6Params
		.amdhsa_group_segment_fixed_size 0
		.amdhsa_private_segment_fixed_size 0
		.amdhsa_kernarg_size 568
		.amdhsa_user_sgpr_count 2
		.amdhsa_user_sgpr_dispatch_ptr 0
		.amdhsa_user_sgpr_queue_ptr 0
		.amdhsa_user_sgpr_kernarg_segment_ptr 1
		.amdhsa_user_sgpr_dispatch_id 0
		.amdhsa_user_sgpr_kernarg_preload_length 0
		.amdhsa_user_sgpr_kernarg_preload_offset 0
		.amdhsa_user_sgpr_private_segment_size 0
		.amdhsa_uses_dynamic_stack 0
		.amdhsa_enable_private_segment 0
		.amdhsa_system_sgpr_workgroup_id_x 1
		.amdhsa_system_sgpr_workgroup_id_y 0
		.amdhsa_system_sgpr_workgroup_id_z 0
		.amdhsa_system_sgpr_workgroup_info 0
		.amdhsa_system_vgpr_workitem_id 2
		.amdhsa_next_free_vgpr 256
		.amdhsa_next_free_sgpr 100
		.amdhsa_accum_offset 256
		.amdhsa_reserve_vcc 1
		.amdhsa_float_round_mode_32 0
		.amdhsa_float_round_mode_16_64 0
		.amdhsa_float_denorm_mode_32 3
		.amdhsa_float_denorm_mode_16_64 3
		.amdhsa_dx10_clamp 1
		.amdhsa_ieee_mode 1
		.amdhsa_fp16_overflow 0
		.amdhsa_tg_split 0
		.amdhsa_exception_fp_ieee_invalid_op 0
		.amdhsa_exception_fp_denorm_src 0
		.amdhsa_exception_fp_ieee_div_zero 0
		.amdhsa_exception_fp_ieee_overflow 0
		.amdhsa_exception_fp_ieee_underflow 0
		.amdhsa_exception_fp_ieee_inexact 0
		.amdhsa_exception_int_div_zero 0
	.end_amdhsa_kernel

; __global__ void __launch_bounds__(512) mega(Params p) {
;     extern __shared__ __attribute__((aligned(16))) char lds[];
;     cg::grid_group grid = cg::this_grid();
;     const int tid = threadIdx.x, wid = tid >> 6, lane = tid & 63;
amdhsa.kernels:
  - .agpr_count:     0
    .args:
      - .offset:         0
        .size:           312
        .value_kind:     by_value
      - .offset:         312
        .size:           4
        .value_kind:     hidden_block_count_x
      - .offset:         316
        .size:           4
        .value_kind:     hidden_block_count_y
      - .offset:         320
        .size:           4
        .value_kind:     hidden_block_count_z
      - .offset:         324
        .size:           2
        .value_kind:     hidden_group_size_x
      - .offset:         326
        .size:           2
        .value_kind:     hidden_group_size_y
      - .offset:         328
        .size:           2
        .value_kind:     hidden_group_size_z
      - .offset:         330
        .size:           2
        .value_kind:     hidden_remainder_x
      - .offset:         332
        .size:           2
        .value_kind:     hidden_remainder_y
      - .offset:         334
        .size:           2
        .value_kind:     hidden_remainder_z
      - .offset:         352
        .size:           8
        .value_kind:     hidden_global_offset_x
      - .offset:         360
        .size:           8
        .value_kind:     hidden_global_offset_y
      - .offset:         368
        .size:           8
        .value_kind:     hidden_global_offset_z
      - .offset:         376
        .size:           2
        .value_kind:     hidden_grid_dims
      - .offset:         400
        .size:           8
        .value_kind:     hidden_multigrid_sync_arg
      - .offset:         432
        .size:           4
        .value_kind:     hidden_dynamic_lds_size
    .group_segment_fixed_size: 0
    .kernarg_segment_align: 8
    .kernarg_segment_size: 568
    .language:       OpenCL C
    .language_version:
      - 2
      - 0
    .max_flat_workgroup_size: 512
    .name:           _Z4mega6Params
    .private_segment_fixed_size: 0
    .sgpr_count:     106
    .sgpr_spill_count: 84
    .symbol:         _Z4mega6Params.kd
    .uniform_work_group_size: 1
    .uses_dynamic_stack: false
    .vgpr_count:     256
    .vgpr_spill_count: 0
    .wavefront_size: 64
